# all flat_load/flat_store (generic address space) converted to global_load/global_store: no LGKM coupling with LDS traffic
# speedup vs baseline: 1.0065x; 1.0029x over previous
; __device__ __forceinline__ unsigned cvt_pk_bf16_m(float lo, float hi) { const f32x2_cv v = {lo, hi}; const bf16x2_cv b = __builtin_convertvector(v, bf16x2_cv); return __builtin_bit_cast(unsigned, b); }
; __device__ __forceinline__ void attn_unit_mla(LAS unsigned char* lds, const AttnDesc& A, int tid_in, int wid, int lane_in) {
;     ...
;     const float ltot = lrun + __shfl_xor(lrun, 32);
;     const float inv = 1.0f / ltot;
;     bf16_t* op = A.o + (size_t)r32 * A.ldo + 4 * h;
; #pragma unroll
;     for (int g4 = 0; g4 < 4; ++g4) {
;         u32x2 w;
;         w.x = cvt_pk_bf16_m(o0[4 * g4 + 0] * inv, o0[4 * g4 + 1] * inv); w.y = cvt_pk_bf16_m(o0[4 * g4 + 2] * inv, o0[4 * g4 + 3] * inv);
;         *(u32x2*)(op + 8 * g4) = w;
;         w.x = cvt_pk_bf16_m(o1[4 * g4 + 0] * inv, o1[4 * g4 + 1] * inv); w.y = cvt_pk_bf16_m(o1[4 * g4 + 2] * inv, o1[4 * g4 + 3] * inv);
;         *(u32x2*)(op + 32 + 8 * g4) = w;
;     }
;     __syncthreads();
.LBB0_27:
	ds_bpermute_b32 v0, v174, v178
	s_lshl_b64 s[0:1], s[4:5], 11
	v_readlane_b32 s4, v254, 16
	v_readlane_b32 s5, v254, 17
	s_add_u32 s4, s4, s0
	s_waitcnt lgkmcnt(0)
	v_add_f32_e32 v0, v178, v0
	s_addc_u32 s5, s5, s1
	v_div_scale_f32 v34, s[0:1], v0, v0, 1.0
	v_rcp_f32_e32 v35, v34
	s_lshl_b32 s0, s45, 7
	s_add_u32 s0, s4, s0
	s_addc_u32 s1, s5, 0
	v_fma_f32 v36, -v34, v35, 1.0
	v_fmac_f32_e32 v35, v36, v35
	v_div_scale_f32 v36, vcc, 1.0, v0, 1.0
	v_mul_f32_e32 v37, v36, v35
	v_fma_f32 v38, -v34, v37, v36
	v_fmac_f32_e32 v37, v38, v35
	v_fma_f32 v34, -v34, v37, v36
	v_div_fmas_f32 v34, v34, v35, v37
	v_div_fixup_f32 v34, v34, v0, 1.0
	v_lshlrev_b32_e32 v0, 11, v156
	v_lshl_add_u64 v[36:37], s[0:1], 0, v[0:1]
	v_lshlrev_b32_e32 v0, 3, v157
	v_pk_mul_f32 v[2:3], v[2:3], v[34:35] op_sel_hi:[1,0]
	v_pk_mul_f32 v[4:5], v[4:5], v[34:35] op_sel_hi:[1,0]
	v_lshl_add_u64 v[36:37], v[36:37], 0, v[0:1]
	v_cvt_pk_bf16_f32 v2, v2, v3
	v_cvt_pk_bf16_f32 v3, v4, v5
	global_store_dwordx2 v[36:37], v[2:3], off offset:1024
	v_pk_mul_f32 v[2:3], v[18:19], v[34:35] op_sel_hi:[1,0]
	v_pk_mul_f32 v[4:5], v[20:21], v[34:35] op_sel_hi:[1,0]
	v_cvt_pk_bf16_f32 v2, v2, v3
	v_cvt_pk_bf16_f32 v3, v4, v5
	global_store_dwordx2 v[36:37], v[2:3], off offset:1088
	v_pk_mul_f32 v[2:3], v[6:7], v[34:35] op_sel_hi:[1,0]
	v_pk_mul_f32 v[4:5], v[8:9], v[34:35] op_sel_hi:[1,0]
	v_cvt_pk_bf16_f32 v2, v2, v3
	v_cvt_pk_bf16_f32 v3, v4, v5
	global_store_dwordx2 v[36:37], v[2:3], off offset:1040
	v_pk_mul_f32 v[2:3], v[22:23], v[34:35] op_sel_hi:[1,0]
	v_pk_mul_f32 v[4:5], v[24:25], v[34:35] op_sel_hi:[1,0]
	v_cvt_pk_bf16_f32 v2, v2, v3
	v_cvt_pk_bf16_f32 v3, v4, v5
	global_store_dwordx2 v[36:37], v[2:3], off offset:1104
	v_pk_mul_f32 v[2:3], v[10:11], v[34:35] op_sel_hi:[1,0]
	v_pk_mul_f32 v[4:5], v[12:13], v[34:35] op_sel_hi:[1,0]
	v_cvt_pk_bf16_f32 v2, v2, v3
	v_cvt_pk_bf16_f32 v3, v4, v5
	global_store_dwordx2 v[36:37], v[2:3], off offset:1056
	v_pk_mul_f32 v[2:3], v[26:27], v[34:35] op_sel_hi:[1,0]
	v_pk_mul_f32 v[4:5], v[28:29], v[34:35] op_sel_hi:[1,0]
	v_cvt_pk_bf16_f32 v2, v2, v3
	v_cvt_pk_bf16_f32 v3, v4, v5
	global_store_dwordx2 v[36:37], v[2:3], off offset:1120
	v_pk_mul_f32 v[2:3], v[14:15], v[34:35] op_sel_hi:[1,0]
	v_pk_mul_f32 v[4:5], v[16:17], v[34:35] op_sel_hi:[1,0]
	v_cvt_pk_bf16_f32 v2, v2, v3
	v_cvt_pk_bf16_f32 v3, v4, v5
	global_store_dwordx2 v[36:37], v[2:3], off offset:1072
	v_pk_mul_f32 v[2:3], v[30:31], v[34:35] op_sel_hi:[1,0]
	v_pk_mul_f32 v[4:5], v[32:33], v[34:35] op_sel_hi:[1,0]
	v_cvt_pk_bf16_f32 v2, v2, v3
	v_cvt_pk_bf16_f32 v3, v4, v5
	global_store_dwordx2 v[36:37], v[2:3], off offset:1136
	s_waitcnt lgkmcnt(0)
	s_barrier

; #define LAS __attribute__((address_space(3)))
; template <int DQ>
; __device__ __forceinline__ void attn_unit(LAS unsigned char* lds, const AttnDesc& A, int tid_in, int wid, int lane_in) {
;     constexpr int KSTR = (DQ + 8) * 2, NS = DQ / 16;
;     int tid = tid_in; asm volatile("" : "+v"(tid));
;     const int lane = tid & 63; (void)lane_in;
;     const int r32 = lane & 31, h = lane >> 5;
;     const int nt = A.nloc + 4;
;     bf16x8 qf[NS];
; #pragma unroll
;     for (int s = 0; s < NS; ++s) qf[s] = *(const bf16x8*)(A.q + (size_t)r32 * A.ldq + 16 * s + 8 * h);
;     f32x16 o0, o1;
; #pragma unroll
;     for (int r = 0; r < 16; ++r) { o0[r] = 0.f; o1[r] = 0.f; }
;     float mrun = -1e30f, lrun = 0.f;
;     f32x16 zero16;
; #pragma unroll
;     for (int r = 0; r < 16; ++r) zero16[r] = 0.f;
;     asm volatile("" : "+v"(zero16));
;     const int skey = tid >> 3, sch = tid & 7;
;     u32x4 kreg, vreg, krreg = (u32x4){0u, 0u, 0u, 0u};
;     {
;         const int row0 = (0 < A.nloc) ? A.loc_row0 : A.ctx_row0;
;         kreg = *(const u32x4*)(A.k + (size_t)(row0 + skey) * A.ldk + 8 * sch);
;         vreg = *(const u32x4*)(A.v + (size_t)(row0 + skey) * A.ldv + 8 * sch);
;         if (DQ == 96 && tid < 256) krreg = *(const u32x4*)(A.kr + (size_t)(row0 + (tid >> 2)) * A.ldkr + 8 * (tid & 3));
;     }
;     const LAS float* rpbl = (const LAS float*)(lds + ATT_RPB);
;     const int vtr_off = ((lane & 15) >> 2) * 64 + (16 * ((lane >> 4) & 1) + 4 * (lane & 3)) * 2 + 4 * h * 64;
;     ...
;             if (loc && A.mode == 1) {
;                 const int qc = 32 * (wid & 1) + r32;
;                 const int w0 = min(max(qc - 8, 0), 48);
;                 const int rbase = (A.a0 + t - A.a1 + 7) * 31;
; #pragma unroll
;                 for (int r = 0; r < 16; ++r) {
;                     const int kc = (r & 3) + 8 * (r >> 2) + 4 * h;
;                     { const int dc = min(max(kc - qc + 15, 0), 30); const bool ok = (unsigned)(kc - w0) < 16u; const float bv = rpbl[rbase + dc]; s0[r] = ok ? s0[r] + bv : -1e30f; }
;                     { const int kc2 = kc + 32; const int dc = min(max(kc2 - qc + 15, 0), 30); const bool ok = (unsigned)(kc2 - w0) < 16u; const float bv = rpbl[rbase + dc]; s1[r] = ok ? s1[r] + bv : -1e30f; }
.LBB0_54:
	v_mov_b32_e32 v32, v154
	v_mov_b32_e32 v157, v1
	v_and_b32_e32 v165, 31, v32
	v_mul_u32_u24_e32 v0, s40, v165
	v_bfe_u32 v33, v32, 5, 1
	v_lshlrev_b32_e32 v0, 1, v0
	v_lshl_add_u64 v[2:3], s[0:1], 0, v[0:1]
	v_lshlrev_b32_e32 v156, 4, v33
	v_lshl_add_u64 v[2:3], v[2:3], 0, v[156:157]
	global_load_dwordx4 v[130:133], v[2:3], off
	global_load_dwordx4 v[134:137], v[2:3], off offset:32
	global_load_dwordx4 v[138:141], v[2:3], off offset:64
	global_load_dwordx4 v[142:145], v[2:3], off offset:96
	v_mov_b32_e32 v14, v1
	v_mov_b32_e32 v15, v1
	v_mov_b32_e32 v0, v1
	v_mov_b32_e32 v2, v1
	v_mov_b32_e32 v3, v1
	v_mov_b32_e32 v4, v1
	v_mov_b32_e32 v5, v1
	v_mov_b32_e32 v6, v1
	v_mov_b32_e32 v7, v1
	v_mov_b32_e32 v8, v1
	v_mov_b32_e32 v9, v1
	v_mov_b32_e32 v10, v1
	v_mov_b32_e32 v11, v1
	v_mov_b32_e32 v12, v1
	v_mov_b32_e32 v13, v1
	v_mov_b64_e32 v[30:31], v[14:15]
	v_mov_b64_e32 v[28:29], v[12:13]
	v_mov_b64_e32 v[26:27], v[10:11]
	v_mov_b64_e32 v[24:25], v[8:9]
	v_mov_b64_e32 v[22:23], v[6:7]
	v_mov_b64_e32 v[20:21], v[4:5]
	v_mov_b64_e32 v[18:19], v[2:3]
	v_mov_b64_e32 v[16:17], v[0:1]
	s_mov_b32 s41, 0
	s_cmp_lt_i32 s59, -3
	v_lshlrev_b32_e32 v157, 2, v33
	s_cbranch_scc1 .LBB0_137
	s_lshl_b32 s60, s8, 8
	s_add_i32 s56, s59, 4
	s_add_i32 s60, s60, 0x8000
	v_ashrrev_i32_e32 v38, 3, v32
	v_lshlrev_b32_e32 v39, 4, v32
	v_and_b32_e32 v34, 16, v32
	v_lshlrev_b32_e32 v35, 2, v32
	s_cmp_gt_i32 s59, 0
	v_lshlrev_b32_e32 v32, 10, v32
	s_cselect_b32 s0, s57, s60
	v_and_b32_e32 v174, 0x1000, v32
	v_or_b32_e32 v32, s22, v165
	v_and_or_b32 v34, v35, 12, v34
	v_lshlrev_b32_e32 v172, 8, v33
	v_add_u32_e32 v33, s0, v38
	v_sub_u32_e64 v32, v32, 8 clamp
	v_lshlrev_b32_e32 v171, 1, v34
	v_mad_i64_i32 v[34:35], s[0:1], s40, v33, 0
	v_min_u32_e32 v32, 48, v32
	v_or_b32_e32 v33, 1, v157
	v_lshlrev_b64 v[34:35], 1, v[34:35]
	s_movk_i32 s0, 0x90
	v_sub_u32_e32 v33, v33, v32
	v_lshl_add_u64 v[36:37], s[50:51], 0, v[34:35]
	v_and_b32_e32 v158, 0x70, v39
	v_mov_b32_e32 v159, v1
	v_lshl_add_u64 v[34:35], s[48:49], 0, v[34:35]
	v_mul_lo_u32 v173, v38, s0
	v_cmp_gt_u32_e64 s[0:1], 16, v33
	v_or_b32_e32 v33, 33, v157
	v_lshl_add_u64 v[34:35], v[34:35], 0, v[158:159]
	v_writelane_b32 v255, s0, 12
	v_sub_u32_e32 v33, v33, v32
	global_load_dwordx4 v[150:153], v[34:35], off
	v_or_b32_e32 v34, 2, v157
	v_writelane_b32 v255, s1, 13
	v_cmp_gt_u32_e64 s[0:1], 16, v33
	v_sub_u32_e32 v33, v34, v32
	v_or_b32_e32 v35, 3, v157
	v_writelane_b32 v255, s0, 14
	v_lshl_add_u64 v[36:37], v[36:37], 0, v[158:159]
	global_load_dwordx4 v[146:149], v[36:37], off
	v_writelane_b32 v255, s1, 15
	v_cmp_gt_u32_e64 s[0:1], 16, v33
	v_or_b32_e32 v33, 34, v157
	v_sub_u32_e32 v33, v33, v32
	v_writelane_b32 v255, s0, 16
	v_or_b32_e32 v36, 8, v157
	v_or_b32_e32 v37, 9, v157
	v_writelane_b32 v255, s1, 17
	v_cmp_gt_u32_e64 s[0:1], 16, v33
	v_sub_u32_e32 v33, v35, v32
	v_and_b32_e32 v65, 0xc0, v39
	v_writelane_b32 v255, s0, 18
	v_and_b32_e32 v176, 48, v39
	v_or_b32_e32 v39, 10, v157
	v_writelane_b32 v255, s1, 19
	v_cmp_gt_u32_e64 s[0:1], 16, v33
	v_or_b32_e32 v33, 35, v157
	v_sub_u32_e32 v33, v33, v32
	v_writelane_b32 v255, s0, 20
	v_or_b32_e32 v40, 11, v157
	v_or_b32_e32 v41, 16, v157
	v_writelane_b32 v255, s1, 21
	v_cmp_gt_u32_e64 s[0:1], 16, v33
	v_sub_u32_e32 v33, v36, v32
	v_or_b32_e32 v42, 17, v157
	v_writelane_b32 v255, s0, 22
	v_or_b32_e32 v43, 18, v157
	v_or_b32_e32 v44, 19, v157
	v_writelane_b32 v255, s1, 23
	v_cmp_gt_u32_e64 s[0:1], 16, v33
	v_or_b32_e32 v33, 40, v157
	v_sub_u32_e32 v33, v33, v32
	v_writelane_b32 v255, s0, 24
	v_or_b32_e32 v45, 24, v157
	s_mov_b64 s[68:69], s[92:93]
	v_writelane_b32 v255, s1, 25
	v_cmp_gt_u32_e64 s[0:1], 16, v33
	v_sub_u32_e32 v33, v37, v32
	v_or_b32_e32 v46, 25, v157
	v_writelane_b32 v255, s0, 26
	s_mov_b64 s[70:71], s[94:95]
	v_or_b32_e32 v47, 26, v157
	v_writelane_b32 v255, s1, 27
	v_cmp_gt_u32_e64 s[0:1], 16, v33
	v_or_b32_e32 v33, 41, v157
	v_sub_u32_e32 v33, v33, v32
	v_writelane_b32 v255, s0, 28
	s_mov_b64 s[64:65], s[98:99]
	v_or_b32_e32 v48, 27, v157
	v_writelane_b32 v255, s1, 29
	v_cmp_gt_u32_e64 s[0:1], 16, v33
	v_sub_u32_e32 v33, v39, v32
	v_sub_u32_e32 v49, v157, v32
	v_writelane_b32 v255, s0, 30
	v_cmp_gt_u32_e64 s[72:73], 16, v49
	v_or_b32_e32 v49, 32, v157
	v_writelane_b32 v255, s1, 31
	v_cmp_gt_u32_e64 s[0:1], 16, v33
	v_or_b32_e32 v33, 42, v157
	v_sub_u32_e32 v33, v33, v32
	v_writelane_b32 v255, s0, 32
	s_cmp_eq_u32 s53, 1
	v_sub_u32_e32 v49, v49, v32
	v_writelane_b32 v255, s1, 33
	v_cmp_gt_u32_e64 s[0:1], 16, v33
	v_sub_u32_e32 v33, v40, v32
	s_cselect_b64 s[84:85], -1, 0
	v_writelane_b32 v255, s0, 34
	s_add_i32 s58, s61, 8
	s_cmp_eq_u32 s53, 2
	v_writelane_b32 v255, s1, 35
	v_cmp_gt_u32_e64 s[0:1], 16, v33
	v_or_b32_e32 v33, 43, v157
	v_sub_u32_e32 v33, v33, v32
	v_writelane_b32 v255, s0, 36
	v_readlane_b32 s18, v254, 50
	v_lshl_add_u64 v[160:161], s[48:49], 0, v[158:159]
	v_writelane_b32 v255, s1, 37
	v_cmp_gt_u32_e64 s[0:1], 16, v33
	v_sub_u32_e32 v33, v41, v32
	v_lshl_add_u64 v[162:163], s[50:51], 0, v[158:159]
	v_writelane_b32 v255, s0, 38
	s_cselect_b64 s[86:87], -1, 0
	s_add_i32 s63, s52, 0xffffff9f
	v_writelane_b32 v255, s1, 39
	v_cmp_gt_u32_e64 s[0:1], 16, v33
	v_or_b32_e32 v33, 48, v157
	v_sub_u32_e32 v33, v33, v32
	v_writelane_b32 v255, s0, 40
	s_add_i32 s80, s52, 0x41
	v_lshlrev_b32_e32 v175, 6, v38
	v_writelane_b32 v255, s1, 41
	v_cmp_gt_u32_e64 s[0:1], 16, v33
	v_sub_u32_e32 v33, v42, v32
	v_cmp_gt_u32_e64 s[74:75], 16, v49
	v_writelane_b32 v255, s0, 42
	v_add_u32_e32 v211, 64, v38
	v_mul_u32_u24_e32 v177, 0x90, v165
	v_writelane_b32 v255, s1, 43
	v_cmp_gt_u32_e64 s[0:1], 16, v33
	v_or_b32_e32 v33, 49, v157
	v_sub_u32_e32 v33, v33, v32
; template <int DQ>
; __device__ __forceinline__ void attn_unit(LAS unsigned char* lds, const AttnDesc& A, int tid_in, int wid, int lane_in) {
;     ...
;             if (loc && A.mode == 1) {
;                 const int qc = 32 * (wid & 1) + r32;
;                 const int w0 = min(max(qc - 8, 0), 48);
;                 const int rbase = (A.a0 + t - A.a1 + 7) * 31;
; #pragma unroll
;                 for (int r = 0; r < 16; ++r) {
;                     const int kc = (r & 3) + 8 * (r >> 2) + 4 * h;
;                     { const int dc = min(max(kc - qc + 15, 0), 30); const bool ok = (unsigned)(kc - w0) < 16u; const float bv = rpbl[rbase + dc]; s0[r] = ok ? s0[r] + bv : -1e30f; }
;                     { const int kc2 = kc + 32; const int dc = min(max(kc2 - qc + 15, 0), 30); const bool ok = (unsigned)(kc2 - w0) < 16u; const float bv = rpbl[rbase + dc]; s1[r] = ok ? s1[r] + bv : -1e30f; }
;                 }
	v_writelane_b32 v255, s0, 44
	v_mov_b32_e32 v212, 0xf149f2ca
	v_mov_b32_e32 v213, 0xf149f2ca
	v_mov_b32_e32 v64, 0
	v_writelane_b32 v255, s1, 45
	v_cmp_gt_u32_e64 s[0:1], 16, v33
	v_sub_u32_e32 v33, v43, v32
	s_mov_b32 s82, 0
	v_writelane_b32 v255, s0, 46
	s_nop 1
	v_writelane_b32 v255, s1, 47
	v_cmp_gt_u32_e64 s[0:1], 16, v33
	v_or_b32_e32 v33, 50, v157
	v_sub_u32_e32 v33, v33, v32
	v_writelane_b32 v255, s0, 48
	s_nop 1
	v_writelane_b32 v255, s1, 49
	v_cmp_gt_u32_e64 s[0:1], 16, v33
	v_sub_u32_e32 v33, v44, v32
	v_cmp_gt_u32_e64 s[88:89], 16, v33
	v_or_b32_e32 v33, 51, v157
	v_sub_u32_e32 v33, v33, v32
	v_cmp_gt_u32_e64 s[90:91], 16, v33
	v_sub_u32_e32 v33, v45, v32
	v_cmp_gt_u32_e64 s[92:93], 16, v33
	v_or_b32_e32 v33, 56, v157
	v_sub_u32_e32 v33, v33, v32
	v_cmp_gt_u32_e64 s[94:95], 16, v33
	v_sub_u32_e32 v33, v46, v32
	v_cmp_gt_u32_e64 s[96:97], 16, v33
	v_or_b32_e32 v33, 57, v157
	v_sub_u32_e32 v33, v33, v32
	v_writelane_b32 v255, s0, 50
	v_cmp_gt_u32_e64 s[98:99], 16, v33
	v_sub_u32_e32 v33, v47, v32
	v_writelane_b32 v255, s1, 51
	v_cmp_gt_u32_e64 s[0:1], 16, v33
	v_or_b32_e32 v33, 58, v157
	v_sub_u32_e32 v33, v33, v32
	v_cmp_gt_u32_e64 s[4:5], 16, v33
	v_sub_u32_e32 v33, v48, v32
	v_cmp_gt_u32_e64 s[6:7], 16, v33
	v_or_b32_e32 v33, 59, v157
	v_sub_u32_e32 v32, v33, v32
	v_cmp_gt_u32_e64 s[8:9], 16, v32
	v_add_u32_e32 v32, s52, v165
	v_sub_u32_e32 v159, v157, v32
	v_add_u32_e32 v32, s18, v157
	s_mul_i32 s18, s55, 0x7c
	s_mulk_i32 s52, 0x7c
	v_sub_u32_e32 v32, v32, v165
	s_sub_i32 s18, s18, s52
	v_max_i32_e32 v32, -15, v32
	s_add_i32 s81, s18, 0
	v_readlane_b32 s18, v254, 51
	v_lshlrev_b32_e32 v178, 2, v32
	v_mov_b64_e32 v[62:63], v[14:15]
	v_add_u32_e32 v32, s18, v157
	v_sub_u32_e32 v32, v32, v165
	v_max_i32_e32 v32, -15, v32
	v_add_u32_e32 v32, 15, v32
	v_min_u32_e32 v32, 30, v32
	v_readlane_b32 s18, v254, 52
	v_lshlrev_b32_e32 v179, 2, v32
	v_mov_b64_e32 v[60:61], v[12:13]
	v_add_u32_e32 v32, s18, v157
	v_sub_u32_e32 v32, v32, v165
	v_max_i32_e32 v32, -15, v32
	v_readlane_b32 s18, v254, 53
	v_lshlrev_b32_e32 v180, 2, v32
	v_mov_b64_e32 v[58:59], v[10:11]
	v_add_u32_e32 v32, s18, v157
	v_sub_u32_e32 v32, v32, v165
	v_max_i32_e32 v32, -15, v32
	v_add_u32_e32 v32, 15, v32
	v_min_u32_e32 v32, 30, v32
	v_readlane_b32 s18, v254, 54
	v_lshlrev_b32_e32 v182, 2, v32
	v_mov_b64_e32 v[56:57], v[8:9]
	v_add_u32_e32 v32, s18, v157
	v_sub_u32_e32 v32, v32, v165
	v_max_i32_e32 v32, -15, v32
	v_readlane_b32 s18, v254, 55
	v_lshlrev_b32_e32 v183, 2, v32
	v_mov_b64_e32 v[54:55], v[6:7]
	v_add_u32_e32 v32, s18, v157
	v_sub_u32_e32 v32, v32, v165
	v_max_i32_e32 v32, -15, v32
	v_add_u32_e32 v32, 15, v32
	v_min_u32_e32 v32, 30, v32
	v_readlane_b32 s18, v254, 56
	v_lshlrev_b32_e32 v184, 2, v32
	v_mov_b64_e32 v[52:53], v[4:5]
	v_add_u32_e32 v32, s18, v157
	v_sub_u32_e32 v32, v32, v165
	v_max_i32_e32 v32, -15, v32
	v_readlane_b32 s18, v254, 57
	v_lshlrev_b32_e32 v185, 2, v32
	v_mov_b64_e32 v[50:51], v[2:3]
	v_add_u32_e32 v32, s18, v157
	v_sub_u32_e32 v32, v32, v165
	v_max_i32_e32 v32, -15, v32
	v_add_u32_e32 v32, 15, v32
	v_min_u32_e32 v32, 30, v32
	v_readlane_b32 s18, v254, 58
	v_lshlrev_b32_e32 v186, 2, v32
	v_mov_b64_e32 v[48:49], v[0:1]
	v_add_u32_e32 v32, s18, v157
	v_sub_u32_e32 v32, v32, v165
	v_max_i32_e32 v32, -15, v32
	v_readlane_b32 s18, v254, 59
	v_lshlrev_b32_e32 v187, 2, v32
	s_nop 0
	v_add_u32_e32 v32, s18, v157
	v_sub_u32_e32 v32, v32, v165
	v_max_i32_e32 v32, -15, v32
	v_add_u32_e32 v32, 15, v32
	v_min_u32_e32 v32, 30, v32
	v_readlane_b32 s18, v254, 60
	v_lshlrev_b32_e32 v188, 2, v32
	s_nop 0
	v_add_u32_e32 v32, s18, v157
	v_sub_u32_e32 v32, v32, v165
	v_max_i32_e32 v32, -15, v32
	v_readlane_b32 s18, v254, 61
	v_lshlrev_b32_e32 v189, 2, v32
	s_nop 0
	v_add_u32_e32 v32, s18, v157
	v_sub_u32_e32 v32, v32, v165
	v_max_i32_e32 v32, -15, v32
	v_add_u32_e32 v32, 15, v32
	v_min_u32_e32 v32, 30, v32
	v_readlane_b32 s18, v254, 62
	v_lshlrev_b32_e32 v190, 2, v32
	s_nop 0
	v_add_u32_e32 v32, s18, v157
	v_sub_u32_e32 v32, v32, v165
	v_max_i32_e32 v32, -15, v32
	v_readlane_b32 s18, v254, 63
	v_lshlrev_b32_e32 v191, 2, v32
	s_nop 0
	v_add_u32_e32 v32, s18, v157
	v_sub_u32_e32 v32, v32, v165
	v_max_i32_e32 v32, -15, v32
	v_add_u32_e32 v32, 15, v32
	v_min_u32_e32 v32, 30, v32
	v_readlane_b32 s18, v255, 0
	v_lshlrev_b32_e32 v192, 2, v32
	s_nop 0
	v_add_u32_e32 v32, s18, v157
	v_sub_u32_e32 v32, v32, v165
	v_max_i32_e32 v32, -15, v32
	v_readlane_b32 s18, v255, 1
	v_lshlrev_b32_e32 v193, 2, v32
	s_nop 0
	v_add_u32_e32 v32, s18, v157
	v_sub_u32_e32 v32, v32, v165
	v_max_i32_e32 v32, -15, v32
	v_add_u32_e32 v32, 15, v32
	v_min_u32_e32 v32, 30, v32
	v_readlane_b32 s18, v255, 2
	v_lshlrev_b32_e32 v194, 2, v32
	s_nop 0
	v_add_u32_e32 v32, s18, v157
	v_sub_u32_e32 v32, v32, v165
	v_max_i32_e32 v32, -15, v32
	v_add_u32_e32 v32, 15, v32
	v_min_u32_e32 v32, 30, v32
	v_readlane_b32 s18, v255, 3
	v_lshlrev_b32_e32 v195, 2, v32
	s_nop 0
	v_add_u32_e32 v32, s18, v157
	v_sub_u32_e32 v32, v32, v165
	v_min_u32_e32 v32, 30, v32
	v_readlane_b32 s18, v255, 4
	v_lshlrev_b32_e32 v196, 2, v32
	s_nop 0
	v_add_u32_e32 v32, s18, v157
	v_sub_u32_e32 v32, v32, v165
	v_max_i32_e32 v32, -15, v32
	v_add_u32_e32 v32, 15, v32
	v_min_u32_e32 v32, 30, v32
	v_readlane_b32 s18, v255, 5
	v_lshlrev_b32_e32 v197, 2, v32
	s_nop 0
	v_add_u32_e32 v32, s18, v157
	v_sub_u32_e32 v32, v32, v165
	v_min_u32_e32 v32, 30, v32
	v_readlane_b32 s18, v255, 6
	v_lshlrev_b32_e32 v198, 2, v32
	s_nop 0
	v_add_u32_e32 v32, s18, v157
	v_sub_u32_e32 v32, v32, v165
	v_max_i32_e32 v32, -15, v32
	v_add_u32_e32 v32, 15, v32
	v_min_u32_e32 v32, 30, v32
	v_readlane_b32 s18, v255, 7
	v_lshlrev_b32_e32 v199, 2, v32
; #define LAS __attribute__((address_space(3)))
; template <int DQ>
; __device__ __forceinline__ void attn_unit(LAS unsigned char* lds, const AttnDesc& A, int tid_in, int wid, int lane_in) {
;     ...
;     for (int t = 0; t < nt; ++t) {
;         LAS unsigned char* kb = lds + (t & 1) * ATT_KBUF;
;         LAS unsigned char* vb = lds + ATT_VOFF + (t & 1) * 8192;
;         *(LAS u32x4*)(kb + skey * KSTR + sch * 16) = kreg;
;         if (DQ == 96 && tid < 256) *(LAS u32x4*)(kb + (tid >> 2) * KSTR + 128 + (tid & 3) * 16) = krreg;
;         *(LAS u32x4*)(vb + (sch >> 2) * 4096 + skey * 64 + (sch & 3) * 16) = vreg;
;         __syncthreads();
;         if (t + 1 < nt) {
;             const int t1 = t + 1;
;             const int row0 = (t1 < A.nloc) ? A.loc_row0 + 64 * t1 : A.ctx_row0 + 64 * (t1 - A.nloc);
;             kreg = *(const u32x4*)(A.k + (size_t)(row0 + skey) * A.ldk + 8 * sch);
;             vreg = *(const u32x4*)(A.v + (size_t)(row0 + skey) * A.ldv + 8 * sch);
;             if (DQ == 96 && tid < 256) krreg = *(const u32x4*)(A.kr + (size_t)(row0 + (tid >> 2)) * A.ldkr + 8 * (tid & 3));
;         }
;     ...
;             if (loc && A.mode == 1) {
;                 const int qc = 32 * (wid & 1) + r32;
;                 const int w0 = min(max(qc - 8, 0), 48);
;                 const int rbase = (A.a0 + t - A.a1 + 7) * 31;
; #pragma unroll
;                 for (int r = 0; r < 16; ++r) {
;                     const int kc = (r & 3) + 8 * (r >> 2) + 4 * h;
;                     { const int dc = min(max(kc - qc + 15, 0), 30); const bool ok = (unsigned)(kc - w0) < 16u; const float bv = rpbl[rbase + dc]; s0[r] = ok ? s0[r] + bv : -1e30f; }
;                     { const int kc2 = kc + 32; const int dc = min(max(kc2 - qc + 15, 0), 30); const bool ok = (unsigned)(kc2 - w0) < 16u; const float bv = rpbl[rbase + dc]; s1[r] = ok ? s1[r] + bv : -1e30f; }
;                 }
	s_nop 0
	v_add_u32_e32 v32, s18, v157
	v_sub_u32_e32 v32, v32, v165
	v_min_u32_e32 v32, 30, v32
	v_readlane_b32 s18, v255, 8
	v_lshlrev_b32_e32 v200, 2, v32
	s_nop 0
	v_add_u32_e32 v32, s18, v157
	v_sub_u32_e32 v32, v32, v165
	v_max_i32_e32 v32, -15, v32
	v_add_u32_e32 v32, 15, v32
	v_min_u32_e32 v32, 30, v32
	v_readlane_b32 s18, v255, 9
	v_lshlrev_b32_e32 v201, 2, v32
	s_nop 0
	v_add_u32_e32 v32, s18, v157
	v_sub_u32_e32 v32, v32, v165
	v_min_u32_e32 v32, 30, v32
	v_lshlrev_b32_e32 v202, 2, v32
	v_add_u32_e32 v32, s21, v157
	v_sub_u32_e32 v32, v32, v165
	v_max_i32_e32 v32, -15, v32
	v_add_u32_e32 v32, 15, v32
	v_min_u32_e32 v32, 30, v32
	v_lshlrev_b32_e32 v203, 2, v32
	v_add_u32_e32 v32, s23, v157
	v_sub_u32_e32 v32, v32, v165
	v_min_u32_e32 v32, 30, v32
	v_lshlrev_b32_e32 v204, 2, v32
	v_add_u32_e32 v32, s24, v157
	v_sub_u32_e32 v32, v32, v165
	v_max_i32_e32 v32, -15, v32
	v_add_u32_e32 v32, 15, v32
	v_min_u32_e32 v32, 30, v32
	v_lshlrev_b32_e32 v205, 2, v32
	v_add_u32_e32 v32, s25, v157
	v_sub_u32_e32 v32, v32, v165
	v_min_u32_e32 v32, 30, v32
	v_lshlrev_b32_e32 v206, 2, v32
	v_add_u32_e32 v32, s26, v157
	v_sub_u32_e32 v32, v32, v165
	v_max_i32_e32 v32, -15, v32
	v_add_u32_e32 v32, 15, v32
	v_min_u32_e32 v32, 30, v32
	v_lshlrev_b32_e32 v207, 2, v32
	v_add_u32_e32 v32, s27, v157
	v_sub_u32_e32 v32, v32, v165
	v_min_u32_e32 v32, 30, v32
	v_lshlrev_b32_e32 v208, 2, v32
	v_add_u32_e32 v32, s31, v157
	v_sub_u32_e32 v32, v32, v165
	v_max_i32_e32 v32, -15, v32
	v_add_u32_e32 v32, 15, v32
	v_min_u32_e32 v32, 30, v32
	v_lshlrev_b32_e32 v209, 2, v32
	v_add_u32_e32 v32, s46, v157
	v_sub_u32_e32 v32, v32, v165
	v_min_u32_e32 v32, 30, v32
	v_lshlrev_b32_e32 v210, 2, v32
	v_mov_b64_e32 v[46:47], v[14:15]
	v_mov_b64_e32 v[44:45], v[12:13]
	v_mov_b64_e32 v[42:43], v[10:11]
	v_mov_b64_e32 v[40:41], v[8:9]
	v_mov_b64_e32 v[38:39], v[6:7]
	v_mov_b64_e32 v[36:37], v[4:5]
	v_mov_b64_e32 v[34:35], v[2:3]
	v_mov_b64_e32 v[32:33], v[0:1]
	v_min_u32_e32 v0, 464, v236
	v_lshlrev_b32_e32 v0, 2, v0
	ds_write_b32 v0, v241 offset:44868
	v_mov_b32_e32 v2, 1800
	v_mov_b32_e32 v3, 1860
	v_cndmask_b32_e64 v178, v2, v178, s[72:73]
	v_cndmask_b32_e64 v179, v3, v179, s[74:75]
	v_readlane_b32 s50, v255, 12
	v_readlane_b32 s51, v255, 13
	s_nop 1
	v_cndmask_b32_e64 v180, v2, v180, s[50:51]
	v_readlane_b32 s50, v255, 14
	v_readlane_b32 s51, v255, 15
	s_nop 1
	v_cndmask_b32_e64 v182, v3, v182, s[50:51]
	v_readlane_b32 s50, v255, 16
	v_readlane_b32 s51, v255, 17
	s_nop 1
	v_cndmask_b32_e64 v183, v2, v183, s[50:51]
	v_readlane_b32 s50, v255, 18
	v_readlane_b32 s51, v255, 19
	s_nop 1
	v_cndmask_b32_e64 v184, v3, v184, s[50:51]
	v_readlane_b32 s50, v255, 20
	v_readlane_b32 s51, v255, 21
	s_nop 1
	v_cndmask_b32_e64 v185, v2, v185, s[50:51]
	v_readlane_b32 s50, v255, 22
	v_readlane_b32 s51, v255, 23
	s_nop 1
	v_cndmask_b32_e64 v186, v3, v186, s[50:51]
	v_readlane_b32 s50, v255, 24
	v_readlane_b32 s51, v255, 25
	s_nop 1
	v_cndmask_b32_e64 v187, v2, v187, s[50:51]
	v_readlane_b32 s50, v255, 26
	v_readlane_b32 s51, v255, 27
	s_nop 1
	v_cndmask_b32_e64 v188, v3, v188, s[50:51]
	v_readlane_b32 s50, v255, 28
	v_readlane_b32 s51, v255, 29
	s_nop 1
	v_cndmask_b32_e64 v189, v2, v189, s[50:51]
	v_readlane_b32 s50, v255, 30
	v_readlane_b32 s51, v255, 31
	s_nop 1
	v_cndmask_b32_e64 v190, v3, v190, s[50:51]
	v_readlane_b32 s50, v255, 32
	v_readlane_b32 s51, v255, 33
	s_nop 1
	v_cndmask_b32_e64 v191, v2, v191, s[50:51]
	v_readlane_b32 s50, v255, 34
	v_readlane_b32 s51, v255, 35
	s_nop 1
	v_cndmask_b32_e64 v192, v3, v192, s[50:51]
	v_readlane_b32 s50, v255, 36
	v_readlane_b32 s51, v255, 37
	s_nop 1
	v_cndmask_b32_e64 v193, v2, v193, s[50:51]
	v_readlane_b32 s50, v255, 38
	v_readlane_b32 s51, v255, 39
	s_nop 1
	v_cndmask_b32_e64 v194, v3, v194, s[50:51]
	v_readlane_b32 s50, v255, 40
	v_readlane_b32 s51, v255, 41
	s_nop 1
	v_cndmask_b32_e64 v195, v3, v195, s[50:51]
	v_readlane_b32 s50, v255, 42
	v_readlane_b32 s51, v255, 43
	s_nop 1
	v_cndmask_b32_e64 v196, v3, v196, s[50:51]
	v_readlane_b32 s50, v255, 44
	v_readlane_b32 s51, v255, 45
	s_nop 1
	v_cndmask_b32_e64 v197, v3, v197, s[50:51]
	v_readlane_b32 s50, v255, 46
	v_readlane_b32 s51, v255, 47
	s_nop 1
	v_cndmask_b32_e64 v198, v3, v198, s[50:51]
	v_readlane_b32 s50, v255, 48
	v_readlane_b32 s51, v255, 49
	s_nop 1
	v_cndmask_b32_e64 v199, v3, v199, s[50:51]
	v_readlane_b32 s50, v255, 50
	v_readlane_b32 s51, v255, 51
	s_nop 1
	v_cndmask_b32_e64 v200, v3, v200, s[50:51]
	v_cndmask_b32_e64 v201, v3, v201, s[88:89]
	v_cndmask_b32_e64 v202, v3, v202, s[90:91]
	v_cndmask_b32_e64 v203, v3, v203, s[92:93]
	v_cndmask_b32_e64 v204, v3, v204, s[94:95]
	v_cndmask_b32_e64 v205, v3, v205, s[96:97]
	v_cndmask_b32_e64 v206, v3, v206, s[98:99]
	v_cndmask_b32_e64 v207, v3, v207, s[0:1]
	v_cndmask_b32_e64 v208, v3, v208, s[4:5]
	v_cndmask_b32_e64 v209, v3, v209, s[6:7]
	v_cndmask_b32_e64 v210, v3, v210, s[8:9]
.LBB0_56:
	s_and_b32 s18, s82, 1
	s_mul_i32 s19, s18, 0x3400
	s_add_i32 s83, s19, 0
	s_mulk_i32 s18, 0xec00
	s_add_i32 s18, s83, s18
	v_add3_u32 v0, s83, v173, v158
	s_waitcnt vmcnt(0) lgkmcnt(0)
	ds_write_b128 v0, v[150:153]
	v_add_u32_e32 v0, s18, v174
	s_add_i32 s19, s82, 1
	v_add3_u32 v0, v0, v175, v176
	s_cmp_ge_i32 s19, s56
	ds_write_b128 v0, v[146:149] offset:26624
	s_waitcnt lgkmcnt(0)
	s_barrier
	s_cbranch_scc1 .LBB0_58
	s_cmp_lt_i32 s19, s59
	s_cselect_b32 s48, 0, s59
	s_cselect_b32 s49, s57, s60
	s_lshl_b32 s48, s48, 6
	s_sub_i32 s48, s49, s48
	s_add_i32 s48, s48, s41
	v_add_u32_e32 v0, s48, v211
	v_mad_i64_i32 v[2:3], s[48:49], s40, v0, 0
	v_lshlrev_b64 v[2:3], 1, v[2:3]
	v_lshl_add_u64 v[4:5], v[160:161], 0, v[2:3]
	v_lshl_add_u64 v[2:3], v[162:163], 0, v[2:3]
	global_load_dwordx4 v[150:153], v[4:5], off
	global_load_dwordx4 v[146:149], v[2:3], off

; __device__ __forceinline__ unsigned cvt_pk_bf16_m(float lo, float hi) { const f32x2_cv v = {lo, hi}; const bf16x2_cv b = __builtin_convertvector(v, bf16x2_cv); return __builtin_bit_cast(unsigned, b); }
; template <int DQ>
; __device__ __forceinline__ void attn_unit(LAS unsigned char* lds, const AttnDesc& A, int tid_in, int wid, int lane_in) {
;     ...
;     float ltot = lrun + __shfl_xor(lrun, 32);
;     ltot += __builtin_amdgcn_exp2f(A.sink - mrun);
;     const float inv = 1.0f / ltot;
;     bf16_t* op = A.o + (size_t)r32 * A.ldo + 4 * h;
; #pragma unroll
;     for (int g4 = 0; g4 < 4; ++g4) {
;         u32x2 w;
;         w.x = cvt_pk_bf16_m(o0[4 * g4 + 0] * inv, o0[4 * g4 + 1] * inv); w.y = cvt_pk_bf16_m(o0[4 * g4 + 2] * inv, o0[4 * g4 + 3] * inv);
;         *(u32x2*)(op + 8 * g4) = w;
;         w.x = cvt_pk_bf16_m(o1[4 * g4 + 0] * inv, o1[4 * g4 + 1] * inv); w.y = cvt_pk_bf16_m(o1[4 * g4 + 2] * inv, o1[4 * g4 + 3] * inv);
;         *(u32x2*)(op + 32 + 8 * g4) = w;
;     }
;     __syncthreads();
.LBB0_139:
	v_and_b32_e32 v2, 64, v242
	v_xor_b32_e32 v0, 32, v242
	v_add_u32_e32 v2, 64, v2
	v_cmp_lt_i32_e32 vcc, v0, v2
	v_sub_f32_e32 v2, v164, v212
	v_exp_f32_e32 v2, v2
	v_cndmask_b32_e32 v0, v242, v0, vcc
	v_lshlrev_b32_e32 v0, 2, v0
	ds_bpermute_b32 v0, v0, v64
	s_waitcnt lgkmcnt(0)
	v_add_f32_e32 v0, v64, v0
	v_add_f32_e32 v0, v2, v0
	v_div_scale_f32 v2, s[0:1], v0, v0, 1.0
	v_rcp_f32_e32 v3, v2
	v_div_scale_f32 v4, vcc, 1.0, v0, 1.0
	v_fma_f32 v5, -v2, v3, 1.0
	v_fmac_f32_e32 v3, v5, v3
	v_mul_f32_e32 v5, v4, v3
	v_fma_f32 v6, -v2, v5, v4
	v_fmac_f32_e32 v5, v6, v3
	v_fma_f32 v2, -v2, v5, v4
	v_div_fmas_f32 v2, v2, v3, v5
	v_div_fixup_f32 v2, v2, v0, 1.0
	v_lshlrev_b32_e32 v0, 11, v165
	v_lshl_add_u64 v[4:5], s[44:45], 0, v[0:1]
	v_lshlrev_b32_e32 v0, 1, v157
	v_pk_mul_f32 v[6:7], v[48:49], v[2:3] op_sel_hi:[1,0]
	v_pk_mul_f32 v[8:9], v[50:51], v[2:3] op_sel_hi:[1,0]
	v_lshl_add_u64 v[4:5], v[4:5], 0, v[0:1]
	v_cvt_pk_bf16_f32 v6, v6, v7
	v_cvt_pk_bf16_f32 v7, v8, v9
	global_store_dwordx2 v[4:5], v[6:7], off
	v_pk_mul_f32 v[6:7], v[32:33], v[2:3] op_sel_hi:[1,0]
	v_pk_mul_f32 v[8:9], v[34:35], v[2:3] op_sel_hi:[1,0]
	v_cvt_pk_bf16_f32 v6, v6, v7
	v_cvt_pk_bf16_f32 v7, v8, v9
	global_store_dwordx2 v[4:5], v[6:7], off offset:64
	v_pk_mul_f32 v[6:7], v[52:53], v[2:3] op_sel_hi:[1,0]
	v_pk_mul_f32 v[8:9], v[54:55], v[2:3] op_sel_hi:[1,0]
	v_cvt_pk_bf16_f32 v6, v6, v7
	v_cvt_pk_bf16_f32 v7, v8, v9
	global_store_dwordx2 v[4:5], v[6:7], off offset:16
	v_pk_mul_f32 v[6:7], v[36:37], v[2:3] op_sel_hi:[1,0]
	v_pk_mul_f32 v[8:9], v[38:39], v[2:3] op_sel_hi:[1,0]
	v_cvt_pk_bf16_f32 v6, v6, v7
	v_cvt_pk_bf16_f32 v7, v8, v9
	global_store_dwordx2 v[4:5], v[6:7], off offset:80
	v_pk_mul_f32 v[6:7], v[56:57], v[2:3] op_sel_hi:[1,0]
	v_pk_mul_f32 v[8:9], v[58:59], v[2:3] op_sel_hi:[1,0]
	v_cvt_pk_bf16_f32 v6, v6, v7
	v_cvt_pk_bf16_f32 v7, v8, v9
	global_store_dwordx2 v[4:5], v[6:7], off offset:32
	v_pk_mul_f32 v[6:7], v[40:41], v[2:3] op_sel_hi:[1,0]
	v_pk_mul_f32 v[8:9], v[42:43], v[2:3] op_sel_hi:[1,0]
	v_cvt_pk_bf16_f32 v6, v6, v7
	v_cvt_pk_bf16_f32 v7, v8, v9
	global_store_dwordx2 v[4:5], v[6:7], off offset:96
	v_pk_mul_f32 v[6:7], v[60:61], v[2:3] op_sel_hi:[1,0]
	v_pk_mul_f32 v[8:9], v[62:63], v[2:3] op_sel_hi:[1,0]
	v_cvt_pk_bf16_f32 v6, v6, v7
	v_cvt_pk_bf16_f32 v7, v8, v9
	global_store_dwordx2 v[4:5], v[6:7], off offset:48
	v_pk_mul_f32 v[6:7], v[44:45], v[2:3] op_sel_hi:[1,0]
	v_pk_mul_f32 v[2:3], v[46:47], v[2:3] op_sel_hi:[1,0]
	v_cvt_pk_bf16_f32 v6, v6, v7
	v_cvt_pk_bf16_f32 v7, v2, v3
	global_store_dwordx2 v[4:5], v[6:7], off offset:112
	s_waitcnt lgkmcnt(0)
	s_barrier

; #define LAS __attribute__((address_space(3)))
; __device__ __forceinline__ void attn_unit_mla(LAS unsigned char* lds, const AttnDesc& A, int tid_in, int wid, int lane_in) {
;     constexpr int KSTR = (96 + 8) * 2, NS = 6;
;     int tid = tid_in; asm volatile("" : "+v"(tid));
;     const int lane = tid & 63; (void)lane_in;
;     const int r32 = lane & 31, h = lane >> 5;
;     const int nt = A.nloc + 4, nstg = nt >> 1;
;     bf16x8 qf[NS];
; #pragma unroll
;     for (int s = 0; s < NS; ++s) qf[s] = *(const bf16x8*)(A.q + (size_t)r32 * A.ldq + 16 * s + 8 * h);
;     f32x16 o0, o1;
; #pragma unroll
;     for (int r = 0; r < 16; ++r) { o0[r] = 0.f; o1[r] = 0.f; }
;     float mrun = -1e30f, lrun = 0.f;
;     const int skey = tid >> 3, sch = tid & 7;
;     u32x4 ka, va, kra = (u32x4){0u, 0u, 0u, 0u}, kb_, vb_, krb = (u32x4){0u, 0u, 0u, 0u};
;     ...
;     MLA_LOAD(ka, va, kra, 0); MLA_LOAD(kb_, vb_, krb, 1);
.LBB0_145:
	s_add_i32 s4, s0, s11
	s_and_b32 s45, s1, 7
	s_mul_i32 s1, s4, 0x600
	s_mul_hi_i32 s0, s4, 0x600
	s_add_u32 s1, s66, s1
	s_addc_u32 s5, s67, s0
	s_mul_i32 s0, s45, 0xc0
	s_add_u32 s0, s1, s0
	s_addc_u32 s1, s5, 0
	v_mov_b32_e32 v6, v154
	s_lshl_b32 s5, s45, 8
	v_mov_b64_e32 v[2:3], s[0:1]
	v_and_b32_e32 v156, 31, v6
	s_movk_i32 s0, 0x600
	s_add_u32 s6, s76, s5
	v_mad_u64_u32 v[2:3], s[0:1], v156, s0, v[2:3]
	s_addc_u32 s7, s77, 0
	s_lshl_b32 s0, s41, 6
	v_bfe_u32 v157, v6, 5, 1
	s_sub_i32 s5, s40, s0
	v_lshlrev_b32_e32 v0, 4, v157
	s_and_b64 s[0:1], s[42:43], exec
	v_lshl_add_u64 v[2:3], v[2:3], 0, v[0:1]
	v_ashrrev_i32_e32 v171, 3, v6
	s_cselect_b32 s5, s44, s5
	global_load_dwordx4 v[98:101], v[2:3], off
	global_load_dwordx4 v[102:105], v[2:3], off offset:32
	global_load_dwordx4 v[106:109], v[2:3], off offset:64
	global_load_dwordx4 v[110:113], v[2:3], off offset:96
	global_load_dwordx4 v[114:117], v[2:3], off offset:128
	global_load_dwordx4 v[118:121], v[2:3], off offset:160
	v_add_u32_e32 v2, s5, v171
	v_ashrrev_i32_e32 v3, 31, v2
	v_and_b32_e32 v7, 7, v6
	v_lshlrev_b64 v[2:3], 11, v[2:3]
	v_lshl_add_u64 v[2:3], s[6:7], 0, v[2:3]
	v_lshlrev_b32_e32 v158, 4, v7
	v_mov_b32_e32 v159, v1
	v_lshl_add_u64 v[2:3], v[2:3], 0, v[158:159]
	global_load_dwordx4 v[122:125], v[2:3], off
	global_load_dwordx4 v[126:129], v[2:3], off offset:128
	s_movk_i32 s0, 0xff
	v_cmp_lt_i32_e32 vcc, s0, v6
	s_movk_i32 s0, 0x100
	v_lshlrev_b32_e32 v8, 4, v6
	v_cmp_gt_i32_e64 s[0:1], s0, v6
	v_mov_b32_e32 v130, v1
	v_mov_b32_e32 v131, v1
	v_mov_b32_e32 v132, v1
	v_mov_b32_e32 v133, v1
	v_ashrrev_i32_e32 v159, 2, v6
	v_and_b32_e32 v160, 48, v8
	s_and_saveexec_b64 s[8:9], s[0:1]
	s_cbranch_execz .LBB0_147
	v_ashrrev_i32_e32 v2, 2, v6
	v_add_u32_e32 v4, s5, v2
	v_mov_b64_e32 v[2:3], s[92:93]
	v_mad_i64_i32 v[2:3], s[18:19], v4, s90, v[2:3]
	v_mov_b32_e32 v161, v1
	v_lshl_add_u64 v[2:3], v[2:3], 0, v[160:161]
	global_load_dwordx4 v[130:133], v[2:3], off
.LBB0_147:
	s_or_b64 exec, exec, s[8:9]
	s_or_b32 s5, s5, 64
	v_add_u32_e32 v2, s5, v171
	v_ashrrev_i32_e32 v3, 31, v2
	v_lshlrev_b32_e32 v9, 3, v7
	v_lshlrev_b64 v[2:3], 11, v[2:3]
	v_lshl_add_u64 v[4:5], s[6:7], 0, v[2:3]
	v_lshlrev_b32_e32 v2, 1, v9
	v_mov_b32_e32 v3, v1
	v_lshl_add_u64 v[4:5], v[4:5], 0, v[2:3]
	global_load_dwordx4 v[138:141], v[4:5], off
	global_load_dwordx4 v[142:145], v[4:5], off offset:128
	v_lshlrev_b32_e32 v3, 3, v6
	v_and_b32_e32 v4, 24, v3
	s_and_saveexec_b64 s[8:9], vcc
	s_xor_b64 s[8:9], exec, s[8:9]
	v_lshrrev_b32_e32 v159, 2, v6
	v_mov_b32_e32 v5, v1
	s_or_saveexec_b64 s[8:9], s[8:9]
	v_mov_b32_e32 v134, v1
	v_mov_b32_e32 v135, v1
	v_mov_b32_e32 v136, v1
	v_mov_b32_e32 v137, v1
	s_xor_b64 exec, exec, s[8:9]
	s_cbranch_execz .LBB0_151
	v_add_u32_e32 v3, s5, v159
	v_mov_b64_e32 v[10:11], s[92:93]
	v_mad_i64_i32 v[10:11], s[18:19], v3, s90, v[10:11]
	v_lshlrev_b32_e32 v12, 1, v4
	v_mov_b32_e32 v13, v1
	v_lshl_add_u64 v[10:11], v[10:11], 0, v[12:13]
	global_load_dwordx4 v[134:137], v[10:11], off
	v_mov_b32_e32 v5, v1

; #define LAS __attribute__((address_space(3)))
; #define MLA_STORE(KR, VR, KRR, kbp, vbp) do { *(LAS u32x4*)((kbp) + skey * KSTR + sch * 16) = KR; \
;         if (tid < 256) *(LAS u32x4*)((kbp) + (tid >> 2) * KSTR + 128 + (tid & 3) * 16) = KRR; \
;         *(LAS u32x4*)((vbp) + (sch >> 2) * 4096 + skey * 64 + (sch & 3) * 16) = VR; } while (0)
; __device__ __forceinline__ void attn_unit_mla(LAS unsigned char* lds, const AttnDesc& A, int tid_in, int wid, int lane_in) {
;     ...
;     for (int st = 0; st < nstg; ++st) {
;         LAS unsigned char* kbuf = lds + (st & 1) * ATT2_KSTG;
;         LAS unsigned char* vbuf = lds + ATT2_VOFF + (st & 1) * ATT2_VSTG;
;         MLA_STORE(ka, va, kra, kbuf, vbuf); MLA_STORE(kb_, vb_, krb, kbuf + ATT_KBUF, vbuf + 8192);
;         __syncthreads();
;         if (st + 1 < nstg) { MLA_LOAD(ka, va, kra, 2 * st + 2); MLA_LOAD(kb_, vb_, krb, 2 * st + 3); }
.LBB0_155:
	s_or_b64 exec, exec, s[6:7]
	s_mulk_i32 s18, 0xd800
	s_add_i32 s51, s52, s18
	v_add3_u32 v36, s51, v175, v176
	v_add_u32_e32 v36, v36, v160
	ds_write_b128 v36, v[126:129] offset:53248
	s_waitcnt vmcnt(0)
	ds_write_b128 v35, v[138:141] offset:13312
	s_and_saveexec_b64 s[6:7], s[0:1]
	ds_write_b128 v34, v[134:137] offset:13440
	s_or_b64 exec, exec, s[6:7]
	s_cmp_ge_u32 s8, s9
	ds_write_b128 v36, v[142:145] offset:61440
	s_waitcnt lgkmcnt(0)
	s_barrier
	s_cbranch_scc1 .LBB0_163
	s_add_i32 s6, s50, -1
	s_cmp_lt_u32 s6, s41
	s_cselect_b32 s6, 0, s41
	s_cselect_b32 s7, s44, s40
	s_lshl_b32 s6, s6, 6
	s_sub_i32 s18, s7, s6
	v_add_u32_e32 v34, s48, v171
	v_add_u32_e32 v35, s18, v34
	v_add_u32_e32 v36, 0x80, v35
	v_ashrrev_i32_e32 v37, 31, v36
	v_lshlrev_b64 v[36:37], 11, v[36:37]
	v_lshl_add_u64 v[36:37], v[162:163], 0, v[36:37]
	global_load_dwordx4 v[122:125], v[36:37], off
	global_load_dwordx4 v[126:129], v[36:37], off offset:128
	s_and_saveexec_b64 s[6:7], s[0:1]
	s_cbranch_execz .LBB0_160
	s_add_i32 s18, s18, s48
	v_add_u32_e32 v35, s18, v159
	v_add_u32_e32 v35, 0x80, v35
	v_mad_i64_i32 v[36:37], s[18:19], v35, s90, v[164:165]
	global_load_dwordx4 v[130:133], v[36:37], off
.LBB0_160:
	s_or_b64 exec, exec, s[6:7]
	s_cmp_lt_u32 s50, s41
	s_cselect_b32 s6, 0, s41
	s_cselect_b32 s7, s44, s40
	s_lshl_b32 s6, s6, 6
	s_sub_i32 s18, s7, s6
	v_add_u32_e32 v34, s18, v34
	v_add_u32_e32 v34, 0xc0, v34
	v_ashrrev_i32_e32 v35, 31, v34
	v_lshlrev_b64 v[34:35], 11, v[34:35]
	v_lshl_add_u64 v[34:35], v[162:163], 0, v[34:35]
	global_load_dwordx4 v[138:141], v[34:35], off
	global_load_dwordx4 v[142:145], v[34:35], off offset:128
	s_and_saveexec_b64 s[6:7], s[0:1]
	s_cbranch_execz .LBB0_162
	s_add_i32 s18, s18, s48
	v_add_u32_e32 v34, s18, v159
	v_add_u32_e32 v34, 0xc0, v34
	v_mad_i64_i32 v[34:35], s[18:19], v34, s90, v[164:165]
	global_load_dwordx4 v[134:137], v[34:35], off

;     __device__ __forceinline__ void operator()(const f32x4 (&acc)[2][2][4][2], const Unit& u, int wr_in, int wc_in, int fr_in, int fq_in) const {
;     ...
;                 const int row = u.pm * 256 + ai * 128 + wr * 64 + 4 * fr + m;
;                 const float* sp = ssq + (size_t)row * 20;
;                 const f32x4 p0 = *(const f32x4*)(sp), p1 = *(const f32x4*)(sp + 4);
;                 float ss = (p0[0] + p0[1]) + (p0[2] + p0[3]) + (p1[0] + p1[1]) + (p1[2] + p1[3]);
;                 if (nslot == 12) { const f32x4 p2 = *(const f32x4*)(sp + 8); ss += (p2[0] + p2[1]) + (p2[2] + p2[3]); }
.LBB0_190:
	v_mov_b32_e32 v162, v155
	s_mov_b32 s13, s63
	v_mov_b32_e32 v0, v156
	s_mov_b32 s0, s59
	s_lshl_b32 s1, s12, 8
	s_lshl_b32 s0, s0, 6
	v_lshlrev_b32_e32 v0, 2, v0
	s_add_i32 s0, s0, s1
	v_add_u32_e32 v160, s0, v0
	v_mov_b64_e32 v[142:143], s[86:87]
	v_mad_i64_i32 v[144:145], s[0:1], v160, s26, v[142:143]
	global_load_dwordx4 v[146:149], v[144:145], off
	global_load_dwordx4 v[150:153], v[144:145], off offset:16
	s_mov_b64 s[48:49], 0
	s_andn2_b64 vcc, exec, s[6:7]
	s_mov_b64 s[0:1], 0
	s_waitcnt vmcnt(0) lgkmcnt(0)
	v_mov_b32_e32 v142, v147
	v_mov_b32_e32 v143, v148
	v_mov_b32_e32 v147, v149
	v_pk_add_f32 v[142:143], v[142:143], v[146:147]
	v_mov_b32_e32 v146, v152
	v_mov_b32_e32 v147, v150
	v_mov_b32_e32 v150, v153
	v_pk_add_f32 v[142:143], v[142:143], v[142:143] op_sel:[0,1] op_sel_hi:[1,0]
	v_pk_add_f32 v[146:147], v[146:147], v[150:151]
	s_nop 0
	v_pk_add_f32 v[142:143], v[142:143], v[146:147] op_sel:[0,1] op_sel_hi:[1,0]
	s_nop 0
	v_pk_add_f32 v[142:143], v[146:147], v[142:143]
	s_nop 0
	v_cndmask_b32_e64 v143, 0, 1, s[6:7]
	v_cmp_ne_u32_e64 s[42:43], 1, v143
	s_cbranch_vccnz .LBB0_192
	global_load_dwordx4 v[144:147], v[144:145], off offset:32
	s_cmpk_lt_i32 s12, 0x80
	s_cselect_b64 s[0:1], -1, 0
	s_waitcnt vmcnt(0) lgkmcnt(0)
	v_mov_b32_e32 v148, v145
	v_mov_b32_e32 v149, v146
	v_mov_b32_e32 v145, v147
	v_pk_add_f32 v[144:145], v[148:149], v[144:145]
	s_nop 0
	v_add_f32_e32 v143, v144, v145
	v_add_f32_e32 v142, v142, v143

; __device__ __forceinline__ void rope_apply(f32x4& v0, f32x4& v1, int kind, int row, int wc, int fq, const float* tabM, const float* tabS) {
;     const int t = row & 2047, gr = t >> 6, gc = t & 63;
;     const float* tb; float sgn; f32x4 p0, p1;
;     if (kind == 1) {
;         const int pos = (fq < 2) ? gr : gc; tb = tabM + pos * 16; sgn = (fq & 1) ? 1.f : -1.f;
; #pragma unroll
;         for (int e = 0; e < 4; ++e) { p0[e] = __shfl_xor(v0[e], 16); p1[e] = __shfl_xor(v1[e], 16); }
;     } else {
;         const int pos = (wc & 1) ? gc : gr; tb = tabS + pos * 32 + (fq & 1) * 16; sgn = (fq & 2) ? 1.f : -1.f;
; #pragma unroll
;         for (int e = 0; e < 4; ++e) { p0[e] = __shfl_xor(v0[e], 32); p1[e] = __shfl_xor(v1[e], 32); }
;     }
;     const f32x4 c0 = *(const f32x4*)(tb), c1 = *(const f32x4*)(tb + 4), c2 = *(const f32x4*)(tb + 8), c3 = *(const f32x4*)(tb + 12);
;     v0[0] = v0[0] * c0[0] + sgn * p0[0] * c0[1]; v0[1] = v0[1] * c0[2] + sgn * p0[1] * c0[3];
;     v0[2] = v0[2] * c1[0] + sgn * p0[2] * c1[1]; v0[3] = v0[3] * c1[2] + sgn * p0[3] * c1[3];
;     v1[0] = v1[0] * c2[0] + sgn * p1[0] * c2[1]; v1[1] = v1[1] * c2[2] + sgn * p1[1] * c2[3];
;     v1[2] = v1[2] * c3[0] + sgn * p1[2] * c3[1]; v1[3] = v1[3] * c3[2] + sgn * p1[3] * c3[3];
;     __device__ __forceinline__ void operator()(const f32x4 (&acc)[2][2][4][2], const Unit& u, int wr_in, int wc_in, int fr_in, int fq_in) const {
;     ...
;                 const float rs = sc / sqrtf(ss * invn + RMS_EPS);
; #pragma unroll
;                 for (int bj = 0; bj < 2; ++bj) {
;                     const int g32 = u.pn * 8 + bj * 4 + wc;
;                     const int rope = (isq && lat && (g32 % 3 == 2)) ? 1 : 0;
;                     f32x4 v0 = acc[ai][bj][m][0] * rs, v1 = acc[ai][bj][m][1] * rs;
;                     if (rope) rope_apply(v0, v1, 1, row, wc, fq, tabM, tabM);
;                     store_bf16x8(O + (size_t)row * ldo + g32 * 32 + 8 * fq, v0, v1);
.LBB0_194:
	v_fmaak_f32 v142, v154, v142, 0x358637bd
	v_mul_f32_e32 v143, 0x4f800000, v142
	v_cmp_gt_f32_e32 vcc, s28, v142
	v_bfe_u32 v161, v160, 6, 5
	v_cmp_gt_i32_e64 s[44:45], 2, v162
	v_cndmask_b32_e32 v142, v142, v143, vcc
	v_sqrt_f32_e32 v143, v142
	s_nop 0
	v_add_u32_e32 v144, -1, v143
	v_fma_f32 v146, -v144, v143, v142
	v_add_u32_e32 v145, 1, v143
	v_cmp_ge_f32_e64 s[0:1], 0, v146
	s_nop 1
	v_cndmask_b32_e64 v144, v143, v144, s[0:1]
	v_fma_f32 v143, -v145, v143, v142
	v_cmp_lt_f32_e64 s[0:1], 0, v143
	s_nop 1
	v_cndmask_b32_e64 v143, v144, v145, s[0:1]
	v_mul_f32_e32 v144, 0x37800000, v143
	v_cndmask_b32_e32 v143, v143, v144, vcc
	v_cmp_class_f32_e32 vcc, v142, v238
	s_nop 1
	v_cndmask_b32_e32 v142, v143, v142, vcc
	v_div_scale_f32 v143, s[0:1], v142, v142, v158
	v_rcp_f32_e32 v144, v143
	s_nop 0
	v_fma_f32 v145, -v143, v144, 1.0
	v_fmac_f32_e32 v144, v145, v144
	v_div_scale_f32 v145, vcc, v158, v142, v158
	v_mul_f32_e32 v146, v145, v144
	v_fma_f32 v147, -v143, v146, v145
	v_fmac_f32_e32 v146, v147, v144
	v_fma_f32 v143, -v143, v146, v145
	v_div_fmas_f32 v143, v143, v144, v146
	v_div_fixup_f32 v144, v143, v142, v158
	v_and_b32_e32 v143, 60, v0
	v_cndmask_b32_e64 v0, v143, v161, s[44:45]
	v_and_b32_e32 v142, 1, v162
	v_lshlrev_b32_e32 v0, 4, v0
	v_cmp_eq_u32_e32 vcc, 0, v142
	v_pk_mul_f32 v[146:147], v[128:129], v[144:145] op_sel_hi:[1,0]
	v_pk_mul_f32 v[148:149], v[126:127], v[144:145] op_sel_hi:[1,0]
	v_cndmask_b32_e64 v142, 1.0, -1.0, vcc
	v_pk_mul_f32 v[150:151], v[124:125], v[144:145] op_sel_hi:[1,0]
	v_pk_mul_f32 v[152:153], v[122:123], v[144:145] op_sel_hi:[1,0]
	s_andn2_b64 vcc, exec, s[48:49]
	v_lshlrev_b32_e32 v0, 2, v0
	s_cbranch_vccnz .LBB0_196
	v_and_b32_e32 v123, 64, v242
	v_xor_b32_e32 v122, 16, v242
	v_add_u32_e32 v123, 64, v123
	v_cmp_lt_i32_e32 vcc, v122, v123
	v_lshl_add_u64 v[126:127], s[36:37], 0, v[0:1]
	s_nop 0
	v_cndmask_b32_e32 v122, v242, v122, vcc
	v_lshlrev_b32_e32 v122, 2, v122
	ds_bpermute_b32 v172, v122, v148
	ds_bpermute_b32 v174, v122, v152
	ds_bpermute_b32 v173, v122, v149
	ds_bpermute_b32 v175, v122, v153
	ds_bpermute_b32 v145, v122, v146
	ds_bpermute_b32 v163, v122, v150
	ds_bpermute_b32 v178, v122, v147
	ds_bpermute_b32 v179, v122, v151
	global_load_dwordx4 v[164:167], v[126:127], off
	global_load_dwordx4 v[168:171], v[126:127], off offset:16
	global_load_dwordx4 v[122:125], v[126:127], off offset:32
	s_nop 0
	global_load_dwordx4 v[126:129], v[126:127], off offset:48
	s_waitcnt lgkmcnt(0)
	v_mul_f32_e32 v145, v142, v145
	v_pk_mul_f32 v[172:173], v[142:143], v[172:173] op_sel_hi:[0,1]
	s_waitcnt vmcnt(0)
	v_mov_b32_e32 v176, v164
	v_mov_b32_e32 v177, v166
	v_mul_f32_e32 v146, v146, v168
	v_mul_f32_e32 v164, v145, v169
	v_mul_f32_e32 v169, v142, v178
	v_mov_b32_e32 v168, v147
	v_pk_mul_f32 v[148:149], v[148:149], v[176:177]
	v_mov_b32_e32 v166, v165
	v_pk_mul_f32 v[168:169], v[168:169], v[170:171]
	v_pk_fma_f32 v[148:149], v[172:173], v[166:167], v[148:149]
	v_mov_b32_e32 v165, v169
	v_mov_b32_e32 v147, v168
	v_mul_f32_e32 v167, v142, v179
	v_mov_b32_e32 v166, v151
	v_pk_add_f32 v[146:147], v[164:165], v[146:147]
	v_mov_b32_e32 v164, v122
	v_mov_b32_e32 v165, v124
	v_mov_b32_e32 v124, v123
	v_mul_f32_e32 v123, v142, v163
	v_pk_mul_f32 v[128:129], v[166:167], v[128:129]
	v_pk_mul_f32 v[152:153], v[152:153], v[164:165]
	v_pk_mul_f32 v[164:165], v[142:143], v[174:175] op_sel_hi:[0,1]
	v_mul_f32_e32 v122, v150, v126
	v_mul_f32_e32 v126, v123, v127
	v_mov_b32_e32 v127, v129
	v_mov_b32_e32 v123, v128
	v_pk_fma_f32 v[152:153], v[164:165], v[124:125], v[152:153]
	v_pk_add_f32 v[150:151], v[126:127], v[122:123]
.LBB0_196:
	v_mad_i64_i32 v[124:125], s[0:1], v160, s4, 0
	s_lshl_b32 s94, s58, 5
	v_lshlrev_b32_e32 v122, 3, v162
	v_lshl_add_u64 v[124:125], v[124:125], 1, s[84:85]
	s_ashr_i32 s95, s94, 31
	v_ashrrev_i32_e32 v123, 31, v122
	v_lshl_add_u64 v[126:127], s[94:95], 1, v[124:125]
	s_add_i32 s12, s58, 4
	v_lshl_add_u64 v[162:163], v[122:123], 1, v[126:127]
	s_mov_b64 s[0:1], 0
	s_and_b64 vcc, exec, s[40:41]
	s_mul_hi_i32 s13, s12, 0x55555556
	v_cvt_pk_bf16_f32 v126, v148, v149
	v_cvt_pk_bf16_f32 v127, v146, v147
	v_cvt_pk_bf16_f32 v128, v152, v153
	v_cvt_pk_bf16_f32 v129, v150, v151
	global_store_dwordx4 v[162:163], v[126:129], off
	s_cbranch_vccnz .LBB0_198
	s_lshr_b32 s0, s13, 31
	s_add_i32 s0, s13, s0
	s_mul_i32 s0, s0, 3
	s_sub_i32 s0, s12, s0
	s_cmp_eq_u32 s0, 2
	s_cselect_b64 s[0:1], -1, 0
;     __device__ __forceinline__ void operator()(const f32x4 (&acc)[2][2][4][2], const Unit& u, int wr_in, int wc_in, int fr_in, int fq_in) const {
;     ...
;                 const int row = u.pm * 256 + ai * 128 + wr * 64 + 4 * fr + m;
;                 const float* sp = ssq + (size_t)row * 20;
;                 const f32x4 p0 = *(const f32x4*)(sp), p1 = *(const f32x4*)(sp + 4);
;                 float ss = (p0[0] + p0[1]) + (p0[2] + p0[3]) + (p1[0] + p1[1]) + (p1[2] + p1[3]);
;                 if (nslot == 12) { const f32x4 p2 = *(const f32x4*)(sp + 8); ss += (p2[0] + p2[1]) + (p2[2] + p2[3]); }
;     ...
; #pragma unroll
;                 for (int bj = 0; bj < 2; ++bj) {
;                     const int g32 = u.pn * 8 + bj * 4 + wc;
;                     const int rope = (isq && lat && (g32 % 3 == 2)) ? 1 : 0;
;                     f32x4 v0 = acc[ai][bj][m][0] * rs, v1 = acc[ai][bj][m][1] * rs;
;                     if (rope) rope_apply(v0, v1, 1, row, wc, fq, tabM, tabM);
;                     store_bf16x8(O + (size_t)row * ldo + g32 * 32 + 8 * fq, v0, v1);
.LBB0_198:
	v_mov_b32_e32 v145, v144
	v_mov_b32_e32 v146, v144
	v_mov_b32_e32 v147, v144
	v_pk_mul_f32 v[126:127], v[120:121], v[146:147]
	v_pk_mul_f32 v[128:129], v[118:119], v[144:145]
	v_pk_mul_f32 v[146:147], v[116:117], v[146:147]
	s_andn2_b64 vcc, exec, s[0:1]
	v_pk_mul_f32 v[144:145], v[114:115], v[144:145]
	s_cbranch_vccnz .LBB0_200
	v_and_b32_e32 v115, 64, v242
	v_xor_b32_e32 v114, 16, v242
	v_add_u32_e32 v115, 64, v115
	v_cmp_lt_i32_e32 vcc, v114, v115
	v_lshl_add_u64 v[118:119], s[36:37], 0, v[0:1]
	s_nop 0
	v_cndmask_b32_e32 v114, v242, v114, vcc
	v_lshlrev_b32_e32 v114, 2, v114
	ds_bpermute_b32 v152, v114, v128
	ds_bpermute_b32 v166, v114, v144
	ds_bpermute_b32 v153, v114, v129
	ds_bpermute_b32 v167, v114, v145
	ds_bpermute_b32 v170, v114, v126
	ds_bpermute_b32 v171, v114, v146
	ds_bpermute_b32 v172, v114, v127
	ds_bpermute_b32 v173, v114, v147
	global_load_dwordx4 v[148:151], v[118:119], off
	global_load_dwordx4 v[162:165], v[118:119], off offset:16
	global_load_dwordx4 v[114:117], v[118:119], off offset:32
	s_nop 0
	global_load_dwordx4 v[118:121], v[118:119], off offset:48
	s_waitcnt lgkmcnt(0)
	v_mul_f32_e32 v0, v142, v170
	v_pk_mul_f32 v[152:153], v[142:143], v[152:153] op_sel_hi:[0,1]
	s_waitcnt vmcnt(0)
	v_mov_b32_e32 v168, v148
	v_mov_b32_e32 v169, v150
	v_mul_f32_e32 v126, v126, v162
	v_mul_f32_e32 v148, v0, v163
	v_mul_f32_e32 v163, v142, v172
	v_mov_b32_e32 v162, v127
	v_pk_mul_f32 v[128:129], v[128:129], v[168:169]
	v_mov_b32_e32 v150, v149
	v_pk_mul_f32 v[162:163], v[162:163], v[164:165]
	v_pk_fma_f32 v[128:129], v[152:153], v[150:151], v[128:129]
	v_mov_b32_e32 v149, v163
	v_mov_b32_e32 v127, v162
	v_mul_f32_e32 v151, v142, v173
	v_mov_b32_e32 v150, v147
	v_pk_add_f32 v[126:127], v[148:149], v[126:127]
	v_mov_b32_e32 v148, v114
	v_mov_b32_e32 v149, v116
	v_mul_f32_e32 v0, v142, v171
	v_pk_mul_f32 v[120:121], v[150:151], v[120:121]
	v_pk_mul_f32 v[144:145], v[144:145], v[148:149]
	v_pk_mul_f32 v[148:149], v[142:143], v[166:167] op_sel_hi:[0,1]
	v_mov_b32_e32 v116, v115
	v_mul_f32_e32 v114, v146, v118
	v_mul_f32_e32 v118, v0, v119
	v_mov_b32_e32 v119, v121
	v_mov_b32_e32 v115, v120
	v_pk_fma_f32 v[144:145], v[148:149], v[116:117], v[144:145]
	v_pk_add_f32 v[146:147], v[118:119], v[114:115]
.LBB0_200:
	s_lshl_b32 s96, s12, 5
	s_ashr_i32 s97, s96, 31
	v_lshl_add_u64 v[114:115], s[96:97], 1, v[124:125]
	v_lshl_add_u64 v[118:119], v[122:123], 1, v[114:115]
	v_cvt_pk_bf16_f32 v114, v128, v129
	v_cvt_pk_bf16_f32 v115, v126, v127
	v_cvt_pk_bf16_f32 v116, v144, v145
	v_cvt_pk_bf16_f32 v117, v146, v147
	global_store_dwordx4 v[118:119], v[114:117], off
	v_or_b32_e32 v126, 1, v160
	s_and_b64 vcc, exec, s[42:43]
	v_mov_b64_e32 v[114:115], s[86:87]
	v_mad_i64_i32 v[114:115], s[0:1], v126, s26, v[114:115]
	global_load_dwordx4 v[116:119], v[114:115], off
	global_load_dwordx4 v[144:147], v[114:115], off offset:16
	s_waitcnt vmcnt(0) lgkmcnt(0)
	v_mov_b32_e32 v120, v117
	v_mov_b32_e32 v121, v118
	v_mov_b32_e32 v117, v119
	v_pk_add_f32 v[116:117], v[120:121], v[116:117]
	v_mov_b32_e32 v118, v146
	v_mov_b32_e32 v119, v144
	v_mov_b32_e32 v144, v147
	v_pk_add_f32 v[116:117], v[116:117], v[116:117] op_sel:[0,1] op_sel_hi:[1,0]
	v_pk_add_f32 v[118:119], v[118:119], v[144:145]
	s_nop 0
	v_pk_add_f32 v[116:117], v[116:117], v[118:119] op_sel:[0,1] op_sel_hi:[1,0]
	s_nop 0
	v_pk_add_f32 v[116:117], v[118:119], v[116:117]
	s_cbranch_vccnz .LBB0_202
	global_load_dwordx4 v[118:121], v[114:115], off offset:32
	s_waitcnt vmcnt(0) lgkmcnt(0)
	v_mov_b32_e32 v114, v119
	v_mov_b32_e32 v115, v120
	v_mov_b32_e32 v119, v121
	v_pk_add_f32 v[114:115], v[114:115], v[118:119]
	s_nop 0
	v_add_f32_e32 v0, v114, v115
	v_add_f32_e32 v116, v116, v0

; __device__ __forceinline__ void rope_apply(f32x4& v0, f32x4& v1, int kind, int row, int wc, int fq, const float* tabM, const float* tabS) {
;     const int t = row & 2047, gr = t >> 6, gc = t & 63;
;     const float* tb; float sgn; f32x4 p0, p1;
;     if (kind == 1) {
;         const int pos = (fq < 2) ? gr : gc; tb = tabM + pos * 16; sgn = (fq & 1) ? 1.f : -1.f;
; #pragma unroll
;         for (int e = 0; e < 4; ++e) { p0[e] = __shfl_xor(v0[e], 16); p1[e] = __shfl_xor(v1[e], 16); }
;     } else {
;         const int pos = (wc & 1) ? gc : gr; tb = tabS + pos * 32 + (fq & 1) * 16; sgn = (fq & 2) ? 1.f : -1.f;
; #pragma unroll
;         for (int e = 0; e < 4; ++e) { p0[e] = __shfl_xor(v0[e], 32); p1[e] = __shfl_xor(v1[e], 32); }
;     }
;     const f32x4 c0 = *(const f32x4*)(tb), c1 = *(const f32x4*)(tb + 4), c2 = *(const f32x4*)(tb + 8), c3 = *(const f32x4*)(tb + 12);
;     v0[0] = v0[0] * c0[0] + sgn * p0[0] * c0[1]; v0[1] = v0[1] * c0[2] + sgn * p0[1] * c0[3];
;     v0[2] = v0[2] * c1[0] + sgn * p0[2] * c1[1]; v0[3] = v0[3] * c1[2] + sgn * p0[3] * c1[3];
;     v1[0] = v1[0] * c2[0] + sgn * p1[0] * c2[1]; v1[1] = v1[1] * c2[2] + sgn * p1[1] * c2[3];
;     v1[2] = v1[2] * c3[0] + sgn * p1[2] * c3[1]; v1[3] = v1[3] * c3[2] + sgn * p1[3] * c3[3];
;     __device__ __forceinline__ void operator()(const f32x4 (&acc)[2][2][4][2], const Unit& u, int wr_in, int wc_in, int fr_in, int fq_in) const {
;     ...
;                 const float rs = sc / sqrtf(ss * invn + RMS_EPS);
; #pragma unroll
;                 for (int bj = 0; bj < 2; ++bj) {
;                     const int g32 = u.pn * 8 + bj * 4 + wc;
;                     const int rope = (isq && lat && (g32 % 3 == 2)) ? 1 : 0;
;                     f32x4 v0 = acc[ai][bj][m][0] * rs, v1 = acc[ai][bj][m][1] * rs;
;                     if (rope) rope_apply(v0, v1, 1, row, wc, fq, tabM, tabM);
;                     store_bf16x8(O + (size_t)row * ldo + g32 * 32 + 8 * fq, v0, v1);
.LBB0_204:
	v_fmaak_f32 v0, v154, v116, 0x358637bd
	v_mul_f32_e32 v114, 0x4f800000, v0
	v_cmp_gt_f32_e32 vcc, s28, v0
	s_nop 1
	v_cndmask_b32_e32 v0, v0, v114, vcc
	v_sqrt_f32_e32 v114, v0
	s_nop 0
	v_add_u32_e32 v115, -1, v114
	v_fma_f32 v117, -v115, v114, v0
	v_add_u32_e32 v116, 1, v114
	v_cmp_ge_f32_e64 s[0:1], 0, v117
	s_nop 1
	v_cndmask_b32_e64 v115, v114, v115, s[0:1]
	v_fma_f32 v114, -v116, v114, v0
	v_cmp_lt_f32_e64 s[0:1], 0, v114
	s_nop 1
	v_cndmask_b32_e64 v114, v115, v116, s[0:1]
	v_mul_f32_e32 v115, 0x37800000, v114
	v_cndmask_b32_e32 v114, v114, v115, vcc
	v_cmp_class_f32_e32 vcc, v0, v238
	s_nop 1
	v_cndmask_b32_e32 v0, v114, v0, vcc
	v_div_scale_f32 v114, s[0:1], v0, v0, v158
	v_rcp_f32_e32 v115, v114
	s_nop 0
	v_fma_f32 v116, -v114, v115, 1.0
	v_fmac_f32_e32 v115, v116, v115
	v_div_scale_f32 v116, vcc, v158, v0, v158
	v_mul_f32_e32 v117, v116, v115
	v_fma_f32 v118, -v114, v117, v116
	v_fmac_f32_e32 v117, v118, v115
	v_fma_f32 v114, -v114, v117, v116
	v_div_fmas_f32 v114, v114, v115, v117
	v_div_fixup_f32 v114, v114, v0, v158
	v_and_b32_e32 v0, 61, v126
	v_cndmask_b32_e64 v0, v0, v161, s[44:45]
	v_lshlrev_b32_e32 v0, 4, v0
	v_pk_mul_f32 v[116:117], v[112:113], v[114:115] op_sel_hi:[1,0]
	v_pk_mul_f32 v[118:119], v[110:111], v[114:115] op_sel_hi:[1,0]
	v_pk_mul_f32 v[120:121], v[108:109], v[114:115] op_sel_hi:[1,0]
	v_pk_mul_f32 v[124:125], v[106:107], v[114:115] op_sel_hi:[1,0]
	s_andn2_b64 vcc, exec, s[48:49]
	v_lshlrev_b32_e32 v0, 2, v0
	s_cbranch_vccnz .LBB0_206
	v_and_b32_e32 v107, 64, v242
	v_xor_b32_e32 v106, 16, v242
	v_add_u32_e32 v107, 64, v107
	v_cmp_lt_i32_e32 vcc, v106, v107
	v_lshl_add_u64 v[110:111], s[36:37], 0, v[0:1]
	s_nop 0
	v_cndmask_b32_e32 v106, v242, v106, vcc
	v_lshlrev_b32_e32 v106, 2, v106
	ds_bpermute_b32 v128, v106, v118
	ds_bpermute_b32 v152, v106, v124
	ds_bpermute_b32 v129, v106, v119
	ds_bpermute_b32 v153, v106, v125
	ds_bpermute_b32 v115, v106, v116
	ds_bpermute_b32 v127, v106, v120
	ds_bpermute_b32 v164, v106, v117
	ds_bpermute_b32 v165, v106, v121
	global_load_dwordx4 v[144:147], v[110:111], off
	global_load_dwordx4 v[148:151], v[110:111], off offset:16
	global_load_dwordx4 v[106:109], v[110:111], off offset:32
	s_nop 0
	global_load_dwordx4 v[110:113], v[110:111], off offset:48
	s_waitcnt lgkmcnt(0)
	v_mul_f32_e32 v115, v142, v115
	v_pk_mul_f32 v[128:129], v[142:143], v[128:129] op_sel_hi:[0,1]
	s_waitcnt vmcnt(0)
	v_mov_b32_e32 v162, v144
	v_mul_f32_e32 v116, v116, v148
	v_mul_f32_e32 v144, v115, v149
	v_mul_f32_e32 v149, v142, v164
	v_mov_b32_e32 v148, v117
	v_pk_mul_f32 v[148:149], v[148:149], v[150:151]
	v_mov_b32_e32 v163, v146
	v_mov_b32_e32 v146, v145
	v_mov_b32_e32 v145, v149
	v_mov_b32_e32 v117, v148
	v_pk_mul_f32 v[118:119], v[118:119], v[162:163]
	v_pk_add_f32 v[116:117], v[144:145], v[116:117]
	v_mul_f32_e32 v145, v142, v165
	v_mov_b32_e32 v144, v121
	v_pk_fma_f32 v[118:119], v[128:129], v[146:147], v[118:119]
	v_mov_b32_e32 v128, v106
	v_mov_b32_e32 v129, v108
	v_mov_b32_e32 v108, v107
	v_mul_f32_e32 v107, v142, v127
	v_pk_mul_f32 v[112:113], v[144:145], v[112:113]
	v_pk_mul_f32 v[124:125], v[124:125], v[128:129]
	v_pk_mul_f32 v[128:129], v[142:143], v[152:153] op_sel_hi:[0,1]
	v_mul_f32_e32 v106, v120, v110
	v_mul_f32_e32 v110, v107, v111
	v_mov_b32_e32 v111, v113
	v_mov_b32_e32 v107, v112
	v_pk_fma_f32 v[124:125], v[128:129], v[108:109], v[124:125]
	v_pk_add_f32 v[120:121], v[110:111], v[106:107]
.LBB0_206:
	v_mad_i64_i32 v[106:107], s[0:1], v126, s4, 0
	v_lshl_add_u64 v[106:107], v[106:107], 1, s[84:85]
	v_lshl_add_u64 v[108:109], s[94:95], 1, v[106:107]
	v_lshl_add_u64 v[112:113], v[122:123], 1, v[108:109]
	s_and_b64 vcc, exec, s[40:41]
	s_mov_b64 s[0:1], 0
	v_cvt_pk_bf16_f32 v108, v118, v119
	v_cvt_pk_bf16_f32 v109, v116, v117
	v_cvt_pk_bf16_f32 v110, v124, v125
	v_cvt_pk_bf16_f32 v111, v120, v121
	global_store_dwordx4 v[112:113], v[108:111], off
	s_cbranch_vccnz .LBB0_208
	s_lshr_b32 s0, s13, 31
	s_add_i32 s0, s13, s0
	s_mul_i32 s0, s0, 3
	s_sub_i32 s0, s12, s0
	s_cmp_eq_u32 s0, 2
	s_cselect_b64 s[0:1], -1, 0
;     __device__ __forceinline__ void operator()(const f32x4 (&acc)[2][2][4][2], const Unit& u, int wr_in, int wc_in, int fr_in, int fq_in) const {
;     ...
;                 const int row = u.pm * 256 + ai * 128 + wr * 64 + 4 * fr + m;
;                 const float* sp = ssq + (size_t)row * 20;
;                 const f32x4 p0 = *(const f32x4*)(sp), p1 = *(const f32x4*)(sp + 4);
;                 float ss = (p0[0] + p0[1]) + (p0[2] + p0[3]) + (p1[0] + p1[1]) + (p1[2] + p1[3]);
;                 if (nslot == 12) { const f32x4 p2 = *(const f32x4*)(sp + 8); ss += (p2[0] + p2[1]) + (p2[2] + p2[3]); }
;     ...
; #pragma unroll
;                 for (int bj = 0; bj < 2; ++bj) {
;                     const int g32 = u.pn * 8 + bj * 4 + wc;
;                     const int rope = (isq && lat && (g32 % 3 == 2)) ? 1 : 0;
;                     f32x4 v0 = acc[ai][bj][m][0] * rs, v1 = acc[ai][bj][m][1] * rs;
;                     if (rope) rope_apply(v0, v1, 1, row, wc, fq, tabM, tabM);
;                     store_bf16x8(O + (size_t)row * ldo + g32 * 32 + 8 * fq, v0, v1);
.LBB0_208:
	v_mov_b32_e32 v115, v114
	v_mov_b32_e32 v112, v114
	v_mov_b32_e32 v113, v114
	v_pk_mul_f32 v[108:109], v[104:105], v[112:113]
	v_pk_mul_f32 v[110:111], v[102:103], v[114:115]
	v_pk_mul_f32 v[112:113], v[100:101], v[112:113]
	s_andn2_b64 vcc, exec, s[0:1]
	v_pk_mul_f32 v[114:115], v[98:99], v[114:115]
	s_cbranch_vccnz .LBB0_210
	v_and_b32_e32 v99, 64, v242
	v_xor_b32_e32 v98, 16, v242
	v_add_u32_e32 v99, 64, v99
	v_cmp_lt_i32_e32 vcc, v98, v99
	v_lshl_add_u64 v[102:103], s[36:37], 0, v[0:1]
	s_nop 0
	v_cndmask_b32_e32 v98, v242, v98, vcc
	v_lshlrev_b32_e32 v98, 2, v98
	ds_bpermute_b32 v120, v98, v110
	ds_bpermute_b32 v128, v98, v114
	ds_bpermute_b32 v121, v98, v111
	ds_bpermute_b32 v129, v98, v115
	ds_bpermute_b32 v146, v98, v108
	ds_bpermute_b32 v147, v98, v112
	ds_bpermute_b32 v148, v98, v109
	ds_bpermute_b32 v149, v98, v113
	global_load_dwordx4 v[116:119], v[102:103], off
	global_load_dwordx4 v[124:127], v[102:103], off offset:16
	global_load_dwordx4 v[98:101], v[102:103], off offset:32
	s_nop 0
	global_load_dwordx4 v[102:105], v[102:103], off offset:48
	s_waitcnt lgkmcnt(0)
	v_mul_f32_e32 v0, v142, v146
	v_pk_mul_f32 v[120:121], v[142:143], v[120:121] op_sel_hi:[0,1]
	s_waitcnt vmcnt(0)
	v_mov_b32_e32 v144, v116
	v_mov_b32_e32 v145, v118
	v_mul_f32_e32 v108, v108, v124
	v_mul_f32_e32 v116, v0, v125
	v_mul_f32_e32 v125, v142, v148
	v_mov_b32_e32 v124, v109
	v_pk_mul_f32 v[110:111], v[110:111], v[144:145]
	v_mov_b32_e32 v118, v117
	v_pk_mul_f32 v[124:125], v[124:125], v[126:127]
	v_pk_fma_f32 v[110:111], v[120:121], v[118:119], v[110:111]
	v_mov_b32_e32 v117, v125
	v_mov_b32_e32 v109, v124
	v_mul_f32_e32 v119, v142, v149
	v_mov_b32_e32 v118, v113
	v_pk_add_f32 v[108:109], v[116:117], v[108:109]
	v_mov_b32_e32 v116, v98
	v_mov_b32_e32 v117, v100
	v_mul_f32_e32 v0, v142, v147
	v_pk_mul_f32 v[104:105], v[118:119], v[104:105]
	v_pk_mul_f32 v[114:115], v[114:115], v[116:117]
	v_pk_mul_f32 v[116:117], v[142:143], v[128:129] op_sel_hi:[0,1]
	v_mov_b32_e32 v100, v99
	v_mul_f32_e32 v98, v112, v102
	v_mul_f32_e32 v102, v0, v103
	v_mov_b32_e32 v103, v105
	v_mov_b32_e32 v99, v104
	v_pk_fma_f32 v[114:115], v[116:117], v[100:101], v[114:115]
	v_pk_add_f32 v[112:113], v[102:103], v[98:99]
.LBB0_210:
	v_lshl_add_u64 v[98:99], s[96:97], 1, v[106:107]
	v_lshl_add_u64 v[102:103], v[122:123], 1, v[98:99]
	v_cvt_pk_bf16_f32 v98, v110, v111
	v_cvt_pk_bf16_f32 v99, v108, v109
	v_cvt_pk_bf16_f32 v100, v114, v115
	v_cvt_pk_bf16_f32 v101, v112, v113
	global_store_dwordx4 v[102:103], v[98:101], off
	v_or_b32_e32 v108, 2, v160
	s_and_b64 vcc, exec, s[42:43]
	v_mov_b64_e32 v[98:99], s[86:87]
	v_mad_i64_i32 v[98:99], s[0:1], v108, s26, v[98:99]
	global_load_dwordx4 v[100:103], v[98:99], off
	global_load_dwordx4 v[104:107], v[98:99], off offset:16
	s_waitcnt vmcnt(0) lgkmcnt(0)
	v_mov_b32_e32 v110, v101
	v_mov_b32_e32 v111, v102
	v_mov_b32_e32 v101, v103
	v_pk_add_f32 v[100:101], v[110:111], v[100:101]
	v_mov_b32_e32 v102, v106
	v_mov_b32_e32 v103, v104
	v_mov_b32_e32 v104, v107
	v_pk_add_f32 v[100:101], v[100:101], v[100:101] op_sel:[0,1] op_sel_hi:[1,0]
	v_pk_add_f32 v[102:103], v[102:103], v[104:105]
	s_nop 0
	v_pk_add_f32 v[100:101], v[100:101], v[102:103] op_sel:[0,1] op_sel_hi:[1,0]
	s_nop 0
	v_pk_add_f32 v[100:101], v[102:103], v[100:101]
	s_cbranch_vccnz .LBB0_212
	global_load_dwordx4 v[102:105], v[98:99], off offset:32
	s_waitcnt vmcnt(0) lgkmcnt(0)
	v_mov_b32_e32 v98, v103
	v_mov_b32_e32 v99, v104
	v_mov_b32_e32 v103, v105
	v_pk_add_f32 v[98:99], v[98:99], v[102:103]
	s_nop 0
	v_add_f32_e32 v0, v98, v99
	v_add_f32_e32 v100, v100, v0

; __device__ __forceinline__ void rope_apply(f32x4& v0, f32x4& v1, int kind, int row, int wc, int fq, const float* tabM, const float* tabS) {
;     const int t = row & 2047, gr = t >> 6, gc = t & 63;
;     const float* tb; float sgn; f32x4 p0, p1;
;     if (kind == 1) {
;         const int pos = (fq < 2) ? gr : gc; tb = tabM + pos * 16; sgn = (fq & 1) ? 1.f : -1.f;
; #pragma unroll
;         for (int e = 0; e < 4; ++e) { p0[e] = __shfl_xor(v0[e], 16); p1[e] = __shfl_xor(v1[e], 16); }
;     } else {
;         const int pos = (wc & 1) ? gc : gr; tb = tabS + pos * 32 + (fq & 1) * 16; sgn = (fq & 2) ? 1.f : -1.f;
; #pragma unroll
;         for (int e = 0; e < 4; ++e) { p0[e] = __shfl_xor(v0[e], 32); p1[e] = __shfl_xor(v1[e], 32); }
;     }
;     const f32x4 c0 = *(const f32x4*)(tb), c1 = *(const f32x4*)(tb + 4), c2 = *(const f32x4*)(tb + 8), c3 = *(const f32x4*)(tb + 12);
;     v0[0] = v0[0] * c0[0] + sgn * p0[0] * c0[1]; v0[1] = v0[1] * c0[2] + sgn * p0[1] * c0[3];
;     v0[2] = v0[2] * c1[0] + sgn * p0[2] * c1[1]; v0[3] = v0[3] * c1[2] + sgn * p0[3] * c1[3];
;     v1[0] = v1[0] * c2[0] + sgn * p1[0] * c2[1]; v1[1] = v1[1] * c2[2] + sgn * p1[1] * c2[3];
;     v1[2] = v1[2] * c3[0] + sgn * p1[2] * c3[1]; v1[3] = v1[3] * c3[2] + sgn * p1[3] * c3[3];
;     __device__ __forceinline__ void operator()(const f32x4 (&acc)[2][2][4][2], const Unit& u, int wr_in, int wc_in, int fr_in, int fq_in) const {
;     ...
;                 const float rs = sc / sqrtf(ss * invn + RMS_EPS);
; #pragma unroll
;                 for (int bj = 0; bj < 2; ++bj) {
;                     const int g32 = u.pn * 8 + bj * 4 + wc;
;                     const int rope = (isq && lat && (g32 % 3 == 2)) ? 1 : 0;
;                     f32x4 v0 = acc[ai][bj][m][0] * rs, v1 = acc[ai][bj][m][1] * rs;
;                     if (rope) rope_apply(v0, v1, 1, row, wc, fq, tabM, tabM);
;                     store_bf16x8(O + (size_t)row * ldo + g32 * 32 + 8 * fq, v0, v1);
.LBB0_214:
	v_fmaak_f32 v0, v154, v100, 0x358637bd
	v_mul_f32_e32 v98, 0x4f800000, v0
	v_cmp_gt_f32_e32 vcc, s28, v0
	s_nop 1
	v_cndmask_b32_e32 v0, v0, v98, vcc
	v_sqrt_f32_e32 v98, v0
	s_nop 0
	v_add_u32_e32 v99, -1, v98
	v_fma_f32 v101, -v99, v98, v0
	v_add_u32_e32 v100, 1, v98
	v_cmp_ge_f32_e64 s[0:1], 0, v101
	s_nop 1
	v_cndmask_b32_e64 v99, v98, v99, s[0:1]
	v_fma_f32 v98, -v100, v98, v0
	v_cmp_lt_f32_e64 s[0:1], 0, v98
	s_nop 1
	v_cndmask_b32_e64 v98, v99, v100, s[0:1]
	v_mul_f32_e32 v99, 0x37800000, v98
	v_cndmask_b32_e32 v98, v98, v99, vcc
	v_cmp_class_f32_e32 vcc, v0, v238
	s_nop 1
	v_cndmask_b32_e32 v0, v98, v0, vcc
	v_div_scale_f32 v98, s[0:1], v0, v0, v158
	v_rcp_f32_e32 v99, v98
	s_nop 0
	v_fma_f32 v100, -v98, v99, 1.0
	v_fmac_f32_e32 v99, v100, v99
	v_div_scale_f32 v100, vcc, v158, v0, v158
	v_mul_f32_e32 v101, v100, v99
	v_fma_f32 v102, -v98, v101, v100
	v_fmac_f32_e32 v101, v102, v99
	v_fma_f32 v98, -v98, v101, v100
	v_div_fmas_f32 v98, v98, v99, v101
	v_div_fixup_f32 v98, v98, v0, v158
	v_and_b32_e32 v0, 62, v108
	v_cndmask_b32_e64 v0, v0, v161, s[44:45]
	v_lshlrev_b32_e32 v0, 4, v0
	v_pk_mul_f32 v[100:101], v[96:97], v[98:99] op_sel_hi:[1,0]
	v_pk_mul_f32 v[102:103], v[94:95], v[98:99] op_sel_hi:[1,0]
	v_pk_mul_f32 v[104:105], v[92:93], v[98:99] op_sel_hi:[1,0]
	v_pk_mul_f32 v[106:107], v[90:91], v[98:99] op_sel_hi:[1,0]
	s_andn2_b64 vcc, exec, s[48:49]
	v_lshlrev_b32_e32 v0, 2, v0
	s_cbranch_vccnz .LBB0_216
	v_and_b32_e32 v91, 64, v242
	v_xor_b32_e32 v90, 16, v242
	v_add_u32_e32 v91, 64, v91
	v_cmp_lt_i32_e32 vcc, v90, v91
	v_lshl_add_u64 v[94:95], s[36:37], 0, v[0:1]
	s_nop 0
	v_cndmask_b32_e32 v90, v242, v90, vcc
	v_lshlrev_b32_e32 v90, 2, v90
	ds_bpermute_b32 v118, v90, v102
	ds_bpermute_b32 v120, v90, v106
	ds_bpermute_b32 v119, v90, v103
	ds_bpermute_b32 v121, v90, v107
	ds_bpermute_b32 v99, v90, v100
	ds_bpermute_b32 v109, v90, v104
	ds_bpermute_b32 v126, v90, v101
	ds_bpermute_b32 v127, v90, v105
	global_load_dwordx4 v[110:113], v[94:95], off
	global_load_dwordx4 v[114:117], v[94:95], off offset:16
	global_load_dwordx4 v[90:93], v[94:95], off offset:32
	s_nop 0
	global_load_dwordx4 v[94:97], v[94:95], off offset:48
	s_waitcnt lgkmcnt(0)
	v_mul_f32_e32 v99, v142, v99
	v_pk_mul_f32 v[118:119], v[142:143], v[118:119] op_sel_hi:[0,1]
	s_waitcnt vmcnt(0)
	v_mov_b32_e32 v124, v110
	v_mov_b32_e32 v125, v112
	v_mul_f32_e32 v100, v100, v114
	v_mul_f32_e32 v110, v99, v115
	v_mul_f32_e32 v115, v142, v126
	v_mov_b32_e32 v114, v101
	v_pk_mul_f32 v[102:103], v[102:103], v[124:125]
	v_mov_b32_e32 v112, v111
	v_pk_mul_f32 v[114:115], v[114:115], v[116:117]
	v_pk_fma_f32 v[102:103], v[118:119], v[112:113], v[102:103]
	v_mov_b32_e32 v111, v115
	v_mov_b32_e32 v101, v114
	v_mul_f32_e32 v113, v142, v127
	v_mov_b32_e32 v112, v105
	v_pk_add_f32 v[100:101], v[110:111], v[100:101]
	v_mov_b32_e32 v110, v90
	v_mov_b32_e32 v111, v92
	v_mov_b32_e32 v92, v91
	v_mul_f32_e32 v91, v142, v109
	v_pk_mul_f32 v[96:97], v[112:113], v[96:97]
	v_pk_mul_f32 v[106:107], v[106:107], v[110:111]
	v_pk_mul_f32 v[110:111], v[142:143], v[120:121] op_sel_hi:[0,1]
	v_mul_f32_e32 v90, v104, v94
	v_mul_f32_e32 v94, v91, v95
	v_mov_b32_e32 v95, v97
	v_mov_b32_e32 v91, v96
	v_pk_fma_f32 v[106:107], v[110:111], v[92:93], v[106:107]
	v_pk_add_f32 v[104:105], v[94:95], v[90:91]
.LBB0_216:
	v_mad_i64_i32 v[90:91], s[0:1], v108, s4, 0
	v_lshl_add_u64 v[90:91], v[90:91], 1, s[84:85]
	v_lshl_add_u64 v[92:93], s[94:95], 1, v[90:91]
	v_lshl_add_u64 v[96:97], v[122:123], 1, v[92:93]
	s_and_b64 vcc, exec, s[40:41]
	s_mov_b64 s[0:1], 0
	v_cvt_pk_bf16_f32 v92, v102, v103
	v_cvt_pk_bf16_f32 v93, v100, v101
	v_cvt_pk_bf16_f32 v94, v106, v107
	v_cvt_pk_bf16_f32 v95, v104, v105
	global_store_dwordx4 v[96:97], v[92:95], off
	s_cbranch_vccnz .LBB0_218
	s_lshr_b32 s0, s13, 31
	s_add_i32 s0, s13, s0
	s_mul_i32 s0, s0, 3
	s_sub_i32 s0, s12, s0
	s_cmp_eq_u32 s0, 2
	s_cselect_b64 s[0:1], -1, 0
;     __device__ __forceinline__ void operator()(const f32x4 (&acc)[2][2][4][2], const Unit& u, int wr_in, int wc_in, int fr_in, int fq_in) const {
;     ...
;                 const int row = u.pm * 256 + ai * 128 + wr * 64 + 4 * fr + m;
;                 const float* sp = ssq + (size_t)row * 20;
;                 const f32x4 p0 = *(const f32x4*)(sp), p1 = *(const f32x4*)(sp + 4);
;                 float ss = (p0[0] + p0[1]) + (p0[2] + p0[3]) + (p1[0] + p1[1]) + (p1[2] + p1[3]);
;                 if (nslot == 12) { const f32x4 p2 = *(const f32x4*)(sp + 8); ss += (p2[0] + p2[1]) + (p2[2] + p2[3]); }
;     ...
; #pragma unroll
;                 for (int bj = 0; bj < 2; ++bj) {
;                     const int g32 = u.pn * 8 + bj * 4 + wc;
;                     const int rope = (isq && lat && (g32 % 3 == 2)) ? 1 : 0;
;                     f32x4 v0 = acc[ai][bj][m][0] * rs, v1 = acc[ai][bj][m][1] * rs;
;                     if (rope) rope_apply(v0, v1, 1, row, wc, fq, tabM, tabM);
;                     store_bf16x8(O + (size_t)row * ldo + g32 * 32 + 8 * fq, v0, v1);
.LBB0_218:
	v_mov_b32_e32 v99, v98
	v_mov_b32_e32 v96, v98
	v_mov_b32_e32 v97, v98
	v_pk_mul_f32 v[92:93], v[88:89], v[96:97]
	v_pk_mul_f32 v[94:95], v[86:87], v[98:99]
	v_pk_mul_f32 v[96:97], v[84:85], v[96:97]
	s_andn2_b64 vcc, exec, s[0:1]
	v_pk_mul_f32 v[98:99], v[82:83], v[98:99]
	s_cbranch_vccnz .LBB0_220
	v_and_b32_e32 v83, 64, v242
	v_xor_b32_e32 v82, 16, v242
	v_add_u32_e32 v83, 64, v83
	v_cmp_lt_i32_e32 vcc, v82, v83
	v_lshl_add_u64 v[86:87], s[36:37], 0, v[0:1]
	s_nop 0
	v_cndmask_b32_e32 v82, v242, v82, vcc
	v_lshlrev_b32_e32 v82, 2, v82
	ds_bpermute_b32 v108, v82, v94
	ds_bpermute_b32 v110, v82, v98
	ds_bpermute_b32 v109, v82, v95
	ds_bpermute_b32 v111, v82, v99
	ds_bpermute_b32 v114, v82, v92
	ds_bpermute_b32 v115, v82, v96
	ds_bpermute_b32 v116, v82, v93
	ds_bpermute_b32 v117, v82, v97
	global_load_dwordx4 v[100:103], v[86:87], off
	global_load_dwordx4 v[104:107], v[86:87], off offset:16
	global_load_dwordx4 v[82:85], v[86:87], off offset:32
	s_nop 0
	global_load_dwordx4 v[86:89], v[86:87], off offset:48
	s_waitcnt lgkmcnt(0)
	v_mul_f32_e32 v0, v142, v114
	v_pk_mul_f32 v[108:109], v[142:143], v[108:109] op_sel_hi:[0,1]
	s_waitcnt vmcnt(0)
	v_mov_b32_e32 v112, v100
	v_mov_b32_e32 v113, v102
	v_mul_f32_e32 v92, v92, v104
	v_mul_f32_e32 v100, v0, v105
	v_mul_f32_e32 v105, v142, v116
	v_mov_b32_e32 v104, v93
	v_pk_mul_f32 v[94:95], v[94:95], v[112:113]
	v_mov_b32_e32 v102, v101
	v_pk_mul_f32 v[104:105], v[104:105], v[106:107]
	v_pk_fma_f32 v[94:95], v[108:109], v[102:103], v[94:95]
	v_mov_b32_e32 v101, v105
	v_mov_b32_e32 v93, v104
	v_mul_f32_e32 v103, v142, v117
	v_mov_b32_e32 v102, v97
	v_pk_add_f32 v[92:93], v[100:101], v[92:93]
	v_mov_b32_e32 v100, v82
	v_mov_b32_e32 v101, v84
	v_mul_f32_e32 v0, v142, v115
	v_pk_mul_f32 v[88:89], v[102:103], v[88:89]
	v_pk_mul_f32 v[98:99], v[98:99], v[100:101]
	v_pk_mul_f32 v[100:101], v[142:143], v[110:111] op_sel_hi:[0,1]
	v_mov_b32_e32 v84, v83
	v_mul_f32_e32 v82, v96, v86
	v_mul_f32_e32 v86, v0, v87
	v_mov_b32_e32 v87, v89
	v_mov_b32_e32 v83, v88
	v_pk_fma_f32 v[98:99], v[100:101], v[84:85], v[98:99]
	v_pk_add_f32 v[96:97], v[86:87], v[82:83]
.LBB0_220:
	v_lshl_add_u64 v[82:83], s[96:97], 1, v[90:91]
	v_lshl_add_u64 v[86:87], v[122:123], 1, v[82:83]
	v_cvt_pk_bf16_f32 v82, v94, v95
	v_cvt_pk_bf16_f32 v83, v92, v93
	v_cvt_pk_bf16_f32 v84, v98, v99
	v_cvt_pk_bf16_f32 v85, v96, v97
	global_store_dwordx4 v[86:87], v[82:85], off
	v_or_b32_e32 v92, 3, v160
	s_and_b64 vcc, exec, s[42:43]
	v_mov_b64_e32 v[82:83], s[86:87]
	v_mad_i64_i32 v[82:83], s[0:1], v92, s26, v[82:83]
	global_load_dwordx4 v[84:87], v[82:83], off
	global_load_dwordx4 v[88:91], v[82:83], off offset:16
	s_waitcnt vmcnt(0) lgkmcnt(0)
	v_mov_b32_e32 v94, v85
	v_mov_b32_e32 v95, v86
	v_mov_b32_e32 v85, v87
	v_pk_add_f32 v[84:85], v[94:95], v[84:85]
	v_mov_b32_e32 v86, v90
	v_mov_b32_e32 v87, v88
	v_mov_b32_e32 v88, v91
	v_pk_add_f32 v[84:85], v[84:85], v[84:85] op_sel:[0,1] op_sel_hi:[1,0]
	v_pk_add_f32 v[86:87], v[86:87], v[88:89]
	s_nop 0
	v_pk_add_f32 v[84:85], v[84:85], v[86:87] op_sel:[0,1] op_sel_hi:[1,0]
	s_nop 0
	v_pk_add_f32 v[84:85], v[86:87], v[84:85]
	s_cbranch_vccnz .LBB0_222
	global_load_dwordx4 v[86:89], v[82:83], off offset:32
	s_waitcnt vmcnt(0) lgkmcnt(0)
	v_mov_b32_e32 v82, v87
	v_mov_b32_e32 v83, v88
	v_mov_b32_e32 v87, v89
	v_pk_add_f32 v[82:83], v[82:83], v[86:87]
	s_nop 0
	v_add_f32_e32 v0, v82, v83
	v_add_f32_e32 v84, v84, v0

; __device__ __forceinline__ void rope_apply(f32x4& v0, f32x4& v1, int kind, int row, int wc, int fq, const float* tabM, const float* tabS) {
;     const int t = row & 2047, gr = t >> 6, gc = t & 63;
;     const float* tb; float sgn; f32x4 p0, p1;
;     if (kind == 1) {
;         const int pos = (fq < 2) ? gr : gc; tb = tabM + pos * 16; sgn = (fq & 1) ? 1.f : -1.f;
; #pragma unroll
;         for (int e = 0; e < 4; ++e) { p0[e] = __shfl_xor(v0[e], 16); p1[e] = __shfl_xor(v1[e], 16); }
;     } else {
;         const int pos = (wc & 1) ? gc : gr; tb = tabS + pos * 32 + (fq & 1) * 16; sgn = (fq & 2) ? 1.f : -1.f;
; #pragma unroll
;         for (int e = 0; e < 4; ++e) { p0[e] = __shfl_xor(v0[e], 32); p1[e] = __shfl_xor(v1[e], 32); }
;     }
;     const f32x4 c0 = *(const f32x4*)(tb), c1 = *(const f32x4*)(tb + 4), c2 = *(const f32x4*)(tb + 8), c3 = *(const f32x4*)(tb + 12);
;     v0[0] = v0[0] * c0[0] + sgn * p0[0] * c0[1]; v0[1] = v0[1] * c0[2] + sgn * p0[1] * c0[3];
;     v0[2] = v0[2] * c1[0] + sgn * p0[2] * c1[1]; v0[3] = v0[3] * c1[2] + sgn * p0[3] * c1[3];
;     v1[0] = v1[0] * c2[0] + sgn * p1[0] * c2[1]; v1[1] = v1[1] * c2[2] + sgn * p1[1] * c2[3];
;     v1[2] = v1[2] * c3[0] + sgn * p1[2] * c3[1]; v1[3] = v1[3] * c3[2] + sgn * p1[3] * c3[3];
;     __device__ __forceinline__ void operator()(const f32x4 (&acc)[2][2][4][2], const Unit& u, int wr_in, int wc_in, int fr_in, int fq_in) const {
;     ...
;                 const float rs = sc / sqrtf(ss * invn + RMS_EPS);
; #pragma unroll
;                 for (int bj = 0; bj < 2; ++bj) {
;                     const int g32 = u.pn * 8 + bj * 4 + wc;
;                     const int rope = (isq && lat && (g32 % 3 == 2)) ? 1 : 0;
;                     f32x4 v0 = acc[ai][bj][m][0] * rs, v1 = acc[ai][bj][m][1] * rs;
;                     if (rope) rope_apply(v0, v1, 1, row, wc, fq, tabM, tabM);
;                     store_bf16x8(O + (size_t)row * ldo + g32 * 32 + 8 * fq, v0, v1);
.LBB0_224:
	v_fmaak_f32 v0, v154, v84, 0x358637bd
	v_mul_f32_e32 v82, 0x4f800000, v0
	v_cmp_gt_f32_e32 vcc, s28, v0
	s_nop 1
	v_cndmask_b32_e32 v0, v0, v82, vcc
	v_sqrt_f32_e32 v82, v0
	s_nop 0
	v_add_u32_e32 v83, -1, v82
	v_fma_f32 v85, -v83, v82, v0
	v_add_u32_e32 v84, 1, v82
	v_cmp_ge_f32_e64 s[0:1], 0, v85
	s_nop 1
	v_cndmask_b32_e64 v83, v82, v83, s[0:1]
	v_fma_f32 v82, -v84, v82, v0
	v_cmp_lt_f32_e64 s[0:1], 0, v82
	s_nop 1
	v_cndmask_b32_e64 v82, v83, v84, s[0:1]
	v_mul_f32_e32 v83, 0x37800000, v82
	v_cndmask_b32_e32 v82, v82, v83, vcc
	v_cmp_class_f32_e32 vcc, v0, v238
	s_nop 1
	v_cndmask_b32_e32 v0, v82, v0, vcc
	v_div_scale_f32 v82, s[0:1], v0, v0, v158
	v_rcp_f32_e32 v83, v82
	s_nop 0
	v_fma_f32 v84, -v82, v83, 1.0
	v_fmac_f32_e32 v83, v84, v83
	v_div_scale_f32 v84, vcc, v158, v0, v158
	v_mul_f32_e32 v85, v84, v83
	v_fma_f32 v86, -v82, v85, v84
	v_fmac_f32_e32 v85, v86, v83
	v_fma_f32 v82, -v82, v85, v84
	v_div_fmas_f32 v82, v82, v83, v85
	v_div_fixup_f32 v82, v82, v0, v158
	v_and_b32_e32 v0, 63, v92
	v_cndmask_b32_e64 v0, v0, v161, s[44:45]
	v_lshlrev_b32_e32 v0, 4, v0
	v_pk_mul_f32 v[84:85], v[80:81], v[82:83] op_sel_hi:[1,0]
	v_pk_mul_f32 v[86:87], v[78:79], v[82:83] op_sel_hi:[1,0]
	v_pk_mul_f32 v[88:89], v[76:77], v[82:83] op_sel_hi:[1,0]
	v_pk_mul_f32 v[90:91], v[74:75], v[82:83] op_sel_hi:[1,0]
	s_andn2_b64 vcc, exec, s[48:49]
	v_lshlrev_b32_e32 v0, 2, v0
	s_cbranch_vccnz .LBB0_226
	v_and_b32_e32 v75, 64, v242
	v_xor_b32_e32 v74, 16, v242
	v_add_u32_e32 v75, 64, v75
	v_cmp_lt_i32_e32 vcc, v74, v75
	v_lshl_add_u64 v[78:79], s[36:37], 0, v[0:1]
	s_nop 0
	v_cndmask_b32_e32 v74, v242, v74, vcc
	v_lshlrev_b32_e32 v74, 2, v74
	ds_bpermute_b32 v102, v74, v86
	ds_bpermute_b32 v104, v74, v90
	ds_bpermute_b32 v103, v74, v87
	ds_bpermute_b32 v105, v74, v91
	ds_bpermute_b32 v83, v74, v84
	ds_bpermute_b32 v93, v74, v88
	ds_bpermute_b32 v108, v74, v85
	ds_bpermute_b32 v109, v74, v89
	global_load_dwordx4 v[94:97], v[78:79], off
	global_load_dwordx4 v[98:101], v[78:79], off offset:16
	global_load_dwordx4 v[74:77], v[78:79], off offset:32
	s_nop 0
	global_load_dwordx4 v[78:81], v[78:79], off offset:48
	s_waitcnt lgkmcnt(0)
	v_mul_f32_e32 v83, v142, v83
	v_pk_mul_f32 v[102:103], v[142:143], v[102:103] op_sel_hi:[0,1]
	s_waitcnt vmcnt(0)
	v_mov_b32_e32 v106, v94
	v_mov_b32_e32 v107, v96
	v_mul_f32_e32 v84, v84, v98
	v_mul_f32_e32 v94, v83, v99
	v_mul_f32_e32 v99, v142, v108
	v_mov_b32_e32 v98, v85
	v_pk_mul_f32 v[86:87], v[86:87], v[106:107]
	v_mov_b32_e32 v96, v95
	v_pk_mul_f32 v[98:99], v[98:99], v[100:101]
	v_pk_fma_f32 v[86:87], v[102:103], v[96:97], v[86:87]
	v_mov_b32_e32 v95, v99
	v_mov_b32_e32 v85, v98
	v_mul_f32_e32 v97, v142, v109
	v_mov_b32_e32 v96, v89
	v_pk_add_f32 v[84:85], v[94:95], v[84:85]
	v_mov_b32_e32 v94, v74
	v_mov_b32_e32 v95, v76
	v_mov_b32_e32 v76, v75
	v_mul_f32_e32 v75, v142, v93
	v_pk_mul_f32 v[80:81], v[96:97], v[80:81]
	v_pk_mul_f32 v[90:91], v[90:91], v[94:95]
	v_pk_mul_f32 v[94:95], v[142:143], v[104:105] op_sel_hi:[0,1]
	v_mul_f32_e32 v74, v88, v78
	v_mul_f32_e32 v78, v75, v79
	v_mov_b32_e32 v79, v81
	v_mov_b32_e32 v75, v80
	v_pk_fma_f32 v[90:91], v[94:95], v[76:77], v[90:91]
	v_pk_add_f32 v[88:89], v[78:79], v[74:75]
.LBB0_226:
	v_mad_i64_i32 v[74:75], s[0:1], v92, s4, 0
	v_lshl_add_u64 v[74:75], v[74:75], 1, s[84:85]
	v_lshl_add_u64 v[76:77], s[94:95], 1, v[74:75]
	v_lshl_add_u64 v[80:81], v[122:123], 1, v[76:77]
	s_and_b64 vcc, exec, s[40:41]
	s_mov_b64 s[0:1], 0
	v_cvt_pk_bf16_f32 v76, v86, v87
	v_cvt_pk_bf16_f32 v77, v84, v85
	v_cvt_pk_bf16_f32 v78, v90, v91
	v_cvt_pk_bf16_f32 v79, v88, v89
	global_store_dwordx4 v[80:81], v[76:79], off
	s_cbranch_vccnz .LBB0_228
	s_lshr_b32 s0, s13, 31
	s_add_i32 s0, s13, s0
	s_mul_i32 s0, s0, 3
	s_sub_i32 s0, s12, s0
	s_cmp_eq_u32 s0, 2
	s_cselect_b64 s[0:1], -1, 0
;     __device__ __forceinline__ void operator()(const f32x4 (&acc)[2][2][4][2], const Unit& u, int wr_in, int wc_in, int fr_in, int fq_in) const {
;     ...
;                 const int row = u.pm * 256 + ai * 128 + wr * 64 + 4 * fr + m;
;                 const float* sp = ssq + (size_t)row * 20;
;                 const f32x4 p0 = *(const f32x4*)(sp), p1 = *(const f32x4*)(sp + 4);
;                 float ss = (p0[0] + p0[1]) + (p0[2] + p0[3]) + (p1[0] + p1[1]) + (p1[2] + p1[3]);
;                 if (nslot == 12) { const f32x4 p2 = *(const f32x4*)(sp + 8); ss += (p2[0] + p2[1]) + (p2[2] + p2[3]); }
;     ...
; #pragma unroll
;                 for (int bj = 0; bj < 2; ++bj) {
;                     const int g32 = u.pn * 8 + bj * 4 + wc;
;                     const int rope = (isq && lat && (g32 % 3 == 2)) ? 1 : 0;
;                     f32x4 v0 = acc[ai][bj][m][0] * rs, v1 = acc[ai][bj][m][1] * rs;
;                     if (rope) rope_apply(v0, v1, 1, row, wc, fq, tabM, tabM);
;                     store_bf16x8(O + (size_t)row * ldo + g32 * 32 + 8 * fq, v0, v1);
.LBB0_228:
	v_mov_b32_e32 v83, v82
	v_mov_b32_e32 v80, v82
	v_mov_b32_e32 v81, v82
	v_pk_mul_f32 v[76:77], v[72:73], v[80:81]
	v_pk_mul_f32 v[78:79], v[70:71], v[82:83]
	v_pk_mul_f32 v[80:81], v[68:69], v[80:81]
	s_andn2_b64 vcc, exec, s[0:1]
	v_pk_mul_f32 v[82:83], v[66:67], v[82:83]
	s_cbranch_vccnz .LBB0_230
	v_and_b32_e32 v67, 64, v242
	v_xor_b32_e32 v66, 16, v242
	v_add_u32_e32 v67, 64, v67
	v_cmp_lt_i32_e32 vcc, v66, v67
	v_lshl_add_u64 v[70:71], s[36:37], 0, v[0:1]
	s_nop 0
	v_cndmask_b32_e32 v66, v242, v66, vcc
	v_lshlrev_b32_e32 v66, 2, v66
	ds_bpermute_b32 v92, v66, v78
	ds_bpermute_b32 v94, v66, v82
	ds_bpermute_b32 v93, v66, v79
	ds_bpermute_b32 v95, v66, v83
	ds_bpermute_b32 v98, v66, v76
	ds_bpermute_b32 v99, v66, v80
	ds_bpermute_b32 v100, v66, v77
	ds_bpermute_b32 v101, v66, v81
	global_load_dwordx4 v[84:87], v[70:71], off
	global_load_dwordx4 v[88:91], v[70:71], off offset:16
	global_load_dwordx4 v[66:69], v[70:71], off offset:32
	s_nop 0
	global_load_dwordx4 v[70:73], v[70:71], off offset:48
	s_waitcnt lgkmcnt(0)
	v_mul_f32_e32 v0, v142, v98
	v_pk_mul_f32 v[92:93], v[142:143], v[92:93] op_sel_hi:[0,1]
	s_waitcnt vmcnt(0)
	v_mov_b32_e32 v96, v84
	v_mov_b32_e32 v97, v86
	v_mul_f32_e32 v76, v76, v88
	v_mul_f32_e32 v84, v0, v89
	v_mul_f32_e32 v89, v142, v100
	v_mov_b32_e32 v88, v77
	v_pk_mul_f32 v[78:79], v[78:79], v[96:97]
	v_mov_b32_e32 v86, v85
	v_pk_mul_f32 v[88:89], v[88:89], v[90:91]
	v_pk_fma_f32 v[78:79], v[92:93], v[86:87], v[78:79]
	v_mov_b32_e32 v85, v89
	v_mov_b32_e32 v77, v88
	v_mul_f32_e32 v87, v142, v101
	v_mov_b32_e32 v86, v81
	v_pk_add_f32 v[76:77], v[84:85], v[76:77]
	v_mov_b32_e32 v84, v66
	v_mov_b32_e32 v85, v68
	v_mul_f32_e32 v0, v142, v99
	v_pk_mul_f32 v[72:73], v[86:87], v[72:73]
	v_pk_mul_f32 v[82:83], v[82:83], v[84:85]
	v_pk_mul_f32 v[84:85], v[142:143], v[94:95] op_sel_hi:[0,1]
	v_mov_b32_e32 v68, v67
	v_mul_f32_e32 v66, v80, v70
	v_mul_f32_e32 v70, v0, v71
	v_mov_b32_e32 v71, v73
	v_mov_b32_e32 v67, v72
	v_pk_fma_f32 v[82:83], v[84:85], v[68:69], v[82:83]
	v_pk_add_f32 v[80:81], v[70:71], v[66:67]
.LBB0_230:
	v_lshl_add_u64 v[66:67], s[96:97], 1, v[74:75]
	v_lshl_add_u64 v[70:71], v[122:123], 1, v[66:67]
	v_cvt_pk_bf16_f32 v66, v78, v79
	v_cvt_pk_bf16_f32 v67, v76, v77
	v_cvt_pk_bf16_f32 v68, v82, v83
	v_cvt_pk_bf16_f32 v69, v80, v81
	global_store_dwordx4 v[70:71], v[66:69], off
	v_add_u32_e32 v77, 0x80, v160
	s_and_b64 vcc, exec, s[42:43]
	v_mov_b64_e32 v[66:67], s[86:87]
	v_mad_i64_i32 v[66:67], s[0:1], v77, s26, v[66:67]
	global_load_dwordx4 v[68:71], v[66:67], off
	global_load_dwordx4 v[72:75], v[66:67], off offset:16
	s_waitcnt vmcnt(0) lgkmcnt(0)
	v_mov_b32_e32 v78, v69
	v_mov_b32_e32 v79, v70
	v_mov_b32_e32 v69, v71
	v_pk_add_f32 v[68:69], v[78:79], v[68:69]
	v_mov_b32_e32 v70, v74
	v_mov_b32_e32 v71, v72
	v_mov_b32_e32 v72, v75
	v_pk_add_f32 v[68:69], v[68:69], v[68:69] op_sel:[0,1] op_sel_hi:[1,0]
	v_pk_add_f32 v[70:71], v[70:71], v[72:73]
	s_nop 0
	v_pk_add_f32 v[68:69], v[68:69], v[70:71] op_sel:[0,1] op_sel_hi:[1,0]
	s_nop 0
	v_pk_add_f32 v[68:69], v[70:71], v[68:69]
	s_cbranch_vccnz .LBB0_232
	global_load_dwordx4 v[70:73], v[66:67], off offset:32
	s_waitcnt vmcnt(0) lgkmcnt(0)
	v_mov_b32_e32 v66, v71
	v_mov_b32_e32 v67, v72
	v_mov_b32_e32 v71, v73
	v_pk_add_f32 v[66:67], v[66:67], v[70:71]
	s_nop 0
	v_add_f32_e32 v0, v66, v67
	v_add_f32_e32 v68, v68, v0

; __device__ __forceinline__ void rope_apply(f32x4& v0, f32x4& v1, int kind, int row, int wc, int fq, const float* tabM, const float* tabS) {
;     const int t = row & 2047, gr = t >> 6, gc = t & 63;
;     const float* tb; float sgn; f32x4 p0, p1;
;     if (kind == 1) {
;         const int pos = (fq < 2) ? gr : gc; tb = tabM + pos * 16; sgn = (fq & 1) ? 1.f : -1.f;
; #pragma unroll
;         for (int e = 0; e < 4; ++e) { p0[e] = __shfl_xor(v0[e], 16); p1[e] = __shfl_xor(v1[e], 16); }
;     } else {
;         const int pos = (wc & 1) ? gc : gr; tb = tabS + pos * 32 + (fq & 1) * 16; sgn = (fq & 2) ? 1.f : -1.f;
; #pragma unroll
;         for (int e = 0; e < 4; ++e) { p0[e] = __shfl_xor(v0[e], 32); p1[e] = __shfl_xor(v1[e], 32); }
;     }
;     const f32x4 c0 = *(const f32x4*)(tb), c1 = *(const f32x4*)(tb + 4), c2 = *(const f32x4*)(tb + 8), c3 = *(const f32x4*)(tb + 12);
;     v0[0] = v0[0] * c0[0] + sgn * p0[0] * c0[1]; v0[1] = v0[1] * c0[2] + sgn * p0[1] * c0[3];
;     v0[2] = v0[2] * c1[0] + sgn * p0[2] * c1[1]; v0[3] = v0[3] * c1[2] + sgn * p0[3] * c1[3];
;     v1[0] = v1[0] * c2[0] + sgn * p1[0] * c2[1]; v1[1] = v1[1] * c2[2] + sgn * p1[1] * c2[3];
;     v1[2] = v1[2] * c3[0] + sgn * p1[2] * c3[1]; v1[3] = v1[3] * c3[2] + sgn * p1[3] * c3[3];
;     __device__ __forceinline__ void operator()(const f32x4 (&acc)[2][2][4][2], const Unit& u, int wr_in, int wc_in, int fr_in, int fq_in) const {
;     ...
;                 const float rs = sc / sqrtf(ss * invn + RMS_EPS);
; #pragma unroll
;                 for (int bj = 0; bj < 2; ++bj) {
;                     const int g32 = u.pn * 8 + bj * 4 + wc;
;                     const int rope = (isq && lat && (g32 % 3 == 2)) ? 1 : 0;
;                     f32x4 v0 = acc[ai][bj][m][0] * rs, v1 = acc[ai][bj][m][1] * rs;
;                     if (rope) rope_apply(v0, v1, 1, row, wc, fq, tabM, tabM);
;                     store_bf16x8(O + (size_t)row * ldo + g32 * 32 + 8 * fq, v0, v1);
.LBB0_234:
	v_fmaak_f32 v0, v154, v68, 0x358637bd
	v_mul_f32_e32 v66, 0x4f800000, v0
	v_cmp_gt_f32_e32 vcc, s28, v0
	v_bfe_u32 v76, v77, 6, 5
	s_nop 0
	v_cndmask_b32_e32 v0, v0, v66, vcc
	v_sqrt_f32_e32 v66, v0
	s_nop 0
	v_add_u32_e32 v67, -1, v66
	v_fma_f32 v69, -v67, v66, v0
	v_add_u32_e32 v68, 1, v66
	v_cmp_ge_f32_e64 s[0:1], 0, v69
	s_nop 1
	v_cndmask_b32_e64 v67, v66, v67, s[0:1]
	v_fma_f32 v66, -v68, v66, v0
	v_cmp_lt_f32_e64 s[0:1], 0, v66
	s_nop 1
	v_cndmask_b32_e64 v66, v67, v68, s[0:1]
	v_mul_f32_e32 v67, 0x37800000, v66
	v_cndmask_b32_e32 v66, v66, v67, vcc
	v_cmp_class_f32_e32 vcc, v0, v238
	s_nop 1
	v_cndmask_b32_e32 v0, v66, v0, vcc
	v_div_scale_f32 v66, s[0:1], v0, v0, v158
	v_rcp_f32_e32 v67, v66
	s_nop 0
	v_fma_f32 v68, -v66, v67, 1.0
	v_fmac_f32_e32 v67, v68, v67
	v_div_scale_f32 v68, vcc, v158, v0, v158
	v_mul_f32_e32 v69, v68, v67
	v_fma_f32 v70, -v66, v69, v68
	v_fmac_f32_e32 v69, v70, v67
	v_fma_f32 v66, -v66, v69, v68
	v_div_fmas_f32 v66, v66, v67, v69
	v_div_fixup_f32 v66, v66, v0, v158
	v_cndmask_b32_e64 v0, v143, v76, s[44:45]
	v_lshlrev_b32_e32 v0, 4, v0
	v_pk_mul_f32 v[68:69], v[64:65], v[66:67] op_sel_hi:[1,0]
	v_pk_mul_f32 v[70:71], v[62:63], v[66:67] op_sel_hi:[1,0]
	v_pk_mul_f32 v[72:73], v[60:61], v[66:67] op_sel_hi:[1,0]
	v_pk_mul_f32 v[74:75], v[58:59], v[66:67] op_sel_hi:[1,0]
	s_andn2_b64 vcc, exec, s[48:49]
	v_lshlrev_b32_e32 v0, 2, v0
	s_cbranch_vccnz .LBB0_236
	v_and_b32_e32 v59, 64, v242
	v_xor_b32_e32 v58, 16, v242
	v_add_u32_e32 v59, 64, v59
	v_cmp_lt_i32_e32 vcc, v58, v59
	v_lshl_add_u64 v[62:63], s[36:37], 0, v[0:1]
	s_nop 0
	v_cndmask_b32_e32 v58, v242, v58, vcc
	v_lshlrev_b32_e32 v58, 2, v58
	ds_bpermute_b32 v86, v58, v70
	ds_bpermute_b32 v88, v58, v74
	ds_bpermute_b32 v87, v58, v71
	ds_bpermute_b32 v89, v58, v75
	ds_bpermute_b32 v67, v58, v68
	ds_bpermute_b32 v92, v58, v72
	ds_bpermute_b32 v93, v58, v69
	ds_bpermute_b32 v94, v58, v73
	global_load_dwordx4 v[78:81], v[62:63], off
	global_load_dwordx4 v[82:85], v[62:63], off offset:16
	global_load_dwordx4 v[58:61], v[62:63], off offset:32
	s_nop 0
	global_load_dwordx4 v[62:65], v[62:63], off offset:48
	s_waitcnt lgkmcnt(0)
	v_mul_f32_e32 v67, v142, v67
	v_pk_mul_f32 v[86:87], v[142:143], v[86:87] op_sel_hi:[0,1]
	s_waitcnt vmcnt(0)
	v_mov_b32_e32 v90, v78
	v_mov_b32_e32 v91, v80
	v_mul_f32_e32 v68, v68, v82
	v_mul_f32_e32 v78, v67, v83
	v_mul_f32_e32 v83, v142, v93
	v_mov_b32_e32 v82, v69
	v_pk_mul_f32 v[70:71], v[70:71], v[90:91]
	v_mov_b32_e32 v80, v79
	v_pk_mul_f32 v[82:83], v[82:83], v[84:85]
	v_pk_fma_f32 v[70:71], v[86:87], v[80:81], v[70:71]
	v_mov_b32_e32 v79, v83
	v_mov_b32_e32 v69, v82
	v_mul_f32_e32 v81, v142, v94
	v_mov_b32_e32 v80, v73
	v_pk_add_f32 v[68:69], v[78:79], v[68:69]
	v_mov_b32_e32 v78, v58
	v_mov_b32_e32 v79, v60
	v_mov_b32_e32 v60, v59
	v_mul_f32_e32 v59, v142, v92
	v_pk_mul_f32 v[64:65], v[80:81], v[64:65]
	v_pk_mul_f32 v[74:75], v[74:75], v[78:79]
	v_pk_mul_f32 v[78:79], v[142:143], v[88:89] op_sel_hi:[0,1]
	v_mul_f32_e32 v58, v72, v62
	v_mul_f32_e32 v62, v59, v63
	v_mov_b32_e32 v63, v65
	v_mov_b32_e32 v59, v64
	v_pk_fma_f32 v[74:75], v[78:79], v[60:61], v[74:75]
	v_pk_add_f32 v[72:73], v[62:63], v[58:59]
.LBB0_236:
	v_mad_i64_i32 v[58:59], s[0:1], v77, s4, 0
	v_lshl_add_u64 v[58:59], v[58:59], 1, s[84:85]
	v_lshl_add_u64 v[60:61], s[94:95], 1, v[58:59]
	v_lshl_add_u64 v[64:65], v[122:123], 1, v[60:61]
	s_and_b64 vcc, exec, s[40:41]
	s_mov_b64 s[0:1], 0
	v_cvt_pk_bf16_f32 v60, v70, v71
	v_cvt_pk_bf16_f32 v61, v68, v69
	v_cvt_pk_bf16_f32 v62, v74, v75
	v_cvt_pk_bf16_f32 v63, v72, v73
	global_store_dwordx4 v[64:65], v[60:63], off
	s_cbranch_vccnz .LBB0_238
	s_lshr_b32 s0, s13, 31
	s_add_i32 s0, s13, s0
	s_mul_i32 s0, s0, 3
	s_sub_i32 s0, s12, s0
	s_cmp_eq_u32 s0, 2
	s_cselect_b64 s[0:1], -1, 0
;     __device__ __forceinline__ void operator()(const f32x4 (&acc)[2][2][4][2], const Unit& u, int wr_in, int wc_in, int fr_in, int fq_in) const {
;     ...
;                 const int row = u.pm * 256 + ai * 128 + wr * 64 + 4 * fr + m;
;                 const float* sp = ssq + (size_t)row * 20;
;                 const f32x4 p0 = *(const f32x4*)(sp), p1 = *(const f32x4*)(sp + 4);
;                 float ss = (p0[0] + p0[1]) + (p0[2] + p0[3]) + (p1[0] + p1[1]) + (p1[2] + p1[3]);
;                 if (nslot == 12) { const f32x4 p2 = *(const f32x4*)(sp + 8); ss += (p2[0] + p2[1]) + (p2[2] + p2[3]); }
;     ...
; #pragma unroll
;                 for (int bj = 0; bj < 2; ++bj) {
;                     const int g32 = u.pn * 8 + bj * 4 + wc;
;                     const int rope = (isq && lat && (g32 % 3 == 2)) ? 1 : 0;
;                     f32x4 v0 = acc[ai][bj][m][0] * rs, v1 = acc[ai][bj][m][1] * rs;
;                     if (rope) rope_apply(v0, v1, 1, row, wc, fq, tabM, tabM);
;                     store_bf16x8(O + (size_t)row * ldo + g32 * 32 + 8 * fq, v0, v1);
.LBB0_238:
	v_mov_b32_e32 v67, v66
	v_mov_b32_e32 v64, v66
	v_mov_b32_e32 v65, v66
	v_pk_mul_f32 v[60:61], v[56:57], v[64:65]
	v_pk_mul_f32 v[62:63], v[54:55], v[66:67]
	v_pk_mul_f32 v[64:65], v[52:53], v[64:65]
	s_andn2_b64 vcc, exec, s[0:1]
	v_pk_mul_f32 v[66:67], v[50:51], v[66:67]
	s_cbranch_vccnz .LBB0_240
	v_and_b32_e32 v51, 64, v242
	v_xor_b32_e32 v50, 16, v242
	v_add_u32_e32 v51, 64, v51
	v_cmp_lt_i32_e32 vcc, v50, v51
	v_lshl_add_u64 v[54:55], s[36:37], 0, v[0:1]
	s_nop 0
	v_cndmask_b32_e32 v50, v242, v50, vcc
	v_lshlrev_b32_e32 v50, 2, v50
	ds_bpermute_b32 v78, v50, v62
	ds_bpermute_b32 v80, v50, v66
	ds_bpermute_b32 v79, v50, v63
	ds_bpermute_b32 v81, v50, v67
	ds_bpermute_b32 v84, v50, v60
	ds_bpermute_b32 v85, v50, v64
	ds_bpermute_b32 v86, v50, v61
	ds_bpermute_b32 v87, v50, v65
	global_load_dwordx4 v[68:71], v[54:55], off
	global_load_dwordx4 v[72:75], v[54:55], off offset:16
	global_load_dwordx4 v[50:53], v[54:55], off offset:32
	s_nop 0
	global_load_dwordx4 v[54:57], v[54:55], off offset:48
	s_waitcnt lgkmcnt(0)
	v_mul_f32_e32 v0, v142, v84
	v_pk_mul_f32 v[78:79], v[142:143], v[78:79] op_sel_hi:[0,1]
	s_waitcnt vmcnt(0)
	v_mov_b32_e32 v82, v68
	v_mov_b32_e32 v83, v70
	v_mul_f32_e32 v60, v60, v72
	v_mul_f32_e32 v68, v0, v73
	v_mul_f32_e32 v73, v142, v86
	v_mov_b32_e32 v72, v61
	v_pk_mul_f32 v[62:63], v[62:63], v[82:83]
	v_mov_b32_e32 v70, v69
	v_pk_mul_f32 v[72:73], v[72:73], v[74:75]
	v_pk_fma_f32 v[62:63], v[78:79], v[70:71], v[62:63]
	v_mov_b32_e32 v69, v73
	v_mov_b32_e32 v61, v72
	v_mul_f32_e32 v71, v142, v87
	v_mov_b32_e32 v70, v65
	v_pk_add_f32 v[60:61], v[68:69], v[60:61]
	v_mov_b32_e32 v68, v50
	v_mov_b32_e32 v69, v52
	v_mul_f32_e32 v0, v142, v85
	v_pk_mul_f32 v[56:57], v[70:71], v[56:57]
	v_pk_mul_f32 v[66:67], v[66:67], v[68:69]
	v_pk_mul_f32 v[68:69], v[142:143], v[80:81] op_sel_hi:[0,1]
	v_mov_b32_e32 v52, v51
	v_mul_f32_e32 v50, v64, v54
	v_mul_f32_e32 v54, v0, v55
	v_mov_b32_e32 v55, v57
	v_mov_b32_e32 v51, v56
	v_pk_fma_f32 v[66:67], v[68:69], v[52:53], v[66:67]
	v_pk_add_f32 v[64:65], v[54:55], v[50:51]
.LBB0_240:
	v_lshl_add_u64 v[50:51], s[96:97], 1, v[58:59]
	v_lshl_add_u64 v[54:55], v[122:123], 1, v[50:51]
	v_cvt_pk_bf16_f32 v50, v62, v63
	v_cvt_pk_bf16_f32 v51, v60, v61
	v_cvt_pk_bf16_f32 v52, v66, v67
	v_cvt_pk_bf16_f32 v53, v64, v65
	global_store_dwordx4 v[54:55], v[50:53], off
	v_or_b32_e32 v60, 1, v77
	s_and_b64 vcc, exec, s[42:43]
	v_mov_b64_e32 v[50:51], s[86:87]
	v_mad_i64_i32 v[50:51], s[0:1], v60, s26, v[50:51]
	global_load_dwordx4 v[52:55], v[50:51], off
	global_load_dwordx4 v[56:59], v[50:51], off offset:16
	s_waitcnt vmcnt(0) lgkmcnt(0)
	v_mov_b32_e32 v62, v53
	v_mov_b32_e32 v63, v54
	v_mov_b32_e32 v53, v55
	v_pk_add_f32 v[52:53], v[62:63], v[52:53]
	v_mov_b32_e32 v54, v58
	v_mov_b32_e32 v55, v56
	v_mov_b32_e32 v56, v59
	v_pk_add_f32 v[52:53], v[52:53], v[52:53] op_sel:[0,1] op_sel_hi:[1,0]
	v_pk_add_f32 v[54:55], v[54:55], v[56:57]
	s_nop 0
	v_pk_add_f32 v[52:53], v[52:53], v[54:55] op_sel:[0,1] op_sel_hi:[1,0]
	s_nop 0
	v_pk_add_f32 v[52:53], v[54:55], v[52:53]
	s_cbranch_vccnz .LBB0_242
	global_load_dwordx4 v[54:57], v[50:51], off offset:32
	s_waitcnt vmcnt(0) lgkmcnt(0)
	v_mov_b32_e32 v50, v55
	v_mov_b32_e32 v51, v56
	v_mov_b32_e32 v55, v57
	v_pk_add_f32 v[50:51], v[50:51], v[54:55]
	s_nop 0
	v_add_f32_e32 v0, v50, v51
	v_add_f32_e32 v52, v52, v0

; __device__ __forceinline__ void rope_apply(f32x4& v0, f32x4& v1, int kind, int row, int wc, int fq, const float* tabM, const float* tabS) {
;     const int t = row & 2047, gr = t >> 6, gc = t & 63;
;     const float* tb; float sgn; f32x4 p0, p1;
;     if (kind == 1) {
;         const int pos = (fq < 2) ? gr : gc; tb = tabM + pos * 16; sgn = (fq & 1) ? 1.f : -1.f;
; #pragma unroll
;         for (int e = 0; e < 4; ++e) { p0[e] = __shfl_xor(v0[e], 16); p1[e] = __shfl_xor(v1[e], 16); }
;     } else {
;         const int pos = (wc & 1) ? gc : gr; tb = tabS + pos * 32 + (fq & 1) * 16; sgn = (fq & 2) ? 1.f : -1.f;
; #pragma unroll
;         for (int e = 0; e < 4; ++e) { p0[e] = __shfl_xor(v0[e], 32); p1[e] = __shfl_xor(v1[e], 32); }
;     }
;     const f32x4 c0 = *(const f32x4*)(tb), c1 = *(const f32x4*)(tb + 4), c2 = *(const f32x4*)(tb + 8), c3 = *(const f32x4*)(tb + 12);
;     v0[0] = v0[0] * c0[0] + sgn * p0[0] * c0[1]; v0[1] = v0[1] * c0[2] + sgn * p0[1] * c0[3];
;     v0[2] = v0[2] * c1[0] + sgn * p0[2] * c1[1]; v0[3] = v0[3] * c1[2] + sgn * p0[3] * c1[3];
;     v1[0] = v1[0] * c2[0] + sgn * p1[0] * c2[1]; v1[1] = v1[1] * c2[2] + sgn * p1[1] * c2[3];
;     v1[2] = v1[2] * c3[0] + sgn * p1[2] * c3[1]; v1[3] = v1[3] * c3[2] + sgn * p1[3] * c3[3];
;     __device__ __forceinline__ void operator()(const f32x4 (&acc)[2][2][4][2], const Unit& u, int wr_in, int wc_in, int fr_in, int fq_in) const {
;     ...
;                 const float rs = sc / sqrtf(ss * invn + RMS_EPS);
; #pragma unroll
;                 for (int bj = 0; bj < 2; ++bj) {
;                     const int g32 = u.pn * 8 + bj * 4 + wc;
;                     const int rope = (isq && lat && (g32 % 3 == 2)) ? 1 : 0;
;                     f32x4 v0 = acc[ai][bj][m][0] * rs, v1 = acc[ai][bj][m][1] * rs;
;                     if (rope) rope_apply(v0, v1, 1, row, wc, fq, tabM, tabM);
;                     store_bf16x8(O + (size_t)row * ldo + g32 * 32 + 8 * fq, v0, v1);
.LBB0_244:
	v_fmaak_f32 v0, v154, v52, 0x358637bd
	v_mul_f32_e32 v50, 0x4f800000, v0
	v_cmp_gt_f32_e32 vcc, s28, v0
	s_nop 1
	v_cndmask_b32_e32 v0, v0, v50, vcc
	v_sqrt_f32_e32 v50, v0
	s_nop 0
	v_add_u32_e32 v51, -1, v50
	v_fma_f32 v53, -v51, v50, v0
	v_add_u32_e32 v52, 1, v50
	v_cmp_ge_f32_e64 s[0:1], 0, v53
	s_nop 1
	v_cndmask_b32_e64 v51, v50, v51, s[0:1]
	v_fma_f32 v50, -v52, v50, v0
	v_cmp_lt_f32_e64 s[0:1], 0, v50
	s_nop 1
	v_cndmask_b32_e64 v50, v51, v52, s[0:1]
	v_mul_f32_e32 v51, 0x37800000, v50
	v_cndmask_b32_e32 v50, v50, v51, vcc
	v_cmp_class_f32_e32 vcc, v0, v238
	s_nop 1
	v_cndmask_b32_e32 v0, v50, v0, vcc
	v_div_scale_f32 v50, s[0:1], v0, v0, v158
	v_rcp_f32_e32 v51, v50
	s_nop 0
	v_fma_f32 v52, -v50, v51, 1.0
	v_fmac_f32_e32 v51, v52, v51
	v_div_scale_f32 v52, vcc, v158, v0, v158
	v_mul_f32_e32 v53, v52, v51
	v_fma_f32 v54, -v50, v53, v52
	v_fmac_f32_e32 v53, v54, v51
	v_fma_f32 v50, -v50, v53, v52
	v_div_fmas_f32 v50, v50, v51, v53
	v_div_fixup_f32 v50, v50, v0, v158
	v_and_b32_e32 v0, 61, v60
	v_cndmask_b32_e64 v0, v0, v76, s[44:45]
	v_lshlrev_b32_e32 v0, 4, v0
	v_pk_mul_f32 v[52:53], v[48:49], v[50:51] op_sel_hi:[1,0]
	v_pk_mul_f32 v[54:55], v[46:47], v[50:51] op_sel_hi:[1,0]
	v_pk_mul_f32 v[56:57], v[44:45], v[50:51] op_sel_hi:[1,0]
	v_pk_mul_f32 v[58:59], v[42:43], v[50:51] op_sel_hi:[1,0]
	s_andn2_b64 vcc, exec, s[48:49]
	v_lshlrev_b32_e32 v0, 2, v0
	s_cbranch_vccnz .LBB0_246
	v_and_b32_e32 v43, 64, v242
	v_xor_b32_e32 v42, 16, v242
	v_add_u32_e32 v43, 64, v43
	v_cmp_lt_i32_e32 vcc, v42, v43
	v_lshl_add_u64 v[46:47], s[36:37], 0, v[0:1]
	s_nop 0
	v_cndmask_b32_e32 v42, v242, v42, vcc
	v_lshlrev_b32_e32 v42, 2, v42
	ds_bpermute_b32 v70, v42, v54
	ds_bpermute_b32 v72, v42, v58
	ds_bpermute_b32 v71, v42, v55
	ds_bpermute_b32 v73, v42, v59
	ds_bpermute_b32 v51, v42, v52
	ds_bpermute_b32 v61, v42, v56
	ds_bpermute_b32 v78, v42, v53
	ds_bpermute_b32 v79, v42, v57
	global_load_dwordx4 v[62:65], v[46:47], off
	global_load_dwordx4 v[66:69], v[46:47], off offset:16
	global_load_dwordx4 v[42:45], v[46:47], off offset:32
	s_nop 0
	global_load_dwordx4 v[46:49], v[46:47], off offset:48
	s_waitcnt lgkmcnt(0)
	v_mul_f32_e32 v51, v142, v51
	v_pk_mul_f32 v[70:71], v[142:143], v[70:71] op_sel_hi:[0,1]
	s_waitcnt vmcnt(0)
	v_mov_b32_e32 v74, v62
	v_mov_b32_e32 v75, v64
	v_mul_f32_e32 v52, v52, v66
	v_mul_f32_e32 v62, v51, v67
	v_mul_f32_e32 v67, v142, v78
	v_mov_b32_e32 v66, v53
	v_pk_mul_f32 v[54:55], v[54:55], v[74:75]
	v_mov_b32_e32 v64, v63
	v_pk_mul_f32 v[66:67], v[66:67], v[68:69]
	v_pk_fma_f32 v[54:55], v[70:71], v[64:65], v[54:55]
	v_mov_b32_e32 v63, v67
	v_mov_b32_e32 v53, v66
	v_mul_f32_e32 v65, v142, v79
	v_mov_b32_e32 v64, v57
	v_pk_add_f32 v[52:53], v[62:63], v[52:53]
	v_mov_b32_e32 v62, v42
	v_mov_b32_e32 v63, v44
	v_mov_b32_e32 v44, v43
	v_mul_f32_e32 v43, v142, v61
	v_pk_mul_f32 v[48:49], v[64:65], v[48:49]
	v_pk_mul_f32 v[58:59], v[58:59], v[62:63]
	v_pk_mul_f32 v[62:63], v[142:143], v[72:73] op_sel_hi:[0,1]
	v_mul_f32_e32 v42, v56, v46
	v_mul_f32_e32 v46, v43, v47
	v_mov_b32_e32 v47, v49
	v_mov_b32_e32 v43, v48
	v_pk_fma_f32 v[58:59], v[62:63], v[44:45], v[58:59]
	v_pk_add_f32 v[56:57], v[46:47], v[42:43]
.LBB0_246:
	v_mad_i64_i32 v[42:43], s[0:1], v60, s4, 0
	v_lshl_add_u64 v[42:43], v[42:43], 1, s[84:85]
	v_lshl_add_u64 v[44:45], s[94:95], 1, v[42:43]
	v_lshl_add_u64 v[48:49], v[122:123], 1, v[44:45]
	s_and_b64 vcc, exec, s[40:41]
	s_mov_b64 s[0:1], 0
	v_cvt_pk_bf16_f32 v44, v54, v55
	v_cvt_pk_bf16_f32 v45, v52, v53
	v_cvt_pk_bf16_f32 v46, v58, v59
	v_cvt_pk_bf16_f32 v47, v56, v57
	global_store_dwordx4 v[48:49], v[44:47], off
	s_cbranch_vccnz .LBB0_248
	s_lshr_b32 s0, s13, 31
	s_add_i32 s0, s13, s0
	s_mul_i32 s0, s0, 3
	s_sub_i32 s0, s12, s0
	s_cmp_eq_u32 s0, 2
	s_cselect_b64 s[0:1], -1, 0
;     __device__ __forceinline__ void operator()(const f32x4 (&acc)[2][2][4][2], const Unit& u, int wr_in, int wc_in, int fr_in, int fq_in) const {
;     ...
;                 const int row = u.pm * 256 + ai * 128 + wr * 64 + 4 * fr + m;
;                 const float* sp = ssq + (size_t)row * 20;
;                 const f32x4 p0 = *(const f32x4*)(sp), p1 = *(const f32x4*)(sp + 4);
;                 float ss = (p0[0] + p0[1]) + (p0[2] + p0[3]) + (p1[0] + p1[1]) + (p1[2] + p1[3]);
;                 if (nslot == 12) { const f32x4 p2 = *(const f32x4*)(sp + 8); ss += (p2[0] + p2[1]) + (p2[2] + p2[3]); }
;     ...
; #pragma unroll
;                 for (int bj = 0; bj < 2; ++bj) {
;                     const int g32 = u.pn * 8 + bj * 4 + wc;
;                     const int rope = (isq && lat && (g32 % 3 == 2)) ? 1 : 0;
;                     f32x4 v0 = acc[ai][bj][m][0] * rs, v1 = acc[ai][bj][m][1] * rs;
;                     if (rope) rope_apply(v0, v1, 1, row, wc, fq, tabM, tabM);
;                     store_bf16x8(O + (size_t)row * ldo + g32 * 32 + 8 * fq, v0, v1);
.LBB0_248:
	v_mov_b32_e32 v51, v50
	v_mov_b32_e32 v48, v50
	v_mov_b32_e32 v49, v50
	v_pk_mul_f32 v[44:45], v[40:41], v[48:49]
	v_pk_mul_f32 v[46:47], v[38:39], v[50:51]
	v_pk_mul_f32 v[48:49], v[36:37], v[48:49]
	s_andn2_b64 vcc, exec, s[0:1]
	v_pk_mul_f32 v[50:51], v[34:35], v[50:51]
	s_cbranch_vccnz .LBB0_250
	v_and_b32_e32 v35, 64, v242
	v_xor_b32_e32 v34, 16, v242
	v_add_u32_e32 v35, 64, v35
	v_cmp_lt_i32_e32 vcc, v34, v35
	v_lshl_add_u64 v[38:39], s[36:37], 0, v[0:1]
	s_nop 0
	v_cndmask_b32_e32 v34, v242, v34, vcc
	v_lshlrev_b32_e32 v34, 2, v34
	ds_bpermute_b32 v60, v34, v46
	ds_bpermute_b32 v62, v34, v50
	ds_bpermute_b32 v61, v34, v47
	ds_bpermute_b32 v63, v34, v51
	ds_bpermute_b32 v66, v34, v44
	ds_bpermute_b32 v67, v34, v48
	ds_bpermute_b32 v68, v34, v45
	ds_bpermute_b32 v69, v34, v49
	global_load_dwordx4 v[52:55], v[38:39], off
	global_load_dwordx4 v[56:59], v[38:39], off offset:16
	global_load_dwordx4 v[34:37], v[38:39], off offset:32
	s_nop 0
	global_load_dwordx4 v[38:41], v[38:39], off offset:48
	s_waitcnt lgkmcnt(0)
	v_mul_f32_e32 v0, v142, v66
	v_pk_mul_f32 v[60:61], v[142:143], v[60:61] op_sel_hi:[0,1]
	s_waitcnt vmcnt(0)
	v_mov_b32_e32 v64, v52
	v_mov_b32_e32 v65, v54
	v_mul_f32_e32 v44, v44, v56
	v_mul_f32_e32 v52, v0, v57
	v_mul_f32_e32 v57, v142, v68
	v_mov_b32_e32 v56, v45
	v_pk_mul_f32 v[46:47], v[46:47], v[64:65]
	v_mov_b32_e32 v54, v53
	v_pk_mul_f32 v[56:57], v[56:57], v[58:59]
	v_pk_fma_f32 v[46:47], v[60:61], v[54:55], v[46:47]
	v_mov_b32_e32 v53, v57
	v_mov_b32_e32 v45, v56
	v_mul_f32_e32 v55, v142, v69
	v_mov_b32_e32 v54, v49
	v_pk_add_f32 v[44:45], v[52:53], v[44:45]
	v_mov_b32_e32 v52, v34
	v_mov_b32_e32 v53, v36
	v_mul_f32_e32 v0, v142, v67
	v_pk_mul_f32 v[40:41], v[54:55], v[40:41]
	v_pk_mul_f32 v[50:51], v[50:51], v[52:53]
	v_pk_mul_f32 v[52:53], v[142:143], v[62:63] op_sel_hi:[0,1]
	v_mov_b32_e32 v36, v35
	v_mul_f32_e32 v34, v48, v38
	v_mul_f32_e32 v38, v0, v39
	v_mov_b32_e32 v39, v41
	v_mov_b32_e32 v35, v40
	v_pk_fma_f32 v[50:51], v[52:53], v[36:37], v[50:51]
	v_pk_add_f32 v[48:49], v[38:39], v[34:35]
.LBB0_250:
	v_lshl_add_u64 v[34:35], s[96:97], 1, v[42:43]
	v_lshl_add_u64 v[38:39], v[122:123], 1, v[34:35]
	v_cvt_pk_bf16_f32 v34, v46, v47
	v_cvt_pk_bf16_f32 v35, v44, v45
	v_cvt_pk_bf16_f32 v36, v50, v51
	v_cvt_pk_bf16_f32 v37, v48, v49
	global_store_dwordx4 v[38:39], v[34:37], off
	v_or_b32_e32 v44, 2, v77
	s_and_b64 vcc, exec, s[42:43]
	v_mov_b64_e32 v[34:35], s[86:87]
	v_mad_i64_i32 v[34:35], s[0:1], v44, s26, v[34:35]
	global_load_dwordx4 v[36:39], v[34:35], off
	global_load_dwordx4 v[40:43], v[34:35], off offset:16
	s_waitcnt vmcnt(0) lgkmcnt(0)
	v_mov_b32_e32 v46, v37
	v_mov_b32_e32 v47, v38
	v_mov_b32_e32 v37, v39
	v_pk_add_f32 v[36:37], v[46:47], v[36:37]
	v_mov_b32_e32 v38, v42
	v_mov_b32_e32 v39, v40
	v_mov_b32_e32 v40, v43
	v_pk_add_f32 v[36:37], v[36:37], v[36:37] op_sel:[0,1] op_sel_hi:[1,0]
	v_pk_add_f32 v[38:39], v[38:39], v[40:41]
	s_nop 0
	v_pk_add_f32 v[36:37], v[36:37], v[38:39] op_sel:[0,1] op_sel_hi:[1,0]
	s_nop 0
	v_pk_add_f32 v[36:37], v[38:39], v[36:37]
	s_cbranch_vccnz .LBB0_252
	global_load_dwordx4 v[38:41], v[34:35], off offset:32
	s_waitcnt vmcnt(0) lgkmcnt(0)
	v_mov_b32_e32 v34, v39
	v_mov_b32_e32 v35, v40
	v_mov_b32_e32 v39, v41
	v_pk_add_f32 v[34:35], v[34:35], v[38:39]
	s_nop 0
	v_add_f32_e32 v0, v34, v35
	v_add_f32_e32 v36, v36, v0

; __device__ __forceinline__ void rope_apply(f32x4& v0, f32x4& v1, int kind, int row, int wc, int fq, const float* tabM, const float* tabS) {
;     const int t = row & 2047, gr = t >> 6, gc = t & 63;
;     const float* tb; float sgn; f32x4 p0, p1;
;     if (kind == 1) {
;         const int pos = (fq < 2) ? gr : gc; tb = tabM + pos * 16; sgn = (fq & 1) ? 1.f : -1.f;
; #pragma unroll
;         for (int e = 0; e < 4; ++e) { p0[e] = __shfl_xor(v0[e], 16); p1[e] = __shfl_xor(v1[e], 16); }
;     } else {
;         const int pos = (wc & 1) ? gc : gr; tb = tabS + pos * 32 + (fq & 1) * 16; sgn = (fq & 2) ? 1.f : -1.f;
; #pragma unroll
;         for (int e = 0; e < 4; ++e) { p0[e] = __shfl_xor(v0[e], 32); p1[e] = __shfl_xor(v1[e], 32); }
;     }
;     const f32x4 c0 = *(const f32x4*)(tb), c1 = *(const f32x4*)(tb + 4), c2 = *(const f32x4*)(tb + 8), c3 = *(const f32x4*)(tb + 12);
;     v0[0] = v0[0] * c0[0] + sgn * p0[0] * c0[1]; v0[1] = v0[1] * c0[2] + sgn * p0[1] * c0[3];
;     v0[2] = v0[2] * c1[0] + sgn * p0[2] * c1[1]; v0[3] = v0[3] * c1[2] + sgn * p0[3] * c1[3];
;     v1[0] = v1[0] * c2[0] + sgn * p1[0] * c2[1]; v1[1] = v1[1] * c2[2] + sgn * p1[1] * c2[3];
;     v1[2] = v1[2] * c3[0] + sgn * p1[2] * c3[1]; v1[3] = v1[3] * c3[2] + sgn * p1[3] * c3[3];
;     __device__ __forceinline__ void operator()(const f32x4 (&acc)[2][2][4][2], const Unit& u, int wr_in, int wc_in, int fr_in, int fq_in) const {
;     ...
;                 const float rs = sc / sqrtf(ss * invn + RMS_EPS);
; #pragma unroll
;                 for (int bj = 0; bj < 2; ++bj) {
;                     const int g32 = u.pn * 8 + bj * 4 + wc;
;                     const int rope = (isq && lat && (g32 % 3 == 2)) ? 1 : 0;
;                     f32x4 v0 = acc[ai][bj][m][0] * rs, v1 = acc[ai][bj][m][1] * rs;
;                     if (rope) rope_apply(v0, v1, 1, row, wc, fq, tabM, tabM);
;                     store_bf16x8(O + (size_t)row * ldo + g32 * 32 + 8 * fq, v0, v1);
.LBB0_254:
	v_fmaak_f32 v0, v154, v36, 0x358637bd
	v_mul_f32_e32 v34, 0x4f800000, v0
	v_cmp_gt_f32_e32 vcc, s28, v0
	s_nop 1
	v_cndmask_b32_e32 v0, v0, v34, vcc
	v_sqrt_f32_e32 v34, v0
	s_nop 0
	v_add_u32_e32 v35, -1, v34
	v_fma_f32 v37, -v35, v34, v0
	v_add_u32_e32 v36, 1, v34
	v_cmp_ge_f32_e64 s[0:1], 0, v37
	s_nop 1
	v_cndmask_b32_e64 v35, v34, v35, s[0:1]
	v_fma_f32 v34, -v36, v34, v0
	v_cmp_lt_f32_e64 s[0:1], 0, v34
	s_nop 1
	v_cndmask_b32_e64 v34, v35, v36, s[0:1]
	v_mul_f32_e32 v35, 0x37800000, v34
	v_cndmask_b32_e32 v34, v34, v35, vcc
	v_cmp_class_f32_e32 vcc, v0, v238
	s_nop 1
	v_cndmask_b32_e32 v0, v34, v0, vcc
	v_div_scale_f32 v34, s[0:1], v0, v0, v158
	v_rcp_f32_e32 v35, v34
	s_nop 0
	v_fma_f32 v36, -v34, v35, 1.0
	v_fmac_f32_e32 v35, v36, v35
	v_div_scale_f32 v36, vcc, v158, v0, v158
	v_mul_f32_e32 v37, v36, v35
	v_fma_f32 v38, -v34, v37, v36
	v_fmac_f32_e32 v37, v38, v35
	v_fma_f32 v34, -v34, v37, v36
	v_div_fmas_f32 v34, v34, v35, v37
	v_div_fixup_f32 v34, v34, v0, v158
	v_and_b32_e32 v0, 62, v44
	v_cndmask_b32_e64 v0, v0, v76, s[44:45]
	v_lshlrev_b32_e32 v0, 4, v0
	v_pk_mul_f32 v[36:37], v[32:33], v[34:35] op_sel_hi:[1,0]
	v_pk_mul_f32 v[38:39], v[30:31], v[34:35] op_sel_hi:[1,0]
	v_pk_mul_f32 v[40:41], v[28:29], v[34:35] op_sel_hi:[1,0]
	v_pk_mul_f32 v[42:43], v[26:27], v[34:35] op_sel_hi:[1,0]
	s_andn2_b64 vcc, exec, s[48:49]
	v_lshlrev_b32_e32 v0, 2, v0
	s_cbranch_vccnz .LBB0_256
	v_and_b32_e32 v27, 64, v242
	v_xor_b32_e32 v26, 16, v242
	v_add_u32_e32 v27, 64, v27
	v_cmp_lt_i32_e32 vcc, v26, v27
	v_lshl_add_u64 v[30:31], s[36:37], 0, v[0:1]
	s_nop 0
	v_cndmask_b32_e32 v26, v242, v26, vcc
	v_lshlrev_b32_e32 v26, 2, v26
	ds_bpermute_b32 v54, v26, v38
	ds_bpermute_b32 v56, v26, v42
	ds_bpermute_b32 v55, v26, v39
	ds_bpermute_b32 v57, v26, v43
	ds_bpermute_b32 v35, v26, v36
	ds_bpermute_b32 v45, v26, v40
	ds_bpermute_b32 v60, v26, v37
	ds_bpermute_b32 v61, v26, v41
	global_load_dwordx4 v[46:49], v[30:31], off
	global_load_dwordx4 v[50:53], v[30:31], off offset:16
	global_load_dwordx4 v[26:29], v[30:31], off offset:32
	s_nop 0
	global_load_dwordx4 v[30:33], v[30:31], off offset:48
	s_waitcnt lgkmcnt(0)
	v_mul_f32_e32 v35, v142, v35
	v_pk_mul_f32 v[54:55], v[142:143], v[54:55] op_sel_hi:[0,1]
	s_waitcnt vmcnt(0)
	v_mov_b32_e32 v58, v46
	v_mov_b32_e32 v59, v48
	v_mul_f32_e32 v36, v36, v50
	v_mul_f32_e32 v46, v35, v51
	v_mul_f32_e32 v51, v142, v60
	v_mov_b32_e32 v50, v37
	v_pk_mul_f32 v[38:39], v[38:39], v[58:59]
	v_mov_b32_e32 v48, v47
	v_pk_mul_f32 v[50:51], v[50:51], v[52:53]
	v_pk_fma_f32 v[38:39], v[54:55], v[48:49], v[38:39]
	v_mov_b32_e32 v47, v51
	v_mov_b32_e32 v37, v50
	v_mul_f32_e32 v49, v142, v61
	v_mov_b32_e32 v48, v41
	v_pk_add_f32 v[36:37], v[46:47], v[36:37]
	v_mov_b32_e32 v46, v26
	v_mov_b32_e32 v47, v28
	v_mov_b32_e32 v28, v27
	v_mul_f32_e32 v27, v142, v45
	v_pk_mul_f32 v[32:33], v[48:49], v[32:33]
	v_pk_mul_f32 v[42:43], v[42:43], v[46:47]
	v_pk_mul_f32 v[46:47], v[142:143], v[56:57] op_sel_hi:[0,1]
	v_mul_f32_e32 v26, v40, v30
	v_mul_f32_e32 v30, v27, v31
	v_mov_b32_e32 v31, v33
	v_mov_b32_e32 v27, v32
	v_pk_fma_f32 v[42:43], v[46:47], v[28:29], v[42:43]
	v_pk_add_f32 v[40:41], v[30:31], v[26:27]
.LBB0_256:
	v_mad_i64_i32 v[26:27], s[0:1], v44, s4, 0
	v_lshl_add_u64 v[26:27], v[26:27], 1, s[84:85]
	v_lshl_add_u64 v[28:29], s[94:95], 1, v[26:27]
	v_lshl_add_u64 v[32:33], v[122:123], 1, v[28:29]
	s_and_b64 vcc, exec, s[40:41]
	s_mov_b64 s[0:1], 0
	v_cvt_pk_bf16_f32 v28, v38, v39
	v_cvt_pk_bf16_f32 v29, v36, v37
	v_cvt_pk_bf16_f32 v30, v42, v43
	v_cvt_pk_bf16_f32 v31, v40, v41
	global_store_dwordx4 v[32:33], v[28:31], off
	s_cbranch_vccnz .LBB0_258
	s_lshr_b32 s0, s13, 31
	s_add_i32 s0, s13, s0
	s_mul_i32 s0, s0, 3
	s_sub_i32 s0, s12, s0
	s_cmp_eq_u32 s0, 2
	s_cselect_b64 s[0:1], -1, 0
; __device__ __forceinline__ void rope_apply(f32x4& v0, f32x4& v1, int kind, int row, int wc, int fq, const float* tabM, const float* tabS) {
;     const int t = row & 2047, gr = t >> 6, gc = t & 63;
;     const float* tb; float sgn; f32x4 p0, p1;
;     if (kind == 1) {
;         const int pos = (fq < 2) ? gr : gc; tb = tabM + pos * 16; sgn = (fq & 1) ? 1.f : -1.f;
; #pragma unroll
;         for (int e = 0; e < 4; ++e) { p0[e] = __shfl_xor(v0[e], 16); p1[e] = __shfl_xor(v1[e], 16); }
;     } else {
;         const int pos = (wc & 1) ? gc : gr; tb = tabS + pos * 32 + (fq & 1) * 16; sgn = (fq & 2) ? 1.f : -1.f;
; #pragma unroll
;         for (int e = 0; e < 4; ++e) { p0[e] = __shfl_xor(v0[e], 32); p1[e] = __shfl_xor(v1[e], 32); }
;     }
;     const f32x4 c0 = *(const f32x4*)(tb), c1 = *(const f32x4*)(tb + 4), c2 = *(const f32x4*)(tb + 8), c3 = *(const f32x4*)(tb + 12);
;     v0[0] = v0[0] * c0[0] + sgn * p0[0] * c0[1]; v0[1] = v0[1] * c0[2] + sgn * p0[1] * c0[3];
;     v0[2] = v0[2] * c1[0] + sgn * p0[2] * c1[1]; v0[3] = v0[3] * c1[2] + sgn * p0[3] * c1[3];
;     v1[0] = v1[0] * c2[0] + sgn * p1[0] * c2[1]; v1[1] = v1[1] * c2[2] + sgn * p1[1] * c2[3];
;     __device__ __forceinline__ void operator()(const f32x4 (&acc)[2][2][4][2], const Unit& u, int wr_in, int wc_in, int fr_in, int fq_in) const {
;     ...
;             for (int m = 0; m < 4; ++m) {
;                 const int row = u.pm * 256 + ai * 128 + wr * 64 + 4 * fr + m;
;                 const float* sp = ssq + (size_t)row * 20;
;                 const f32x4 p0 = *(const f32x4*)(sp), p1 = *(const f32x4*)(sp + 4);
;                 float ss = (p0[0] + p0[1]) + (p0[2] + p0[3]) + (p1[0] + p1[1]) + (p1[2] + p1[3]);
;                 if (nslot == 12) { const f32x4 p2 = *(const f32x4*)(sp + 8); ss += (p2[0] + p2[1]) + (p2[2] + p2[3]); }
;                 const float rs = sc / sqrtf(ss * invn + RMS_EPS);
; #pragma unroll
;                 for (int bj = 0; bj < 2; ++bj) {
;                     const int g32 = u.pn * 8 + bj * 4 + wc;
;                     const int rope = (isq && lat && (g32 % 3 == 2)) ? 1 : 0;
;                     f32x4 v0 = acc[ai][bj][m][0] * rs, v1 = acc[ai][bj][m][1] * rs;
;                     if (rope) rope_apply(v0, v1, 1, row, wc, fq, tabM, tabM);
;                     store_bf16x8(O + (size_t)row * ldo + g32 * 32 + 8 * fq, v0, v1);
;                 }
.LBB0_258:
	v_mov_b32_e32 v35, v34
	v_mov_b32_e32 v32, v34
	v_mov_b32_e32 v33, v34
	v_pk_mul_f32 v[28:29], v[24:25], v[32:33]
	v_pk_mul_f32 v[30:31], v[22:23], v[34:35]
	v_pk_mul_f32 v[32:33], v[20:21], v[32:33]
	s_andn2_b64 vcc, exec, s[0:1]
	v_pk_mul_f32 v[34:35], v[18:19], v[34:35]
	s_cbranch_vccnz .LBB0_260
	v_and_b32_e32 v19, 64, v242
	v_xor_b32_e32 v18, 16, v242
	v_add_u32_e32 v19, 64, v19
	v_cmp_lt_i32_e32 vcc, v18, v19
	v_lshl_add_u64 v[22:23], s[36:37], 0, v[0:1]
	s_nop 0
	v_cndmask_b32_e32 v18, v242, v18, vcc
	v_lshlrev_b32_e32 v18, 2, v18
	ds_bpermute_b32 v44, v18, v30
	ds_bpermute_b32 v46, v18, v34
	ds_bpermute_b32 v45, v18, v31
	ds_bpermute_b32 v47, v18, v35
	ds_bpermute_b32 v50, v18, v28
	ds_bpermute_b32 v51, v18, v32
	ds_bpermute_b32 v52, v18, v29
	ds_bpermute_b32 v53, v18, v33
	global_load_dwordx4 v[36:39], v[22:23], off
	global_load_dwordx4 v[40:43], v[22:23], off offset:16
	global_load_dwordx4 v[18:21], v[22:23], off offset:32
	s_nop 0
	global_load_dwordx4 v[22:25], v[22:23], off offset:48
	s_waitcnt lgkmcnt(0)
	v_mul_f32_e32 v0, v142, v50
	v_pk_mul_f32 v[44:45], v[142:143], v[44:45] op_sel_hi:[0,1]
	s_waitcnt vmcnt(0)
	v_mov_b32_e32 v48, v36
	v_mov_b32_e32 v49, v38
	v_mul_f32_e32 v28, v28, v40
	v_mul_f32_e32 v36, v0, v41
	v_mul_f32_e32 v41, v142, v52
	v_mov_b32_e32 v40, v29
	v_pk_mul_f32 v[30:31], v[30:31], v[48:49]
	v_mov_b32_e32 v38, v37
	v_pk_mul_f32 v[40:41], v[40:41], v[42:43]
	v_pk_fma_f32 v[30:31], v[44:45], v[38:39], v[30:31]
	v_mov_b32_e32 v37, v41
	v_mov_b32_e32 v29, v40
	v_mul_f32_e32 v39, v142, v53
	v_mov_b32_e32 v38, v33
	v_pk_add_f32 v[28:29], v[36:37], v[28:29]
	v_mov_b32_e32 v36, v18
	v_mov_b32_e32 v37, v20
	v_mul_f32_e32 v0, v142, v51
	v_pk_mul_f32 v[24:25], v[38:39], v[24:25]
	v_pk_mul_f32 v[34:35], v[34:35], v[36:37]
	v_pk_mul_f32 v[36:37], v[142:143], v[46:47] op_sel_hi:[0,1]
	v_mov_b32_e32 v20, v19
	v_mul_f32_e32 v18, v32, v22
	v_mul_f32_e32 v22, v0, v23
	v_mov_b32_e32 v23, v25
	v_mov_b32_e32 v19, v24
	v_pk_fma_f32 v[34:35], v[36:37], v[20:21], v[34:35]
	v_pk_add_f32 v[32:33], v[22:23], v[18:19]
.LBB0_260:
	v_lshl_add_u64 v[18:19], s[96:97], 1, v[26:27]
	v_lshl_add_u64 v[22:23], v[122:123], 1, v[18:19]
	v_cvt_pk_bf16_f32 v18, v30, v31
	v_cvt_pk_bf16_f32 v19, v28, v29
	v_cvt_pk_bf16_f32 v20, v34, v35
	v_cvt_pk_bf16_f32 v21, v32, v33
	global_store_dwordx4 v[22:23], v[18:21], off
	v_or_b32_e32 v28, 3, v77
	s_and_b64 vcc, exec, s[42:43]
	v_mov_b64_e32 v[18:19], s[86:87]
	v_mad_i64_i32 v[18:19], s[0:1], v28, s26, v[18:19]
	global_load_dwordx4 v[20:23], v[18:19], off
	global_load_dwordx4 v[24:27], v[18:19], off offset:16
	s_waitcnt vmcnt(0) lgkmcnt(0)
	v_mov_b32_e32 v30, v21
	v_mov_b32_e32 v31, v22
	v_mov_b32_e32 v21, v23
	v_pk_add_f32 v[20:21], v[30:31], v[20:21]
	v_mov_b32_e32 v22, v26
	v_mov_b32_e32 v23, v24
	v_mov_b32_e32 v24, v27
	v_pk_add_f32 v[20:21], v[20:21], v[20:21] op_sel:[0,1] op_sel_hi:[1,0]
	v_pk_add_f32 v[22:23], v[22:23], v[24:25]
	s_nop 0
	v_pk_add_f32 v[20:21], v[20:21], v[22:23] op_sel:[0,1] op_sel_hi:[1,0]
	s_nop 0
	v_pk_add_f32 v[20:21], v[22:23], v[20:21]
	s_cbranch_vccnz .LBB0_262
	global_load_dwordx4 v[22:25], v[18:19], off offset:32
	s_waitcnt vmcnt(0) lgkmcnt(0)
	v_mov_b32_e32 v18, v23
	v_mov_b32_e32 v19, v24
	v_mov_b32_e32 v23, v25
	v_pk_add_f32 v[18:19], v[18:19], v[22:23]
	s_nop 0
	v_add_f32_e32 v0, v18, v19
	v_add_f32_e32 v20, v20, v0

; __device__ __forceinline__ void rope_apply(f32x4& v0, f32x4& v1, int kind, int row, int wc, int fq, const float* tabM, const float* tabS) {
;     const int t = row & 2047, gr = t >> 6, gc = t & 63;
;     const float* tb; float sgn; f32x4 p0, p1;
;     if (kind == 1) {
;         const int pos = (fq < 2) ? gr : gc; tb = tabM + pos * 16; sgn = (fq & 1) ? 1.f : -1.f;
; #pragma unroll
;         for (int e = 0; e < 4; ++e) { p0[e] = __shfl_xor(v0[e], 16); p1[e] = __shfl_xor(v1[e], 16); }
;     } else {
;         const int pos = (wc & 1) ? gc : gr; tb = tabS + pos * 32 + (fq & 1) * 16; sgn = (fq & 2) ? 1.f : -1.f;
; #pragma unroll
;         for (int e = 0; e < 4; ++e) { p0[e] = __shfl_xor(v0[e], 32); p1[e] = __shfl_xor(v1[e], 32); }
;     }
;     const f32x4 c0 = *(const f32x4*)(tb), c1 = *(const f32x4*)(tb + 4), c2 = *(const f32x4*)(tb + 8), c3 = *(const f32x4*)(tb + 12);
;     v0[0] = v0[0] * c0[0] + sgn * p0[0] * c0[1]; v0[1] = v0[1] * c0[2] + sgn * p0[1] * c0[3];
;     v0[2] = v0[2] * c1[0] + sgn * p0[2] * c1[1]; v0[3] = v0[3] * c1[2] + sgn * p0[3] * c1[3];
;     v1[0] = v1[0] * c2[0] + sgn * p1[0] * c2[1]; v1[1] = v1[1] * c2[2] + sgn * p1[1] * c2[3];
;     v1[2] = v1[2] * c3[0] + sgn * p1[2] * c3[1]; v1[3] = v1[3] * c3[2] + sgn * p1[3] * c3[3];
;     __device__ __forceinline__ void operator()(const f32x4 (&acc)[2][2][4][2], const Unit& u, int wr_in, int wc_in, int fr_in, int fq_in) const {
;     ...
;                 const float rs = sc / sqrtf(ss * invn + RMS_EPS);
; #pragma unroll
;                 for (int bj = 0; bj < 2; ++bj) {
;                     const int g32 = u.pn * 8 + bj * 4 + wc;
;                     const int rope = (isq && lat && (g32 % 3 == 2)) ? 1 : 0;
;                     f32x4 v0 = acc[ai][bj][m][0] * rs, v1 = acc[ai][bj][m][1] * rs;
;                     if (rope) rope_apply(v0, v1, 1, row, wc, fq, tabM, tabM);
;                     store_bf16x8(O + (size_t)row * ldo + g32 * 32 + 8 * fq, v0, v1);
;                 }
.LBB0_264:
	v_fmaak_f32 v0, v154, v20, 0x358637bd
	v_mul_f32_e32 v18, 0x4f800000, v0
	v_cmp_gt_f32_e32 vcc, s28, v0
	s_nop 1
	v_cndmask_b32_e32 v0, v0, v18, vcc
	v_sqrt_f32_e32 v18, v0
	s_nop 0
	v_add_u32_e32 v19, -1, v18
	v_fma_f32 v21, -v19, v18, v0
	v_add_u32_e32 v20, 1, v18
	v_cmp_ge_f32_e64 s[0:1], 0, v21
	s_nop 1
	v_cndmask_b32_e64 v19, v18, v19, s[0:1]
	v_fma_f32 v18, -v20, v18, v0
	v_cmp_lt_f32_e64 s[0:1], 0, v18
	s_nop 1
	v_cndmask_b32_e64 v18, v19, v20, s[0:1]
	v_mul_f32_e32 v19, 0x37800000, v18
	v_cndmask_b32_e32 v18, v18, v19, vcc
	v_cmp_class_f32_e32 vcc, v0, v238
	s_nop 1
	v_cndmask_b32_e32 v0, v18, v0, vcc
	v_div_scale_f32 v18, s[0:1], v0, v0, v158
	v_rcp_f32_e32 v19, v18
	s_nop 0
	v_fma_f32 v20, -v18, v19, 1.0
	v_fmac_f32_e32 v19, v20, v19
	v_div_scale_f32 v20, vcc, v158, v0, v158
	v_mul_f32_e32 v21, v20, v19
	v_fma_f32 v22, -v18, v21, v20
	v_fmac_f32_e32 v21, v22, v19
	v_fma_f32 v18, -v18, v21, v20
	v_div_fmas_f32 v18, v18, v19, v21
	v_div_fixup_f32 v18, v18, v0, v158
	v_and_b32_e32 v0, 63, v28
	v_cndmask_b32_e64 v0, v0, v76, s[44:45]
	v_lshlrev_b32_e32 v0, 4, v0
	v_pk_mul_f32 v[20:21], v[16:17], v[18:19] op_sel_hi:[1,0]
	v_pk_mul_f32 v[22:23], v[14:15], v[18:19] op_sel_hi:[1,0]
	v_pk_mul_f32 v[24:25], v[12:13], v[18:19] op_sel_hi:[1,0]
	v_pk_mul_f32 v[26:27], v[10:11], v[18:19] op_sel_hi:[1,0]
	s_andn2_b64 vcc, exec, s[42:43]
	v_lshlrev_b32_e32 v0, 2, v0
	s_cbranch_vccnz .LBB0_266
	v_and_b32_e32 v11, 64, v242
	v_xor_b32_e32 v10, 16, v242
	v_add_u32_e32 v11, 64, v11
	v_cmp_lt_i32_e32 vcc, v10, v11
	v_lshl_add_u64 v[14:15], s[36:37], 0, v[0:1]
	s_nop 0
	v_cndmask_b32_e32 v10, v242, v10, vcc
	v_lshlrev_b32_e32 v10, 2, v10
	ds_bpermute_b32 v38, v10, v22
	ds_bpermute_b32 v40, v10, v26
	ds_bpermute_b32 v39, v10, v23
	ds_bpermute_b32 v41, v10, v27
	ds_bpermute_b32 v19, v10, v20
	ds_bpermute_b32 v29, v10, v24
	ds_bpermute_b32 v44, v10, v21
	ds_bpermute_b32 v45, v10, v25
	global_load_dwordx4 v[30:33], v[14:15], off
	global_load_dwordx4 v[34:37], v[14:15], off offset:16
	global_load_dwordx4 v[10:13], v[14:15], off offset:32
	s_nop 0
	global_load_dwordx4 v[14:17], v[14:15], off offset:48
	s_waitcnt lgkmcnt(0)
	v_mul_f32_e32 v19, v142, v19
	v_pk_mul_f32 v[38:39], v[142:143], v[38:39] op_sel_hi:[0,1]
	s_waitcnt vmcnt(0)
	v_mov_b32_e32 v42, v30
	v_mov_b32_e32 v43, v32
	v_mul_f32_e32 v20, v20, v34
	v_mul_f32_e32 v30, v19, v35
	v_mul_f32_e32 v35, v142, v44
	v_mov_b32_e32 v34, v21
	v_pk_mul_f32 v[22:23], v[22:23], v[42:43]
	v_mov_b32_e32 v32, v31
	v_pk_mul_f32 v[34:35], v[34:35], v[36:37]
	v_pk_fma_f32 v[22:23], v[38:39], v[32:33], v[22:23]
	v_mov_b32_e32 v31, v35
	v_mov_b32_e32 v21, v34
	v_mul_f32_e32 v33, v142, v45
	v_mov_b32_e32 v32, v25
	v_pk_add_f32 v[20:21], v[30:31], v[20:21]
	v_mov_b32_e32 v30, v10
	v_mov_b32_e32 v31, v12
	v_mov_b32_e32 v12, v11
	v_mul_f32_e32 v11, v142, v29
	v_pk_mul_f32 v[16:17], v[32:33], v[16:17]
	v_pk_mul_f32 v[26:27], v[26:27], v[30:31]
	v_pk_mul_f32 v[30:31], v[142:143], v[40:41] op_sel_hi:[0,1]
	v_mul_f32_e32 v10, v24, v14
	v_mul_f32_e32 v14, v11, v15
	v_mov_b32_e32 v15, v17
	v_mov_b32_e32 v11, v16
	v_pk_fma_f32 v[26:27], v[30:31], v[12:13], v[26:27]
	v_pk_add_f32 v[24:25], v[14:15], v[10:11]
.LBB0_266:
	v_mad_i64_i32 v[10:11], s[0:1], v28, s4, 0
	v_lshl_add_u64 v[10:11], v[10:11], 1, s[84:85]
	v_lshl_add_u64 v[12:13], s[94:95], 1, v[10:11]
	v_lshl_add_u64 v[16:17], v[122:123], 1, v[12:13]
	s_and_b64 vcc, exec, s[40:41]
	s_mov_b64 s[0:1], 0
	v_cvt_pk_bf16_f32 v12, v22, v23
	v_cvt_pk_bf16_f32 v13, v20, v21
	v_cvt_pk_bf16_f32 v14, v26, v27
	v_cvt_pk_bf16_f32 v15, v24, v25
	global_store_dwordx4 v[16:17], v[12:15], off
	s_cbranch_vccnz .LBB0_268
	s_lshr_b32 s0, s13, 31
	s_add_i32 s0, s13, s0
	s_mul_i32 s0, s0, 3
	s_sub_i32 s0, s12, s0
	s_cmp_eq_u32 s0, 2
	s_cselect_b64 s[0:1], -1, 0
.LBB0_268:
	v_mov_b32_e32 v19, v18
	v_mov_b32_e32 v16, v18
	v_mov_b32_e32 v17, v18
	v_pk_mul_f32 v[12:13], v[8:9], v[16:17]
	v_pk_mul_f32 v[14:15], v[6:7], v[18:19]
	v_pk_mul_f32 v[16:17], v[4:5], v[16:17]
	s_andn2_b64 vcc, exec, s[0:1]
	v_pk_mul_f32 v[18:19], v[2:3], v[18:19]
	s_cbranch_vccnz .LBB0_270
	v_and_b32_e32 v3, 64, v242
	v_xor_b32_e32 v2, 16, v242
	v_add_u32_e32 v3, 64, v3
	v_cmp_lt_i32_e32 vcc, v2, v3
	v_lshl_add_u64 v[6:7], s[36:37], 0, v[0:1]
	s_nop 0
	v_cndmask_b32_e32 v2, v242, v2, vcc
	v_lshlrev_b32_e32 v2, 2, v2
	ds_bpermute_b32 v28, v2, v14
	ds_bpermute_b32 v30, v2, v18
	ds_bpermute_b32 v29, v2, v15
	ds_bpermute_b32 v31, v2, v19
	ds_bpermute_b32 v34, v2, v12
	ds_bpermute_b32 v35, v2, v16
	ds_bpermute_b32 v36, v2, v13
	ds_bpermute_b32 v37, v2, v17
	global_load_dwordx4 v[20:23], v[6:7], off
	global_load_dwordx4 v[24:27], v[6:7], off offset:16
	global_load_dwordx4 v[2:5], v[6:7], off offset:32
	s_nop 0
	global_load_dwordx4 v[6:9], v[6:7], off offset:48
	s_waitcnt lgkmcnt(0)
	v_mul_f32_e32 v0, v142, v34
	v_pk_mul_f32 v[28:29], v[142:143], v[28:29] op_sel_hi:[0,1]
	s_waitcnt vmcnt(0)
	v_mov_b32_e32 v32, v20
	v_mov_b32_e32 v33, v22
	v_mul_f32_e32 v12, v12, v24
	v_mul_f32_e32 v20, v0, v25
	v_mul_f32_e32 v25, v142, v36
	v_mov_b32_e32 v24, v13
	v_pk_mul_f32 v[14:15], v[14:15], v[32:33]
	v_mov_b32_e32 v22, v21
	v_pk_mul_f32 v[24:25], v[24:25], v[26:27]
	v_pk_fma_f32 v[14:15], v[28:29], v[22:23], v[14:15]
	v_mov_b32_e32 v21, v25
	v_mov_b32_e32 v13, v24
	v_mul_f32_e32 v23, v142, v37
	v_mov_b32_e32 v22, v17
	v_pk_add_f32 v[12:13], v[20:21], v[12:13]
	v_mov_b32_e32 v20, v2
	v_mov_b32_e32 v21, v4
	v_mul_f32_e32 v0, v142, v35
	v_pk_mul_f32 v[8:9], v[22:23], v[8:9]
	v_pk_mul_f32 v[18:19], v[18:19], v[20:21]
	v_pk_mul_f32 v[20:21], v[142:143], v[30:31] op_sel_hi:[0,1]
	v_mov_b32_e32 v4, v3
	v_mul_f32_e32 v2, v16, v6
	v_mul_f32_e32 v6, v0, v7
	v_mov_b32_e32 v7, v9
	v_mov_b32_e32 v3, v8
	v_pk_fma_f32 v[18:19], v[20:21], v[4:5], v[18:19]
	v_pk_add_f32 v[16:17], v[6:7], v[2:3]
.LBB0_270:
	v_lshl_add_u64 v[2:3], s[96:97], 1, v[10:11]
	v_lshl_add_u64 v[6:7], v[122:123], 1, v[2:3]
	s_and_b64 vcc, exec, s[38:39]
	s_mov_b64 s[0:1], -1
	v_cvt_pk_bf16_f32 v2, v14, v15
	v_cvt_pk_bf16_f32 v3, v12, v13
	v_cvt_pk_bf16_f32 v4, v18, v19
	v_cvt_pk_bf16_f32 v5, v16, v17
	global_store_dwordx4 v[6:7], v[2:5], off
	s_cbranch_vccnz .LBB0_179
	s_andn2_b64 vcc, exec, s[8:9]
	s_cbranch_vccnz .LBB0_178
	s_barrier
	s_branch .LBB0_178

;     __device__ __forceinline__ void operator()(const f32x4 (&acc)[2][2][4][2], const Unit& u, int wr_in, int wc_in, int fr_in, int fq_in) const {
;     ...
;             if (!odd && g32 >= 48 && g32 < 68) {
; #pragma unroll
;                 for (int ai = 0; ai < 2; ++ai)
; #pragma unroll
;                     for (int m = 0; m < 4; ++m) {
;                         const f32x4 a = acc[ai][bj][m][0], b = acc[ai][bj][m][1];
;                         float ss = (a[0] * a[0] + a[1] * a[1]) + (a[2] * a[2] + a[3] * a[3]) + (b[0] * b[0] + b[1] * b[1]) + (b[2] * b[2] + b[3] * b[3]);
;                         ss += __shfl_xor(ss, 16); ss += __shfl_xor(ss, 32);
;                         if (fq == 0) ssq[(size_t)(u.pm * 256 + ai * 128 + wr * 64 + 4 * fr + m) * 20 + (g32 - 48)] = ss;
;                     }
.LBB0_358:
	v_mov_b32_e32 v0, v154
	s_mov_b32 s1, s11
	v_mov_b32_e32 v151, v155
	s_mov_b32 s26, s17
	s_lshl_b32 s4, s4, 3
	s_add_i32 s46, s26, s4
	s_lshl_b32 s4, s0, 8
	s_lshl_b32 s1, s1, 6
	v_lshlrev_b32_e32 v0, 2, v0
	s_add_i32 s1, s1, s4
	v_add_u32_e32 v163, s1, v0
	s_sub_i32 s1, s46, 48
	s_cmp_lt_u32 s1, 20
	s_cselect_b64 s[4:5], -1, 0
	s_and_b64 s[4:5], s[58:59], s[4:5]
	s_andn2_b64 vcc, exec, s[4:5]
	v_cmp_eq_u32_e64 s[44:45], 0, v151
	s_cbranch_vccnz .LBB0_376
	v_mul_f32_e32 v132, v127, v127
	v_mul_f32_e32 v133, v129, v129
	v_fmac_f32_e32 v132, v126, v126
	v_fmac_f32_e32 v133, v128, v128
	v_and_b32_e32 v131, 64, v242
	v_add_f32_e32 v132, v132, v133
	v_mul_f32_e32 v133, v123, v123
	v_xor_b32_e32 v130, 16, v242
	v_add_u32_e32 v131, 64, v131
	v_fmac_f32_e32 v133, v122, v122
	v_cmp_lt_i32_e32 vcc, v130, v131
	v_add_f32_e32 v132, v132, v133
	v_mul_f32_e32 v133, v125, v125
	v_cndmask_b32_e32 v130, v242, v130, vcc
	v_fmac_f32_e32 v133, v124, v124
	v_lshlrev_b32_e32 v130, 2, v130
	v_add_f32_e32 v132, v133, v132
	ds_bpermute_b32 v133, v130, v132
	v_xor_b32_e32 v134, 32, v242
	v_cmp_lt_i32_e32 vcc, v134, v131
	s_lshl_b64 s[4:5], s[46:47], 2
	v_readlane_b32 s1, v254, 25
	v_cndmask_b32_e32 v131, v242, v134, vcc
	v_lshlrev_b32_e32 v131, 2, v131
	s_waitcnt lgkmcnt(0)
	v_add_f32_e32 v132, v132, v133
	ds_bpermute_b32 v133, v131, v132
	s_add_u32 s4, s1, s4
	v_readlane_b32 s1, v254, 26
	s_addc_u32 s5, s1, s5
	s_and_saveexec_b64 s[40:41], s[44:45]
	s_cbranch_execz .LBB0_361
	s_waitcnt lgkmcnt(0)
	v_add_f32_e32 v134, v132, v133
	v_mov_b64_e32 v[132:133], s[4:5]
	v_mad_i64_i32 v[132:133], s[42:43], v163, s30, v[132:133]
	v_add_co_u32_e32 v132, vcc, 0xffffff40, v132
	s_nop 1
	v_addc_co_u32_e32 v133, vcc, -1, v133, vcc
	global_store_dword v[132:133], v134, off
.LBB0_361:
	s_or_b64 exec, exec, s[40:41]
	v_mul_f32_e32 v132, v119, v119
	s_waitcnt lgkmcnt(0)
	v_mul_f32_e32 v133, v121, v121
	v_fmac_f32_e32 v132, v118, v118
	v_fmac_f32_e32 v133, v120, v120
	v_add_f32_e32 v132, v132, v133
	v_mul_f32_e32 v133, v115, v115
	v_fmac_f32_e32 v133, v114, v114
	v_add_f32_e32 v132, v132, v133
	v_mul_f32_e32 v133, v117, v117
	v_fmac_f32_e32 v133, v116, v116
	v_add_f32_e32 v132, v133, v132
	ds_bpermute_b32 v133, v130, v132
	s_waitcnt lgkmcnt(0)
	v_add_f32_e32 v132, v132, v133
	ds_bpermute_b32 v133, v131, v132
	s_and_saveexec_b64 s[40:41], s[44:45]
	s_cbranch_execz .LBB0_363
	s_waitcnt lgkmcnt(0)
	v_add_f32_e32 v134, v132, v133
	v_or_b32_e32 v135, 1, v163
	v_mov_b64_e32 v[132:133], s[4:5]
	v_mad_i64_i32 v[132:133], s[42:43], v135, s30, v[132:133]
	v_add_co_u32_e32 v132, vcc, 0xffffff40, v132
	s_nop 1
	v_addc_co_u32_e32 v133, vcc, -1, v133, vcc
	global_store_dword v[132:133], v134, off
.LBB0_363:
	s_or_b64 exec, exec, s[40:41]
	v_mul_f32_e32 v132, v111, v111
	s_waitcnt lgkmcnt(0)
	v_mul_f32_e32 v133, v113, v113
	v_fmac_f32_e32 v132, v110, v110
	v_fmac_f32_e32 v133, v112, v112
	v_add_f32_e32 v132, v132, v133
	v_mul_f32_e32 v133, v107, v107
	v_fmac_f32_e32 v133, v106, v106
	v_add_f32_e32 v132, v132, v133
	v_mul_f32_e32 v133, v109, v109
	v_fmac_f32_e32 v133, v108, v108
	v_add_f32_e32 v132, v133, v132
	ds_bpermute_b32 v133, v130, v132
	s_waitcnt lgkmcnt(0)
	v_add_f32_e32 v132, v132, v133
	ds_bpermute_b32 v133, v131, v132
	s_and_saveexec_b64 s[40:41], s[44:45]
	s_cbranch_execz .LBB0_365
	s_waitcnt lgkmcnt(0)
	v_add_f32_e32 v134, v132, v133
	v_or_b32_e32 v135, 2, v163
	v_mov_b64_e32 v[132:133], s[4:5]
	v_mad_i64_i32 v[132:133], s[42:43], v135, s30, v[132:133]
	v_add_co_u32_e32 v132, vcc, 0xffffff40, v132
	s_nop 1
	v_addc_co_u32_e32 v133, vcc, -1, v133, vcc
	global_store_dword v[132:133], v134, off
.LBB0_365:
	s_or_b64 exec, exec, s[40:41]
	v_mul_f32_e32 v132, v103, v103
	s_waitcnt lgkmcnt(0)
	v_mul_f32_e32 v133, v105, v105
	v_fmac_f32_e32 v132, v102, v102
	v_fmac_f32_e32 v133, v104, v104
	v_add_f32_e32 v132, v132, v133
	v_mul_f32_e32 v133, v99, v99
	v_fmac_f32_e32 v133, v98, v98
	v_add_f32_e32 v132, v132, v133
	v_mul_f32_e32 v133, v101, v101
	v_fmac_f32_e32 v133, v100, v100
	v_add_f32_e32 v132, v133, v132
	ds_bpermute_b32 v133, v130, v132
	s_waitcnt lgkmcnt(0)
	v_add_f32_e32 v132, v132, v133
	ds_bpermute_b32 v133, v131, v132
	s_and_saveexec_b64 s[40:41], s[44:45]
	s_cbranch_execz .LBB0_367
	s_waitcnt lgkmcnt(0)
	v_add_f32_e32 v134, v132, v133
	v_or_b32_e32 v135, 3, v163
	v_mov_b64_e32 v[132:133], s[4:5]
	v_mad_i64_i32 v[132:133], s[42:43], v135, s30, v[132:133]
	v_add_co_u32_e32 v132, vcc, 0xffffff40, v132
	s_nop 1
	v_addc_co_u32_e32 v133, vcc, -1, v133, vcc
	global_store_dword v[132:133], v134, off
;     __device__ __forceinline__ void operator()(const f32x4 (&acc)[2][2][4][2], const Unit& u, int wr_in, int wc_in, int fr_in, int fq_in) const {
;     ...
;             if (!odd && g32 >= 48 && g32 < 68) {
; #pragma unroll
;                 for (int ai = 0; ai < 2; ++ai)
; #pragma unroll
;                     for (int m = 0; m < 4; ++m) {
;                         const f32x4 a = acc[ai][bj][m][0], b = acc[ai][bj][m][1];
;                         float ss = (a[0] * a[0] + a[1] * a[1]) + (a[2] * a[2] + a[3] * a[3]) + (b[0] * b[0] + b[1] * b[1]) + (b[2] * b[2] + b[3] * b[3]);
;                         ss += __shfl_xor(ss, 16); ss += __shfl_xor(ss, 32);
;                         if (fq == 0) ssq[(size_t)(u.pm * 256 + ai * 128 + wr * 64 + 4 * fr + m) * 20 + (g32 - 48)] = ss;
;                     }
.LBB0_367:
	s_or_b64 exec, exec, s[40:41]
	v_mul_f32_e32 v132, v95, v95
	s_waitcnt lgkmcnt(0)
	v_mul_f32_e32 v133, v97, v97
	v_fmac_f32_e32 v132, v94, v94
	v_fmac_f32_e32 v133, v96, v96
	v_add_f32_e32 v132, v132, v133
	v_mul_f32_e32 v133, v91, v91
	v_fmac_f32_e32 v133, v90, v90
	v_add_f32_e32 v132, v132, v133
	v_mul_f32_e32 v133, v93, v93
	v_fmac_f32_e32 v133, v92, v92
	v_add_f32_e32 v132, v133, v132
	ds_bpermute_b32 v133, v130, v132
	s_waitcnt lgkmcnt(0)
	v_add_f32_e32 v132, v132, v133
	ds_bpermute_b32 v133, v131, v132
	s_and_saveexec_b64 s[40:41], s[44:45]
	s_cbranch_execz .LBB0_369
	v_add_u32_e32 v134, 0x80, v163
	s_waitcnt lgkmcnt(0)
	v_add_f32_e32 v135, v132, v133
	v_mov_b64_e32 v[132:133], s[4:5]
	v_mad_i64_i32 v[132:133], s[42:43], v134, s30, v[132:133]
	v_add_co_u32_e32 v132, vcc, 0xffffff40, v132
	s_nop 1
	v_addc_co_u32_e32 v133, vcc, -1, v133, vcc
	global_store_dword v[132:133], v135, off
.LBB0_369:
	s_or_b64 exec, exec, s[40:41]
	v_mul_f32_e32 v132, v87, v87
	s_waitcnt lgkmcnt(0)
	v_mul_f32_e32 v133, v89, v89
	v_fmac_f32_e32 v132, v86, v86
	v_fmac_f32_e32 v133, v88, v88
	v_add_f32_e32 v132, v132, v133
	v_mul_f32_e32 v133, v83, v83
	v_fmac_f32_e32 v133, v82, v82
	v_add_f32_e32 v132, v132, v133
	v_mul_f32_e32 v133, v85, v85
	v_fmac_f32_e32 v133, v84, v84
	v_add_f32_e32 v132, v133, v132
	ds_bpermute_b32 v133, v130, v132
	s_waitcnt lgkmcnt(0)
	v_add_f32_e32 v132, v132, v133
	ds_bpermute_b32 v133, v131, v132
	s_and_saveexec_b64 s[40:41], s[44:45]
	s_cbranch_execz .LBB0_371
	s_waitcnt lgkmcnt(0)
	v_add_f32_e32 v134, v132, v133
	v_add_u32_e32 v135, 0x81, v163
	v_mov_b64_e32 v[132:133], s[4:5]
	v_mad_i64_i32 v[132:133], s[42:43], v135, s30, v[132:133]
	v_add_co_u32_e32 v132, vcc, 0xffffff40, v132
	s_nop 1
	v_addc_co_u32_e32 v133, vcc, -1, v133, vcc
	global_store_dword v[132:133], v134, off
.LBB0_371:
	s_or_b64 exec, exec, s[40:41]
	v_mul_f32_e32 v132, v79, v79
	s_waitcnt lgkmcnt(0)
	v_mul_f32_e32 v133, v81, v81
	v_fmac_f32_e32 v132, v78, v78
	v_fmac_f32_e32 v133, v80, v80
	v_add_f32_e32 v132, v132, v133
	v_mul_f32_e32 v133, v75, v75
	v_fmac_f32_e32 v133, v74, v74
	v_add_f32_e32 v132, v132, v133
	v_mul_f32_e32 v133, v77, v77
	v_fmac_f32_e32 v133, v76, v76
	v_add_f32_e32 v132, v133, v132
	ds_bpermute_b32 v133, v130, v132
	s_waitcnt lgkmcnt(0)
	v_add_f32_e32 v132, v132, v133
	ds_bpermute_b32 v133, v131, v132
	s_and_saveexec_b64 s[40:41], s[44:45]
	s_cbranch_execz .LBB0_373
	s_waitcnt lgkmcnt(0)
	v_add_f32_e32 v134, v132, v133
	v_add_u32_e32 v135, 0x82, v163
	v_mov_b64_e32 v[132:133], s[4:5]
	v_mad_i64_i32 v[132:133], s[42:43], v135, s30, v[132:133]
	v_add_co_u32_e32 v132, vcc, 0xffffff40, v132
	s_nop 1
	v_addc_co_u32_e32 v133, vcc, -1, v133, vcc
	global_store_dword v[132:133], v134, off
.LBB0_373:
	s_or_b64 exec, exec, s[40:41]
	v_mul_f32_e32 v132, v71, v71
	s_waitcnt lgkmcnt(0)
	v_mul_f32_e32 v133, v73, v73
	v_fmac_f32_e32 v132, v70, v70
	v_fmac_f32_e32 v133, v72, v72
	v_add_f32_e32 v132, v132, v133
	v_mul_f32_e32 v133, v67, v67
	v_fmac_f32_e32 v133, v66, v66
	v_add_f32_e32 v132, v132, v133
	v_mul_f32_e32 v133, v69, v69
	v_fmac_f32_e32 v133, v68, v68
	v_add_f32_e32 v132, v133, v132
	ds_bpermute_b32 v130, v130, v132
	s_waitcnt lgkmcnt(0)
	v_add_f32_e32 v130, v132, v130
	ds_bpermute_b32 v131, v131, v130
	s_and_saveexec_b64 s[40:41], s[44:45]
	s_cbranch_execz .LBB0_375
	s_waitcnt lgkmcnt(0)
	v_add_f32_e32 v132, v130, v131
	v_add_u32_e32 v133, 0x83, v163
	v_mov_b64_e32 v[130:131], s[4:5]
	v_mad_i64_i32 v[130:131], s[4:5], v133, s30, v[130:131]
	v_add_co_u32_e32 v130, vcc, 0xffffff40, v130
	s_nop 1
	v_addc_co_u32_e32 v131, vcc, -1, v131, vcc
	global_store_dword v[130:131], v132, off

; __device__ __forceinline__ void rope_apply(f32x4& v0, f32x4& v1, int kind, int row, int wc, int fq, const float* tabM, const float* tabS) {
;     const int t = row & 2047, gr = t >> 6, gc = t & 63;
;     const float* tb; float sgn; f32x4 p0, p1;
;     if (kind == 1) {
;         const int pos = (fq < 2) ? gr : gc; tb = tabM + pos * 16; sgn = (fq & 1) ? 1.f : -1.f;
; #pragma unroll
;         for (int e = 0; e < 4; ++e) { p0[e] = __shfl_xor(v0[e], 16); p1[e] = __shfl_xor(v1[e], 16); }
;     } else {
;         const int pos = (wc & 1) ? gc : gr; tb = tabS + pos * 32 + (fq & 1) * 16; sgn = (fq & 2) ? 1.f : -1.f;
; #pragma unroll
;         for (int e = 0; e < 4; ++e) { p0[e] = __shfl_xor(v0[e], 32); p1[e] = __shfl_xor(v1[e], 32); }
;     }
;     const f32x4 c0 = *(const f32x4*)(tb), c1 = *(const f32x4*)(tb + 4), c2 = *(const f32x4*)(tb + 8), c3 = *(const f32x4*)(tb + 12);
;     v0[0] = v0[0] * c0[0] + sgn * p0[0] * c0[1]; v0[1] = v0[1] * c0[2] + sgn * p0[1] * c0[3];
;     v0[2] = v0[2] * c1[0] + sgn * p0[2] * c1[1]; v0[3] = v0[3] * c1[2] + sgn * p0[3] * c1[3];
;     v1[0] = v1[0] * c2[0] + sgn * p1[0] * c2[1]; v1[1] = v1[1] * c2[2] + sgn * p1[1] * c2[3];
;     v1[2] = v1[2] * c3[0] + sgn * p1[2] * c3[1]; v1[3] = v1[3] * c3[2] + sgn * p1[3] * c3[3];
;     __device__ __forceinline__ void operator()(const f32x4 (&acc)[2][2][4][2], const Unit& u, int wr_in, int wc_in, int fr_in, int fq_in) const {
;     ...
;             const int col0 = g32 * 32 + 8 * fq;
; #pragma unroll
;             for (int ai = 0; ai < 2; ++ai)
; #pragma unroll
;                 for (int m = 0; m < 4; ++m) {
;                     const int row = u.pm * 256 + ai * 128 + wr * 64 + 4 * fr + m;
;                     f32x4 v0 = acc[ai][bj][m][0], v1 = acc[ai][bj][m][1];
;                     if (rope) rope_apply(v0, v1, rope, row, wc, fq, tabM, tabS);
;                     v0 = v0 * sc; v1 = v1 * sc;
;                     store_bf16x8(Z + (size_t)row * ldz + col0, v0, v1);
;                 }
.LBB0_385:
	global_load_dwordx4 v[164:167], v[152:153], off
	global_load_dwordx4 v[168:171], v[152:153], off offset:16
	global_load_dwordx4 v[172:175], v[152:153], off offset:32
	global_load_dwordx4 v[176:179], v[152:153], off offset:48
	v_cmp_eq_u32_e32 vcc, 0, v0
	v_mov_b32_e32 v152, v129
	v_mov_b32_e32 v182, v125
	v_cndmask_b32_e64 v0, 1.0, -1.0, vcc
	s_waitcnt lgkmcnt(0)
	v_mul_f32_e32 v153, v0, v137
	v_mul_f32_e32 v183, v0, v133
	v_mul_f32_e32 v125, v0, v136
	v_mul_f32_e32 v129, v0, v132
	v_pk_mul_f32 v[134:135], v[0:1], v[134:135] op_sel_hi:[0,1]
	v_pk_mul_f32 v[130:131], v[0:1], v[130:131] op_sel_hi:[0,1]
	s_waitcnt vmcnt(0)
	v_mov_b32_e32 v132, v164
	v_mov_b32_e32 v133, v166
	v_mov_b32_e32 v166, v165
	v_pk_mul_f32 v[152:153], v[152:153], v[170:171]
	v_mov_b32_e32 v164, v172
	v_mov_b32_e32 v165, v174
	v_pk_mul_f32 v[170:171], v[182:183], v[178:179]
	v_mul_f32_e32 v128, v128, v168
	v_mul_f32_e32 v136, v125, v169
	v_mov_b32_e32 v174, v173
	v_mul_f32_e32 v124, v124, v176
	v_mul_f32_e32 v168, v129, v177
	v_pk_mul_f32 v[126:127], v[126:127], v[132:133]
	v_mov_b32_e32 v137, v153
	v_mov_b32_e32 v129, v152
	v_pk_mul_f32 v[122:123], v[122:123], v[164:165]
	v_mov_b32_e32 v169, v171
	v_mov_b32_e32 v125, v170
	v_pk_fma_f32 v[126:127], v[134:135], v[166:167], v[126:127]
	v_pk_add_f32 v[128:129], v[136:137], v[128:129]
	v_pk_fma_f32 v[122:123], v[130:131], v[174:175], v[122:123]
	v_pk_add_f32 v[124:125], v[168:169], v[124:125]
.LBB0_386:
	s_nop 0
	v_pk_mul_f32 v[134:135], v[150:151], v[124:125] op_sel_hi:[0,1]
	v_pk_mul_f32 v[124:125], v[150:151], v[122:123] op_sel_hi:[0,1]
	v_mad_i64_i32 v[122:123], s[26:27], v163, s2, 0
	v_lshlrev_b32_e32 v137, 3, v151
	v_readlane_b32 s26, v254, 23
	v_lshl_add_u32 v132, s46, 5, v137
	v_readlane_b32 s27, v254, 24
	v_ashrrev_i32_e32 v133, 31, v132
	v_pk_mul_f32 v[128:129], v[150:151], v[128:129] op_sel_hi:[0,1]
	s_waitcnt lgkmcnt(0)
	v_lshl_add_u64 v[130:131], v[122:123], 1, s[26:27]
	v_lshl_add_u64 v[152:153], v[132:133], 1, v[130:131]
	v_pk_mul_f32 v[126:127], v[150:151], v[126:127] op_sel_hi:[0,1]
	v_cvt_pk_bf16_f32 v122, v126, v127
	v_cvt_pk_bf16_f32 v123, v128, v129
	v_cvt_pk_bf16_f32 v124, v124, v125
	v_cvt_pk_bf16_f32 v125, v134, v135
	global_store_dwordx4 v[152:153], v[122:125], off
	v_or_b32_e32 v152, 1, v163
	v_cndmask_b32_e64 v0, 0, 1, s[4:5]
	s_and_b64 vcc, exec, s[0:1]
	v_and_b32_e32 v136, 61, v152
	v_cmp_ne_u32_e64 s[4:5], 1, v0
	s_cbranch_vccnz .LBB0_392
	v_and_b32_e32 v0, 64, v242
	v_add_u32_e32 v151, 64, v0
	s_and_b64 vcc, exec, s[4:5]
	s_mov_b64 s[48:49], -1
	s_cbranch_vccnz .LBB0_389
	v_xor_b32_e32 v122, 32, v242
	v_cmp_lt_i32_e32 vcc, v122, v151
	v_cndmask_b32_e64 v0, v136, v162, s[42:43]
	v_lshlrev_b32_e32 v0, 7, v0
	v_cndmask_b32_e32 v122, v242, v122, vcc
	v_lshlrev_b32_e32 v125, 2, v122
	ds_bpermute_b32 v126, v125, v118
	ds_bpermute_b32 v122, v125, v114
	ds_bpermute_b32 v127, v125, v119
	ds_bpermute_b32 v123, v125, v115
	ds_bpermute_b32 v128, v125, v120
	ds_bpermute_b32 v124, v125, v116
	ds_bpermute_b32 v129, v125, v121
	ds_bpermute_b32 v125, v125, v117
	v_lshl_add_u64 v[134:135], s[98:99], 0, v[0:1]
	v_lshlrev_b32_e32 v0, 2, v160
	v_lshl_add_u64 v[134:135], v[134:135], 0, v[0:1]
	s_mov_b64 s[48:49], 0

; __device__ __forceinline__ void rope_apply(f32x4& v0, f32x4& v1, int kind, int row, int wc, int fq, const float* tabM, const float* tabS) {
;     const int t = row & 2047, gr = t >> 6, gc = t & 63;
;     const float* tb; float sgn; f32x4 p0, p1;
;     if (kind == 1) {
;         const int pos = (fq < 2) ? gr : gc; tb = tabM + pos * 16; sgn = (fq & 1) ? 1.f : -1.f;
; #pragma unroll
;         for (int e = 0; e < 4; ++e) { p0[e] = __shfl_xor(v0[e], 16); p1[e] = __shfl_xor(v1[e], 16); }
;     } else {
;         const int pos = (wc & 1) ? gc : gr; tb = tabS + pos * 32 + (fq & 1) * 16; sgn = (fq & 2) ? 1.f : -1.f;
; #pragma unroll
;         for (int e = 0; e < 4; ++e) { p0[e] = __shfl_xor(v0[e], 32); p1[e] = __shfl_xor(v1[e], 32); }
;     }
;     const f32x4 c0 = *(const f32x4*)(tb), c1 = *(const f32x4*)(tb + 4), c2 = *(const f32x4*)(tb + 8), c3 = *(const f32x4*)(tb + 12);
;     v0[0] = v0[0] * c0[0] + sgn * p0[0] * c0[1]; v0[1] = v0[1] * c0[2] + sgn * p0[1] * c0[3];
;     v0[2] = v0[2] * c1[0] + sgn * p0[2] * c1[1]; v0[3] = v0[3] * c1[2] + sgn * p0[3] * c1[3];
;     v1[0] = v1[0] * c2[0] + sgn * p1[0] * c2[1]; v1[1] = v1[1] * c2[2] + sgn * p1[1] * c2[3];
;     v1[2] = v1[2] * c3[0] + sgn * p1[2] * c3[1]; v1[3] = v1[3] * c3[2] + sgn * p1[3] * c3[3];
;     __device__ __forceinline__ void operator()(const f32x4 (&acc)[2][2][4][2], const Unit& u, int wr_in, int wc_in, int fr_in, int fq_in) const {
;     ...
;             const int col0 = g32 * 32 + 8 * fq;
; #pragma unroll
;             for (int ai = 0; ai < 2; ++ai)
; #pragma unroll
;                 for (int m = 0; m < 4; ++m) {
;                     const int row = u.pm * 256 + ai * 128 + wr * 64 + 4 * fr + m;
;                     f32x4 v0 = acc[ai][bj][m][0], v1 = acc[ai][bj][m][1];
;                     if (rope) rope_apply(v0, v1, rope, row, wc, fq, tabM, tabS);
;                     v0 = v0 * sc; v1 = v1 * sc;
;                     store_bf16x8(Z + (size_t)row * ldz + col0, v0, v1);
;                 }
.LBB0_391:
	global_load_dwordx4 v[164:167], v[134:135], off
	global_load_dwordx4 v[168:171], v[134:135], off offset:16
	global_load_dwordx4 v[172:175], v[134:135], off offset:32
	global_load_dwordx4 v[176:179], v[134:135], off offset:48
	v_cmp_eq_u32_e32 vcc, 0, v0
	v_mov_b32_e32 v134, v121
	v_mov_b32_e32 v182, v117
	v_cndmask_b32_e64 v0, 1.0, -1.0, vcc
	s_waitcnt lgkmcnt(0)
	v_mul_f32_e32 v135, v0, v129
	v_mul_f32_e32 v183, v0, v125
	v_mul_f32_e32 v117, v0, v128
	v_mul_f32_e32 v121, v0, v124
	v_pk_mul_f32 v[126:127], v[0:1], v[126:127] op_sel_hi:[0,1]
	v_pk_mul_f32 v[122:123], v[0:1], v[122:123] op_sel_hi:[0,1]
	s_waitcnt vmcnt(0)
	v_mov_b32_e32 v124, v164
	v_mov_b32_e32 v125, v166
	v_mov_b32_e32 v166, v165
	v_pk_mul_f32 v[134:135], v[134:135], v[170:171]
	v_mov_b32_e32 v164, v172
	v_mov_b32_e32 v165, v174
	v_pk_mul_f32 v[170:171], v[182:183], v[178:179]
	v_mul_f32_e32 v120, v120, v168
	v_mul_f32_e32 v128, v117, v169
	v_mov_b32_e32 v174, v173
	v_mul_f32_e32 v116, v116, v176
	v_mul_f32_e32 v168, v121, v177
	v_pk_mul_f32 v[118:119], v[118:119], v[124:125]
	v_mov_b32_e32 v129, v135
	v_mov_b32_e32 v121, v134
	v_pk_mul_f32 v[114:115], v[114:115], v[164:165]
	v_mov_b32_e32 v169, v171
	v_mov_b32_e32 v117, v170
	v_pk_fma_f32 v[118:119], v[126:127], v[166:167], v[118:119]
	v_pk_add_f32 v[120:121], v[128:129], v[120:121]
	v_pk_fma_f32 v[114:115], v[122:123], v[174:175], v[114:115]
	v_pk_add_f32 v[116:117], v[168:169], v[116:117]
.LBB0_392:
	v_mov_b32_e32 v151, v150
	v_mov_b32_e32 v122, v150
	v_mov_b32_e32 v123, v150
	v_pk_mul_f32 v[124:125], v[122:123], v[116:117]
	v_pk_mul_f32 v[116:117], v[150:151], v[114:115]
	v_mad_i64_i32 v[114:115], s[26:27], v152, s2, 0
	v_readlane_b32 s26, v254, 23
	v_readlane_b32 s27, v254, 24
	v_pk_mul_f32 v[120:121], v[122:123], v[120:121]
	v_pk_mul_f32 v[118:119], v[150:151], v[118:119]
	v_lshl_add_u64 v[122:123], v[114:115], 1, s[26:27]
	v_lshl_add_u64 v[126:127], v[132:133], 1, v[122:123]
	v_cvt_pk_bf16_f32 v114, v118, v119
	v_cvt_pk_bf16_f32 v115, v120, v121
	v_cvt_pk_bf16_f32 v116, v116, v117
	v_cvt_pk_bf16_f32 v117, v124, v125
	global_store_dwordx4 v[126:127], v[114:117], off
	v_or_b32_e32 v127, 2, v163
	s_and_b64 vcc, exec, s[0:1]
	v_and_b32_e32 v126, 62, v127
	s_cbranch_vccnz .LBB0_398
	v_and_b32_e32 v0, 64, v242
	v_add_u32_e32 v128, 64, v0
	s_and_b64 vcc, exec, s[4:5]
	s_mov_b64 s[48:49], -1
	s_cbranch_vccnz .LBB0_395
	v_xor_b32_e32 v114, 32, v242
	v_cmp_lt_i32_e32 vcc, v114, v128
	v_cndmask_b32_e64 v0, v126, v162, s[42:43]
	v_lshlrev_b32_e32 v0, 7, v0
	v_cndmask_b32_e32 v114, v242, v114, vcc
	v_lshlrev_b32_e32 v117, 2, v114
	ds_bpermute_b32 v118, v117, v110
	ds_bpermute_b32 v114, v117, v106
	ds_bpermute_b32 v119, v117, v111
	ds_bpermute_b32 v115, v117, v107
	ds_bpermute_b32 v120, v117, v112
	ds_bpermute_b32 v116, v117, v108
	ds_bpermute_b32 v121, v117, v113
	ds_bpermute_b32 v117, v117, v109
	v_lshl_add_u64 v[124:125], s[98:99], 0, v[0:1]
	v_lshlrev_b32_e32 v0, 2, v160
	v_lshl_add_u64 v[124:125], v[124:125], 0, v[0:1]
	s_mov_b64 s[48:49], 0

; __device__ __forceinline__ void rope_apply(f32x4& v0, f32x4& v1, int kind, int row, int wc, int fq, const float* tabM, const float* tabS) {
;     const int t = row & 2047, gr = t >> 6, gc = t & 63;
;     const float* tb; float sgn; f32x4 p0, p1;
;     if (kind == 1) {
;         const int pos = (fq < 2) ? gr : gc; tb = tabM + pos * 16; sgn = (fq & 1) ? 1.f : -1.f;
; #pragma unroll
;         for (int e = 0; e < 4; ++e) { p0[e] = __shfl_xor(v0[e], 16); p1[e] = __shfl_xor(v1[e], 16); }
;     } else {
;         const int pos = (wc & 1) ? gc : gr; tb = tabS + pos * 32 + (fq & 1) * 16; sgn = (fq & 2) ? 1.f : -1.f;
; #pragma unroll
;         for (int e = 0; e < 4; ++e) { p0[e] = __shfl_xor(v0[e], 32); p1[e] = __shfl_xor(v1[e], 32); }
;     }
;     const f32x4 c0 = *(const f32x4*)(tb), c1 = *(const f32x4*)(tb + 4), c2 = *(const f32x4*)(tb + 8), c3 = *(const f32x4*)(tb + 12);
;     v0[0] = v0[0] * c0[0] + sgn * p0[0] * c0[1]; v0[1] = v0[1] * c0[2] + sgn * p0[1] * c0[3];
;     v0[2] = v0[2] * c1[0] + sgn * p0[2] * c1[1]; v0[3] = v0[3] * c1[2] + sgn * p0[3] * c1[3];
;     v1[0] = v1[0] * c2[0] + sgn * p1[0] * c2[1]; v1[1] = v1[1] * c2[2] + sgn * p1[1] * c2[3];
;     v1[2] = v1[2] * c3[0] + sgn * p1[2] * c3[1]; v1[3] = v1[3] * c3[2] + sgn * p1[3] * c3[3];
;     __device__ __forceinline__ void operator()(const f32x4 (&acc)[2][2][4][2], const Unit& u, int wr_in, int wc_in, int fr_in, int fq_in) const {
;     ...
;             const int col0 = g32 * 32 + 8 * fq;
; #pragma unroll
;             for (int ai = 0; ai < 2; ++ai)
; #pragma unroll
;                 for (int m = 0; m < 4; ++m) {
;                     const int row = u.pm * 256 + ai * 128 + wr * 64 + 4 * fr + m;
;                     f32x4 v0 = acc[ai][bj][m][0], v1 = acc[ai][bj][m][1];
;                     if (rope) rope_apply(v0, v1, rope, row, wc, fq, tabM, tabS);
;                     v0 = v0 * sc; v1 = v1 * sc;
;                     store_bf16x8(Z + (size_t)row * ldz + col0, v0, v1);
;                 }
.LBB0_397:
	global_load_dwordx4 v[164:167], v[124:125], off
	global_load_dwordx4 v[168:171], v[124:125], off offset:16
	global_load_dwordx4 v[172:175], v[124:125], off offset:32
	global_load_dwordx4 v[176:179], v[124:125], off offset:48
	v_cmp_eq_u32_e32 vcc, 0, v0
	v_mov_b32_e32 v124, v113
	v_mov_b32_e32 v128, v109
	v_cndmask_b32_e64 v0, 1.0, -1.0, vcc
	s_waitcnt lgkmcnt(0)
	v_mul_f32_e32 v125, v0, v121
	v_mul_f32_e32 v129, v0, v117
	v_mul_f32_e32 v109, v0, v120
	v_mul_f32_e32 v113, v0, v116
	v_pk_mul_f32 v[118:119], v[0:1], v[118:119] op_sel_hi:[0,1]
	v_pk_mul_f32 v[114:115], v[0:1], v[114:115] op_sel_hi:[0,1]
	s_waitcnt vmcnt(0)
	v_mov_b32_e32 v116, v164
	v_mov_b32_e32 v117, v166
	v_pk_mul_f32 v[124:125], v[124:125], v[170:171]
	v_mov_b32_e32 v134, v172
	v_mov_b32_e32 v135, v174
	v_pk_mul_f32 v[128:129], v[128:129], v[178:179]
	v_mov_b32_e32 v166, v165
	v_mul_f32_e32 v112, v112, v168
	v_mul_f32_e32 v120, v109, v169
	v_mov_b32_e32 v174, v173
	v_mul_f32_e32 v108, v108, v176
	v_mul_f32_e32 v164, v113, v177
	v_pk_mul_f32 v[110:111], v[110:111], v[116:117]
	v_mov_b32_e32 v121, v125
	v_mov_b32_e32 v113, v124
	v_pk_mul_f32 v[106:107], v[106:107], v[134:135]
	v_mov_b32_e32 v165, v129
	v_mov_b32_e32 v109, v128
	v_pk_fma_f32 v[110:111], v[118:119], v[166:167], v[110:111]
	v_pk_add_f32 v[112:113], v[120:121], v[112:113]
	v_pk_fma_f32 v[106:107], v[114:115], v[174:175], v[106:107]
	v_pk_add_f32 v[108:109], v[164:165], v[108:109]
.LBB0_398:
	v_mov_b32_e32 v114, v150
	v_mov_b32_e32 v115, v150
	v_pk_mul_f32 v[116:117], v[114:115], v[108:109]
	v_pk_mul_f32 v[108:109], v[150:151], v[106:107]
	v_mad_i64_i32 v[106:107], s[26:27], v127, s2, 0
	v_readlane_b32 s26, v254, 23
	v_readlane_b32 s27, v254, 24
	v_pk_mul_f32 v[112:113], v[114:115], v[112:113]
	v_pk_mul_f32 v[110:111], v[150:151], v[110:111]
	v_lshl_add_u64 v[114:115], v[106:107], 1, s[26:27]
	v_lshl_add_u64 v[118:119], v[132:133], 1, v[114:115]
	v_cvt_pk_bf16_f32 v106, v110, v111
	v_cvt_pk_bf16_f32 v107, v112, v113
	v_cvt_pk_bf16_f32 v108, v108, v109
	v_cvt_pk_bf16_f32 v109, v116, v117
	global_store_dwordx4 v[118:119], v[106:109], off
	v_or_b32_e32 v119, 3, v163
	s_and_b64 vcc, exec, s[0:1]
	v_and_b32_e32 v118, 63, v119
	s_cbranch_vccnz .LBB0_404
	v_and_b32_e32 v0, 64, v242
	v_add_u32_e32 v120, 64, v0
	s_and_b64 vcc, exec, s[4:5]
	s_mov_b64 s[48:49], -1
	s_cbranch_vccnz .LBB0_401
	v_xor_b32_e32 v106, 32, v242
	v_cmp_lt_i32_e32 vcc, v106, v120
	v_cndmask_b32_e64 v0, v118, v162, s[42:43]
	v_lshlrev_b32_e32 v0, 7, v0
	v_cndmask_b32_e32 v106, v242, v106, vcc
	v_lshlrev_b32_e32 v109, 2, v106
	ds_bpermute_b32 v110, v109, v102
	ds_bpermute_b32 v106, v109, v98
	ds_bpermute_b32 v111, v109, v103
	ds_bpermute_b32 v107, v109, v99
	ds_bpermute_b32 v112, v109, v104
	ds_bpermute_b32 v108, v109, v100
	ds_bpermute_b32 v113, v109, v105
	ds_bpermute_b32 v109, v109, v101
	v_lshl_add_u64 v[116:117], s[98:99], 0, v[0:1]
	v_lshlrev_b32_e32 v0, 2, v160
	v_lshl_add_u64 v[116:117], v[116:117], 0, v[0:1]
	s_mov_b64 s[48:49], 0

; __device__ __forceinline__ void rope_apply(f32x4& v0, f32x4& v1, int kind, int row, int wc, int fq, const float* tabM, const float* tabS) {
;     const int t = row & 2047, gr = t >> 6, gc = t & 63;
;     const float* tb; float sgn; f32x4 p0, p1;
;     if (kind == 1) {
;         const int pos = (fq < 2) ? gr : gc; tb = tabM + pos * 16; sgn = (fq & 1) ? 1.f : -1.f;
; #pragma unroll
;         for (int e = 0; e < 4; ++e) { p0[e] = __shfl_xor(v0[e], 16); p1[e] = __shfl_xor(v1[e], 16); }
;     } else {
;         const int pos = (wc & 1) ? gc : gr; tb = tabS + pos * 32 + (fq & 1) * 16; sgn = (fq & 2) ? 1.f : -1.f;
; #pragma unroll
;         for (int e = 0; e < 4; ++e) { p0[e] = __shfl_xor(v0[e], 32); p1[e] = __shfl_xor(v1[e], 32); }
;     }
;     const f32x4 c0 = *(const f32x4*)(tb), c1 = *(const f32x4*)(tb + 4), c2 = *(const f32x4*)(tb + 8), c3 = *(const f32x4*)(tb + 12);
;     v0[0] = v0[0] * c0[0] + sgn * p0[0] * c0[1]; v0[1] = v0[1] * c0[2] + sgn * p0[1] * c0[3];
;     v0[2] = v0[2] * c1[0] + sgn * p0[2] * c1[1]; v0[3] = v0[3] * c1[2] + sgn * p0[3] * c1[3];
;     v1[0] = v1[0] * c2[0] + sgn * p1[0] * c2[1]; v1[1] = v1[1] * c2[2] + sgn * p1[1] * c2[3];
;     v1[2] = v1[2] * c3[0] + sgn * p1[2] * c3[1]; v1[3] = v1[3] * c3[2] + sgn * p1[3] * c3[3];
;     __device__ __forceinline__ void operator()(const f32x4 (&acc)[2][2][4][2], const Unit& u, int wr_in, int wc_in, int fr_in, int fq_in) const {
;     ...
;             const int col0 = g32 * 32 + 8 * fq;
; #pragma unroll
;             for (int ai = 0; ai < 2; ++ai)
; #pragma unroll
;                 for (int m = 0; m < 4; ++m) {
;                     const int row = u.pm * 256 + ai * 128 + wr * 64 + 4 * fr + m;
;                     f32x4 v0 = acc[ai][bj][m][0], v1 = acc[ai][bj][m][1];
;                     if (rope) rope_apply(v0, v1, rope, row, wc, fq, tabM, tabS);
;                     v0 = v0 * sc; v1 = v1 * sc;
;                     store_bf16x8(Z + (size_t)row * ldz + col0, v0, v1);
;                 }
.LBB0_403:
	global_load_dwordx4 v[164:167], v[116:117], off
	global_load_dwordx4 v[168:171], v[116:117], off offset:16
	global_load_dwordx4 v[172:175], v[116:117], off offset:32
	global_load_dwordx4 v[176:179], v[116:117], off offset:48
	v_cmp_eq_u32_e32 vcc, 0, v0
	v_mov_b32_e32 v116, v105
	v_mov_b32_e32 v120, v101
	v_cndmask_b32_e64 v0, 1.0, -1.0, vcc
	s_waitcnt lgkmcnt(0)
	v_mul_f32_e32 v117, v0, v113
	v_mul_f32_e32 v121, v0, v109
	v_mul_f32_e32 v101, v0, v112
	v_mul_f32_e32 v105, v0, v108
	v_pk_mul_f32 v[110:111], v[0:1], v[110:111] op_sel_hi:[0,1]
	v_pk_mul_f32 v[106:107], v[0:1], v[106:107] op_sel_hi:[0,1]
	s_waitcnt vmcnt(0)
	v_mov_b32_e32 v108, v164
	v_mov_b32_e32 v109, v166
	v_pk_mul_f32 v[116:117], v[116:117], v[170:171]
	v_mov_b32_e32 v124, v172
	v_mov_b32_e32 v125, v174
	v_pk_mul_f32 v[120:121], v[120:121], v[178:179]
	v_mov_b32_e32 v166, v165
	v_mul_f32_e32 v104, v104, v168
	v_mul_f32_e32 v112, v101, v169
	v_mov_b32_e32 v174, v173
	v_mul_f32_e32 v100, v100, v176
	v_mul_f32_e32 v128, v105, v177
	v_pk_mul_f32 v[102:103], v[102:103], v[108:109]
	v_mov_b32_e32 v113, v117
	v_mov_b32_e32 v105, v116
	v_pk_mul_f32 v[98:99], v[98:99], v[124:125]
	v_mov_b32_e32 v129, v121
	v_mov_b32_e32 v101, v120
	v_pk_fma_f32 v[102:103], v[110:111], v[166:167], v[102:103]
	v_pk_add_f32 v[104:105], v[112:113], v[104:105]
	v_pk_fma_f32 v[98:99], v[106:107], v[174:175], v[98:99]
	v_pk_add_f32 v[100:101], v[128:129], v[100:101]
.LBB0_404:
	v_mov_b32_e32 v106, v150
	v_mov_b32_e32 v107, v150
	v_pk_mul_f32 v[108:109], v[106:107], v[100:101]
	v_pk_mul_f32 v[100:101], v[150:151], v[98:99]
	v_mad_i64_i32 v[98:99], s[26:27], v119, s2, 0
	v_readlane_b32 s26, v254, 23
	v_readlane_b32 s27, v254, 24
	v_pk_mul_f32 v[104:105], v[106:107], v[104:105]
	v_pk_mul_f32 v[102:103], v[150:151], v[102:103]
	v_lshl_add_u64 v[106:107], v[98:99], 1, s[26:27]
	v_lshl_add_u64 v[110:111], v[132:133], 1, v[106:107]
	v_cvt_pk_bf16_f32 v98, v102, v103
	v_cvt_pk_bf16_f32 v99, v104, v105
	v_cvt_pk_bf16_f32 v100, v100, v101
	v_cvt_pk_bf16_f32 v101, v108, v109
	global_store_dwordx4 v[110:111], v[98:101], off
	v_add_u32_e32 v111, 0x80, v163
	s_and_b64 vcc, exec, s[0:1]
	v_bfe_u32 v110, v111, 6, 5
	s_cbranch_vccnz .LBB0_410
	v_and_b32_e32 v0, 64, v242
	v_add_u32_e32 v112, 64, v0
	s_and_b64 vcc, exec, s[4:5]
	s_mov_b64 s[48:49], -1
	s_cbranch_vccnz .LBB0_407
	v_xor_b32_e32 v98, 32, v242
	v_cmp_lt_i32_e32 vcc, v98, v112
	v_cndmask_b32_e64 v0, v161, v110, s[42:43]
	v_lshlrev_b32_e32 v0, 7, v0
	v_cndmask_b32_e32 v98, v242, v98, vcc
	v_lshlrev_b32_e32 v101, 2, v98
	ds_bpermute_b32 v102, v101, v94
	ds_bpermute_b32 v98, v101, v90
	ds_bpermute_b32 v103, v101, v95
	ds_bpermute_b32 v99, v101, v91
	ds_bpermute_b32 v104, v101, v96
	ds_bpermute_b32 v100, v101, v92
	ds_bpermute_b32 v105, v101, v97
	ds_bpermute_b32 v101, v101, v93
	v_lshl_add_u64 v[108:109], s[98:99], 0, v[0:1]
	v_lshlrev_b32_e32 v0, 2, v160
	v_lshl_add_u64 v[108:109], v[108:109], 0, v[0:1]
	s_mov_b64 s[48:49], 0

; __device__ __forceinline__ void rope_apply(f32x4& v0, f32x4& v1, int kind, int row, int wc, int fq, const float* tabM, const float* tabS) {
;     const int t = row & 2047, gr = t >> 6, gc = t & 63;
;     const float* tb; float sgn; f32x4 p0, p1;
;     if (kind == 1) {
;         const int pos = (fq < 2) ? gr : gc; tb = tabM + pos * 16; sgn = (fq & 1) ? 1.f : -1.f;
; #pragma unroll
;         for (int e = 0; e < 4; ++e) { p0[e] = __shfl_xor(v0[e], 16); p1[e] = __shfl_xor(v1[e], 16); }
;     } else {
;         const int pos = (wc & 1) ? gc : gr; tb = tabS + pos * 32 + (fq & 1) * 16; sgn = (fq & 2) ? 1.f : -1.f;
; #pragma unroll
;         for (int e = 0; e < 4; ++e) { p0[e] = __shfl_xor(v0[e], 32); p1[e] = __shfl_xor(v1[e], 32); }
;     }
;     const f32x4 c0 = *(const f32x4*)(tb), c1 = *(const f32x4*)(tb + 4), c2 = *(const f32x4*)(tb + 8), c3 = *(const f32x4*)(tb + 12);
;     v0[0] = v0[0] * c0[0] + sgn * p0[0] * c0[1]; v0[1] = v0[1] * c0[2] + sgn * p0[1] * c0[3];
;     v0[2] = v0[2] * c1[0] + sgn * p0[2] * c1[1]; v0[3] = v0[3] * c1[2] + sgn * p0[3] * c1[3];
;     v1[0] = v1[0] * c2[0] + sgn * p1[0] * c2[1]; v1[1] = v1[1] * c2[2] + sgn * p1[1] * c2[3];
;     v1[2] = v1[2] * c3[0] + sgn * p1[2] * c3[1]; v1[3] = v1[3] * c3[2] + sgn * p1[3] * c3[3];
;     __device__ __forceinline__ void operator()(const f32x4 (&acc)[2][2][4][2], const Unit& u, int wr_in, int wc_in, int fr_in, int fq_in) const {
;     ...
;             const int col0 = g32 * 32 + 8 * fq;
; #pragma unroll
;             for (int ai = 0; ai < 2; ++ai)
; #pragma unroll
;                 for (int m = 0; m < 4; ++m) {
;                     const int row = u.pm * 256 + ai * 128 + wr * 64 + 4 * fr + m;
;                     f32x4 v0 = acc[ai][bj][m][0], v1 = acc[ai][bj][m][1];
;                     if (rope) rope_apply(v0, v1, rope, row, wc, fq, tabM, tabS);
;                     v0 = v0 * sc; v1 = v1 * sc;
;                     store_bf16x8(Z + (size_t)row * ldz + col0, v0, v1);
;                 }
.LBB0_409:
	global_load_dwordx4 v[164:167], v[108:109], off
	global_load_dwordx4 v[168:171], v[108:109], off offset:16
	global_load_dwordx4 v[172:175], v[108:109], off offset:32
	global_load_dwordx4 v[176:179], v[108:109], off offset:48
	v_cmp_eq_u32_e32 vcc, 0, v0
	v_mov_b32_e32 v108, v97
	v_mov_b32_e32 v112, v93
	v_cndmask_b32_e64 v0, 1.0, -1.0, vcc
	s_waitcnt lgkmcnt(0)
	v_mul_f32_e32 v109, v0, v105
	v_mul_f32_e32 v113, v0, v101
	v_mul_f32_e32 v93, v0, v104
	v_mul_f32_e32 v97, v0, v100
	v_pk_mul_f32 v[102:103], v[0:1], v[102:103] op_sel_hi:[0,1]
	v_pk_mul_f32 v[98:99], v[0:1], v[98:99] op_sel_hi:[0,1]
	s_waitcnt vmcnt(0)
	v_mov_b32_e32 v100, v164
	v_mov_b32_e32 v101, v166
	v_pk_mul_f32 v[108:109], v[108:109], v[170:171]
	v_mov_b32_e32 v116, v172
	v_mov_b32_e32 v117, v174
	v_pk_mul_f32 v[112:113], v[112:113], v[178:179]
	v_mov_b32_e32 v166, v165
	v_mul_f32_e32 v96, v96, v168
	v_mul_f32_e32 v104, v93, v169
	v_mov_b32_e32 v174, v173
	v_mul_f32_e32 v92, v92, v176
	v_mul_f32_e32 v120, v97, v177
	v_pk_mul_f32 v[94:95], v[94:95], v[100:101]
	v_mov_b32_e32 v105, v109
	v_mov_b32_e32 v97, v108
	v_pk_mul_f32 v[90:91], v[90:91], v[116:117]
	v_mov_b32_e32 v121, v113
	v_mov_b32_e32 v93, v112
	v_pk_fma_f32 v[94:95], v[102:103], v[166:167], v[94:95]
	v_pk_add_f32 v[96:97], v[104:105], v[96:97]
	v_pk_fma_f32 v[90:91], v[98:99], v[174:175], v[90:91]
	v_pk_add_f32 v[92:93], v[120:121], v[92:93]
.LBB0_410:
	v_mov_b32_e32 v98, v150
	v_mov_b32_e32 v99, v150
	v_pk_mul_f32 v[100:101], v[98:99], v[92:93]
	v_pk_mul_f32 v[92:93], v[150:151], v[90:91]
	v_mad_i64_i32 v[90:91], s[26:27], v111, s2, 0
	v_readlane_b32 s26, v254, 23
	v_readlane_b32 s27, v254, 24
	v_pk_mul_f32 v[96:97], v[98:99], v[96:97]
	v_pk_mul_f32 v[94:95], v[150:151], v[94:95]
	v_lshl_add_u64 v[98:99], v[90:91], 1, s[26:27]
	v_lshl_add_u64 v[102:103], v[132:133], 1, v[98:99]
	v_cvt_pk_bf16_f32 v90, v94, v95
	v_cvt_pk_bf16_f32 v91, v96, v97
	v_cvt_pk_bf16_f32 v92, v92, v93
	v_cvt_pk_bf16_f32 v93, v100, v101
	global_store_dwordx4 v[102:103], v[90:93], off
	v_or_b32_e32 v103, 1, v111
	s_and_b64 vcc, exec, s[0:1]
	v_and_b32_e32 v102, 61, v103
	s_cbranch_vccnz .LBB0_416
	v_and_b32_e32 v0, 64, v242
	v_add_u32_e32 v104, 64, v0
	s_and_b64 vcc, exec, s[4:5]
	s_mov_b64 s[48:49], -1
	s_cbranch_vccnz .LBB0_413
	v_xor_b32_e32 v90, 32, v242
	v_cmp_lt_i32_e32 vcc, v90, v104
	v_cndmask_b32_e64 v0, v102, v110, s[42:43]
	v_lshlrev_b32_e32 v0, 7, v0
	v_cndmask_b32_e32 v90, v242, v90, vcc
	v_lshlrev_b32_e32 v93, 2, v90
	ds_bpermute_b32 v94, v93, v86
	ds_bpermute_b32 v90, v93, v82
	ds_bpermute_b32 v95, v93, v87
	ds_bpermute_b32 v91, v93, v83
	ds_bpermute_b32 v96, v93, v88
	ds_bpermute_b32 v92, v93, v84
	ds_bpermute_b32 v97, v93, v89
	ds_bpermute_b32 v93, v93, v85
	v_lshl_add_u64 v[100:101], s[98:99], 0, v[0:1]
	v_lshlrev_b32_e32 v0, 2, v160
	v_lshl_add_u64 v[100:101], v[100:101], 0, v[0:1]
	s_mov_b64 s[48:49], 0

; __device__ __forceinline__ void rope_apply(f32x4& v0, f32x4& v1, int kind, int row, int wc, int fq, const float* tabM, const float* tabS) {
;     const int t = row & 2047, gr = t >> 6, gc = t & 63;
;     const float* tb; float sgn; f32x4 p0, p1;
;     if (kind == 1) {
;         const int pos = (fq < 2) ? gr : gc; tb = tabM + pos * 16; sgn = (fq & 1) ? 1.f : -1.f;
; #pragma unroll
;         for (int e = 0; e < 4; ++e) { p0[e] = __shfl_xor(v0[e], 16); p1[e] = __shfl_xor(v1[e], 16); }
;     } else {
;         const int pos = (wc & 1) ? gc : gr; tb = tabS + pos * 32 + (fq & 1) * 16; sgn = (fq & 2) ? 1.f : -1.f;
; #pragma unroll
;         for (int e = 0; e < 4; ++e) { p0[e] = __shfl_xor(v0[e], 32); p1[e] = __shfl_xor(v1[e], 32); }
;     }
;     const f32x4 c0 = *(const f32x4*)(tb), c1 = *(const f32x4*)(tb + 4), c2 = *(const f32x4*)(tb + 8), c3 = *(const f32x4*)(tb + 12);
;     v0[0] = v0[0] * c0[0] + sgn * p0[0] * c0[1]; v0[1] = v0[1] * c0[2] + sgn * p0[1] * c0[3];
;     v0[2] = v0[2] * c1[0] + sgn * p0[2] * c1[1]; v0[3] = v0[3] * c1[2] + sgn * p0[3] * c1[3];
;     v1[0] = v1[0] * c2[0] + sgn * p1[0] * c2[1]; v1[1] = v1[1] * c2[2] + sgn * p1[1] * c2[3];
;     v1[2] = v1[2] * c3[0] + sgn * p1[2] * c3[1]; v1[3] = v1[3] * c3[2] + sgn * p1[3] * c3[3];
;     __device__ __forceinline__ void operator()(const f32x4 (&acc)[2][2][4][2], const Unit& u, int wr_in, int wc_in, int fr_in, int fq_in) const {
;     ...
;             const int col0 = g32 * 32 + 8 * fq;
; #pragma unroll
;             for (int ai = 0; ai < 2; ++ai)
; #pragma unroll
;                 for (int m = 0; m < 4; ++m) {
;                     const int row = u.pm * 256 + ai * 128 + wr * 64 + 4 * fr + m;
;                     f32x4 v0 = acc[ai][bj][m][0], v1 = acc[ai][bj][m][1];
;                     if (rope) rope_apply(v0, v1, rope, row, wc, fq, tabM, tabS);
;                     v0 = v0 * sc; v1 = v1 * sc;
;                     store_bf16x8(Z + (size_t)row * ldz + col0, v0, v1);
;                 }
.LBB0_415:
	global_load_dwordx4 v[164:167], v[100:101], off
	global_load_dwordx4 v[168:171], v[100:101], off offset:16
	global_load_dwordx4 v[172:175], v[100:101], off offset:32
	global_load_dwordx4 v[176:179], v[100:101], off offset:48
	v_cmp_eq_u32_e32 vcc, 0, v0
	v_mov_b32_e32 v100, v89
	v_mov_b32_e32 v104, v85
	v_cndmask_b32_e64 v0, 1.0, -1.0, vcc
	s_waitcnt lgkmcnt(0)
	v_mul_f32_e32 v101, v0, v97
	v_mul_f32_e32 v105, v0, v93
	v_mul_f32_e32 v85, v0, v96
	v_mul_f32_e32 v89, v0, v92
	v_pk_mul_f32 v[94:95], v[0:1], v[94:95] op_sel_hi:[0,1]
	v_pk_mul_f32 v[90:91], v[0:1], v[90:91] op_sel_hi:[0,1]
	s_waitcnt vmcnt(0)
	v_mov_b32_e32 v92, v164
	v_mov_b32_e32 v93, v166
	v_pk_mul_f32 v[100:101], v[100:101], v[170:171]
	v_mov_b32_e32 v108, v172
	v_mov_b32_e32 v109, v174
	v_pk_mul_f32 v[104:105], v[104:105], v[178:179]
	v_mov_b32_e32 v166, v165
	v_mul_f32_e32 v88, v88, v168
	v_mul_f32_e32 v96, v85, v169
	v_mov_b32_e32 v174, v173
	v_mul_f32_e32 v84, v84, v176
	v_mul_f32_e32 v112, v89, v177
	v_pk_mul_f32 v[86:87], v[86:87], v[92:93]
	v_mov_b32_e32 v97, v101
	v_mov_b32_e32 v89, v100
	v_pk_mul_f32 v[82:83], v[82:83], v[108:109]
	v_mov_b32_e32 v113, v105
	v_mov_b32_e32 v85, v104
	v_pk_fma_f32 v[86:87], v[94:95], v[166:167], v[86:87]
	v_pk_add_f32 v[88:89], v[96:97], v[88:89]
	v_pk_fma_f32 v[82:83], v[90:91], v[174:175], v[82:83]
	v_pk_add_f32 v[84:85], v[112:113], v[84:85]
.LBB0_416:
	v_mov_b32_e32 v90, v150
	v_mov_b32_e32 v91, v150
	v_pk_mul_f32 v[92:93], v[90:91], v[84:85]
	v_pk_mul_f32 v[84:85], v[150:151], v[82:83]
	v_mad_i64_i32 v[82:83], s[26:27], v103, s2, 0
	v_readlane_b32 s26, v254, 23
	v_readlane_b32 s27, v254, 24
	v_pk_mul_f32 v[88:89], v[90:91], v[88:89]
	v_pk_mul_f32 v[86:87], v[150:151], v[86:87]
	v_lshl_add_u64 v[90:91], v[82:83], 1, s[26:27]
	v_lshl_add_u64 v[94:95], v[132:133], 1, v[90:91]
	v_cvt_pk_bf16_f32 v82, v86, v87
	v_cvt_pk_bf16_f32 v83, v88, v89
	v_cvt_pk_bf16_f32 v84, v84, v85
	v_cvt_pk_bf16_f32 v85, v92, v93
	global_store_dwordx4 v[94:95], v[82:85], off
	v_or_b32_e32 v95, 2, v111
	s_and_b64 vcc, exec, s[0:1]
	v_and_b32_e32 v94, 62, v95
	s_cbranch_vccnz .LBB0_422
	v_and_b32_e32 v0, 64, v242
	v_add_u32_e32 v96, 64, v0
	s_and_b64 vcc, exec, s[4:5]
	s_mov_b64 s[48:49], -1
	s_cbranch_vccnz .LBB0_419
	v_xor_b32_e32 v82, 32, v242
	v_cmp_lt_i32_e32 vcc, v82, v96
	v_cndmask_b32_e64 v0, v94, v110, s[42:43]
	v_lshlrev_b32_e32 v0, 7, v0
	v_cndmask_b32_e32 v82, v242, v82, vcc
	v_lshlrev_b32_e32 v85, 2, v82
	ds_bpermute_b32 v86, v85, v78
	ds_bpermute_b32 v82, v85, v74
	ds_bpermute_b32 v87, v85, v79
	ds_bpermute_b32 v83, v85, v75
	ds_bpermute_b32 v88, v85, v80
	ds_bpermute_b32 v84, v85, v76
	ds_bpermute_b32 v89, v85, v81
	ds_bpermute_b32 v85, v85, v77
	v_lshl_add_u64 v[92:93], s[98:99], 0, v[0:1]
	v_lshlrev_b32_e32 v0, 2, v160
	v_lshl_add_u64 v[92:93], v[92:93], 0, v[0:1]
	s_mov_b64 s[48:49], 0

; __device__ __forceinline__ void rope_apply(f32x4& v0, f32x4& v1, int kind, int row, int wc, int fq, const float* tabM, const float* tabS) {
;     const int t = row & 2047, gr = t >> 6, gc = t & 63;
;     const float* tb; float sgn; f32x4 p0, p1;
;     if (kind == 1) {
;         const int pos = (fq < 2) ? gr : gc; tb = tabM + pos * 16; sgn = (fq & 1) ? 1.f : -1.f;
; #pragma unroll
;         for (int e = 0; e < 4; ++e) { p0[e] = __shfl_xor(v0[e], 16); p1[e] = __shfl_xor(v1[e], 16); }
;     } else {
;         const int pos = (wc & 1) ? gc : gr; tb = tabS + pos * 32 + (fq & 1) * 16; sgn = (fq & 2) ? 1.f : -1.f;
; #pragma unroll
;         for (int e = 0; e < 4; ++e) { p0[e] = __shfl_xor(v0[e], 32); p1[e] = __shfl_xor(v1[e], 32); }
;     }
;     const f32x4 c0 = *(const f32x4*)(tb), c1 = *(const f32x4*)(tb + 4), c2 = *(const f32x4*)(tb + 8), c3 = *(const f32x4*)(tb + 12);
;     v0[0] = v0[0] * c0[0] + sgn * p0[0] * c0[1]; v0[1] = v0[1] * c0[2] + sgn * p0[1] * c0[3];
;     v0[2] = v0[2] * c1[0] + sgn * p0[2] * c1[1]; v0[3] = v0[3] * c1[2] + sgn * p0[3] * c1[3];
;     v1[0] = v1[0] * c2[0] + sgn * p1[0] * c2[1]; v1[1] = v1[1] * c2[2] + sgn * p1[1] * c2[3];
;     v1[2] = v1[2] * c3[0] + sgn * p1[2] * c3[1]; v1[3] = v1[3] * c3[2] + sgn * p1[3] * c3[3];
;     __device__ __forceinline__ void operator()(const f32x4 (&acc)[2][2][4][2], const Unit& u, int wr_in, int wc_in, int fr_in, int fq_in) const {
;     ...
;             const int col0 = g32 * 32 + 8 * fq;
; #pragma unroll
;             for (int ai = 0; ai < 2; ++ai)
; #pragma unroll
;                 for (int m = 0; m < 4; ++m) {
;                     const int row = u.pm * 256 + ai * 128 + wr * 64 + 4 * fr + m;
;                     f32x4 v0 = acc[ai][bj][m][0], v1 = acc[ai][bj][m][1];
;                     if (rope) rope_apply(v0, v1, rope, row, wc, fq, tabM, tabS);
;                     v0 = v0 * sc; v1 = v1 * sc;
;                     store_bf16x8(Z + (size_t)row * ldz + col0, v0, v1);
;                 }
.LBB0_421:
	global_load_dwordx4 v[164:167], v[92:93], off
	global_load_dwordx4 v[168:171], v[92:93], off offset:16
	global_load_dwordx4 v[172:175], v[92:93], off offset:32
	global_load_dwordx4 v[176:179], v[92:93], off offset:48
	v_cmp_eq_u32_e32 vcc, 0, v0
	v_mov_b32_e32 v92, v81
	v_mov_b32_e32 v96, v77
	v_cndmask_b32_e64 v0, 1.0, -1.0, vcc
	s_waitcnt lgkmcnt(0)
	v_mul_f32_e32 v93, v0, v89
	v_mul_f32_e32 v97, v0, v85
	v_mul_f32_e32 v77, v0, v88
	v_mul_f32_e32 v81, v0, v84
	v_pk_mul_f32 v[86:87], v[0:1], v[86:87] op_sel_hi:[0,1]
	v_pk_mul_f32 v[82:83], v[0:1], v[82:83] op_sel_hi:[0,1]
	s_waitcnt vmcnt(0)
	v_mov_b32_e32 v84, v164
	v_mov_b32_e32 v85, v166
	v_pk_mul_f32 v[92:93], v[92:93], v[170:171]
	v_mov_b32_e32 v100, v172
	v_mov_b32_e32 v101, v174
	v_pk_mul_f32 v[96:97], v[96:97], v[178:179]
	v_mov_b32_e32 v166, v165
	v_mul_f32_e32 v80, v80, v168
	v_mul_f32_e32 v88, v77, v169
	v_mov_b32_e32 v174, v173
	v_mul_f32_e32 v76, v76, v176
	v_mul_f32_e32 v104, v81, v177
	v_pk_mul_f32 v[78:79], v[78:79], v[84:85]
	v_mov_b32_e32 v89, v93
	v_mov_b32_e32 v81, v92
	v_pk_mul_f32 v[74:75], v[74:75], v[100:101]
	v_mov_b32_e32 v105, v97
	v_mov_b32_e32 v77, v96
	v_pk_fma_f32 v[78:79], v[86:87], v[166:167], v[78:79]
	v_pk_add_f32 v[80:81], v[88:89], v[80:81]
	v_pk_fma_f32 v[74:75], v[82:83], v[174:175], v[74:75]
	v_pk_add_f32 v[76:77], v[104:105], v[76:77]
.LBB0_422:
	v_mov_b32_e32 v82, v150
	v_mov_b32_e32 v83, v150
	v_pk_mul_f32 v[84:85], v[82:83], v[76:77]
	v_pk_mul_f32 v[76:77], v[150:151], v[74:75]
	v_mad_i64_i32 v[74:75], s[26:27], v95, s2, 0
	v_readlane_b32 s26, v254, 23
	v_readlane_b32 s27, v254, 24
	v_pk_mul_f32 v[80:81], v[82:83], v[80:81]
	v_pk_mul_f32 v[78:79], v[150:151], v[78:79]
	v_lshl_add_u64 v[82:83], v[74:75], 1, s[26:27]
	v_lshl_add_u64 v[86:87], v[132:133], 1, v[82:83]
	v_cvt_pk_bf16_f32 v74, v78, v79
	v_cvt_pk_bf16_f32 v75, v80, v81
	v_cvt_pk_bf16_f32 v76, v76, v77
	v_cvt_pk_bf16_f32 v77, v84, v85
	global_store_dwordx4 v[86:87], v[74:77], off
	v_or_b32_e32 v87, 3, v111
	s_and_b64 vcc, exec, s[0:1]
	v_and_b32_e32 v86, 63, v87
	s_cbranch_vccnz .LBB0_428
	v_and_b32_e32 v0, 64, v242
	v_add_u32_e32 v88, 64, v0
	s_and_b64 vcc, exec, s[4:5]
	s_mov_b64 s[0:1], -1
	s_cbranch_vccnz .LBB0_425
	v_xor_b32_e32 v74, 32, v242
	v_cmp_lt_i32_e32 vcc, v74, v88
	v_cndmask_b32_e64 v0, v86, v110, s[42:43]
	v_lshlrev_b32_e32 v0, 7, v0
	v_cndmask_b32_e32 v74, v242, v74, vcc
	v_lshlrev_b32_e32 v77, 2, v74
	ds_bpermute_b32 v78, v77, v70
	ds_bpermute_b32 v74, v77, v66
	ds_bpermute_b32 v79, v77, v71
	ds_bpermute_b32 v75, v77, v67
	ds_bpermute_b32 v80, v77, v72
	ds_bpermute_b32 v76, v77, v68
	ds_bpermute_b32 v81, v77, v73
	ds_bpermute_b32 v77, v77, v69
	v_lshl_add_u64 v[84:85], s[98:99], 0, v[0:1]
	v_lshlrev_b32_e32 v0, 2, v160
	v_lshl_add_u64 v[84:85], v[84:85], 0, v[0:1]
	s_mov_b64 s[0:1], 0

;     __device__ __forceinline__ void operator()(const f32x4 (&acc)[2][2][4][2], const Unit& u, int wr_in, int wc_in, int fr_in, int fq_in) const {
;     ...
;             if (!odd && g32 >= 48 && g32 < 68) {
; #pragma unroll
;                 for (int ai = 0; ai < 2; ++ai)
; #pragma unroll
;                     for (int m = 0; m < 4; ++m) {
;                         const f32x4 a = acc[ai][bj][m][0], b = acc[ai][bj][m][1];
;                         float ss = (a[0] * a[0] + a[1] * a[1]) + (a[2] * a[2] + a[3] * a[3]) + (b[0] * b[0] + b[1] * b[1]) + (b[2] * b[2] + b[3] * b[3]);
;                         ss += __shfl_xor(ss, 16); ss += __shfl_xor(ss, 32);
;                         if (fq == 0) ssq[(size_t)(u.pm * 256 + ai * 128 + wr * 64 + 4 * fr + m) * 20 + (g32 - 48)] = ss;
;                     }
;     ...
;             const int col0 = g32 * 32 + 8 * fq;
; #pragma unroll
;             for (int ai = 0; ai < 2; ++ai)
; #pragma unroll
;                 for (int m = 0; m < 4; ++m) {
;                     const int row = u.pm * 256 + ai * 128 + wr * 64 + 4 * fr + m;
;                     f32x4 v0 = acc[ai][bj][m][0], v1 = acc[ai][bj][m][1];
;                     if (rope) rope_apply(v0, v1, rope, row, wc, fq, tabM, tabS);
;                     v0 = v0 * sc; v1 = v1 * sc;
;                     store_bf16x8(Z + (size_t)row * ldz + col0, v0, v1);
;                 }
.LBB0_427:
	global_load_dwordx4 v[164:167], v[84:85], off
	global_load_dwordx4 v[168:171], v[84:85], off offset:16
	global_load_dwordx4 v[172:175], v[84:85], off offset:32
	global_load_dwordx4 v[176:179], v[84:85], off offset:48
	v_cmp_eq_u32_e32 vcc, 0, v0
	v_mov_b32_e32 v84, v73
	v_mov_b32_e32 v88, v69
	v_cndmask_b32_e64 v0, 1.0, -1.0, vcc
	s_waitcnt lgkmcnt(0)
	v_mul_f32_e32 v85, v0, v81
	v_mul_f32_e32 v89, v0, v77
	v_mul_f32_e32 v69, v0, v80
	v_mul_f32_e32 v73, v0, v76
	v_pk_mul_f32 v[78:79], v[0:1], v[78:79] op_sel_hi:[0,1]
	v_pk_mul_f32 v[74:75], v[0:1], v[74:75] op_sel_hi:[0,1]
	s_waitcnt vmcnt(0)
	v_mov_b32_e32 v76, v164
	v_mov_b32_e32 v77, v166
	v_pk_mul_f32 v[84:85], v[84:85], v[170:171]
	v_mov_b32_e32 v92, v172
	v_mov_b32_e32 v93, v174
	v_pk_mul_f32 v[88:89], v[88:89], v[178:179]
	v_mov_b32_e32 v166, v165
	v_mul_f32_e32 v72, v72, v168
	v_mul_f32_e32 v80, v69, v169
	v_mov_b32_e32 v174, v173
	v_mul_f32_e32 v68, v68, v176
	v_mul_f32_e32 v96, v73, v177
	v_pk_mul_f32 v[70:71], v[70:71], v[76:77]
	v_mov_b32_e32 v81, v85
	v_mov_b32_e32 v73, v84
	v_pk_mul_f32 v[66:67], v[66:67], v[92:93]
	v_mov_b32_e32 v97, v89
	v_mov_b32_e32 v69, v88
	v_pk_fma_f32 v[70:71], v[78:79], v[166:167], v[70:71]
	v_pk_add_f32 v[72:73], v[80:81], v[72:73]
	v_pk_fma_f32 v[66:67], v[74:75], v[174:175], v[66:67]
	v_pk_add_f32 v[68:69], v[96:97], v[68:69]
.LBB0_428:
	v_mov_b32_e32 v74, v150
	v_mov_b32_e32 v75, v150
	v_pk_mul_f32 v[76:77], v[74:75], v[68:69]
	v_pk_mul_f32 v[68:69], v[150:151], v[66:67]
	v_mad_i64_i32 v[66:67], s[0:1], v87, s2, 0
	v_readlane_b32 s0, v254, 23
	v_readlane_b32 s1, v254, 24
	v_pk_mul_f32 v[72:73], v[74:75], v[72:73]
	s_add_i32 s94, s46, 4
	v_lshl_add_u64 v[74:75], v[66:67], 1, s[0:1]
	s_sub_i32 s0, s46, 44
	s_cmp_lt_u32 s0, 20
	s_cselect_b64 s[0:1], -1, 0
	s_and_b64 s[0:1], s[58:59], s[0:1]
	v_lshl_add_u64 v[78:79], v[132:133], 1, v[74:75]
	s_andn2_b64 vcc, exec, s[0:1]
	v_pk_mul_f32 v[70:71], v[150:151], v[70:71]
	v_cvt_pk_bf16_f32 v67, v72, v73
	v_cvt_pk_bf16_f32 v68, v68, v69
	v_cvt_pk_bf16_f32 v69, v76, v77
	s_nop 0
	v_cvt_pk_bf16_f32 v66, v70, v71
	global_store_dwordx4 v[78:79], v[66:69], off
	s_cbranch_vccnz .LBB0_446
	s_nop 0
	v_mul_f32_e32 v67, v63, v63
	v_mul_f32_e32 v68, v65, v65
	v_fmac_f32_e32 v67, v62, v62
	v_fmac_f32_e32 v68, v64, v64
	v_and_b32_e32 v66, 64, v242
	v_add_f32_e32 v67, v67, v68
	v_mul_f32_e32 v68, v59, v59
	v_xor_b32_e32 v0, 16, v242
	v_add_u32_e32 v66, 64, v66
	v_fmac_f32_e32 v68, v58, v58
	v_cmp_lt_i32_e32 vcc, v0, v66
	v_add_f32_e32 v67, v67, v68
	v_mul_f32_e32 v68, v61, v61
	v_cndmask_b32_e32 v0, v242, v0, vcc
	v_fmac_f32_e32 v68, v60, v60
	v_lshlrev_b32_e32 v0, 2, v0
	v_add_f32_e32 v67, v68, v67
	ds_bpermute_b32 v68, v0, v67
	v_xor_b32_e32 v69, 32, v242
	v_cmp_lt_i32_e32 vcc, v69, v66
	s_mov_b32 s95, s47
	s_lshl_b64 s[0:1], s[94:95], 2
	v_cndmask_b32_e32 v66, v242, v69, vcc
	v_lshlrev_b32_e32 v66, 2, v66
	s_waitcnt lgkmcnt(0)
	v_add_f32_e32 v67, v67, v68
	ds_bpermute_b32 v68, v66, v67
	v_readlane_b32 s4, v254, 25
	s_add_u32 s0, s4, s0
	v_readlane_b32 s4, v254, 26
	s_addc_u32 s1, s4, s1
	s_and_saveexec_b64 s[4:5], s[44:45]
	s_cbranch_execz .LBB0_431
	s_waitcnt lgkmcnt(0)
	v_add_f32_e32 v67, v67, v68
	v_mov_b64_e32 v[68:69], s[0:1]
	v_mad_i64_i32 v[68:69], s[26:27], v163, s30, v[68:69]
	v_add_co_u32_e32 v68, vcc, 0xffffff40, v68
	s_nop 1
	v_addc_co_u32_e32 v69, vcc, -1, v69, vcc
	global_store_dword v[68:69], v67, off
.LBB0_431:
	s_or_b64 exec, exec, s[4:5]
	v_mul_f32_e32 v67, v55, v55
	s_waitcnt lgkmcnt(0)
	v_mul_f32_e32 v68, v57, v57
	v_fmac_f32_e32 v67, v54, v54
	v_fmac_f32_e32 v68, v56, v56
	v_add_f32_e32 v67, v67, v68
	v_mul_f32_e32 v68, v51, v51
	v_fmac_f32_e32 v68, v50, v50
	v_add_f32_e32 v67, v67, v68
	v_mul_f32_e32 v68, v53, v53
	v_fmac_f32_e32 v68, v52, v52
	v_add_f32_e32 v67, v68, v67
	ds_bpermute_b32 v68, v0, v67
	s_waitcnt lgkmcnt(0)
	v_add_f32_e32 v67, v67, v68
	ds_bpermute_b32 v68, v66, v67
	s_and_saveexec_b64 s[4:5], s[44:45]
	s_cbranch_execz .LBB0_433
	s_waitcnt lgkmcnt(0)
	v_add_f32_e32 v67, v67, v68
	v_mov_b64_e32 v[68:69], s[0:1]
	v_mad_i64_i32 v[68:69], s[26:27], v152, s30, v[68:69]
	v_add_co_u32_e32 v68, vcc, 0xffffff40, v68
	s_nop 1
	v_addc_co_u32_e32 v69, vcc, -1, v69, vcc
	global_store_dword v[68:69], v67, off
;     __device__ __forceinline__ void operator()(const f32x4 (&acc)[2][2][4][2], const Unit& u, int wr_in, int wc_in, int fr_in, int fq_in) const {
;     ...
;             if (!odd && g32 >= 48 && g32 < 68) {
; #pragma unroll
;                 for (int ai = 0; ai < 2; ++ai)
; #pragma unroll
;                     for (int m = 0; m < 4; ++m) {
;                         const f32x4 a = acc[ai][bj][m][0], b = acc[ai][bj][m][1];
;                         float ss = (a[0] * a[0] + a[1] * a[1]) + (a[2] * a[2] + a[3] * a[3]) + (b[0] * b[0] + b[1] * b[1]) + (b[2] * b[2] + b[3] * b[3]);
;                         ss += __shfl_xor(ss, 16); ss += __shfl_xor(ss, 32);
;                         if (fq == 0) ssq[(size_t)(u.pm * 256 + ai * 128 + wr * 64 + 4 * fr + m) * 20 + (g32 - 48)] = ss;
;                     }
.LBB0_433:
	s_or_b64 exec, exec, s[4:5]
	v_mul_f32_e32 v67, v47, v47
	s_waitcnt lgkmcnt(0)
	v_mul_f32_e32 v68, v49, v49
	v_fmac_f32_e32 v67, v46, v46
	v_fmac_f32_e32 v68, v48, v48
	v_add_f32_e32 v67, v67, v68
	v_mul_f32_e32 v68, v43, v43
	v_fmac_f32_e32 v68, v42, v42
	v_add_f32_e32 v67, v67, v68
	v_mul_f32_e32 v68, v45, v45
	v_fmac_f32_e32 v68, v44, v44
	v_add_f32_e32 v67, v68, v67
	ds_bpermute_b32 v68, v0, v67
	s_waitcnt lgkmcnt(0)
	v_add_f32_e32 v67, v67, v68
	ds_bpermute_b32 v68, v66, v67
	s_and_saveexec_b64 s[4:5], s[44:45]
	s_cbranch_execz .LBB0_435
	s_waitcnt lgkmcnt(0)
	v_add_f32_e32 v67, v67, v68
	v_mov_b64_e32 v[68:69], s[0:1]
	v_mad_i64_i32 v[68:69], s[26:27], v127, s30, v[68:69]
	v_add_co_u32_e32 v68, vcc, 0xffffff40, v68
	s_nop 1
	v_addc_co_u32_e32 v69, vcc, -1, v69, vcc
	global_store_dword v[68:69], v67, off
.LBB0_435:
	s_or_b64 exec, exec, s[4:5]
	v_mul_f32_e32 v67, v39, v39
	s_waitcnt lgkmcnt(0)
	v_mul_f32_e32 v68, v41, v41
	v_fmac_f32_e32 v67, v38, v38
	v_fmac_f32_e32 v68, v40, v40
	v_add_f32_e32 v67, v67, v68
	v_mul_f32_e32 v68, v35, v35
	v_fmac_f32_e32 v68, v34, v34
	v_add_f32_e32 v67, v67, v68
	v_mul_f32_e32 v68, v37, v37
	v_fmac_f32_e32 v68, v36, v36
	v_add_f32_e32 v67, v68, v67
	ds_bpermute_b32 v68, v0, v67
	s_waitcnt lgkmcnt(0)
	v_add_f32_e32 v67, v67, v68
	ds_bpermute_b32 v68, v66, v67
	s_and_saveexec_b64 s[4:5], s[44:45]
	s_cbranch_execz .LBB0_437
	s_waitcnt lgkmcnt(0)
	v_add_f32_e32 v67, v67, v68
	v_mov_b64_e32 v[68:69], s[0:1]
	v_mad_i64_i32 v[68:69], s[26:27], v119, s30, v[68:69]
	v_add_co_u32_e32 v68, vcc, 0xffffff40, v68
	s_nop 1
	v_addc_co_u32_e32 v69, vcc, -1, v69, vcc
	global_store_dword v[68:69], v67, off
.LBB0_437:
	s_or_b64 exec, exec, s[4:5]
	v_mul_f32_e32 v67, v31, v31
	s_waitcnt lgkmcnt(0)
	v_mul_f32_e32 v68, v33, v33
	v_fmac_f32_e32 v67, v30, v30
	v_fmac_f32_e32 v68, v32, v32
	v_add_f32_e32 v67, v67, v68
	v_mul_f32_e32 v68, v27, v27
	v_fmac_f32_e32 v68, v26, v26
	v_add_f32_e32 v67, v67, v68
	v_mul_f32_e32 v68, v29, v29
	v_fmac_f32_e32 v68, v28, v28
	v_add_f32_e32 v67, v68, v67
	ds_bpermute_b32 v68, v0, v67
	s_waitcnt lgkmcnt(0)
	v_add_f32_e32 v67, v67, v68
	ds_bpermute_b32 v68, v66, v67
	s_and_saveexec_b64 s[4:5], s[44:45]
	s_cbranch_execz .LBB0_439
	s_waitcnt lgkmcnt(0)
	v_add_f32_e32 v67, v67, v68
	v_mov_b64_e32 v[68:69], s[0:1]
	v_mad_i64_i32 v[68:69], s[26:27], v111, s30, v[68:69]
	v_add_co_u32_e32 v68, vcc, 0xffffff40, v68
	s_nop 1
	v_addc_co_u32_e32 v69, vcc, -1, v69, vcc
	global_store_dword v[68:69], v67, off
.LBB0_439:
	s_or_b64 exec, exec, s[4:5]
	v_mul_f32_e32 v67, v23, v23
	s_waitcnt lgkmcnt(0)
	v_mul_f32_e32 v68, v25, v25
	v_fmac_f32_e32 v67, v22, v22
	v_fmac_f32_e32 v68, v24, v24
	v_add_f32_e32 v67, v67, v68
	v_mul_f32_e32 v68, v19, v19
	v_fmac_f32_e32 v68, v18, v18
	v_add_f32_e32 v67, v67, v68
	v_mul_f32_e32 v68, v21, v21
	v_fmac_f32_e32 v68, v20, v20
	v_add_f32_e32 v67, v68, v67
	ds_bpermute_b32 v68, v0, v67
	s_waitcnt lgkmcnt(0)
	v_add_f32_e32 v67, v67, v68
	ds_bpermute_b32 v68, v66, v67
	s_and_saveexec_b64 s[4:5], s[44:45]
	s_cbranch_execz .LBB0_441
	s_waitcnt lgkmcnt(0)
	v_add_f32_e32 v67, v67, v68
	v_add_u32_e32 v70, 0x81, v163
	v_mov_b64_e32 v[68:69], s[0:1]
	v_mad_i64_i32 v[68:69], s[26:27], v70, s30, v[68:69]
	v_add_co_u32_e32 v68, vcc, 0xffffff40, v68
	s_nop 1
	v_addc_co_u32_e32 v69, vcc, -1, v69, vcc
	global_store_dword v[68:69], v67, off
.LBB0_441:
	s_or_b64 exec, exec, s[4:5]
	v_mul_f32_e32 v67, v15, v15
	s_waitcnt lgkmcnt(0)
	v_mul_f32_e32 v68, v17, v17
	v_fmac_f32_e32 v67, v14, v14
	v_fmac_f32_e32 v68, v16, v16
	v_add_f32_e32 v67, v67, v68
	v_mul_f32_e32 v68, v11, v11
	v_fmac_f32_e32 v68, v10, v10
	v_add_f32_e32 v67, v67, v68
	v_mul_f32_e32 v68, v13, v13
	v_fmac_f32_e32 v68, v12, v12
	v_add_f32_e32 v67, v68, v67
	ds_bpermute_b32 v68, v0, v67
	s_waitcnt lgkmcnt(0)
	v_add_f32_e32 v67, v67, v68
	ds_bpermute_b32 v68, v66, v67
	s_and_saveexec_b64 s[4:5], s[44:45]
	s_cbranch_execz .LBB0_443
	s_waitcnt lgkmcnt(0)
	v_add_f32_e32 v67, v67, v68
	v_add_u32_e32 v70, 0x82, v163
	v_mov_b64_e32 v[68:69], s[0:1]
	v_mad_i64_i32 v[68:69], s[26:27], v70, s30, v[68:69]
	v_add_co_u32_e32 v68, vcc, 0xffffff40, v68
	s_nop 1
	v_addc_co_u32_e32 v69, vcc, -1, v69, vcc
	global_store_dword v[68:69], v67, off
.LBB0_443:
	s_or_b64 exec, exec, s[4:5]
	v_mul_f32_e32 v67, v7, v7
	s_waitcnt lgkmcnt(0)
	v_mul_f32_e32 v68, v9, v9
	v_fmac_f32_e32 v67, v6, v6
	v_fmac_f32_e32 v68, v8, v8
	v_add_f32_e32 v67, v67, v68
	v_mul_f32_e32 v68, v3, v3
	v_fmac_f32_e32 v68, v2, v2
	v_add_f32_e32 v67, v67, v68
	v_mul_f32_e32 v68, v5, v5
	v_fmac_f32_e32 v68, v4, v4
	v_add_f32_e32 v67, v68, v67
	ds_bpermute_b32 v0, v0, v67
	s_waitcnt lgkmcnt(0)
	v_add_f32_e32 v0, v67, v0
	ds_bpermute_b32 v66, v66, v0
	s_and_saveexec_b64 s[4:5], s[44:45]
	s_cbranch_execz .LBB0_445
	s_waitcnt lgkmcnt(0)
	v_add_f32_e32 v0, v0, v66
	v_add_u32_e32 v68, 0x83, v163
	v_mov_b64_e32 v[66:67], s[0:1]
	v_mad_i64_i32 v[66:67], s[0:1], v68, s30, v[66:67]
	v_add_co_u32_e32 v66, vcc, 0xffffff40, v66
	s_nop 1
	v_addc_co_u32_e32 v67, vcc, -1, v67, vcc
	global_store_dword v[66:67], v0, off

; __device__ __forceinline__ void rope_apply(f32x4& v0, f32x4& v1, int kind, int row, int wc, int fq, const float* tabM, const float* tabS) {
;     const int t = row & 2047, gr = t >> 6, gc = t & 63;
;     const float* tb; float sgn; f32x4 p0, p1;
;     if (kind == 1) {
;         const int pos = (fq < 2) ? gr : gc; tb = tabM + pos * 16; sgn = (fq & 1) ? 1.f : -1.f;
; #pragma unroll
;         for (int e = 0; e < 4; ++e) { p0[e] = __shfl_xor(v0[e], 16); p1[e] = __shfl_xor(v1[e], 16); }
;     } else {
;         const int pos = (wc & 1) ? gc : gr; tb = tabS + pos * 32 + (fq & 1) * 16; sgn = (fq & 2) ? 1.f : -1.f;
; #pragma unroll
;         for (int e = 0; e < 4; ++e) { p0[e] = __shfl_xor(v0[e], 32); p1[e] = __shfl_xor(v1[e], 32); }
;     }
;     const f32x4 c0 = *(const f32x4*)(tb), c1 = *(const f32x4*)(tb + 4), c2 = *(const f32x4*)(tb + 8), c3 = *(const f32x4*)(tb + 12);
;     v0[0] = v0[0] * c0[0] + sgn * p0[0] * c0[1]; v0[1] = v0[1] * c0[2] + sgn * p0[1] * c0[3];
;     v0[2] = v0[2] * c1[0] + sgn * p0[2] * c1[1]; v0[3] = v0[3] * c1[2] + sgn * p0[3] * c1[3];
;     v1[0] = v1[0] * c2[0] + sgn * p1[0] * c2[1]; v1[1] = v1[1] * c2[2] + sgn * p1[1] * c2[3];
;     v1[2] = v1[2] * c3[0] + sgn * p1[2] * c3[1]; v1[3] = v1[3] * c3[2] + sgn * p1[3] * c3[3];
;     __device__ __forceinline__ void operator()(const f32x4 (&acc)[2][2][4][2], const Unit& u, int wr_in, int wc_in, int fr_in, int fq_in) const {
;     ...
;             const int col0 = g32 * 32 + 8 * fq;
; #pragma unroll
;             for (int ai = 0; ai < 2; ++ai)
; #pragma unroll
;                 for (int m = 0; m < 4; ++m) {
;                     const int row = u.pm * 256 + ai * 128 + wr * 64 + 4 * fr + m;
;                     f32x4 v0 = acc[ai][bj][m][0], v1 = acc[ai][bj][m][1];
;                     if (rope) rope_apply(v0, v1, rope, row, wc, fq, tabM, tabS);
;                     v0 = v0 * sc; v1 = v1 * sc;
;                     store_bf16x8(Z + (size_t)row * ldz + col0, v0, v1);
;                 }
.LBB0_455:
	global_load_dwordx4 v[132:135], v[78:79], off
	global_load_dwordx4 v[150:153], v[78:79], off offset:16
	global_load_dwordx4 v[164:167], v[78:79], off offset:32
	s_nop 0
	global_load_dwordx4 v[78:81], v[78:79], off offset:48
	v_cmp_eq_u32_e32 vcc, 0, v0
	v_mov_b32_e32 v84, v65
	v_mov_b32_e32 v88, v61
	v_cndmask_b32_e64 v0, 1.0, -1.0, vcc
	s_waitcnt lgkmcnt(0)
	v_mul_f32_e32 v85, v0, v73
	v_mul_f32_e32 v89, v0, v69
	v_mul_f32_e32 v61, v0, v72
	v_mul_f32_e32 v65, v0, v68
	v_pk_mul_f32 v[70:71], v[0:1], v[70:71] op_sel_hi:[0,1]
	v_pk_mul_f32 v[66:67], v[0:1], v[66:67] op_sel_hi:[0,1]
	s_waitcnt vmcnt(0)
	v_mov_b32_e32 v68, v132
	v_mov_b32_e32 v69, v134
	v_pk_mul_f32 v[84:85], v[84:85], v[152:153]
	v_mov_b32_e32 v92, v164
	v_mov_b32_e32 v93, v166
	v_pk_mul_f32 v[80:81], v[88:89], v[80:81]
	v_mov_b32_e32 v134, v133
	v_mul_f32_e32 v64, v64, v150
	v_mul_f32_e32 v72, v61, v151
	v_mov_b32_e32 v166, v165
	v_mul_f32_e32 v60, v60, v78
	v_mul_f32_e32 v78, v65, v79
	v_pk_mul_f32 v[62:63], v[62:63], v[68:69]
	v_mov_b32_e32 v73, v85
	v_mov_b32_e32 v65, v84
	v_pk_mul_f32 v[58:59], v[58:59], v[92:93]
	v_mov_b32_e32 v79, v81
	v_mov_b32_e32 v61, v80
	v_pk_fma_f32 v[62:63], v[70:71], v[134:135], v[62:63]
	v_pk_add_f32 v[64:65], v[72:73], v[64:65]
	v_pk_fma_f32 v[58:59], v[66:67], v[166:167], v[58:59]
	v_pk_add_f32 v[60:61], v[78:79], v[60:61]
.LBB0_456:
	s_waitcnt lgkmcnt(0)
	v_lshl_add_u32 v66, s94, 5, v137
	v_ashrrev_i32_e32 v67, 31, v66
	v_pk_mul_f32 v[68:69], v[76:77], v[60:61] op_sel_hi:[0,1]
	v_pk_mul_f32 v[60:61], v[76:77], v[58:59] op_sel_hi:[0,1]
	v_lshl_add_u64 v[70:71], v[66:67], 1, v[130:131]
	s_and_b64 vcc, exec, s[4:5]
	v_pk_mul_f32 v[64:65], v[76:77], v[64:65] op_sel_hi:[0,1]
	v_pk_mul_f32 v[62:63], v[76:77], v[62:63] op_sel_hi:[0,1]
	v_cvt_pk_bf16_f32 v58, v62, v63
	v_cvt_pk_bf16_f32 v59, v64, v65
	v_cvt_pk_bf16_f32 v60, v60, v61
	v_cvt_pk_bf16_f32 v61, v68, v69
	global_store_dwordx4 v[70:71], v[58:61], off
	s_cbranch_vccnz .LBB0_462
	v_and_b32_e32 v0, 64, v242
	v_add_u32_e32 v70, 64, v0
	s_and_b64 vcc, exec, s[0:1]
	s_mov_b64 s[44:45], -1
	s_cbranch_vccnz .LBB0_459
	v_xor_b32_e32 v58, 32, v242
	v_cmp_lt_i32_e32 vcc, v58, v70
	v_cndmask_b32_e64 v0, v136, v162, s[42:43]
	v_lshlrev_b32_e32 v0, 7, v0
	v_cndmask_b32_e32 v58, v242, v58, vcc
	v_lshlrev_b32_e32 v61, 2, v58
	ds_bpermute_b32 v62, v61, v54
	ds_bpermute_b32 v58, v61, v50
	ds_bpermute_b32 v63, v61, v55
	ds_bpermute_b32 v59, v61, v51
	ds_bpermute_b32 v64, v61, v56
	ds_bpermute_b32 v60, v61, v52
	ds_bpermute_b32 v65, v61, v57
	ds_bpermute_b32 v61, v61, v53
	v_lshl_add_u64 v[68:69], s[98:99], 0, v[0:1]
	v_lshlrev_b32_e32 v0, 2, v160
	v_lshl_add_u64 v[68:69], v[68:69], 0, v[0:1]
	s_mov_b64 s[44:45], 0

; __device__ __forceinline__ void rope_apply(f32x4& v0, f32x4& v1, int kind, int row, int wc, int fq, const float* tabM, const float* tabS) {
;     const int t = row & 2047, gr = t >> 6, gc = t & 63;
;     const float* tb; float sgn; f32x4 p0, p1;
;     if (kind == 1) {
;         const int pos = (fq < 2) ? gr : gc; tb = tabM + pos * 16; sgn = (fq & 1) ? 1.f : -1.f;
; #pragma unroll
;         for (int e = 0; e < 4; ++e) { p0[e] = __shfl_xor(v0[e], 16); p1[e] = __shfl_xor(v1[e], 16); }
;     } else {
;         const int pos = (wc & 1) ? gc : gr; tb = tabS + pos * 32 + (fq & 1) * 16; sgn = (fq & 2) ? 1.f : -1.f;
; #pragma unroll
;         for (int e = 0; e < 4; ++e) { p0[e] = __shfl_xor(v0[e], 32); p1[e] = __shfl_xor(v1[e], 32); }
;     }
;     const f32x4 c0 = *(const f32x4*)(tb), c1 = *(const f32x4*)(tb + 4), c2 = *(const f32x4*)(tb + 8), c3 = *(const f32x4*)(tb + 12);
;     v0[0] = v0[0] * c0[0] + sgn * p0[0] * c0[1]; v0[1] = v0[1] * c0[2] + sgn * p0[1] * c0[3];
;     v0[2] = v0[2] * c1[0] + sgn * p0[2] * c1[1]; v0[3] = v0[3] * c1[2] + sgn * p0[3] * c1[3];
;     v1[0] = v1[0] * c2[0] + sgn * p1[0] * c2[1]; v1[1] = v1[1] * c2[2] + sgn * p1[1] * c2[3];
;     v1[2] = v1[2] * c3[0] + sgn * p1[2] * c3[1]; v1[3] = v1[3] * c3[2] + sgn * p1[3] * c3[3];
;     __device__ __forceinline__ void operator()(const f32x4 (&acc)[2][2][4][2], const Unit& u, int wr_in, int wc_in, int fr_in, int fq_in) const {
;     ...
;             const int col0 = g32 * 32 + 8 * fq;
; #pragma unroll
;             for (int ai = 0; ai < 2; ++ai)
; #pragma unroll
;                 for (int m = 0; m < 4; ++m) {
;                     const int row = u.pm * 256 + ai * 128 + wr * 64 + 4 * fr + m;
;                     f32x4 v0 = acc[ai][bj][m][0], v1 = acc[ai][bj][m][1];
;                     if (rope) rope_apply(v0, v1, rope, row, wc, fq, tabM, tabS);
;                     v0 = v0 * sc; v1 = v1 * sc;
;                     store_bf16x8(Z + (size_t)row * ldz + col0, v0, v1);
;                 }
.LBB0_461:
	global_load_dwordx4 v[70:73], v[68:69], off
	global_load_dwordx4 v[78:81], v[68:69], off offset:16
	global_load_dwordx4 v[128:131], v[68:69], off offset:32
	global_load_dwordx4 v[132:135], v[68:69], off offset:48
	v_cmp_eq_u32_e32 vcc, 0, v0
	v_mov_b32_e32 v68, v57
	v_mov_b32_e32 v84, v53
	v_cndmask_b32_e64 v0, 1.0, -1.0, vcc
	s_waitcnt lgkmcnt(0)
	v_mul_f32_e32 v69, v0, v65
	v_mul_f32_e32 v85, v0, v61
	v_mul_f32_e32 v53, v0, v64
	v_mul_f32_e32 v57, v0, v60
	v_pk_mul_f32 v[62:63], v[0:1], v[62:63] op_sel_hi:[0,1]
	v_pk_mul_f32 v[58:59], v[0:1], v[58:59] op_sel_hi:[0,1]
	s_waitcnt vmcnt(0)
	v_mov_b32_e32 v60, v70
	v_mov_b32_e32 v61, v72
	v_mov_b32_e32 v72, v71
	v_pk_mul_f32 v[68:69], v[68:69], v[80:81]
	v_mov_b32_e32 v70, v128
	v_mov_b32_e32 v71, v130
	v_pk_mul_f32 v[80:81], v[84:85], v[134:135]
	v_mul_f32_e32 v56, v56, v78
	v_mul_f32_e32 v64, v53, v79
	v_mov_b32_e32 v130, v129
	v_mul_f32_e32 v52, v52, v132
	v_mul_f32_e32 v78, v57, v133
	v_pk_mul_f32 v[54:55], v[54:55], v[60:61]
	v_mov_b32_e32 v65, v69
	v_mov_b32_e32 v57, v68
	v_pk_mul_f32 v[50:51], v[50:51], v[70:71]
	v_mov_b32_e32 v79, v81
	v_mov_b32_e32 v53, v80
	v_pk_fma_f32 v[54:55], v[62:63], v[72:73], v[54:55]
	v_pk_add_f32 v[56:57], v[64:65], v[56:57]
	v_pk_fma_f32 v[50:51], v[58:59], v[130:131], v[50:51]
	v_pk_add_f32 v[52:53], v[78:79], v[52:53]
.LBB0_462:
	v_mov_b32_e32 v77, v76
	v_mov_b32_e32 v58, v76
	v_mov_b32_e32 v59, v76
	v_pk_mul_f32 v[56:57], v[58:59], v[56:57]
	v_pk_mul_f32 v[58:59], v[58:59], v[52:53]
	v_pk_mul_f32 v[52:53], v[76:77], v[50:51]
	v_lshl_add_u64 v[60:61], v[66:67], 1, v[122:123]
	s_and_b64 vcc, exec, s[4:5]
	v_pk_mul_f32 v[54:55], v[76:77], v[54:55]
	v_cvt_pk_bf16_f32 v51, v56, v57
	v_cvt_pk_bf16_f32 v52, v52, v53
	v_cvt_pk_bf16_f32 v53, v58, v59
	s_nop 0
	v_cvt_pk_bf16_f32 v50, v54, v55
	global_store_dwordx4 v[60:61], v[50:53], off
	s_cbranch_vccnz .LBB0_468
	v_and_b32_e32 v0, 64, v242
	v_add_u32_e32 v60, 64, v0
	s_and_b64 vcc, exec, s[0:1]
	s_mov_b64 s[44:45], -1
	s_cbranch_vccnz .LBB0_465
	v_xor_b32_e32 v50, 32, v242
	v_cmp_lt_i32_e32 vcc, v50, v60
	v_cndmask_b32_e64 v0, v126, v162, s[42:43]
	v_lshlrev_b32_e32 v0, 7, v0
	v_cndmask_b32_e32 v50, v242, v50, vcc
	v_lshlrev_b32_e32 v53, 2, v50
	ds_bpermute_b32 v54, v53, v46
	ds_bpermute_b32 v50, v53, v42
	ds_bpermute_b32 v55, v53, v47
	ds_bpermute_b32 v51, v53, v43
	ds_bpermute_b32 v56, v53, v48
	ds_bpermute_b32 v52, v53, v44
	ds_bpermute_b32 v57, v53, v49
	ds_bpermute_b32 v53, v53, v45
	v_lshl_add_u64 v[58:59], s[98:99], 0, v[0:1]
	v_lshlrev_b32_e32 v0, 2, v160
	v_lshl_add_u64 v[58:59], v[58:59], 0, v[0:1]
	s_mov_b64 s[44:45], 0

; __device__ __forceinline__ void rope_apply(f32x4& v0, f32x4& v1, int kind, int row, int wc, int fq, const float* tabM, const float* tabS) {
;     const int t = row & 2047, gr = t >> 6, gc = t & 63;
;     const float* tb; float sgn; f32x4 p0, p1;
;     if (kind == 1) {
;         const int pos = (fq < 2) ? gr : gc; tb = tabM + pos * 16; sgn = (fq & 1) ? 1.f : -1.f;
; #pragma unroll
;         for (int e = 0; e < 4; ++e) { p0[e] = __shfl_xor(v0[e], 16); p1[e] = __shfl_xor(v1[e], 16); }
;     } else {
;         const int pos = (wc & 1) ? gc : gr; tb = tabS + pos * 32 + (fq & 1) * 16; sgn = (fq & 2) ? 1.f : -1.f;
; #pragma unroll
;         for (int e = 0; e < 4; ++e) { p0[e] = __shfl_xor(v0[e], 32); p1[e] = __shfl_xor(v1[e], 32); }
;     }
;     const f32x4 c0 = *(const f32x4*)(tb), c1 = *(const f32x4*)(tb + 4), c2 = *(const f32x4*)(tb + 8), c3 = *(const f32x4*)(tb + 12);
;     v0[0] = v0[0] * c0[0] + sgn * p0[0] * c0[1]; v0[1] = v0[1] * c0[2] + sgn * p0[1] * c0[3];
;     v0[2] = v0[2] * c1[0] + sgn * p0[2] * c1[1]; v0[3] = v0[3] * c1[2] + sgn * p0[3] * c1[3];
;     v1[0] = v1[0] * c2[0] + sgn * p1[0] * c2[1]; v1[1] = v1[1] * c2[2] + sgn * p1[1] * c2[3];
;     v1[2] = v1[2] * c3[0] + sgn * p1[2] * c3[1]; v1[3] = v1[3] * c3[2] + sgn * p1[3] * c3[3];
;     __device__ __forceinline__ void operator()(const f32x4 (&acc)[2][2][4][2], const Unit& u, int wr_in, int wc_in, int fr_in, int fq_in) const {
;     ...
;             const int col0 = g32 * 32 + 8 * fq;
; #pragma unroll
;             for (int ai = 0; ai < 2; ++ai)
; #pragma unroll
;                 for (int m = 0; m < 4; ++m) {
;                     const int row = u.pm * 256 + ai * 128 + wr * 64 + 4 * fr + m;
;                     f32x4 v0 = acc[ai][bj][m][0], v1 = acc[ai][bj][m][1];
;                     if (rope) rope_apply(v0, v1, rope, row, wc, fq, tabM, tabS);
;                     v0 = v0 * sc; v1 = v1 * sc;
;                     store_bf16x8(Z + (size_t)row * ldz + col0, v0, v1);
;                 }
.LBB0_467:
	global_load_dwordx4 v[60:63], v[58:59], off
	global_load_dwordx4 v[68:71], v[58:59], off offset:16
	global_load_dwordx4 v[78:81], v[58:59], off offset:32
	global_load_dwordx4 v[120:123], v[58:59], off offset:48
	v_cmp_eq_u32_e32 vcc, 0, v0
	v_mov_b32_e32 v58, v49
	v_mov_b32_e32 v64, v45
	v_cndmask_b32_e64 v0, 1.0, -1.0, vcc
	s_waitcnt lgkmcnt(0)
	v_mul_f32_e32 v59, v0, v57
	v_mul_f32_e32 v65, v0, v53
	v_mul_f32_e32 v45, v0, v56
	v_mul_f32_e32 v49, v0, v52
	v_pk_mul_f32 v[54:55], v[0:1], v[54:55] op_sel_hi:[0,1]
	v_pk_mul_f32 v[50:51], v[0:1], v[50:51] op_sel_hi:[0,1]
	s_waitcnt vmcnt(0)
	v_mov_b32_e32 v52, v60
	v_mov_b32_e32 v53, v62
	v_mov_b32_e32 v62, v61
	v_pk_mul_f32 v[58:59], v[58:59], v[70:71]
	v_mov_b32_e32 v60, v78
	v_mov_b32_e32 v61, v80
	v_pk_mul_f32 v[64:65], v[64:65], v[122:123]
	v_mul_f32_e32 v48, v48, v68
	v_mul_f32_e32 v56, v45, v69
	v_mov_b32_e32 v80, v79
	v_mul_f32_e32 v44, v44, v120
	v_mul_f32_e32 v68, v49, v121
	v_pk_mul_f32 v[46:47], v[46:47], v[52:53]
	v_mov_b32_e32 v57, v59
	v_mov_b32_e32 v49, v58
	v_pk_mul_f32 v[42:43], v[42:43], v[60:61]
	v_mov_b32_e32 v69, v65
	v_mov_b32_e32 v45, v64
	v_pk_fma_f32 v[46:47], v[54:55], v[62:63], v[46:47]
	v_pk_add_f32 v[48:49], v[56:57], v[48:49]
	v_pk_fma_f32 v[42:43], v[50:51], v[80:81], v[42:43]
	v_pk_add_f32 v[44:45], v[68:69], v[44:45]
.LBB0_468:
	s_nop 0
	v_mov_b32_e32 v50, v76
	v_mov_b32_e32 v51, v76
	v_pk_mul_f32 v[48:49], v[50:51], v[48:49]
	v_pk_mul_f32 v[50:51], v[50:51], v[44:45]
	v_pk_mul_f32 v[44:45], v[76:77], v[42:43]
	v_lshl_add_u64 v[52:53], v[66:67], 1, v[114:115]
	s_and_b64 vcc, exec, s[4:5]
	v_pk_mul_f32 v[46:47], v[76:77], v[46:47]
	v_cvt_pk_bf16_f32 v43, v48, v49
	v_cvt_pk_bf16_f32 v44, v44, v45
	v_cvt_pk_bf16_f32 v45, v50, v51
	s_nop 0
	v_cvt_pk_bf16_f32 v42, v46, v47
	global_store_dwordx4 v[52:53], v[42:45], off
	s_cbranch_vccnz .LBB0_474
	v_and_b32_e32 v0, 64, v242
	v_add_u32_e32 v52, 64, v0
	s_and_b64 vcc, exec, s[0:1]
	s_mov_b64 s[44:45], -1
	s_cbranch_vccnz .LBB0_471
	v_xor_b32_e32 v42, 32, v242
	v_cmp_lt_i32_e32 vcc, v42, v52
	v_cndmask_b32_e64 v0, v118, v162, s[42:43]
	v_lshlrev_b32_e32 v0, 7, v0
	v_cndmask_b32_e32 v42, v242, v42, vcc
	v_lshlrev_b32_e32 v45, 2, v42
	ds_bpermute_b32 v46, v45, v38
	ds_bpermute_b32 v42, v45, v34
	ds_bpermute_b32 v47, v45, v39
	ds_bpermute_b32 v43, v45, v35
	ds_bpermute_b32 v48, v45, v40
	ds_bpermute_b32 v44, v45, v36
	ds_bpermute_b32 v49, v45, v41
	ds_bpermute_b32 v45, v45, v37
	v_lshl_add_u64 v[50:51], s[98:99], 0, v[0:1]
	v_lshlrev_b32_e32 v0, 2, v160
	v_lshl_add_u64 v[50:51], v[50:51], 0, v[0:1]
	s_mov_b64 s[44:45], 0

; __device__ __forceinline__ void rope_apply(f32x4& v0, f32x4& v1, int kind, int row, int wc, int fq, const float* tabM, const float* tabS) {
;     const int t = row & 2047, gr = t >> 6, gc = t & 63;
;     const float* tb; float sgn; f32x4 p0, p1;
;     if (kind == 1) {
;         const int pos = (fq < 2) ? gr : gc; tb = tabM + pos * 16; sgn = (fq & 1) ? 1.f : -1.f;
; #pragma unroll
;         for (int e = 0; e < 4; ++e) { p0[e] = __shfl_xor(v0[e], 16); p1[e] = __shfl_xor(v1[e], 16); }
;     } else {
;         const int pos = (wc & 1) ? gc : gr; tb = tabS + pos * 32 + (fq & 1) * 16; sgn = (fq & 2) ? 1.f : -1.f;
; #pragma unroll
;         for (int e = 0; e < 4; ++e) { p0[e] = __shfl_xor(v0[e], 32); p1[e] = __shfl_xor(v1[e], 32); }
;     }
;     const f32x4 c0 = *(const f32x4*)(tb), c1 = *(const f32x4*)(tb + 4), c2 = *(const f32x4*)(tb + 8), c3 = *(const f32x4*)(tb + 12);
;     v0[0] = v0[0] * c0[0] + sgn * p0[0] * c0[1]; v0[1] = v0[1] * c0[2] + sgn * p0[1] * c0[3];
;     v0[2] = v0[2] * c1[0] + sgn * p0[2] * c1[1]; v0[3] = v0[3] * c1[2] + sgn * p0[3] * c1[3];
;     v1[0] = v1[0] * c2[0] + sgn * p1[0] * c2[1]; v1[1] = v1[1] * c2[2] + sgn * p1[1] * c2[3];
;     v1[2] = v1[2] * c3[0] + sgn * p1[2] * c3[1]; v1[3] = v1[3] * c3[2] + sgn * p1[3] * c3[3];
;     __device__ __forceinline__ void operator()(const f32x4 (&acc)[2][2][4][2], const Unit& u, int wr_in, int wc_in, int fr_in, int fq_in) const {
;     ...
;             const int col0 = g32 * 32 + 8 * fq;
; #pragma unroll
;             for (int ai = 0; ai < 2; ++ai)
; #pragma unroll
;                 for (int m = 0; m < 4; ++m) {
;                     const int row = u.pm * 256 + ai * 128 + wr * 64 + 4 * fr + m;
;                     f32x4 v0 = acc[ai][bj][m][0], v1 = acc[ai][bj][m][1];
;                     if (rope) rope_apply(v0, v1, rope, row, wc, fq, tabM, tabS);
;                     v0 = v0 * sc; v1 = v1 * sc;
;                     store_bf16x8(Z + (size_t)row * ldz + col0, v0, v1);
;                 }
.LBB0_473:
	global_load_dwordx4 v[52:55], v[50:51], off
	global_load_dwordx4 v[56:59], v[50:51], off offset:16
	global_load_dwordx4 v[60:63], v[50:51], off offset:32
	global_load_dwordx4 v[68:71], v[50:51], off offset:48
	v_cmp_eq_u32_e32 vcc, 0, v0
	v_mov_b32_e32 v50, v41
	v_mov_b32_e32 v64, v37
	v_cndmask_b32_e64 v0, 1.0, -1.0, vcc
	s_waitcnt lgkmcnt(0)
	v_mul_f32_e32 v51, v0, v49
	v_mul_f32_e32 v65, v0, v45
	v_mul_f32_e32 v37, v0, v48
	v_mul_f32_e32 v41, v0, v44
	v_pk_mul_f32 v[46:47], v[0:1], v[46:47] op_sel_hi:[0,1]
	v_pk_mul_f32 v[42:43], v[0:1], v[42:43] op_sel_hi:[0,1]
	s_waitcnt vmcnt(0)
	v_mov_b32_e32 v44, v52
	v_mov_b32_e32 v45, v54
	v_mov_b32_e32 v54, v53
	v_pk_mul_f32 v[50:51], v[50:51], v[58:59]
	v_mov_b32_e32 v52, v60
	v_mov_b32_e32 v53, v62
	v_pk_mul_f32 v[58:59], v[64:65], v[70:71]
	v_mul_f32_e32 v40, v40, v56
	v_mul_f32_e32 v48, v37, v57
	v_mov_b32_e32 v62, v61
	v_mul_f32_e32 v36, v36, v68
	v_mul_f32_e32 v56, v41, v69
	v_pk_mul_f32 v[38:39], v[38:39], v[44:45]
	v_mov_b32_e32 v49, v51
	v_mov_b32_e32 v41, v50
	v_pk_mul_f32 v[34:35], v[34:35], v[52:53]
	v_mov_b32_e32 v57, v59
	v_mov_b32_e32 v37, v58
	v_pk_fma_f32 v[38:39], v[46:47], v[54:55], v[38:39]
	v_pk_add_f32 v[40:41], v[48:49], v[40:41]
	v_pk_fma_f32 v[34:35], v[42:43], v[62:63], v[34:35]
	v_pk_add_f32 v[36:37], v[56:57], v[36:37]
.LBB0_474:
	s_nop 0
	v_mov_b32_e32 v42, v76
	v_mov_b32_e32 v43, v76
	v_pk_mul_f32 v[40:41], v[42:43], v[40:41]
	v_pk_mul_f32 v[42:43], v[42:43], v[36:37]
	v_pk_mul_f32 v[36:37], v[76:77], v[34:35]
	v_lshl_add_u64 v[44:45], v[66:67], 1, v[106:107]
	s_and_b64 vcc, exec, s[4:5]
	v_pk_mul_f32 v[38:39], v[76:77], v[38:39]
	v_cvt_pk_bf16_f32 v35, v40, v41
	v_cvt_pk_bf16_f32 v36, v36, v37
	v_cvt_pk_bf16_f32 v37, v42, v43
	s_nop 0
	v_cvt_pk_bf16_f32 v34, v38, v39
	global_store_dwordx4 v[44:45], v[34:37], off
	s_cbranch_vccnz .LBB0_480
	v_and_b32_e32 v0, 64, v242
	v_add_u32_e32 v44, 64, v0
	s_and_b64 vcc, exec, s[0:1]
	s_mov_b64 s[44:45], -1
	s_cbranch_vccnz .LBB0_477
	v_xor_b32_e32 v34, 32, v242
	v_cmp_lt_i32_e32 vcc, v34, v44
	v_cndmask_b32_e64 v0, v161, v110, s[42:43]
	v_lshlrev_b32_e32 v0, 7, v0
	v_cndmask_b32_e32 v34, v242, v34, vcc
	v_lshlrev_b32_e32 v37, 2, v34
	ds_bpermute_b32 v38, v37, v30
	ds_bpermute_b32 v34, v37, v26
	ds_bpermute_b32 v39, v37, v31
	ds_bpermute_b32 v35, v37, v27
	ds_bpermute_b32 v40, v37, v32
	ds_bpermute_b32 v36, v37, v28
	ds_bpermute_b32 v41, v37, v33
	ds_bpermute_b32 v37, v37, v29
	v_lshl_add_u64 v[42:43], s[98:99], 0, v[0:1]
	v_lshlrev_b32_e32 v0, 2, v160
	v_lshl_add_u64 v[42:43], v[42:43], 0, v[0:1]
	s_mov_b64 s[44:45], 0

; __device__ __forceinline__ void rope_apply(f32x4& v0, f32x4& v1, int kind, int row, int wc, int fq, const float* tabM, const float* tabS) {
;     const int t = row & 2047, gr = t >> 6, gc = t & 63;
;     const float* tb; float sgn; f32x4 p0, p1;
;     if (kind == 1) {
;         const int pos = (fq < 2) ? gr : gc; tb = tabM + pos * 16; sgn = (fq & 1) ? 1.f : -1.f;
; #pragma unroll
;         for (int e = 0; e < 4; ++e) { p0[e] = __shfl_xor(v0[e], 16); p1[e] = __shfl_xor(v1[e], 16); }
;     } else {
;         const int pos = (wc & 1) ? gc : gr; tb = tabS + pos * 32 + (fq & 1) * 16; sgn = (fq & 2) ? 1.f : -1.f;
; #pragma unroll
;         for (int e = 0; e < 4; ++e) { p0[e] = __shfl_xor(v0[e], 32); p1[e] = __shfl_xor(v1[e], 32); }
;     }
;     const f32x4 c0 = *(const f32x4*)(tb), c1 = *(const f32x4*)(tb + 4), c2 = *(const f32x4*)(tb + 8), c3 = *(const f32x4*)(tb + 12);
;     v0[0] = v0[0] * c0[0] + sgn * p0[0] * c0[1]; v0[1] = v0[1] * c0[2] + sgn * p0[1] * c0[3];
;     v0[2] = v0[2] * c1[0] + sgn * p0[2] * c1[1]; v0[3] = v0[3] * c1[2] + sgn * p0[3] * c1[3];
;     v1[0] = v1[0] * c2[0] + sgn * p1[0] * c2[1]; v1[1] = v1[1] * c2[2] + sgn * p1[1] * c2[3];
;     v1[2] = v1[2] * c3[0] + sgn * p1[2] * c3[1]; v1[3] = v1[3] * c3[2] + sgn * p1[3] * c3[3];
;     __device__ __forceinline__ void operator()(const f32x4 (&acc)[2][2][4][2], const Unit& u, int wr_in, int wc_in, int fr_in, int fq_in) const {
;     ...
;             const int col0 = g32 * 32 + 8 * fq;
; #pragma unroll
;             for (int ai = 0; ai < 2; ++ai)
; #pragma unroll
;                 for (int m = 0; m < 4; ++m) {
;                     const int row = u.pm * 256 + ai * 128 + wr * 64 + 4 * fr + m;
;                     f32x4 v0 = acc[ai][bj][m][0], v1 = acc[ai][bj][m][1];
;                     if (rope) rope_apply(v0, v1, rope, row, wc, fq, tabM, tabS);
;                     v0 = v0 * sc; v1 = v1 * sc;
;                     store_bf16x8(Z + (size_t)row * ldz + col0, v0, v1);
;                 }
.LBB0_479:
	global_load_dwordx4 v[44:47], v[42:43], off
	global_load_dwordx4 v[48:51], v[42:43], off offset:16
	global_load_dwordx4 v[52:55], v[42:43], off offset:32
	global_load_dwordx4 v[56:59], v[42:43], off offset:48
	v_cmp_eq_u32_e32 vcc, 0, v0
	v_mov_b32_e32 v42, v33
	v_mov_b32_e32 v60, v29
	v_cndmask_b32_e64 v0, 1.0, -1.0, vcc
	s_waitcnt lgkmcnt(0)
	v_mul_f32_e32 v43, v0, v41
	v_mul_f32_e32 v61, v0, v37
	v_mul_f32_e32 v29, v0, v40
	v_mul_f32_e32 v33, v0, v36
	v_pk_mul_f32 v[38:39], v[0:1], v[38:39] op_sel_hi:[0,1]
	v_pk_mul_f32 v[34:35], v[0:1], v[34:35] op_sel_hi:[0,1]
	s_waitcnt vmcnt(0)
	v_mov_b32_e32 v36, v44
	v_mov_b32_e32 v37, v46
	v_mov_b32_e32 v46, v45
	v_pk_mul_f32 v[42:43], v[42:43], v[50:51]
	v_mov_b32_e32 v44, v52
	v_mov_b32_e32 v45, v54
	v_pk_mul_f32 v[50:51], v[60:61], v[58:59]
	v_mul_f32_e32 v32, v32, v48
	v_mul_f32_e32 v40, v29, v49
	v_mov_b32_e32 v54, v53
	v_mul_f32_e32 v28, v28, v56
	v_mul_f32_e32 v48, v33, v57
	v_pk_mul_f32 v[30:31], v[30:31], v[36:37]
	v_mov_b32_e32 v41, v43
	v_mov_b32_e32 v33, v42
	v_pk_mul_f32 v[26:27], v[26:27], v[44:45]
	v_mov_b32_e32 v49, v51
	v_mov_b32_e32 v29, v50
	v_pk_fma_f32 v[30:31], v[38:39], v[46:47], v[30:31]
	v_pk_add_f32 v[32:33], v[40:41], v[32:33]
	v_pk_fma_f32 v[26:27], v[34:35], v[54:55], v[26:27]
	v_pk_add_f32 v[28:29], v[48:49], v[28:29]
.LBB0_480:
	s_nop 0
	v_mov_b32_e32 v34, v76
	v_mov_b32_e32 v35, v76
	v_pk_mul_f32 v[32:33], v[34:35], v[32:33]
	v_pk_mul_f32 v[34:35], v[34:35], v[28:29]
	v_pk_mul_f32 v[28:29], v[76:77], v[26:27]
	v_lshl_add_u64 v[36:37], v[66:67], 1, v[98:99]
	s_and_b64 vcc, exec, s[4:5]
	v_pk_mul_f32 v[30:31], v[76:77], v[30:31]
	v_cvt_pk_bf16_f32 v27, v32, v33
	v_cvt_pk_bf16_f32 v28, v28, v29
	v_cvt_pk_bf16_f32 v29, v34, v35
	s_nop 0
	v_cvt_pk_bf16_f32 v26, v30, v31
	global_store_dwordx4 v[36:37], v[26:29], off
	s_cbranch_vccnz .LBB0_486
	v_and_b32_e32 v0, 64, v242
	v_add_u32_e32 v36, 64, v0
	s_and_b64 vcc, exec, s[0:1]
	s_mov_b64 s[44:45], -1
	s_cbranch_vccnz .LBB0_483
	v_xor_b32_e32 v26, 32, v242
	v_cmp_lt_i32_e32 vcc, v26, v36
	v_cndmask_b32_e64 v0, v102, v110, s[42:43]
	v_lshlrev_b32_e32 v0, 7, v0
	v_cndmask_b32_e32 v26, v242, v26, vcc
	v_lshlrev_b32_e32 v29, 2, v26
	ds_bpermute_b32 v30, v29, v22
	ds_bpermute_b32 v26, v29, v18
	ds_bpermute_b32 v31, v29, v23
	ds_bpermute_b32 v27, v29, v19
	ds_bpermute_b32 v32, v29, v24
	ds_bpermute_b32 v28, v29, v20
	ds_bpermute_b32 v33, v29, v25
	ds_bpermute_b32 v29, v29, v21
	v_lshl_add_u64 v[34:35], s[98:99], 0, v[0:1]
	v_lshlrev_b32_e32 v0, 2, v160
	v_lshl_add_u64 v[34:35], v[34:35], 0, v[0:1]
	s_mov_b64 s[44:45], 0

; __device__ __forceinline__ void rope_apply(f32x4& v0, f32x4& v1, int kind, int row, int wc, int fq, const float* tabM, const float* tabS) {
;     const int t = row & 2047, gr = t >> 6, gc = t & 63;
;     const float* tb; float sgn; f32x4 p0, p1;
;     if (kind == 1) {
;         const int pos = (fq < 2) ? gr : gc; tb = tabM + pos * 16; sgn = (fq & 1) ? 1.f : -1.f;
; #pragma unroll
;         for (int e = 0; e < 4; ++e) { p0[e] = __shfl_xor(v0[e], 16); p1[e] = __shfl_xor(v1[e], 16); }
;     } else {
;         const int pos = (wc & 1) ? gc : gr; tb = tabS + pos * 32 + (fq & 1) * 16; sgn = (fq & 2) ? 1.f : -1.f;
; #pragma unroll
;         for (int e = 0; e < 4; ++e) { p0[e] = __shfl_xor(v0[e], 32); p1[e] = __shfl_xor(v1[e], 32); }
;     }
;     const f32x4 c0 = *(const f32x4*)(tb), c1 = *(const f32x4*)(tb + 4), c2 = *(const f32x4*)(tb + 8), c3 = *(const f32x4*)(tb + 12);
;     v0[0] = v0[0] * c0[0] + sgn * p0[0] * c0[1]; v0[1] = v0[1] * c0[2] + sgn * p0[1] * c0[3];
;     v0[2] = v0[2] * c1[0] + sgn * p0[2] * c1[1]; v0[3] = v0[3] * c1[2] + sgn * p0[3] * c1[3];
;     v1[0] = v1[0] * c2[0] + sgn * p1[0] * c2[1]; v1[1] = v1[1] * c2[2] + sgn * p1[1] * c2[3];
;     v1[2] = v1[2] * c3[0] + sgn * p1[2] * c3[1]; v1[3] = v1[3] * c3[2] + sgn * p1[3] * c3[3];
;     __device__ __forceinline__ void operator()(const f32x4 (&acc)[2][2][4][2], const Unit& u, int wr_in, int wc_in, int fr_in, int fq_in) const {
;     ...
;             const int col0 = g32 * 32 + 8 * fq;
; #pragma unroll
;             for (int ai = 0; ai < 2; ++ai)
; #pragma unroll
;                 for (int m = 0; m < 4; ++m) {
;                     const int row = u.pm * 256 + ai * 128 + wr * 64 + 4 * fr + m;
;                     f32x4 v0 = acc[ai][bj][m][0], v1 = acc[ai][bj][m][1];
;                     if (rope) rope_apply(v0, v1, rope, row, wc, fq, tabM, tabS);
;                     v0 = v0 * sc; v1 = v1 * sc;
;                     store_bf16x8(Z + (size_t)row * ldz + col0, v0, v1);
;                 }
.LBB0_485:
	global_load_dwordx4 v[36:39], v[34:35], off
	global_load_dwordx4 v[40:43], v[34:35], off offset:16
	global_load_dwordx4 v[44:47], v[34:35], off offset:32
	global_load_dwordx4 v[48:51], v[34:35], off offset:48
	v_cmp_eq_u32_e32 vcc, 0, v0
	v_mov_b32_e32 v34, v25
	v_mov_b32_e32 v52, v21
	v_cndmask_b32_e64 v0, 1.0, -1.0, vcc
	s_waitcnt lgkmcnt(0)
	v_mul_f32_e32 v35, v0, v33
	v_mul_f32_e32 v53, v0, v29
	v_mul_f32_e32 v21, v0, v32
	v_mul_f32_e32 v25, v0, v28
	v_pk_mul_f32 v[30:31], v[0:1], v[30:31] op_sel_hi:[0,1]
	v_pk_mul_f32 v[26:27], v[0:1], v[26:27] op_sel_hi:[0,1]
	s_waitcnt vmcnt(0)
	v_mov_b32_e32 v28, v36
	v_mov_b32_e32 v29, v38
	v_mov_b32_e32 v38, v37
	v_pk_mul_f32 v[34:35], v[34:35], v[42:43]
	v_mov_b32_e32 v36, v44
	v_mov_b32_e32 v37, v46
	v_pk_mul_f32 v[42:43], v[52:53], v[50:51]
	v_mul_f32_e32 v24, v24, v40
	v_mul_f32_e32 v32, v21, v41
	v_mov_b32_e32 v46, v45
	v_mul_f32_e32 v20, v20, v48
	v_mul_f32_e32 v40, v25, v49
	v_pk_mul_f32 v[22:23], v[22:23], v[28:29]
	v_mov_b32_e32 v33, v35
	v_mov_b32_e32 v25, v34
	v_pk_mul_f32 v[18:19], v[18:19], v[36:37]
	v_mov_b32_e32 v41, v43
	v_mov_b32_e32 v21, v42
	v_pk_fma_f32 v[22:23], v[30:31], v[38:39], v[22:23]
	v_pk_add_f32 v[24:25], v[32:33], v[24:25]
	v_pk_fma_f32 v[18:19], v[26:27], v[46:47], v[18:19]
	v_pk_add_f32 v[20:21], v[40:41], v[20:21]
.LBB0_486:
	s_nop 0
	v_mov_b32_e32 v26, v76
	v_mov_b32_e32 v27, v76
	v_pk_mul_f32 v[24:25], v[26:27], v[24:25]
	v_pk_mul_f32 v[26:27], v[26:27], v[20:21]
	v_pk_mul_f32 v[20:21], v[76:77], v[18:19]
	v_lshl_add_u64 v[28:29], v[66:67], 1, v[90:91]
	s_and_b64 vcc, exec, s[4:5]
	v_pk_mul_f32 v[22:23], v[76:77], v[22:23]
	v_cvt_pk_bf16_f32 v19, v24, v25
	v_cvt_pk_bf16_f32 v20, v20, v21
	v_cvt_pk_bf16_f32 v21, v26, v27
	s_nop 0
	v_cvt_pk_bf16_f32 v18, v22, v23
	global_store_dwordx4 v[28:29], v[18:21], off
	s_cbranch_vccnz .LBB0_492
	v_and_b32_e32 v0, 64, v242
	v_add_u32_e32 v28, 64, v0
	s_and_b64 vcc, exec, s[0:1]
	s_mov_b64 s[44:45], -1
	s_cbranch_vccnz .LBB0_489
	v_xor_b32_e32 v18, 32, v242
	v_cmp_lt_i32_e32 vcc, v18, v28
	v_cndmask_b32_e64 v0, v94, v110, s[42:43]
	v_lshlrev_b32_e32 v0, 7, v0
	v_cndmask_b32_e32 v18, v242, v18, vcc
	v_lshlrev_b32_e32 v21, 2, v18
	ds_bpermute_b32 v22, v21, v14
	ds_bpermute_b32 v18, v21, v10
	ds_bpermute_b32 v23, v21, v15
	ds_bpermute_b32 v19, v21, v11
	ds_bpermute_b32 v24, v21, v16
	ds_bpermute_b32 v20, v21, v12
	ds_bpermute_b32 v25, v21, v17
	ds_bpermute_b32 v21, v21, v13
	v_lshl_add_u64 v[26:27], s[98:99], 0, v[0:1]
	v_lshlrev_b32_e32 v0, 2, v160
	v_lshl_add_u64 v[26:27], v[26:27], 0, v[0:1]
	s_mov_b64 s[44:45], 0

; __device__ __forceinline__ void rope_apply(f32x4& v0, f32x4& v1, int kind, int row, int wc, int fq, const float* tabM, const float* tabS) {
;     const int t = row & 2047, gr = t >> 6, gc = t & 63;
;     const float* tb; float sgn; f32x4 p0, p1;
;     if (kind == 1) {
;         const int pos = (fq < 2) ? gr : gc; tb = tabM + pos * 16; sgn = (fq & 1) ? 1.f : -1.f;
; #pragma unroll
;         for (int e = 0; e < 4; ++e) { p0[e] = __shfl_xor(v0[e], 16); p1[e] = __shfl_xor(v1[e], 16); }
;     } else {
;         const int pos = (wc & 1) ? gc : gr; tb = tabS + pos * 32 + (fq & 1) * 16; sgn = (fq & 2) ? 1.f : -1.f;
; #pragma unroll
;         for (int e = 0; e < 4; ++e) { p0[e] = __shfl_xor(v0[e], 32); p1[e] = __shfl_xor(v1[e], 32); }
;     }
;     const f32x4 c0 = *(const f32x4*)(tb), c1 = *(const f32x4*)(tb + 4), c2 = *(const f32x4*)(tb + 8), c3 = *(const f32x4*)(tb + 12);
;     v0[0] = v0[0] * c0[0] + sgn * p0[0] * c0[1]; v0[1] = v0[1] * c0[2] + sgn * p0[1] * c0[3];
;     v0[2] = v0[2] * c1[0] + sgn * p0[2] * c1[1]; v0[3] = v0[3] * c1[2] + sgn * p0[3] * c1[3];
;     v1[0] = v1[0] * c2[0] + sgn * p1[0] * c2[1]; v1[1] = v1[1] * c2[2] + sgn * p1[1] * c2[3];
;     v1[2] = v1[2] * c3[0] + sgn * p1[2] * c3[1]; v1[3] = v1[3] * c3[2] + sgn * p1[3] * c3[3];
;     __device__ __forceinline__ void operator()(const f32x4 (&acc)[2][2][4][2], const Unit& u, int wr_in, int wc_in, int fr_in, int fq_in) const {
;     ...
;             const int col0 = g32 * 32 + 8 * fq;
; #pragma unroll
;             for (int ai = 0; ai < 2; ++ai)
; #pragma unroll
;                 for (int m = 0; m < 4; ++m) {
;                     const int row = u.pm * 256 + ai * 128 + wr * 64 + 4 * fr + m;
;                     f32x4 v0 = acc[ai][bj][m][0], v1 = acc[ai][bj][m][1];
;                     if (rope) rope_apply(v0, v1, rope, row, wc, fq, tabM, tabS);
;                     v0 = v0 * sc; v1 = v1 * sc;
;                     store_bf16x8(Z + (size_t)row * ldz + col0, v0, v1);
;                 }
.LBB0_491:
	global_load_dwordx4 v[28:31], v[26:27], off
	global_load_dwordx4 v[32:35], v[26:27], off offset:16
	global_load_dwordx4 v[36:39], v[26:27], off offset:32
	global_load_dwordx4 v[40:43], v[26:27], off offset:48
	v_cmp_eq_u32_e32 vcc, 0, v0
	v_mov_b32_e32 v26, v17
	v_mov_b32_e32 v44, v13
	v_cndmask_b32_e64 v0, 1.0, -1.0, vcc
	s_waitcnt lgkmcnt(0)
	v_mul_f32_e32 v27, v0, v25
	v_mul_f32_e32 v45, v0, v21
	v_mul_f32_e32 v13, v0, v24
	v_mul_f32_e32 v17, v0, v20
	v_pk_mul_f32 v[22:23], v[0:1], v[22:23] op_sel_hi:[0,1]
	v_pk_mul_f32 v[18:19], v[0:1], v[18:19] op_sel_hi:[0,1]
	s_waitcnt vmcnt(0)
	v_mov_b32_e32 v20, v28
	v_mov_b32_e32 v21, v30
	v_mov_b32_e32 v30, v29
	v_pk_mul_f32 v[26:27], v[26:27], v[34:35]
	v_mov_b32_e32 v28, v36
	v_mov_b32_e32 v29, v38
	v_pk_mul_f32 v[34:35], v[44:45], v[42:43]
	v_mul_f32_e32 v16, v16, v32
	v_mul_f32_e32 v24, v13, v33
	v_mov_b32_e32 v38, v37
	v_mul_f32_e32 v12, v12, v40
	v_mul_f32_e32 v32, v17, v41
	v_pk_mul_f32 v[14:15], v[14:15], v[20:21]
	v_mov_b32_e32 v25, v27
	v_mov_b32_e32 v17, v26
	v_pk_mul_f32 v[10:11], v[10:11], v[28:29]
	v_mov_b32_e32 v33, v35
	v_mov_b32_e32 v13, v34
	v_pk_fma_f32 v[14:15], v[22:23], v[30:31], v[14:15]
	v_pk_add_f32 v[16:17], v[24:25], v[16:17]
	v_pk_fma_f32 v[10:11], v[18:19], v[38:39], v[10:11]
	v_pk_add_f32 v[12:13], v[32:33], v[12:13]
.LBB0_492:
	s_nop 0
	v_mov_b32_e32 v18, v76
	v_mov_b32_e32 v19, v76
	v_pk_mul_f32 v[16:17], v[18:19], v[16:17]
	v_pk_mul_f32 v[18:19], v[18:19], v[12:13]
	v_pk_mul_f32 v[12:13], v[76:77], v[10:11]
	v_lshl_add_u64 v[20:21], v[66:67], 1, v[82:83]
	s_and_b64 vcc, exec, s[4:5]
	v_pk_mul_f32 v[14:15], v[76:77], v[14:15]
	v_cvt_pk_bf16_f32 v11, v16, v17
	v_cvt_pk_bf16_f32 v12, v12, v13
	v_cvt_pk_bf16_f32 v13, v18, v19
	s_nop 0
	v_cvt_pk_bf16_f32 v10, v14, v15
	global_store_dwordx4 v[20:21], v[10:13], off
	s_cbranch_vccnz .LBB0_498
	v_and_b32_e32 v0, 64, v242
	v_add_u32_e32 v20, 64, v0
	s_and_b64 vcc, exec, s[0:1]
	s_mov_b64 s[0:1], -1
	s_cbranch_vccnz .LBB0_495
	v_xor_b32_e32 v10, 32, v242
	v_cmp_lt_i32_e32 vcc, v10, v20
	v_cndmask_b32_e64 v0, v86, v110, s[42:43]
	v_lshlrev_b32_e32 v0, 7, v0
	v_cndmask_b32_e32 v10, v242, v10, vcc
	v_lshlrev_b32_e32 v13, 2, v10
	ds_bpermute_b32 v14, v13, v6
	ds_bpermute_b32 v10, v13, v2
	ds_bpermute_b32 v15, v13, v7
	ds_bpermute_b32 v11, v13, v3
	ds_bpermute_b32 v16, v13, v8
	ds_bpermute_b32 v12, v13, v4
	ds_bpermute_b32 v17, v13, v9
	ds_bpermute_b32 v13, v13, v5
	v_lshl_add_u64 v[18:19], s[98:99], 0, v[0:1]
	v_lshlrev_b32_e32 v0, 2, v160
	v_lshl_add_u64 v[18:19], v[18:19], 0, v[0:1]
	s_mov_b64 s[0:1], 0

; __device__ __forceinline__ void rope_apply(f32x4& v0, f32x4& v1, int kind, int row, int wc, int fq, const float* tabM, const float* tabS) {
;     const int t = row & 2047, gr = t >> 6, gc = t & 63;
;     const float* tb; float sgn; f32x4 p0, p1;
;     if (kind == 1) {
;         const int pos = (fq < 2) ? gr : gc; tb = tabM + pos * 16; sgn = (fq & 1) ? 1.f : -1.f;
; #pragma unroll
;         for (int e = 0; e < 4; ++e) { p0[e] = __shfl_xor(v0[e], 16); p1[e] = __shfl_xor(v1[e], 16); }
;     } else {
;         const int pos = (wc & 1) ? gc : gr; tb = tabS + pos * 32 + (fq & 1) * 16; sgn = (fq & 2) ? 1.f : -1.f;
; #pragma unroll
;         for (int e = 0; e < 4; ++e) { p0[e] = __shfl_xor(v0[e], 32); p1[e] = __shfl_xor(v1[e], 32); }
;     }
;     const f32x4 c0 = *(const f32x4*)(tb), c1 = *(const f32x4*)(tb + 4), c2 = *(const f32x4*)(tb + 8), c3 = *(const f32x4*)(tb + 12);
;     v0[0] = v0[0] * c0[0] + sgn * p0[0] * c0[1]; v0[1] = v0[1] * c0[2] + sgn * p0[1] * c0[3];
;     v0[2] = v0[2] * c1[0] + sgn * p0[2] * c1[1]; v0[3] = v0[3] * c1[2] + sgn * p0[3] * c1[3];
;     v1[0] = v1[0] * c2[0] + sgn * p1[0] * c2[1]; v1[1] = v1[1] * c2[2] + sgn * p1[1] * c2[3];
;     v1[2] = v1[2] * c3[0] + sgn * p1[2] * c3[1]; v1[3] = v1[3] * c3[2] + sgn * p1[3] * c3[3];
;     __device__ __forceinline__ void operator()(const f32x4 (&acc)[2][2][4][2], const Unit& u, int wr_in, int wc_in, int fr_in, int fq_in) const {
;     ...
;             const int col0 = g32 * 32 + 8 * fq;
; #pragma unroll
;             for (int ai = 0; ai < 2; ++ai)
; #pragma unroll
;                 for (int m = 0; m < 4; ++m) {
;                     const int row = u.pm * 256 + ai * 128 + wr * 64 + 4 * fr + m;
;                     f32x4 v0 = acc[ai][bj][m][0], v1 = acc[ai][bj][m][1];
;                     if (rope) rope_apply(v0, v1, rope, row, wc, fq, tabM, tabS);
;                     v0 = v0 * sc; v1 = v1 * sc;
;                     store_bf16x8(Z + (size_t)row * ldz + col0, v0, v1);
;                 }
.LBB0_497:
	global_load_dwordx4 v[20:23], v[18:19], off
	global_load_dwordx4 v[24:27], v[18:19], off offset:16
	global_load_dwordx4 v[28:31], v[18:19], off offset:32
	global_load_dwordx4 v[32:35], v[18:19], off offset:48
	v_cmp_eq_u32_e32 vcc, 0, v159
	v_mov_b32_e32 v18, v9
	v_mov_b32_e32 v36, v5
	v_cndmask_b32_e64 v0, 1.0, -1.0, vcc
	s_waitcnt lgkmcnt(0)
	v_mul_f32_e32 v19, v0, v17
	v_mul_f32_e32 v37, v0, v13
	v_mul_f32_e32 v5, v0, v16
	v_mul_f32_e32 v9, v0, v12
	v_pk_mul_f32 v[14:15], v[0:1], v[14:15] op_sel_hi:[0,1]
	v_pk_mul_f32 v[10:11], v[0:1], v[10:11] op_sel_hi:[0,1]
	s_waitcnt vmcnt(0)
	v_mov_b32_e32 v12, v20
	v_mov_b32_e32 v13, v22
	v_mov_b32_e32 v22, v21
	v_pk_mul_f32 v[18:19], v[18:19], v[26:27]
	v_mov_b32_e32 v20, v28
	v_mov_b32_e32 v21, v30
	v_pk_mul_f32 v[26:27], v[36:37], v[34:35]
	v_mul_f32_e32 v8, v8, v24
	v_mul_f32_e32 v16, v5, v25
	v_mov_b32_e32 v30, v29
	v_mul_f32_e32 v4, v4, v32
	v_mul_f32_e32 v24, v9, v33
	v_pk_mul_f32 v[6:7], v[6:7], v[12:13]
	v_mov_b32_e32 v17, v19
	v_mov_b32_e32 v9, v18
	v_pk_mul_f32 v[2:3], v[2:3], v[20:21]
	v_mov_b32_e32 v25, v27
	v_mov_b32_e32 v5, v26
	v_pk_fma_f32 v[6:7], v[14:15], v[22:23], v[6:7]
	v_pk_add_f32 v[8:9], v[16:17], v[8:9]
	v_pk_fma_f32 v[2:3], v[10:11], v[30:31], v[2:3]
	v_pk_add_f32 v[4:5], v[24:25], v[4:5]
.LBB0_498:
	s_nop 0
	v_mov_b32_e32 v10, v76
	v_mov_b32_e32 v11, v76
	v_pk_mul_f32 v[8:9], v[10:11], v[8:9]
	v_pk_mul_f32 v[10:11], v[10:11], v[4:5]
	v_pk_mul_f32 v[4:5], v[76:77], v[2:3]
	v_lshl_add_u64 v[12:13], v[66:67], 1, v[74:75]
	s_andn2_b64 vcc, exec, s[38:39]
	s_mov_b64 s[0:1], -1
	v_pk_mul_f32 v[6:7], v[76:77], v[6:7]
	v_cvt_pk_bf16_f32 v3, v8, v9
	v_cvt_pk_bf16_f32 v4, v4, v5
	v_cvt_pk_bf16_f32 v5, v10, v11
	s_nop 0
	v_cvt_pk_bf16_f32 v2, v6, v7
	global_store_dwordx4 v[12:13], v[2:5], off
	s_cbranch_vccnz .LBB0_351
	s_andn2_b64 vcc, exec, s[8:9]
	s_cbranch_vccnz .LBB0_350
	s_barrier
	s_branch .LBB0_350

; __device__ __forceinline__ unsigned cvt_pk_bf16(float lo, float hi) { unsigned r; asm("v_cvt_pk_bf16_f32 %0, %1, %2" : "=v"(r) : "v"(lo), "v"(hi)); return r; }
; __global__ void __launch_bounds__(512, 2) mk_fwd(Args args) {
;     ...
;             for (int row = gw; row < MT; row += NGW) {
;                 const bool lat = row < ML;
;                 const float* xr = lat ? args.in[IN_X] + (size_t)row * DM : args.in[IN_CTX] + (size_t)(row - ML) * DM;
;                 const float* mp = MODS + (size_t)(lat ? (row >> 11) : 16) * 6144;
; #pragma unroll
;                 for (int j = 0; j < 4; ++j) { const int col = 4 * lane + 256 * j;
;                     const f32x4 v = *(const f32x4*)(xr + col), sh = *(const f32x4*)(mp + col), sc = *(const f32x4*)(mp + 1024 + col);
;                     const f32x4 hv = v * (sc + 1.0f) + sh;
;                     u32x2 w; w.x = cvt_pk_bf16(hv[0], hv[1]); w.y = cvt_pk_bf16(hv[2], hv[3]);
;                     *(u32x2*)(HO + (size_t)row * DM + col) = w; }
;             }
.LBB0_507:
	s_min_i32 s2, s0, 0x8000
	s_ashr_i32 s2, s2, 11
	s_mul_hi_i32 s3, s2, 0x6000
	s_mulk_i32 s2, 0x6000
	s_add_u32 s2, s12, s2
	s_addc_u32 s3, s13, s3
	s_add_u32 s8, s2, 0x1000
	s_addc_u32 s9, s3, 0
	v_lshl_add_u64 v[10:11], s[8:9], 0, v[0:1]
	v_lshl_add_u64 v[22:23], s[2:3], 0, v[0:1]
	global_load_dwordx4 v[10:13], v[10:11], off
	s_nop 0
	global_load_dwordx4 v[14:17], v0, s[6:7]
	global_load_dwordx4 v[18:21], v[22:23], off
	s_lshl_b64 s[2:3], s[38:39], 11
	v_mov_b32_e32 v5, v1
	v_lshl_add_u64 v[24:25], v[2:3], 0, s[2:3]
	v_lshl_add_u64 v[26:27], s[8:9], 0, v[4:5]
	v_mov_b32_e32 v7, v1
	v_mov_b32_e32 v9, v1
	s_add_u32 s0, s0, s24
	s_addc_u32 s1, s1, s25
	s_add_u32 s4, s4, s10
	s_addc_u32 s5, s5, s11
	s_cmp_gt_i32 s0, 0x8fff
	s_waitcnt vmcnt(0) lgkmcnt(0)
	v_pk_add_f32 v[10:11], v[10:11], 1.0 op_sel_hi:[1,0]
	v_pk_add_f32 v[12:13], v[12:13], 1.0 op_sel_hi:[1,0]
	v_pk_fma_f32 v[10:11], v[14:15], v[10:11], v[18:19]
	v_pk_fma_f32 v[12:13], v[16:17], v[12:13], v[20:21]
	v_cvt_pk_bf16_f32 v10, v10, v11
	s_nop 0
	v_cvt_pk_bf16_f32 v11, v12, v13
	global_store_dwordx2 v[24:25], v[10:11], off
	global_load_dwordx4 v[10:13], v[26:27], off
	s_nop 0
	global_load_dwordx4 v[14:17], v[22:23], off offset:1024
	global_load_dwordx4 v[18:21], v0, s[6:7] offset:1024
	v_lshl_add_u64 v[26:27], s[8:9], 0, v[6:7]
	s_waitcnt vmcnt(0) lgkmcnt(0)
	v_pk_add_f32 v[10:11], v[10:11], 1.0 op_sel_hi:[1,0]
	v_pk_add_f32 v[12:13], v[12:13], 1.0 op_sel_hi:[1,0]
	v_pk_fma_f32 v[10:11], v[18:19], v[10:11], v[14:15]
	v_pk_fma_f32 v[12:13], v[20:21], v[12:13], v[16:17]
	v_cvt_pk_bf16_f32 v10, v10, v11
	s_nop 0
	v_cvt_pk_bf16_f32 v11, v12, v13
	global_store_dwordx2 v[24:25], v[10:11], off offset:512
	global_load_dwordx4 v[10:13], v[26:27], off
	s_nop 0
	global_load_dwordx4 v[14:17], v[22:23], off offset:2048
	global_load_dwordx4 v[18:21], v0, s[6:7] offset:2048
	v_lshl_add_u64 v[26:27], s[8:9], 0, v[8:9]
	s_waitcnt vmcnt(0) lgkmcnt(0)
	v_pk_add_f32 v[10:11], v[10:11], 1.0 op_sel_hi:[1,0]
	v_pk_add_f32 v[12:13], v[12:13], 1.0 op_sel_hi:[1,0]
	v_pk_fma_f32 v[10:11], v[18:19], v[10:11], v[14:15]
	v_pk_fma_f32 v[12:13], v[20:21], v[12:13], v[16:17]
	v_cvt_pk_bf16_f32 v10, v10, v11
	s_nop 0
	v_cvt_pk_bf16_f32 v11, v12, v13
	global_store_dwordx2 v[24:25], v[10:11], off offset:1024
	global_load_dwordx4 v[10:13], v[26:27], off
	s_nop 0
	global_load_dwordx4 v[14:17], v[22:23], off offset:3072
	global_load_dwordx4 v[18:21], v0, s[6:7] offset:3072
	s_waitcnt vmcnt(0) lgkmcnt(0)
	v_pk_add_f32 v[10:11], v[10:11], 1.0 op_sel_hi:[1,0]
	v_pk_add_f32 v[12:13], v[12:13], 1.0 op_sel_hi:[1,0]
	v_pk_fma_f32 v[10:11], v[18:19], v[10:11], v[14:15]
	v_pk_fma_f32 v[12:13], v[20:21], v[12:13], v[16:17]
	v_cvt_pk_bf16_f32 v10, v10, v11
	s_nop 0
	v_cvt_pk_bf16_f32 v11, v12, v13
	global_store_dwordx2 v[24:25], v[10:11], off offset:1536
	s_cbranch_scc1 .LBB0_511

; __global__ void __launch_bounds__(512, 2) mk_fwd(Args args) {
;     ...
;                 for (int x = tid; x < 17 * 32; x += 512) { const int b = x >> 5, c2 = x & 31; float sm = args.in[IN_BADA][l * 6144 + col0 + c2];
; #pragma unroll
;                     for (int w = 0; w < 8; ++w) sm += red[(w * 17 + b) * 32 + c2];
;                     MODS[(size_t)(l * 17 + b) * 6144 + col0 + c2] = sm; }
.LBB0_553:
	global_load_dword v80, v[74:75], off
	v_ashrrev_i32_e32 v78, 5, v0
	v_lshl_add_u32 v81, v78, 7, v132
	ds_read_b32 v82, v81
	ds_read_b32 v83, v81 offset:2176
	ds_read_b32 v84, v81 offset:4352
	ds_read_b32 v85, v81 offset:6528
	ds_read_b32 v86, v81 offset:8704
	ds_read_b32 v87, v81 offset:10880
	ds_read_b32 v88, v81 offset:13056
	ds_read_b32 v81, v81 offset:15232
	v_add_u32_e32 v79, 0x200, v0
	v_cmp_lt_i32_e32 vcc, 31, v0
	v_add_u32_e32 v78, s6, v78
	s_or_b64 s[0:1], vcc, s[0:1]
	v_mov_b32_e32 v0, v79
	v_mad_i64_i32 v[78:79], s[8:9], v78, s33, v[76:77]
	s_waitcnt vmcnt(0) lgkmcnt(0)
	v_add_f32_e32 v80, v80, v82
	s_waitcnt lgkmcnt(6)
	v_add_f32_e32 v80, v80, v83
	s_waitcnt lgkmcnt(5)
	v_add_f32_e32 v80, v80, v84
	s_waitcnt lgkmcnt(4)
	v_add_f32_e32 v80, v80, v85
	s_waitcnt lgkmcnt(3)
	v_add_f32_e32 v80, v80, v86
	s_waitcnt lgkmcnt(2)
	v_add_f32_e32 v80, v80, v87
	s_waitcnt lgkmcnt(1)
	v_add_f32_e32 v80, v80, v88
	s_waitcnt lgkmcnt(0)
	v_add_f32_e32 v80, v80, v81
	global_store_dword v[78:79], v80, off
	s_andn2_b64 exec, exec, s[0:1]
	s_cbranch_execnz .LBB0_553
	s_branch .LBB0_514

; __device__ __forceinline__ void sincos_d(double a, float& c, float& s) {
;     const double twopi = 6.283185307179586476925;
;     const double k = __builtin_rint(a / twopi);
;     const double r = a - k * twopi;
;     const double r2 = r * r;
;     double cs = 1.0, sn = r, tc = 1.0, ts = r;
; #pragma unroll 1
;     for (int i = 1; i <= 14; ++i) { tc = -tc * r2 / (double)((2 * i - 1) * (2 * i)); ts = -ts * r2 / (double)((2 * i) * (2 * i + 1)); cs += tc; sn += ts; }
;     c = (float)cs; s = (float)sn;
; }
; __global__ void __launch_bounds__(512, 2) mk_fwd(Args args) {
;     ...
;                 for (int x = tid; x < 64 * 8 + 64 * 16; x += 512) {
;                     const bool isM = x < 512; const int y = isM ? x : x - 512; const int nf = isM ? 8 : 16; const int pos = y / nf, f = y % nf;
;                     const double base = isM ? 0.31622776601683794 : 0.5623413251903491;
;                     double inv = 1.0; for (int i = 0; i < f; ++i) inv *= base;
;                     const float ang = (float)pos * (float)inv;
;                     float c, s; sincos_d((double)ang, c, s);
;                     float* tp = isM ? tabM : tabS; tp[2 * y] = c; tp[2 * y + 1] = s;
;                 }
.LBB0_561:
	s_add_i32 s4, s2, -1
	s_mul_i32 s4, s4, s2
	v_cvt_f64_i32_e32 v[14:15], s4
	s_add_i32 s4, s4, s10
	v_mul_f64 v[12:13], v[6:7], -v[12:13]
	v_mul_f64 v[10:11], v[8:9], -v[10:11]
	v_cvt_f64_u32_e32 v[16:17], s4
	v_div_scale_f64 v[18:19], s[4:5], v[14:15], v[14:15], v[12:13]
	v_div_scale_f64 v[22:23], s[12:13], v[16:17], v[16:17], v[10:11]
	v_rcp_f64_e32 v[26:27], v[18:19]
	v_rcp_f64_e32 v[28:29], v[22:23]
	v_div_scale_f64 v[20:21], s[4:5], v[12:13], v[14:15], v[12:13]
	v_fma_f64 v[30:31], -v[18:19], v[26:27], 1.0
	v_fma_f64 v[32:33], -v[22:23], v[28:29], 1.0
	v_fmac_f64_e32 v[26:27], v[26:27], v[30:31]
	v_fmac_f64_e32 v[28:29], v[28:29], v[32:33]
	v_fma_f64 v[30:31], -v[18:19], v[26:27], 1.0
	v_fma_f64 v[32:33], -v[22:23], v[28:29], 1.0
	v_div_scale_f64 v[24:25], vcc, v[10:11], v[16:17], v[10:11]
	v_fmac_f64_e32 v[26:27], v[26:27], v[30:31]
	v_fmac_f64_e32 v[28:29], v[28:29], v[32:33]
	v_mul_f64 v[30:31], v[20:21], v[26:27]
	v_mul_f64 v[32:33], v[24:25], v[28:29]
	v_fma_f64 v[18:19], -v[18:19], v[30:31], v[20:21]
	v_fma_f64 v[20:21], -v[22:23], v[32:33], v[24:25]
	v_div_fmas_f64 v[20:21], v[20:21], v[28:29], v[32:33]
	s_mov_b64 vcc, s[4:5]
	v_div_fixup_f64 v[10:11], v[20:21], v[16:17], v[10:11]
	v_div_fmas_f64 v[16:17], v[18:19], v[26:27], v[30:31]
	s_add_i32 s2, s2, 2
	s_add_i32 s10, s10, 4
	v_div_fixup_f64 v[12:13], v[16:17], v[14:15], v[12:13]
	s_cmp_lg_u32 s2, 30
	v_add_f64 v[4:5], v[4:5], v[10:11]
	v_add_f64 v[2:3], v[2:3], v[12:13]
	s_cbranch_scc1 .LBB0_561
	v_cvt_f32_f64_e32 v5, v[4:5]
	v_cvt_f32_f64_e32 v4, v[2:3]
	v_mov_b32_e32 v2, s99
	v_mov_b32_e32 v3, s37
	v_cndmask_b32_e64 v3, v2, v3, s[0:1]
	v_mov_b32_e32 v2, s98
	v_mov_b32_e32 v6, s36
	v_cndmask_b32_e64 v2, v2, v6, s[0:1]
	v_lshlrev_b32_e32 v6, 1, v0
	v_ashrrev_i32_e32 v7, 31, v6
	v_add_u32_e32 v0, 0x200, v128
	v_cmp_lt_i32_e32 vcc, -1, v128
	v_lshl_add_u64 v[2:3], v[6:7], 2, v[2:3]
	s_or_b64 s[8:9], vcc, s[8:9]
	v_mov_b32_e32 v128, v0
	global_store_dwordx2 v[2:3], v[4:5], off
	s_andn2_b64 exec, exec, s[8:9]
	s_cbranch_execnz .LBB0_556

; #define LAS __attribute__((address_space(3)))
; __device__ __forceinline__ unsigned cvt_pk_bf16(float lo, float hi) { unsigned r; asm("v_cvt_pk_bf16_f32 %0, %1, %2" : "=v"(r) : "v"(lo), "v"(hi)); return r; }
; __device__ __forceinline__ void conv_item(const float* W, int K, int N, int Np, bf16_t* WT, const float* kscale, int mapmode, LAS float* scr, int item, int lane) {
;     ...
;     const int c = lane & 7;
; #pragma unroll
;     for (int j = 0; j < 8; ++j) { const int n = (lane >> 3) + 8 * j; const LAS float* sp = scr + (8 * c) * 65 + n;
;         u32x4 o; o.x = cvt_pk_bf16(sp[0 * 65], sp[1 * 65]); o.y = cvt_pk_bf16(sp[2 * 65], sp[3 * 65]); o.z = cvt_pk_bf16(sp[4 * 65], sp[5 * 65]); o.w = cvt_pk_bf16(sp[6 * 65], sp[7 * 65]);
;         *(u32x4*)(WT + (size_t)(n0 + n) * K + k0 + 8 * c) = o; }
.LBB0_590:
	ds_read_b32 v0, v11
	ds_read_b32 v4, v11 offset:260
	s_ashr_i32 s0, s31, 31
	s_mul_i32 s0, s0, s20
	v_lshl_add_u64 v[2:3], s[98:99], 1, v[16:17]
	s_add_i32 s23, s23, s12
	s_waitcnt lgkmcnt(0)
	v_cvt_pk_bf16_f32 v4, v0, v4
	ds_read_b32 v0, v11 offset:520
	ds_read_b32 v5, v11 offset:780
	s_cmp_ge_i32 s23, s24
	s_waitcnt lgkmcnt(0)
	v_cvt_pk_bf16_f32 v5, v0, v5
	ds_read_b32 v0, v11 offset:1040
	ds_read_b32 v6, v11 offset:1300
	s_waitcnt lgkmcnt(0)
	v_cvt_pk_bf16_f32 v6, v0, v6
	ds_read_b32 v0, v11 offset:1560
	ds_read_b32 v7, v11 offset:1820
	s_waitcnt lgkmcnt(0)
	v_cvt_pk_bf16_f32 v7, v0, v7
	v_or_b32_e32 v0, s31, v9
	v_mad_u64_u32 v[18:19], s[48:49], v0, s20, 0
	v_add_u32_e32 v19, s0, v19
	v_lshl_add_u64 v[18:19], v[18:19], 1, v[2:3]
	global_store_dwordx4 v[18:19], v[4:7], off
	ds_read_b32 v0, v11 offset:32
	ds_read_b32 v4, v11 offset:292
	s_waitcnt lgkmcnt(0)
	v_cvt_pk_bf16_f32 v4, v0, v4
	ds_read_b32 v0, v11 offset:552
	ds_read_b32 v5, v11 offset:812
	s_waitcnt lgkmcnt(0)
	v_cvt_pk_bf16_f32 v5, v0, v5
	ds_read_b32 v0, v11 offset:1072
	ds_read_b32 v6, v11 offset:1332
	s_waitcnt lgkmcnt(0)
	v_cvt_pk_bf16_f32 v6, v0, v6
	ds_read_b32 v0, v11 offset:1592
	ds_read_b32 v7, v11 offset:1852
	s_waitcnt lgkmcnt(0)
	v_cvt_pk_bf16_f32 v7, v0, v7
	v_or_b32_e32 v0, s31, v24
	v_mad_u64_u32 v[18:19], s[48:49], v0, s20, 0
	v_add_u32_e32 v19, s0, v19
	v_lshl_add_u64 v[18:19], v[18:19], 1, v[2:3]
	global_store_dwordx4 v[18:19], v[4:7], off
	ds_read_b32 v0, v11 offset:64
	ds_read_b32 v4, v11 offset:324
	s_waitcnt lgkmcnt(0)
	v_cvt_pk_bf16_f32 v4, v0, v4
	ds_read_b32 v0, v11 offset:584
	ds_read_b32 v5, v11 offset:844
	s_waitcnt lgkmcnt(0)
	v_cvt_pk_bf16_f32 v5, v0, v5
	ds_read_b32 v0, v11 offset:1104
	ds_read_b32 v6, v11 offset:1364
	s_waitcnt lgkmcnt(0)
	v_cvt_pk_bf16_f32 v6, v0, v6
	ds_read_b32 v0, v11 offset:1624
	ds_read_b32 v7, v11 offset:1884
	s_waitcnt lgkmcnt(0)
	v_cvt_pk_bf16_f32 v7, v0, v7
	v_or_b32_e32 v0, s31, v25
	v_mad_u64_u32 v[18:19], s[48:49], v0, s20, 0
	v_add_u32_e32 v19, s0, v19
	v_lshl_add_u64 v[18:19], v[18:19], 1, v[2:3]
	global_store_dwordx4 v[18:19], v[4:7], off
	ds_read_b32 v0, v11 offset:96
	ds_read_b32 v4, v11 offset:356
	s_waitcnt lgkmcnt(0)
	v_cvt_pk_bf16_f32 v4, v0, v4
	ds_read_b32 v0, v11 offset:616
	ds_read_b32 v5, v11 offset:876
	s_waitcnt lgkmcnt(0)
	v_cvt_pk_bf16_f32 v5, v0, v5
	ds_read_b32 v0, v11 offset:1136
	ds_read_b32 v6, v11 offset:1396
	s_waitcnt lgkmcnt(0)
	v_cvt_pk_bf16_f32 v6, v0, v6
	ds_read_b32 v0, v11 offset:1656
	ds_read_b32 v7, v11 offset:1916
	s_waitcnt lgkmcnt(0)
	v_cvt_pk_bf16_f32 v7, v0, v7
	v_or_b32_e32 v0, s31, v26
	v_mad_u64_u32 v[18:19], s[48:49], v0, s20, 0
	v_add_u32_e32 v19, s0, v19
	v_lshl_add_u64 v[18:19], v[18:19], 1, v[2:3]
	global_store_dwordx4 v[18:19], v[4:7], off
	ds_read_b32 v0, v11 offset:128
	ds_read_b32 v4, v11 offset:388
	s_waitcnt lgkmcnt(0)
	v_cvt_pk_bf16_f32 v4, v0, v4
	ds_read_b32 v0, v11 offset:648
	ds_read_b32 v5, v11 offset:908
	s_waitcnt lgkmcnt(0)
	v_cvt_pk_bf16_f32 v5, v0, v5
	ds_read_b32 v0, v11 offset:1168
	ds_read_b32 v6, v11 offset:1428
	s_waitcnt lgkmcnt(0)
	v_cvt_pk_bf16_f32 v6, v0, v6
	ds_read_b32 v0, v11 offset:1688
	ds_read_b32 v7, v11 offset:1948
	s_waitcnt lgkmcnt(0)
	v_cvt_pk_bf16_f32 v7, v0, v7
	v_or_b32_e32 v0, s31, v27
	v_mad_u64_u32 v[18:19], s[48:49], v0, s20, 0
	v_add_u32_e32 v19, s0, v19
	v_lshl_add_u64 v[18:19], v[18:19], 1, v[2:3]
	global_store_dwordx4 v[18:19], v[4:7], off
	ds_read_b32 v0, v11 offset:160
	ds_read_b32 v4, v11 offset:420
	s_waitcnt lgkmcnt(0)
	v_cvt_pk_bf16_f32 v4, v0, v4
	ds_read_b32 v0, v11 offset:680
	ds_read_b32 v5, v11 offset:940
	s_waitcnt lgkmcnt(0)
	v_cvt_pk_bf16_f32 v5, v0, v5
	ds_read_b32 v0, v11 offset:1200
	ds_read_b32 v6, v11 offset:1460
	s_waitcnt lgkmcnt(0)
	v_cvt_pk_bf16_f32 v6, v0, v6
	ds_read_b32 v0, v11 offset:1720
	ds_read_b32 v7, v11 offset:1980
	s_waitcnt lgkmcnt(0)
	v_cvt_pk_bf16_f32 v7, v0, v7
	v_or_b32_e32 v0, s31, v28
	v_mad_u64_u32 v[18:19], s[48:49], v0, s20, 0
	v_add_u32_e32 v19, s0, v19
	v_lshl_add_u64 v[18:19], v[18:19], 1, v[2:3]
	global_store_dwordx4 v[18:19], v[4:7], off
	ds_read_b32 v0, v11 offset:192
	ds_read_b32 v4, v11 offset:452
	s_waitcnt lgkmcnt(0)
	v_cvt_pk_bf16_f32 v4, v0, v4
	ds_read_b32 v0, v11 offset:712
	ds_read_b32 v5, v11 offset:972
	s_waitcnt lgkmcnt(0)
	v_cvt_pk_bf16_f32 v5, v0, v5
	ds_read_b32 v0, v11 offset:1232
	ds_read_b32 v6, v11 offset:1492
	s_waitcnt lgkmcnt(0)
	v_cvt_pk_bf16_f32 v6, v0, v6
	ds_read_b32 v0, v11 offset:1752
	ds_read_b32 v7, v11 offset:2012
	s_waitcnt lgkmcnt(0)
	v_cvt_pk_bf16_f32 v7, v0, v7
	v_or_b32_e32 v0, s31, v29
	v_mad_u64_u32 v[18:19], s[48:49], v0, s20, 0
	v_add_u32_e32 v19, s0, v19
	v_lshl_add_u64 v[18:19], v[18:19], 1, v[2:3]
	global_store_dwordx4 v[18:19], v[4:7], off
	ds_read_b32 v0, v11 offset:224
	ds_read_b32 v4, v11 offset:484
	s_waitcnt lgkmcnt(0)
	v_cvt_pk_bf16_f32 v4, v0, v4
	ds_read_b32 v0, v11 offset:744
	ds_read_b32 v5, v11 offset:1004
	s_waitcnt lgkmcnt(0)
	v_cvt_pk_bf16_f32 v5, v0, v5
	ds_read_b32 v0, v11 offset:1264
	ds_read_b32 v6, v11 offset:1524
	s_waitcnt lgkmcnt(0)
	v_cvt_pk_bf16_f32 v6, v0, v6
	ds_read_b32 v0, v11 offset:1784
	ds_read_b32 v7, v11 offset:2044
	s_waitcnt lgkmcnt(0)
	v_cvt_pk_bf16_f32 v7, v0, v7
	v_or_b32_e32 v0, s31, v30
	v_mad_u64_u32 v[18:19], s[48:49], v0, s20, 0
	v_add_u32_e32 v19, s0, v19
	v_lshl_add_u64 v[2:3], v[18:19], 1, v[2:3]
	global_store_dwordx4 v[2:3], v[4:7], off
	s_cbranch_scc1 .LBB0_569

; __device__ __forceinline__ unsigned cvt_pk_bf16(float lo, float hi) { unsigned r; asm("v_cvt_pk_bf16_f32 %0, %1, %2" : "=v"(r) : "v"(lo), "v"(hi)); return r; }
; __global__ void __launch_bounds__(512, 2) mk_fwd(Args args) {
;     ...
;                 for (int it = gw; it < nitems * 11; it += NGW) {
;                     const int ri = it / 11, chunk = it - ri * 11;
;                     const int g64 = ri >> 1, which = ri & 1; const int row = 64 * g64 + (which ? 63 : 0);
;                     const int tpos = row < ML ? (row & 2047) : ((row - ML) & 255); const int tlen = row < ML ? 2048 : 256;
;                     const float* hc = HALO + (size_t)(g64 * 4 + (which ? 3 : 0)) * FF2;
;                     const float* hp = which ? HALO + (size_t)(g64 * 4 + 2) * FF2 : (tpos > 0 ? HALO + (size_t)((g64 - 1) * 4 + 3) * FF2 : nullptr);
;                     const float* hn = which ? (tpos < tlen - 1 ? HALO + (size_t)((g64 + 1) * 4 + 0) * FF2 : nullptr) : HALO + (size_t)(g64 * 4 + 1) * FF2;
;                     const int c = 256 * chunk + 4 * lane;
;                     const int na = ((c >> 7) << 8) + (c & 127), ng = na + 128;
;                     const f32x4 z4 = (f32x4){0.f, 0.f, 0.f, 0.f};
;                     const f32x4 ac = *(const f32x4*)(hc + na), gc = *(const f32x4*)(hc + ng);
;                     const f32x4 ap = hp ? *(const f32x4*)(hp + na) : z4, gp = hp ? *(const f32x4*)(hp + ng) : z4;
;                     const f32x4 an = hn ? *(const f32x4*)(hn + na) : z4, gn = hn ? *(const f32x4*)(hn + ng) : z4;
;                     const f32x4 av = *(const f32x4*)(cw + c) * ap + *(const f32x4*)(cw + FF2 + c) * ac + *(const f32x4*)(cw + 2 * FF2 + c) * an + *(const f32x4*)(cb + c);
;                     const f32x4 gv = *(const f32x4*)(cw + FFH + c) * gp + *(const f32x4*)(cw + FF2 + FFH + c) * gc + *(const f32x4*)(cw + 2 * FF2 + FFH + c) * gn + *(const f32x4*)(cb + FFH + c);
;                     f32x4 o;
; #pragma unroll
;                     for (int e = 0; e < 4; ++e) o[e] = av[e] * gv[e] / (1.0f + __expf(-gv[e]));
;                     u32x2 w; w.x = cvt_pk_bf16(o[0], o[1]); w.y = cvt_pk_bf16(o[2], o[3]);
;                     *(u32x2*)(GB + (size_t)row * FFH + c) = w;
;                 }
.LBB0_695:
	s_mulk_i32 s14, 0xf500
	v_add_u32_e32 v50, s14, v60
	v_ashrrev_i32_e32 v51, 31, v50
	v_lshlrev_b64 v[6:7], 2, v[50:51]
	v_lshl_add_u64 v[2:3], s[0:1], 0, v[6:7]
	global_load_dwordx4 v[34:37], v[2:3], off
	v_lshl_add_u64 v[2:3], s[6:7], 0, v[6:7]
	global_load_dwordx4 v[38:41], v[2:3], off
	v_lshl_add_u64 v[2:3], s[8:9], 0, v[6:7]
	global_load_dwordx4 v[42:45], v[2:3], off
	v_lshl_add_u64 v[8:9], s[38:39], 0, v[6:7]
	global_load_dwordx4 v[30:33], v[8:9], off
	v_lshl_add_u64 v[8:9], s[44:45], 0, v[6:7]
	global_load_dwordx4 v[26:29], v[8:9], off
	v_lshl_add_u64 v[8:9], s[84:85], 0, v[6:7]
	global_load_dwordx4 v[46:49], v[8:9], off
	v_lshl_add_u64 v[2:3], s[4:5], 0, v[6:7]
	v_lshl_add_u64 v[6:7], s[86:87], 0, v[6:7]
	global_load_dwordx4 v[6:9], v[6:7], off
	v_readlane_b32 s16, v254, 23
	global_load_dwordx4 v[2:5], v[2:3], off
	v_readlane_b32 s17, v254, 24
	s_waitcnt vmcnt(0)
	v_mov_b32_e32 v59, v70
	v_mov_b32_e32 v23, v71
	v_mov_b32_e32 v53, v72
	v_mov_b32_e32 v25, v73
	v_mov_b32_e32 v57, v74
	v_mov_b32_e32 v15, v75
	v_mov_b32_e32 v55, v76
	v_mov_b32_e32 v17, v77
	v_mov_b32_e32 v58, v78
	v_mov_b32_e32 v22, v79
	v_mov_b32_e32 v52, v80
	v_mov_b32_e32 v24, v81
	v_mov_b32_e32 v56, v82
	v_mov_b32_e32 v14, v83
	v_mov_b32_e32 v54, v84
	v_mov_b32_e32 v16, v85
	v_mov_b32_e32 v63, v34
	v_mov_b32_e32 v62, v42
	v_pk_mul_f32 v[58:59], v[62:63], v[58:59]
	v_mov_b32_e32 v34, v43
	s_waitcnt lgkmcnt(0)
	v_fma_f32 v18, v38, v18, v59
	v_add_f32_e32 v180, v58, v18
	v_mov_b32_e32 v59, v30
	v_mov_b32_e32 v58, v46
	v_pk_mul_f32 v[56:57], v[58:59], v[56:57]
	v_pk_mul_f32 v[22:23], v[34:35], v[22:23]
	v_fma_f32 v10, v26, v10, v57
	v_add_f32_e32 v10, v56, v10
	v_add_f32_e32 v6, v6, v10
	v_mul_f32_e32 v10, 0xbfb8aa3b, v6
	v_exp_f32_e32 v57, v10
	v_mov_b32_e32 v56, v2
	v_pk_add_f32 v[56:57], v[56:57], v[180:181]
	s_nop 0
	v_mul_f32_e32 v2, v56, v6
	v_div_scale_f32 v6, s[14:15], v57, v57, v2
	v_rcp_f32_e32 v10, v6
	s_nop 0
	v_fma_f32 v18, -v6, v10, 1.0
	v_fmac_f32_e32 v10, v18, v10
	v_div_scale_f32 v18, vcc, v2, v57, v2
	v_mul_f32_e32 v26, v18, v10
	v_fma_f32 v30, -v6, v26, v18
	v_fmac_f32_e32 v26, v30, v10
	v_fma_f32 v6, -v6, v26, v18
	v_div_fmas_f32 v6, v6, v10, v26
	v_mov_b32_e32 v30, v47
	v_div_fixup_f32 v2, v6, v57, v2
	v_fma_f32 v6, v39, v19, v23
	v_pk_mul_f32 v[14:15], v[30:31], v[14:15]
	v_add_f32_e32 v180, v22, v6
	v_fma_f32 v6, v27, v11, v15
	v_add_f32_e32 v6, v14, v6
	v_add_f32_e32 v10, v7, v6
	v_mul_f32_e32 v6, 0xbfb8aa3b, v10
	v_exp_f32_e32 v7, v6
	v_mov_b32_e32 v6, v3
	v_pk_add_f32 v[6:7], v[6:7], v[180:181]
	s_nop 0
	v_mul_f32_e32 v3, v6, v10
	v_div_scale_f32 v6, s[14:15], v7, v7, v3
	v_rcp_f32_e32 v10, v6
	s_nop 0
	v_fma_f32 v11, -v6, v10, 1.0
	v_fmac_f32_e32 v10, v11, v10
	v_div_scale_f32 v11, vcc, v3, v7, v3
	v_mul_f32_e32 v14, v11, v10
	v_fma_f32 v15, -v6, v14, v11
	v_fmac_f32_e32 v14, v15, v10
	v_fma_f32 v6, -v6, v14, v11
	v_div_fmas_f32 v6, v6, v10, v14
	v_div_fixup_f32 v3, v6, v7, v3
	v_mov_b32_e32 v6, v44
	v_mov_b32_e32 v7, v36
	v_pk_mul_f32 v[6:7], v[6:7], v[52:53]
	v_mov_b32_e32 v36, v45
	v_fma_f32 v7, v40, v20, v7
	v_add_f32_e32 v180, v6, v7
	v_mov_b32_e32 v6, v48
	v_mov_b32_e32 v7, v32
	v_pk_mul_f32 v[6:7], v[6:7], v[54:55]
	v_mov_b32_e32 v32, v49
	v_fma_f32 v7, v28, v12, v7
	v_add_f32_e32 v6, v6, v7
	v_add_f32_e32 v8, v8, v6
	v_mul_f32_e32 v6, 0xbfb8aa3b, v8
	v_exp_f32_e32 v7, v6
	v_mov_b32_e32 v6, v4
	v_cvt_pk_bf16_f32 v2, v2, v3
	v_pk_add_f32 v[6:7], v[6:7], v[180:181]
	s_nop 0
	v_mul_f32_e32 v4, v6, v8
	v_div_scale_f32 v6, s[14:15], v7, v7, v4
	v_rcp_f32_e32 v8, v6
	s_nop 0
	v_fma_f32 v10, -v6, v8, 1.0
	v_fmac_f32_e32 v8, v10, v8
	v_div_scale_f32 v10, vcc, v4, v7, v4
	v_mul_f32_e32 v11, v10, v8
	v_fma_f32 v12, -v6, v11, v10
	v_fmac_f32_e32 v11, v12, v8
	v_fma_f32 v6, -v6, v11, v10
	v_div_fmas_f32 v6, v6, v8, v11
	v_div_fixup_f32 v8, v6, v7, v4
	v_pk_mul_f32 v[6:7], v[36:37], v[24:25]
	s_nop 0
	v_fma_f32 v4, v41, v21, v7
	v_add_f32_e32 v180, v6, v4
	v_pk_mul_f32 v[6:7], v[32:33], v[16:17]
	s_nop 0
	v_fma_f32 v4, v29, v13, v7
	v_add_f32_e32 v4, v6, v4
	v_add_f32_e32 v9, v9, v4
	v_mul_f32_e32 v4, 0xbfb8aa3b, v9
	v_exp_f32_e32 v7, v4
	v_mov_b32_e32 v6, v5
	v_pk_add_f32 v[4:5], v[6:7], v[180:181]
	s_nop 0
	v_mul_f32_e32 v4, v4, v9
	v_div_scale_f32 v6, s[14:15], v5, v5, v4
	v_rcp_f32_e32 v7, v6
	s_mul_hi_i32 s15, s13, 0x1600
	s_mulk_i32 s13, 0x1600
	s_add_u32 s14, s16, s13
	v_fma_f32 v9, -v6, v7, 1.0
	v_fmac_f32_e32 v7, v9, v7
	v_div_scale_f32 v9, vcc, v4, v5, v4
	v_mul_f32_e32 v10, v9, v7
	v_fma_f32 v11, -v6, v10, v9
	v_fmac_f32_e32 v10, v11, v7
	v_fma_f32 v6, -v6, v10, v9
	v_div_fmas_f32 v6, v6, v7, v10
	v_readlane_b32 s13, v253, 23
	v_div_fixup_f32 v4, v6, v5, v4
	s_addc_u32 s15, s17, s15
	s_add_i32 s11, s11, s24
	v_add_u32_e32 v61, s13, v61
	v_readlane_b32 s13, v253, 24
	v_cvt_pk_bf16_f32 v3, v8, v4
	v_lshl_add_u64 v[4:5], v[50:51], 1, s[14:15]
	s_cmp_ge_i32 s11, s12
	v_add_u32_e32 v60, s13, v60
	global_store_dwordx2 v[4:5], v[2:3], off
	s_cbranch_scc1 .LBB0_715

; __global__ void __launch_bounds__(512, 2) mk_fwd(Args args) {
;     ...
;                     const int g64 = ri >> 1, which = ri & 1; const int row = 64 * g64 + (which ? 63 : 0);
;                     const int tpos = row < ML ? (row & 2047) : ((row - ML) & 255); const int tlen = row < ML ? 2048 : 256;
;                     const float* hc = HALO + (size_t)(g64 * 4 + (which ? 3 : 0)) * FF2;
;                     const float* hp = which ? HALO + (size_t)(g64 * 4 + 2) * FF2 : (tpos > 0 ? HALO + (size_t)((g64 - 1) * 4 + 3) * FF2 : nullptr);
;                     const float* hn = which ? (tpos < tlen - 1 ? HALO + (size_t)((g64 + 1) * 4 + 0) * FF2 : nullptr) : HALO + (size_t)(g64 * 4 + 1) * FF2;
;                     const int c = 256 * chunk + 4 * lane;
;                     const int na = ((c >> 7) << 8) + (c & 127), ng = na + 128;
;                     const f32x4 z4 = (f32x4){0.f, 0.f, 0.f, 0.f};
;                     const f32x4 ac = *(const f32x4*)(hc + na), gc = *(const f32x4*)(hc + ng);
;                     const f32x4 ap = hp ? *(const f32x4*)(hp + na) : z4, gp = hp ? *(const f32x4*)(hp + ng) : z4;
;                     const f32x4 an = hn ? *(const f32x4*)(hn + na) : z4, gn = hn ? *(const f32x4*)(hn + ng) : z4;
.LBB0_707:
	s_and_b64 s[16:17], exec, s[48:49]
	s_cselect_b32 s16, 0, 3
	s_or_b32 s15, s16, s15
	s_mul_hi_i32 s17, s15, 0x5800
	s_mulk_i32 s15, 0x5800
	s_add_u32 s16, s76, s15
	s_mul_i32 s15, s14, 0xffffea00
	v_add_u32_e32 v2, s15, v61
	s_movk_i32 s15, 0xff00
	v_and_or_b32 v2, v2, s15, v0
	s_addc_u32 s17, s77, s17
	v_ashrrev_i32_e32 v3, 31, v2
	v_lshl_add_u64 v[4:5], v[2:3], 2, s[16:17]
	global_load_dwordx4 v[18:21], v[4:5], off
	global_load_dwordx4 v[10:13], v[4:5], off offset:512
	v_mov_b32_e32 v70, 0
	v_mov_b32_e32 v71, 0
	v_mov_b32_e32 v72, 0
	v_mov_b32_e32 v73, 0
	v_mov_b32_e32 v74, 0
	v_mov_b32_e32 v75, 0
	v_mov_b32_e32 v76, 0
	v_mov_b32_e32 v77, 0
	v_mov_b32_e32 v78, 0
	v_mov_b32_e32 v79, 0
	v_mov_b32_e32 v80, 0
	v_mov_b32_e32 v81, 0
	v_mov_b32_e32 v82, 0
	v_mov_b32_e32 v83, 0
	v_mov_b32_e32 v84, 0
	v_mov_b32_e32 v85, 0
	v_lshl_add_u64 v[4:5], v[2:3], 2, s[50:51]
	s_cmp_lg_u64 s[50:51], 0
	s_cbranch_scc0 .Lfix_nohp
	global_load_dwordx4 v[70:73], v[4:5], off
	global_load_dwordx4 v[74:77], v[4:5], off offset:512

; #define LAS __attribute__((address_space(3)))
;     __device__ __forceinline__ void operator()(const f32x4 (&acc)[2][2][4][2], const Unit& u, int wr_in, int wc_in, int fr_in, int fq_in) const {
;     ...
;         for (int ai = 0; ai < 2; ++ai) {
;             if (fr == 0 || fr == 15) {
;                 const int g64 = u.pm * 4 + ai * 2 + wr;
;                 float* hp = halo + ((size_t)(g64 * 4 + (fr ? 2 : 0))) * FF2 + tcol0;
; #pragma unroll
;                 for (int n = 0; n < 2; ++n) {
;                     const f32x4 bua = *(const LAS f32x4*)(P + 8 * fq + 4 * n), bug = *(const LAS f32x4*)(P + 160 + 8 * fq + 4 * n);
;                     const f32x4 a0 = fr ? acc[ai][0][2][n] : acc[ai][0][0][n], a1 = fr ? acc[ai][0][3][n] : acc[ai][0][1][n];
;                     const f32x4 g0 = fr ? acc[ai][1][2][n] : acc[ai][1][0][n], g1 = fr ? acc[ai][1][3][n] : acc[ai][1][1][n];
;                     *(f32x4*)(hp + 4 * n) = a0 + bua; *(f32x4*)(hp + 128 + 4 * n) = g0 + bug;
;                     *(f32x4*)(hp + FF2 + 4 * n) = a1 + bua; *(f32x4*)(hp + FF2 + 128 + 4 * n) = g1 + bug;
;                 }
;             }
;             u32x4 pk[4];
; #pragma unroll
;             for (int n = 0; n < 2; ++n)
; #pragma unroll
;                 for (int ep = 0; ep < 2; ++ep) {
;                     const int e0 = 2 * ep; const LAS float* pc = P + 8 * fq + 4 * n + e0;
;                     const f32x2 bua = *(const LAS f32x2*)(pc), w0a = *(const LAS f32x2*)(pc + 32), w1a = *(const LAS f32x2*)(pc + 64), w2a = *(const LAS f32x2*)(pc + 96), cba = *(const LAS f32x2*)(pc + 128);
;                     const f32x2 bug = *(const LAS f32x2*)(pc + 160), w0g = *(const LAS f32x2*)(pc + 192), w1g = *(const LAS f32x2*)(pc + 224), w2g = *(const LAS f32x2*)(pc + 256), cbg = *(const LAS f32x2*)(pc + 288);
;                     f32x2 av[4];
;                     {
;                         f32x2 x[4], pv, nv;
; #pragma unroll
;                         for (int m = 0; m < 4; ++m) { x[m].x = acc[ai][0][m][n][e0]; x[m].y = acc[ai][0][m][n][e0 + 1]; x[m] = x[m] + bua; }
.LBB0_773:
	v_mov_b32_e32 v151, v146
	s_mov_b32 s27, s13
	v_mov_b32_e32 v141, v148
	s_mov_b32 s31, s19
	s_mov_b64 s[48:49], 0
	v_cmp_ne_u32_e64 s[0:1], 0, v151
	v_cmp_eq_u32_e64 s[4:5], 0, v151
	v_cmp_lt_i32_e32 vcc, 14, v151
	v_cmp_eq_u32_e64 s[6:7], 15, v151
	s_and_saveexec_b64 s[8:9], vcc
	s_xor_b64 s[8:9], exec, s[8:9]
	s_and_b64 s[48:49], s[6:7], exec
	s_andn2_saveexec_b64 s[8:9], s[8:9]
	s_andn2_b64 s[48:49], s[48:49], exec
	s_and_b64 s[50:51], s[4:5], exec
	s_or_b64 s[48:49], s[48:49], s[50:51]
	s_or_b64 exec, exec, s[8:9]
	v_lshlrev_b32_e64 v140, 5, s31
	v_lshlrev_b32_e32 v142, 3, v141
	v_lshlrev_b32_e64 v152, 2, s27
	v_add3_u32 v140, v142, v140, s26
	v_add_u32_e32 v143, s31, v152
	s_movk_i32 s8, 0x500
	v_add_u32_e32 v142, s26, v140
	v_mul_lo_u32 v143, v143, s8
	s_add_i32 s8, 0, 0x20000
	v_lshlrev_b32_e32 v141, 5, v141
	v_add3_u32 v144, s8, v143, v141
	v_cndmask_b32_e64 v153, 2, 0, s[4:5]
	v_ashrrev_i32_e32 v143, 31, v142
	s_and_saveexec_b64 s[8:9], s[48:49]
	s_cbranch_execz .LBB0_779
	s_lshl_b32 s26, s98, 4
	v_add_u32_e32 v141, s26, v152
	v_or_b32_e32 v141, v141, v153
	v_mov_b64_e32 v[154:155], s[76:77]
	v_mad_i64_i32 v[154:155], s[48:49], v141, s57, v[154:155]
	v_lshl_add_u64 v[166:167], v[142:143], 2, v[154:155]
	ds_read_b128 v[154:157], v144
	ds_read_b128 v[158:161], v144 offset:640
	v_cndmask_b32_e64 v163, v119, v127, s[4:5]
	v_cndmask_b32_e64 v162, v118, v126, s[4:5]
	v_cndmask_b32_e64 v169, v115, v123, s[4:5]
	v_cndmask_b32_e64 v168, v114, v122, s[4:5]
	s_movk_i32 s26, 0x5000
	v_cndmask_b32_e64 v165, v121, v129, s[4:5]
	v_cndmask_b32_e64 v164, v120, v128, s[4:5]
	v_cndmask_b32_e64 v171, v117, v125, s[4:5]
	v_cndmask_b32_e64 v170, v116, v124, s[4:5]
	s_waitcnt lgkmcnt(0)
	v_pk_add_f32 v[162:163], v[162:163], v[154:155]
	v_pk_add_f32 v[154:155], v[168:169], v[154:155]
	v_add_co_u32_e32 v168, vcc, s26, v166
	v_cndmask_b32_e64 v173, v103, v111, s[4:5]
	v_cndmask_b32_e64 v172, v102, v110, s[4:5]
	v_cndmask_b32_e64 v175, v105, v113, s[4:5]
	v_cndmask_b32_e64 v174, v104, v112, s[4:5]
	v_cndmask_b32_e64 v177, v99, v107, s[4:5]
	v_cndmask_b32_e64 v176, v98, v106, s[4:5]
	v_cndmask_b32_e64 v179, v101, v109, s[4:5]
	v_cndmask_b32_e64 v178, v100, v108, s[4:5]
	v_pk_add_f32 v[164:165], v[164:165], v[156:157]
	v_pk_add_f32 v[156:157], v[170:171], v[156:157]
	v_addc_co_u32_e32 v169, vcc, 0, v167, vcc
	global_store_dwordx4 v[166:167], v[162:165], off
	global_store_dwordx4 v[168:169], v[154:157], off offset:2048
	v_cndmask_b32_e64 v171, v97, v89, s[4:5]
	v_pk_add_f32 v[164:165], v[174:175], v[160:161]
	v_pk_add_f32 v[162:163], v[172:173], v[158:159]
	v_pk_add_f32 v[156:157], v[178:179], v[160:161]
	v_pk_add_f32 v[154:155], v[176:177], v[158:159]
	global_store_dwordx4 v[166:167], v[162:165], off offset:512
	global_store_dwordx4 v[168:169], v[154:157], off offset:2560
	ds_read_b128 v[154:157], v144 offset:16
	ds_read_b128 v[158:161], v144 offset:656
	v_cndmask_b32_e64 v165, v93, v85, s[4:5]
	v_cndmask_b32_e64 v164, v92, v84, s[4:5]
	v_cndmask_b32_e64 v163, v91, v83, s[4:5]
	v_cndmask_b32_e64 v162, v90, v82, s[4:5]
	v_cndmask_b32_e64 v170, v96, v88, s[4:5]
	v_cndmask_b32_e64 v173, v95, v87, s[4:5]
	v_cndmask_b32_e64 v172, v94, v86, s[4:5]
	v_cndmask_b32_e64 v175, v77, v69, s[4:5]
	v_cndmask_b32_e64 v174, v76, v68, s[4:5]
	v_cndmask_b32_e64 v177, v75, v67, s[4:5]
	v_cndmask_b32_e64 v176, v74, v66, s[4:5]
	v_cndmask_b32_e64 v179, v81, v73, s[4:5]
	v_cndmask_b32_e64 v178, v80, v72, s[4:5]
	v_cndmask_b32_e64 v183, v79, v71, s[4:5]
	v_cndmask_b32_e64 v182, v78, v70, s[4:5]
	s_waitcnt lgkmcnt(0)
	v_pk_add_f32 v[162:163], v[162:163], v[154:155]
	v_pk_add_f32 v[164:165], v[164:165], v[156:157]
	v_pk_add_f32 v[154:155], v[172:173], v[154:155]
	v_pk_add_f32 v[156:157], v[170:171], v[156:157]
	global_store_dwordx4 v[166:167], v[162:165], off offset:16
	global_store_dwordx4 v[168:169], v[154:157], off offset:2064
	s_nop 0
	v_pk_add_f32 v[162:163], v[176:177], v[158:159]
	v_pk_add_f32 v[164:165], v[174:175], v[160:161]
	v_pk_add_f32 v[154:155], v[182:183], v[158:159]
	v_pk_add_f32 v[156:157], v[178:179], v[160:161]
	global_store_dwordx4 v[166:167], v[162:165], off offset:528
	global_store_dwordx4 v[168:169], v[154:157], off offset:2576
.LBB0_779:
	s_or_b64 exec, exec, s[8:9]
	ds_read2_b64 v[154:157], v144 offset1:16
	ds_read2_b64 v[158:161], v144 offset0:32 offset1:48
	ds_read2_b64 v[162:165], v144 offset0:64 offset1:80
	ds_read2_b64 v[166:169], v144 offset0:96 offset1:112
	ds_read2_b64 v[170:173], v144 offset0:128 offset1:144
	s_waitcnt lgkmcnt(0)
; #define LAS __attribute__((address_space(3)))
;     __device__ __forceinline__ void operator()(const f32x4 (&acc)[2][2][4][2], const Unit& u, int wr_in, int wc_in, int fr_in, int fq_in) const {
;     ...
;                 for (int ep = 0; ep < 2; ++ep) {
;                     const int e0 = 2 * ep; const LAS float* pc = P + 8 * fq + 4 * n + e0;
;                     const f32x2 bua = *(const LAS f32x2*)(pc), w0a = *(const LAS f32x2*)(pc + 32), w1a = *(const LAS f32x2*)(pc + 64), w2a = *(const LAS f32x2*)(pc + 96), cba = *(const LAS f32x2*)(pc + 128);
;                     const f32x2 bug = *(const LAS f32x2*)(pc + 160), w0g = *(const LAS f32x2*)(pc + 192), w1g = *(const LAS f32x2*)(pc + 224), w2g = *(const LAS f32x2*)(pc + 256), cbg = *(const LAS f32x2*)(pc + 288);
;                     f32x2 av[4];
;                     {
;                         f32x2 x[4], pv, nv;
; #pragma unroll
;                         for (int m = 0; m < 4; ++m) { x[m].x = acc[ai][0][m][n][e0]; x[m].y = acc[ai][0][m][n][e0 + 1]; x[m] = x[m] + bua; }
;                         pv.x = dpp_shr1(x[3].x); pv.y = dpp_shr1(x[3].y); nv.x = dpp_shl1(x[0].x); nv.y = dpp_shl1(x[0].y);
;                         av[0] = w0a * pv + w1a * x[0] + w2a * x[1] + cba;
;                         av[1] = w0a * x[0] + w1a * x[1] + w2a * x[2] + cba;
;                         av[2] = w0a * x[1] + w1a * x[2] + w2a * x[3] + cba;
;                         av[3] = w0a * x[2] + w1a * x[3] + w2a * nv + cba;
;                     }
;                     {
;                         f32x2 x[4], pv, nv, gv[4];
; #pragma unroll
;                         for (int m = 0; m < 4; ++m) { x[m].x = acc[ai][1][m][n][e0]; x[m].y = acc[ai][1][m][n][e0 + 1]; x[m] = x[m] + bug; }
;                         pv.x = dpp_shr1(x[3].x); pv.y = dpp_shr1(x[3].y); nv.x = dpp_shl1(x[0].x); nv.y = dpp_shl1(x[0].y);
;                         gv[0] = w0g * pv + w1g * x[0] + w2g * x[1] + cbg;
;                         gv[1] = w0g * x[0] + w1g * x[1] + w2g * x[2] + cbg;
;                         gv[2] = w0g * x[1] + w1g * x[2] + w2g * x[3] + cbg;
;                         gv[3] = w0g * x[2] + w1g * x[3] + w2g * nv + cbg;
; #pragma unroll
;                         for (int m = 0; m < 4; ++m) {
;                             const f32x2 t = gv[m] * (-LOG2E);
	v_pk_add_f32 v[114:115], v[114:115], v[154:155]
	v_pk_add_f32 v[126:127], v[126:127], v[154:155]
	v_pk_add_f32 v[122:123], v[122:123], v[154:155]
	v_pk_add_f32 v[118:119], v[118:119], v[154:155]
	v_mov_b32_dpp v154, v114 row_shr:1 row_mask:0xf bank_mask:0xf bound_ctrl:1
	v_mov_b32_dpp v155, v115 row_shr:1 row_mask:0xf bank_mask:0xf bound_ctrl:1
	v_pk_mul_f32 v[154:155], v[156:157], v[154:155]
	v_pk_mul_f32 v[176:177], v[122:123], v[158:159]
	v_mov_b32_dpp v174, v126 row_shl:1 row_mask:0xf bank_mask:0xf bound_ctrl:1
	v_mov_b32_dpp v175, v127 row_shl:1 row_mask:0xf bank_mask:0xf bound_ctrl:1
	v_pk_fma_f32 v[154:155], v[126:127], v[158:159], v[154:155]
	v_pk_fma_f32 v[126:127], v[156:157], v[126:127], v[176:177]
	v_pk_mul_f32 v[176:177], v[118:119], v[158:159]
	v_pk_fma_f32 v[154:155], v[122:123], v[160:161], v[154:155]
	v_pk_fma_f32 v[122:123], v[156:157], v[122:123], v[176:177]
	v_pk_add_f32 v[98:99], v[98:99], v[164:165]
	v_pk_fma_f32 v[122:123], v[114:115], v[160:161], v[122:123]
	v_pk_mul_f32 v[114:115], v[114:115], v[158:159]
	v_pk_fma_f32 v[126:127], v[118:119], v[160:161], v[126:127]
	v_pk_fma_f32 v[114:115], v[156:157], v[118:119], v[114:115]
	v_pk_add_f32 v[106:107], v[106:107], v[164:165]
	v_pk_add_f32 v[118:119], v[162:163], v[154:155]
	v_mov_b32_dpp v154, v98 row_shr:1 row_mask:0xf bank_mask:0xf bound_ctrl:1
	v_mov_b32_dpp v155, v99 row_shr:1 row_mask:0xf bank_mask:0xf bound_ctrl:1
	v_pk_add_f32 v[110:111], v[110:111], v[164:165]
	v_pk_add_f32 v[102:103], v[102:103], v[164:165]
	v_pk_mul_f32 v[154:155], v[166:167], v[154:155]
	v_pk_mul_f32 v[158:159], v[106:107], v[168:169]
	v_mov_b32_dpp v156, v110 row_shl:1 row_mask:0xf bank_mask:0xf bound_ctrl:1
	v_mov_b32_dpp v157, v111 row_shl:1 row_mask:0xf bank_mask:0xf bound_ctrl:1
	v_pk_fma_f32 v[154:155], v[110:111], v[168:169], v[154:155]
	v_pk_fma_f32 v[110:111], v[166:167], v[110:111], v[158:159]
	v_pk_mul_f32 v[158:159], v[102:103], v[168:169]
	s_lshl_b32 s8, s98, 8
	s_lshl_b32 s9, s27, 6
	v_pk_fma_f32 v[154:155], v[106:107], v[170:171], v[154:155]
	v_pk_fma_f32 v[106:107], v[166:167], v[106:107], v[158:159]
	s_add_i32 s9, s9, s8
	v_pk_add_f32 v[154:155], v[172:173], v[154:155]
	v_pk_fma_f32 v[106:107], v[98:99], v[170:171], v[106:107]
	v_pk_mul_f32 v[98:99], v[98:99], v[168:169]
	s_mov_b32 s8, 0xbfb8aa3b
	v_pk_fma_f32 v[110:111], v[102:103], v[170:171], v[110:111]
	v_pk_fma_f32 v[98:99], v[166:167], v[102:103], v[98:99]
	v_pk_mul_f32 v[102:103], v[154:155], s[8:9] op_sel_hi:[1,0]
	v_pk_add_f32 v[158:159], v[172:173], v[106:107]
	v_exp_f32_e32 v106, v102
	v_exp_f32_e32 v107, v103
	v_pk_fma_f32 v[98:99], v[170:171], v[156:157], v[98:99]
	v_pk_add_f32 v[110:111], v[172:173], v[110:111]
	v_pk_add_f32 v[102:103], v[172:173], v[98:99]
	v_add_f32_e32 v98, 1.0, v106
	v_add_f32_e32 v99, 1.0, v107
	v_rcp_f32_e32 v98, v98
	v_rcp_f32_e32 v99, v99
	v_pk_mul_f32 v[106:107], v[118:119], v[154:155]
	v_pk_mul_f32 v[118:119], v[110:111], s[8:9] op_sel_hi:[1,0]
	v_pk_add_f32 v[126:127], v[162:163], v[126:127]
	v_exp_f32_e32 v118, v118
	v_pk_mul_f32 v[98:99], v[106:107], v[98:99]
	v_exp_f32_e32 v107, v119
	v_cvt_pk_bf16_f32 v106, v98, v99
	v_add_f32_e32 v98, 1.0, v118
	v_rcp_f32_e32 v98, v98
	v_add_f32_e32 v99, 1.0, v107
	v_rcp_f32_e32 v99, v99
	v_pk_mul_f32 v[118:119], v[158:159], s[8:9] op_sel_hi:[1,0]
	v_pk_mul_f32 v[110:111], v[126:127], v[110:111]
	v_exp_f32_e32 v107, v118
	v_pk_mul_f32 v[98:99], v[110:111], v[98:99]
	v_exp_f32_e32 v111, v119
	v_cvt_pk_bf16_f32 v98, v98, v99
	v_add_f32_e32 v99, 1.0, v107
	v_rcp_f32_e32 v110, v99
	v_add_f32_e32 v99, 1.0, v111
	v_pk_mul_f32 v[118:119], v[102:103], s[8:9] op_sel_hi:[1,0]
	v_rcp_f32_e32 v111, v99
	v_exp_f32_e32 v107, v118
	v_exp_f32_e32 v99, v119
	v_pk_add_f32 v[122:123], v[162:163], v[122:123]
	v_pk_fma_f32 v[114:115], v[160:161], v[174:175], v[114:115]
	v_add_f32_e32 v107, 1.0, v107
	v_add_f32_e32 v99, 1.0, v99
	v_pk_mul_f32 v[118:119], v[122:123], v[158:159]
	v_rcp_f32_e32 v122, v107
	v_rcp_f32_e32 v123, v99
	v_pk_add_f32 v[114:115], v[162:163], v[114:115]
	v_lshl_add_u32 v145, v151, 2, s9
	v_pk_mul_f32 v[102:103], v[114:115], v[102:103]
	v_ashrrev_i32_e32 v141, 31, v140
	v_pk_mul_f32 v[110:111], v[118:119], v[110:111]
	v_pk_mul_f32 v[102:103], v[102:103], v[122:123]
	v_cvt_pk_bf16_f32 v110, v110, v111
	s_nop 0
	v_cvt_pk_bf16_f32 v102, v102, v103
	ds_read2_b64 v[154:157], v144 offset0:1 offset1:17
	ds_read2_b64 v[158:161], v144 offset0:33 offset1:49
	ds_read2_b64 v[162:165], v144 offset0:65 offset1:81
	ds_read2_b64 v[166:169], v144 offset0:97 offset1:113
	ds_read2_b64 v[170:173], v144 offset0:129 offset1:145
	s_waitcnt lgkmcnt(0)
; #define LAS __attribute__((address_space(3)))
;     __device__ __forceinline__ void operator()(const f32x4 (&acc)[2][2][4][2], const Unit& u, int wr_in, int wc_in, int fr_in, int fq_in) const {
;     ...
;                 for (int ep = 0; ep < 2; ++ep) {
;                     const int e0 = 2 * ep; const LAS float* pc = P + 8 * fq + 4 * n + e0;
;                     const f32x2 bua = *(const LAS f32x2*)(pc), w0a = *(const LAS f32x2*)(pc + 32), w1a = *(const LAS f32x2*)(pc + 64), w2a = *(const LAS f32x2*)(pc + 96), cba = *(const LAS f32x2*)(pc + 128);
;                     const f32x2 bug = *(const LAS f32x2*)(pc + 160), w0g = *(const LAS f32x2*)(pc + 192), w1g = *(const LAS f32x2*)(pc + 224), w2g = *(const LAS f32x2*)(pc + 256), cbg = *(const LAS f32x2*)(pc + 288);
;                     f32x2 av[4];
;                     {
;                         f32x2 x[4], pv, nv;
; #pragma unroll
;                         for (int m = 0; m < 4; ++m) { x[m].x = acc[ai][0][m][n][e0]; x[m].y = acc[ai][0][m][n][e0 + 1]; x[m] = x[m] + bua; }
;                         pv.x = dpp_shr1(x[3].x); pv.y = dpp_shr1(x[3].y); nv.x = dpp_shl1(x[0].x); nv.y = dpp_shl1(x[0].y);
;                         av[0] = w0a * pv + w1a * x[0] + w2a * x[1] + cba;
;                         av[1] = w0a * x[0] + w1a * x[1] + w2a * x[2] + cba;
;                         av[2] = w0a * x[1] + w1a * x[2] + w2a * x[3] + cba;
;                         av[3] = w0a * x[2] + w1a * x[3] + w2a * nv + cba;
;                     }
;                     {
;                         f32x2 x[4], pv, nv, gv[4];
; #pragma unroll
;                         for (int m = 0; m < 4; ++m) { x[m].x = acc[ai][1][m][n][e0]; x[m].y = acc[ai][1][m][n][e0 + 1]; x[m] = x[m] + bug; }
;                         pv.x = dpp_shr1(x[3].x); pv.y = dpp_shr1(x[3].y); nv.x = dpp_shl1(x[0].x); nv.y = dpp_shl1(x[0].y);
;                         gv[0] = w0g * pv + w1g * x[0] + w2g * x[1] + cbg;
;                         gv[1] = w0g * x[0] + w1g * x[1] + w2g * x[2] + cbg;
;                         gv[2] = w0g * x[1] + w1g * x[2] + w2g * x[3] + cbg;
;                         gv[3] = w0g * x[2] + w1g * x[3] + w2g * nv + cbg;
; #pragma unroll
;                         for (int m = 0; m < 4; ++m) {
;                             const f32x2 t = gv[m] * (-LOG2E);
	v_pk_add_f32 v[116:117], v[116:117], v[154:155]
	v_pk_add_f32 v[118:119], v[124:125], v[154:155]
	v_pk_add_f32 v[114:115], v[128:129], v[154:155]
	v_mov_b32_dpp v122, v116 row_shr:1 row_mask:0xf bank_mask:0xf bound_ctrl:1
	v_mov_b32_dpp v123, v117 row_shr:1 row_mask:0xf bank_mask:0xf bound_ctrl:1
	v_pk_add_f32 v[120:121], v[120:121], v[154:155]
	v_pk_mul_f32 v[122:123], v[156:157], v[122:123]
	v_pk_mul_f32 v[126:127], v[118:119], v[158:159]
	v_mov_b32_dpp v124, v114 row_shl:1 row_mask:0xf bank_mask:0xf bound_ctrl:1
	v_mov_b32_dpp v125, v115 row_shl:1 row_mask:0xf bank_mask:0xf bound_ctrl:1
	v_pk_fma_f32 v[122:123], v[114:115], v[158:159], v[122:123]
	v_pk_fma_f32 v[114:115], v[156:157], v[114:115], v[126:127]
	v_pk_mul_f32 v[126:127], v[120:121], v[158:159]
	v_pk_fma_f32 v[122:123], v[118:119], v[160:161], v[122:123]
	v_pk_fma_f32 v[118:119], v[156:157], v[118:119], v[126:127]
	v_pk_add_f32 v[100:101], v[100:101], v[164:165]
	v_pk_fma_f32 v[118:119], v[116:117], v[160:161], v[118:119]
	v_pk_mul_f32 v[116:117], v[116:117], v[158:159]
	v_pk_fma_f32 v[114:115], v[120:121], v[160:161], v[114:115]
	v_pk_fma_f32 v[116:117], v[156:157], v[120:121], v[116:117]
	v_pk_add_f32 v[108:109], v[108:109], v[164:165]
	v_pk_add_f32 v[120:121], v[162:163], v[122:123]
	v_mov_b32_dpp v122, v100 row_shr:1 row_mask:0xf bank_mask:0xf bound_ctrl:1
	v_mov_b32_dpp v123, v101 row_shr:1 row_mask:0xf bank_mask:0xf bound_ctrl:1
	v_pk_add_f32 v[112:113], v[112:113], v[164:165]
	v_pk_add_f32 v[104:105], v[104:105], v[164:165]
	v_pk_mul_f32 v[122:123], v[166:167], v[122:123]
	v_pk_mul_f32 v[126:127], v[108:109], v[168:169]
	v_pk_fma_f32 v[116:117], v[160:161], v[124:125], v[116:117]
	v_mov_b32_dpp v124, v112 row_shl:1 row_mask:0xf bank_mask:0xf bound_ctrl:1
	v_mov_b32_dpp v125, v113 row_shl:1 row_mask:0xf bank_mask:0xf bound_ctrl:1
	v_pk_fma_f32 v[122:123], v[112:113], v[168:169], v[122:123]
	v_pk_fma_f32 v[112:113], v[166:167], v[112:113], v[126:127]
	v_pk_mul_f32 v[126:127], v[104:105], v[168:169]
	v_pk_fma_f32 v[122:123], v[108:109], v[170:171], v[122:123]
	v_pk_fma_f32 v[108:109], v[166:167], v[108:109], v[126:127]
	v_pk_add_f32 v[122:123], v[172:173], v[122:123]
	v_pk_fma_f32 v[108:109], v[100:101], v[170:171], v[108:109]
	v_pk_mul_f32 v[100:101], v[100:101], v[168:169]
	v_pk_fma_f32 v[112:113], v[104:105], v[170:171], v[112:113]
	v_pk_fma_f32 v[100:101], v[166:167], v[104:105], v[100:101]
	v_pk_mul_f32 v[104:105], v[122:123], s[8:9] op_sel_hi:[1,0]
	v_pk_add_f32 v[112:113], v[172:173], v[112:113]
	v_exp_f32_e32 v99, v104
	v_exp_f32_e32 v103, v105
	v_pk_mul_f32 v[120:121], v[120:121], v[122:123]
	v_pk_mul_f32 v[122:123], v[112:113], s[8:9] op_sel_hi:[1,0]
	v_add_f32_e32 v99, 1.0, v99
	v_rcp_f32_e32 v104, v99
	v_add_f32_e32 v99, 1.0, v103
	v_rcp_f32_e32 v105, v99
	v_exp_f32_e32 v99, v122
	v_exp_f32_e32 v103, v123
	v_pk_add_f32 v[114:115], v[162:163], v[114:115]
	v_pk_add_f32 v[108:109], v[172:173], v[108:109]
	v_pk_mul_f32 v[104:105], v[120:121], v[104:105]
	v_add_f32_e32 v99, 1.0, v99
	v_cvt_pk_bf16_f32 v107, v104, v105
	v_rcp_f32_e32 v104, v99
	v_add_f32_e32 v99, 1.0, v103
	v_pk_mul_f32 v[112:113], v[114:115], v[112:113]
	v_pk_mul_f32 v[114:115], v[108:109], s[8:9] op_sel_hi:[1,0]
	v_rcp_f32_e32 v105, v99
	v_exp_f32_e32 v103, v114
	v_exp_f32_e32 v111, v115
	v_pk_fma_f32 v[100:101], v[170:171], v[124:125], v[100:101]
	v_pk_mul_f32 v[104:105], v[112:113], v[104:105]
	v_pk_add_f32 v[100:101], v[172:173], v[100:101]
	v_add_f32_e32 v103, 1.0, v103
	v_cvt_pk_bf16_f32 v99, v104, v105
	v_rcp_f32_e32 v104, v103
	v_add_f32_e32 v103, 1.0, v111
	v_pk_mul_f32 v[112:113], v[100:101], s[8:9] op_sel_hi:[1,0]
	v_rcp_f32_e32 v105, v103
	v_exp_f32_e32 v111, v112
	v_exp_f32_e32 v103, v113
	v_pk_add_f32 v[118:119], v[162:163], v[118:119]
	v_pk_add_f32 v[116:117], v[162:163], v[116:117]
	v_add_f32_e32 v111, 1.0, v111
	v_add_f32_e32 v103, 1.0, v103
	v_rcp_f32_e32 v112, v111
	v_rcp_f32_e32 v113, v103
	v_pk_mul_f32 v[108:109], v[118:119], v[108:109]
	v_pk_mul_f32 v[100:101], v[116:117], v[100:101]
	v_pk_mul_f32 v[104:105], v[108:109], v[104:105]
	v_pk_mul_f32 v[100:101], v[100:101], v[112:113]
	v_cvt_pk_bf16_f32 v111, v104, v105
	s_nop 0
	v_cvt_pk_bf16_f32 v103, v100, v101
	ds_read2_b64 v[112:115], v144 offset0:2 offset1:18
	ds_read2_b64 v[116:119], v144 offset0:34 offset1:50
	ds_read2_b64 v[120:123], v144 offset0:66 offset1:82
	ds_read2_b64 v[124:127], v144 offset0:98 offset1:114
	ds_read2_b64 v[154:157], v144 offset0:130 offset1:146
	s_waitcnt lgkmcnt(0)
; #define LAS __attribute__((address_space(3)))
;     __device__ __forceinline__ void operator()(const f32x4 (&acc)[2][2][4][2], const Unit& u, int wr_in, int wc_in, int fr_in, int fq_in) const {
;     ...
;                 for (int ep = 0; ep < 2; ++ep) {
;                     const int e0 = 2 * ep; const LAS float* pc = P + 8 * fq + 4 * n + e0;
;                     const f32x2 bua = *(const LAS f32x2*)(pc), w0a = *(const LAS f32x2*)(pc + 32), w1a = *(const LAS f32x2*)(pc + 64), w2a = *(const LAS f32x2*)(pc + 96), cba = *(const LAS f32x2*)(pc + 128);
;                     const f32x2 bug = *(const LAS f32x2*)(pc + 160), w0g = *(const LAS f32x2*)(pc + 192), w1g = *(const LAS f32x2*)(pc + 224), w2g = *(const LAS f32x2*)(pc + 256), cbg = *(const LAS f32x2*)(pc + 288);
;                     f32x2 av[4];
;                     {
;                         f32x2 x[4], pv, nv;
; #pragma unroll
;                         for (int m = 0; m < 4; ++m) { x[m].x = acc[ai][0][m][n][e0]; x[m].y = acc[ai][0][m][n][e0 + 1]; x[m] = x[m] + bua; }
;                         pv.x = dpp_shr1(x[3].x); pv.y = dpp_shr1(x[3].y); nv.x = dpp_shl1(x[0].x); nv.y = dpp_shl1(x[0].y);
;                         av[0] = w0a * pv + w1a * x[0] + w2a * x[1] + cba;
;                         av[1] = w0a * x[0] + w1a * x[1] + w2a * x[2] + cba;
;                         av[2] = w0a * x[1] + w1a * x[2] + w2a * x[3] + cba;
;                         av[3] = w0a * x[2] + w1a * x[3] + w2a * nv + cba;
;                     }
;                     {
;                         f32x2 x[4], pv, nv, gv[4];
; #pragma unroll
;                         for (int m = 0; m < 4; ++m) { x[m].x = acc[ai][1][m][n][e0]; x[m].y = acc[ai][1][m][n][e0 + 1]; x[m] = x[m] + bug; }
;                         pv.x = dpp_shr1(x[3].x); pv.y = dpp_shr1(x[3].y); nv.x = dpp_shl1(x[0].x); nv.y = dpp_shl1(x[0].y);
;                         gv[0] = w0g * pv + w1g * x[0] + w2g * x[1] + cbg;
;                         gv[1] = w0g * x[0] + w1g * x[1] + w2g * x[2] + cbg;
;                         gv[2] = w0g * x[1] + w1g * x[2] + w2g * x[3] + cbg;
;                         gv[3] = w0g * x[2] + w1g * x[3] + w2g * nv + cbg;
; #pragma unroll
;                         for (int m = 0; m < 4; ++m) {
;                             const f32x2 t = gv[m] * (-LOG2E);
	v_pk_add_f32 v[94:95], v[94:95], v[112:113]
	v_pk_add_f32 v[86:87], v[86:87], v[112:113]
	v_pk_add_f32 v[82:83], v[82:83], v[112:113]
	v_mov_b32_dpp v100, v94 row_shr:1 row_mask:0xf bank_mask:0xf bound_ctrl:1
	v_mov_b32_dpp v101, v95 row_shr:1 row_mask:0xf bank_mask:0xf bound_ctrl:1
	v_pk_add_f32 v[90:91], v[90:91], v[112:113]
	v_pk_mul_f32 v[100:101], v[114:115], v[100:101]
	v_pk_mul_f32 v[108:109], v[86:87], v[116:117]
	v_mov_b32_dpp v104, v82 row_shl:1 row_mask:0xf bank_mask:0xf bound_ctrl:1
	v_mov_b32_dpp v105, v83 row_shl:1 row_mask:0xf bank_mask:0xf bound_ctrl:1
	v_pk_fma_f32 v[100:101], v[82:83], v[116:117], v[100:101]
	v_pk_fma_f32 v[82:83], v[114:115], v[82:83], v[108:109]
	v_pk_mul_f32 v[108:109], v[90:91], v[116:117]
	v_pk_fma_f32 v[100:101], v[86:87], v[118:119], v[100:101]
	v_pk_fma_f32 v[86:87], v[114:115], v[86:87], v[108:109]
	v_pk_add_f32 v[78:79], v[78:79], v[122:123]
	v_pk_fma_f32 v[86:87], v[94:95], v[118:119], v[86:87]
	v_pk_mul_f32 v[94:95], v[94:95], v[116:117]
	v_pk_fma_f32 v[82:83], v[90:91], v[118:119], v[82:83]
	v_pk_fma_f32 v[90:91], v[114:115], v[90:91], v[94:95]
	v_pk_add_f32 v[70:71], v[70:71], v[122:123]
	v_pk_add_f32 v[94:95], v[120:121], v[100:101]
	v_mov_b32_dpp v100, v78 row_shr:1 row_mask:0xf bank_mask:0xf bound_ctrl:1
	v_mov_b32_dpp v101, v79 row_shr:1 row_mask:0xf bank_mask:0xf bound_ctrl:1
	v_pk_add_f32 v[66:67], v[66:67], v[122:123]
	v_pk_add_f32 v[74:75], v[74:75], v[122:123]
	v_pk_mul_f32 v[100:101], v[124:125], v[100:101]
	v_pk_mul_f32 v[108:109], v[70:71], v[126:127]
	v_pk_fma_f32 v[90:91], v[118:119], v[104:105], v[90:91]
	v_mov_b32_dpp v104, v66 row_shl:1 row_mask:0xf bank_mask:0xf bound_ctrl:1
	v_mov_b32_dpp v105, v67 row_shl:1 row_mask:0xf bank_mask:0xf bound_ctrl:1
	v_pk_fma_f32 v[100:101], v[66:67], v[126:127], v[100:101]
	v_pk_fma_f32 v[66:67], v[124:125], v[66:67], v[108:109]
	v_pk_mul_f32 v[108:109], v[74:75], v[126:127]
	v_pk_fma_f32 v[100:101], v[70:71], v[154:155], v[100:101]
	v_pk_fma_f32 v[70:71], v[124:125], v[70:71], v[108:109]
	v_pk_add_f32 v[100:101], v[156:157], v[100:101]
	v_pk_fma_f32 v[70:71], v[78:79], v[154:155], v[70:71]
	v_pk_mul_f32 v[78:79], v[78:79], v[126:127]
	v_pk_fma_f32 v[66:67], v[74:75], v[154:155], v[66:67]
	v_pk_fma_f32 v[74:75], v[124:125], v[74:75], v[78:79]
	v_pk_mul_f32 v[78:79], v[100:101], s[8:9] op_sel_hi:[1,0]
	v_pk_add_f32 v[66:67], v[156:157], v[66:67]
	v_exp_f32_e32 v78, v78
	v_exp_f32_e32 v79, v79
	v_pk_mul_f32 v[94:95], v[94:95], v[100:101]
	v_pk_mul_f32 v[100:101], v[66:67], s[8:9] op_sel_hi:[1,0]
	v_add_f32_e32 v78, 1.0, v78
	v_add_f32_e32 v79, 1.0, v79
	v_rcp_f32_e32 v78, v78
	v_rcp_f32_e32 v79, v79
	v_exp_f32_e32 v100, v100
	v_pk_add_f32 v[82:83], v[120:121], v[82:83]
	v_pk_add_f32 v[70:71], v[156:157], v[70:71]
	v_pk_mul_f32 v[78:79], v[94:95], v[78:79]
	v_exp_f32_e32 v94, v101
	v_cvt_pk_bf16_f32 v108, v78, v79
	v_add_f32_e32 v78, 1.0, v100
	v_rcp_f32_e32 v78, v78
	v_add_f32_e32 v79, 1.0, v94
	v_rcp_f32_e32 v79, v79
	v_pk_mul_f32 v[66:67], v[82:83], v[66:67]
	v_pk_mul_f32 v[82:83], v[70:71], s[8:9] op_sel_hi:[1,0]
	v_pk_fma_f32 v[74:75], v[154:155], v[104:105], v[74:75]
	v_pk_mul_f32 v[66:67], v[66:67], v[78:79]
	v_exp_f32_e32 v78, v83
	v_pk_add_f32 v[74:75], v[156:157], v[74:75]
	v_exp_f32_e32 v82, v82
	v_cvt_pk_bf16_f32 v100, v66, v67
	v_add_f32_e32 v67, 1.0, v78
	v_pk_mul_f32 v[78:79], v[74:75], s[8:9] op_sel_hi:[1,0]
	v_add_f32_e32 v66, 1.0, v82
	v_exp_f32_e32 v78, v78
	v_exp_f32_e32 v79, v79
	v_rcp_f32_e32 v66, v66
	v_rcp_f32_e32 v67, v67
	v_add_f32_e32 v78, 1.0, v78
	v_add_f32_e32 v79, 1.0, v79
	v_pk_add_f32 v[86:87], v[120:121], v[86:87]
	v_rcp_f32_e32 v78, v78
	v_rcp_f32_e32 v79, v79
	v_pk_mul_f32 v[70:71], v[86:87], v[70:71]
	v_pk_add_f32 v[90:91], v[120:121], v[90:91]
	v_pk_mul_f32 v[66:67], v[70:71], v[66:67]
	s_nop 0
	v_cvt_pk_bf16_f32 v112, v66, v67
	v_pk_mul_f32 v[66:67], v[90:91], v[74:75]
	s_nop 0
	v_pk_mul_f32 v[66:67], v[66:67], v[78:79]
	s_nop 0
	v_cvt_pk_bf16_f32 v104, v66, v67
	ds_read2_b64 v[114:117], v144 offset0:3 offset1:19
	ds_read2_b64 v[118:121], v144 offset0:35 offset1:51
	ds_read2_b64 v[122:125], v144 offset0:67 offset1:83
	ds_read2_b64 v[126:129], v144 offset0:99 offset1:115
	ds_read2_b64 v[154:157], v144 offset0:131 offset1:147
	s_waitcnt lgkmcnt(0)
; #define LAS __attribute__((address_space(3)))
;     __device__ __forceinline__ void operator()(const f32x4 (&acc)[2][2][4][2], const Unit& u, int wr_in, int wc_in, int fr_in, int fq_in) const {
;     ...
;                 for (int ep = 0; ep < 2; ++ep) {
;                     const int e0 = 2 * ep; const LAS float* pc = P + 8 * fq + 4 * n + e0;
;                     const f32x2 bua = *(const LAS f32x2*)(pc), w0a = *(const LAS f32x2*)(pc + 32), w1a = *(const LAS f32x2*)(pc + 64), w2a = *(const LAS f32x2*)(pc + 96), cba = *(const LAS f32x2*)(pc + 128);
;                     const f32x2 bug = *(const LAS f32x2*)(pc + 160), w0g = *(const LAS f32x2*)(pc + 192), w1g = *(const LAS f32x2*)(pc + 224), w2g = *(const LAS f32x2*)(pc + 256), cbg = *(const LAS f32x2*)(pc + 288);
;                     f32x2 av[4];
;                     {
;                         f32x2 x[4], pv, nv;
; #pragma unroll
;                         for (int m = 0; m < 4; ++m) { x[m].x = acc[ai][0][m][n][e0]; x[m].y = acc[ai][0][m][n][e0 + 1]; x[m] = x[m] + bua; }
;                         pv.x = dpp_shr1(x[3].x); pv.y = dpp_shr1(x[3].y); nv.x = dpp_shl1(x[0].x); nv.y = dpp_shl1(x[0].y);
;                         av[0] = w0a * pv + w1a * x[0] + w2a * x[1] + cba;
;                         av[1] = w0a * x[0] + w1a * x[1] + w2a * x[2] + cba;
;                         av[2] = w0a * x[1] + w1a * x[2] + w2a * x[3] + cba;
;                         av[3] = w0a * x[2] + w1a * x[3] + w2a * nv + cba;
;                     }
;                     {
;                         f32x2 x[4], pv, nv, gv[4];
; #pragma unroll
;                         for (int m = 0; m < 4; ++m) { x[m].x = acc[ai][1][m][n][e0]; x[m].y = acc[ai][1][m][n][e0 + 1]; x[m] = x[m] + bug; }
;                         pv.x = dpp_shr1(x[3].x); pv.y = dpp_shr1(x[3].y); nv.x = dpp_shl1(x[0].x); nv.y = dpp_shl1(x[0].y);
;                         gv[0] = w0g * pv + w1g * x[0] + w2g * x[1] + cbg;
;                         gv[1] = w0g * x[0] + w1g * x[1] + w2g * x[2] + cbg;
;                         gv[2] = w0g * x[1] + w1g * x[2] + w2g * x[3] + cbg;
;                         gv[3] = w0g * x[2] + w1g * x[3] + w2g * nv + cbg;
; #pragma unroll
;                         for (int m = 0; m < 4; ++m) {
;                             const f32x2 t = gv[m] * (-LOG2E);
	v_pk_add_f32 v[78:79], v[96:97], v[114:115]
	v_pk_add_f32 v[70:71], v[88:89], v[114:115]
	v_pk_add_f32 v[66:67], v[84:85], v[114:115]
	v_mov_b32_dpp v82, v78 row_shr:1 row_mask:0xf bank_mask:0xf bound_ctrl:1
	v_mov_b32_dpp v83, v79 row_shr:1 row_mask:0xf bank_mask:0xf bound_ctrl:1
	v_pk_add_f32 v[74:75], v[92:93], v[114:115]
	v_pk_mul_f32 v[82:83], v[116:117], v[82:83]
	v_pk_mul_f32 v[86:87], v[70:71], v[118:119]
	v_mov_b32_dpp v84, v66 row_shl:1 row_mask:0xf bank_mask:0xf bound_ctrl:1
	v_mov_b32_dpp v85, v67 row_shl:1 row_mask:0xf bank_mask:0xf bound_ctrl:1
	v_pk_fma_f32 v[82:83], v[66:67], v[118:119], v[82:83]
	v_pk_fma_f32 v[66:67], v[116:117], v[66:67], v[86:87]
	v_pk_mul_f32 v[86:87], v[74:75], v[118:119]
	v_pk_fma_f32 v[82:83], v[70:71], v[120:121], v[82:83]
	v_pk_fma_f32 v[70:71], v[116:117], v[70:71], v[86:87]
	v_pk_fma_f32 v[66:67], v[74:75], v[120:121], v[66:67]
	v_pk_fma_f32 v[70:71], v[78:79], v[120:121], v[70:71]
	v_pk_mul_f32 v[78:79], v[78:79], v[118:119]
	v_pk_add_f32 v[72:73], v[72:73], v[124:125]
	v_pk_fma_f32 v[74:75], v[116:117], v[74:75], v[78:79]
	v_pk_add_f32 v[78:79], v[80:81], v[124:125]
	v_pk_add_f32 v[80:81], v[122:123], v[82:83]
	v_pk_add_f32 v[68:69], v[68:69], v[124:125]
	v_mov_b32_dpp v82, v78 row_shr:1 row_mask:0xf bank_mask:0xf bound_ctrl:1
	v_mov_b32_dpp v83, v79 row_shr:1 row_mask:0xf bank_mask:0xf bound_ctrl:1
	v_pk_add_f32 v[76:77], v[76:77], v[124:125]
	v_pk_mul_f32 v[82:83], v[126:127], v[82:83]
	v_pk_mul_f32 v[86:87], v[72:73], v[128:129]
	v_pk_fma_f32 v[74:75], v[120:121], v[84:85], v[74:75]
	v_mov_b32_dpp v84, v68 row_shl:1 row_mask:0xf bank_mask:0xf bound_ctrl:1
	v_mov_b32_dpp v85, v69 row_shl:1 row_mask:0xf bank_mask:0xf bound_ctrl:1
	v_pk_fma_f32 v[82:83], v[68:69], v[128:129], v[82:83]
	v_pk_fma_f32 v[68:69], v[126:127], v[68:69], v[86:87]
	v_pk_mul_f32 v[86:87], v[76:77], v[128:129]
	v_pk_fma_f32 v[82:83], v[72:73], v[154:155], v[82:83]
	v_pk_fma_f32 v[72:73], v[126:127], v[72:73], v[86:87]
	v_pk_add_f32 v[82:83], v[156:157], v[82:83]
	v_pk_fma_f32 v[72:73], v[78:79], v[154:155], v[72:73]
	v_pk_mul_f32 v[78:79], v[78:79], v[128:129]
	v_pk_fma_f32 v[68:69], v[76:77], v[154:155], v[68:69]
	v_pk_fma_f32 v[76:77], v[126:127], v[76:77], v[78:79]
	v_pk_mul_f32 v[78:79], v[82:83], s[8:9] op_sel_hi:[1,0]
	v_pk_add_f32 v[68:69], v[156:157], v[68:69]
	v_exp_f32_e32 v78, v78
	v_exp_f32_e32 v79, v79
	v_pk_mul_f32 v[80:81], v[80:81], v[82:83]
	v_pk_mul_f32 v[82:83], v[68:69], s[8:9] op_sel_hi:[1,0]
	v_add_f32_e32 v78, 1.0, v78
	v_add_f32_e32 v79, 1.0, v79
	v_rcp_f32_e32 v78, v78
	v_rcp_f32_e32 v79, v79
	v_exp_f32_e32 v82, v82
	v_pk_add_f32 v[66:67], v[122:123], v[66:67]
	v_pk_add_f32 v[72:73], v[156:157], v[72:73]
	v_pk_mul_f32 v[78:79], v[80:81], v[78:79]
	v_exp_f32_e32 v80, v83
	v_cvt_pk_bf16_f32 v109, v78, v79
	v_add_f32_e32 v78, 1.0, v82
	v_rcp_f32_e32 v78, v78
	v_add_f32_e32 v79, 1.0, v80
	v_rcp_f32_e32 v79, v79
	v_pk_mul_f32 v[66:67], v[66:67], v[68:69]
	v_pk_mul_f32 v[68:69], v[72:73], s[8:9] op_sel_hi:[1,0]
	v_pk_fma_f32 v[76:77], v[154:155], v[84:85], v[76:77]
	v_exp_f32_e32 v68, v68
	v_exp_f32_e32 v69, v69
	v_pk_add_f32 v[76:77], v[156:157], v[76:77]
	v_pk_mul_f32 v[66:67], v[66:67], v[78:79]
	v_pk_add_f32 v[70:71], v[122:123], v[70:71]
	v_cvt_pk_bf16_f32 v101, v66, v67
	v_add_f32_e32 v66, 1.0, v68
	v_add_f32_e32 v67, 1.0, v69
	v_pk_mul_f32 v[68:69], v[76:77], s[8:9] op_sel_hi:[1,0]
	v_rcp_f32_e32 v66, v66
	v_exp_f32_e32 v78, v68
	v_exp_f32_e32 v79, v69
	v_rcp_f32_e32 v67, v67
	v_pk_mul_f32 v[68:69], v[70:71], v[72:73]
	v_add_f32_e32 v70, 1.0, v78
	v_add_f32_e32 v71, 1.0, v79
	v_rcp_f32_e32 v70, v70
	v_rcp_f32_e32 v71, v71
	v_pk_add_f32 v[74:75], v[122:123], v[74:75]
	v_pk_mul_f32 v[66:67], v[68:69], v[66:67]
	s_nop 0
	v_cvt_pk_bf16_f32 v113, v66, v67
	v_pk_mul_f32 v[66:67], v[74:75], v[76:77]
	s_nop 0
	v_pk_mul_f32 v[66:67], v[66:67], v[70:71]
	s_nop 0
	v_cvt_pk_bf16_f32 v105, v66, v67
	v_readlane_b32 s8, v254, 23
	v_readlane_b32 s9, v254, 24
	s_nop 1
	v_mov_b64_e32 v[66:67], s[8:9]
	s_movk_i32 s8, 0x1600
	v_mad_i64_i32 v[66:67], s[8:9], v145, s8, v[66:67]
	v_lshl_add_u64 v[66:67], v[140:141], 1, v[66:67]
	s_and_saveexec_b64 s[8:9], s[0:1]
	s_cbranch_execz .LBB0_781
	global_store_dwordx4 v[66:67], v[106:109], off
.LBB0_781:
	s_or_b64 exec, exec, s[8:9]
	v_add_co_u32_e32 v68, vcc, 0x1000, v66
	v_cmp_ne_u32_e64 s[8:9], 15, v151
	s_nop 0
	v_addc_co_u32_e32 v69, vcc, 0, v67, vcc
	global_store_dwordx4 v[68:69], v[98:101], off offset:1536
	v_add_co_u32_e32 v68, vcc, 0x2000, v66
	s_nop 1
	v_addc_co_u32_e32 v69, vcc, 0, v67, vcc
	global_store_dwordx4 v[68:69], v[110:113], off offset:3072
	s_and_saveexec_b64 s[48:49], s[8:9]
	s_cbranch_execz .LBB0_783
	v_add_co_u32_e32 v66, vcc, 0x4000, v66
	s_nop 1
	v_addc_co_u32_e32 v67, vcc, 0, v67, vcc
	global_store_dwordx4 v[66:67], v[102:105], off offset:512

; #define LAS __attribute__((address_space(3)))
;     __device__ __forceinline__ void operator()(const f32x4 (&acc)[2][2][4][2], const Unit& u, int wr_in, int wc_in, int fr_in, int fq_in) const {
;     ...
;         for (int ai = 0; ai < 2; ++ai) {
;             if (fr == 0 || fr == 15) {
;                 const int g64 = u.pm * 4 + ai * 2 + wr;
;                 float* hp = halo + ((size_t)(g64 * 4 + (fr ? 2 : 0))) * FF2 + tcol0;
; #pragma unroll
;                 for (int n = 0; n < 2; ++n) {
;                     const f32x4 bua = *(const LAS f32x4*)(P + 8 * fq + 4 * n), bug = *(const LAS f32x4*)(P + 160 + 8 * fq + 4 * n);
;                     const f32x4 a0 = fr ? acc[ai][0][2][n] : acc[ai][0][0][n], a1 = fr ? acc[ai][0][3][n] : acc[ai][0][1][n];
;                     const f32x4 g0 = fr ? acc[ai][1][2][n] : acc[ai][1][0][n], g1 = fr ? acc[ai][1][3][n] : acc[ai][1][1][n];
;                     *(f32x4*)(hp + 4 * n) = a0 + bua; *(f32x4*)(hp + 128 + 4 * n) = g0 + bug;
;                     *(f32x4*)(hp + FF2 + 4 * n) = a1 + bua; *(f32x4*)(hp + FF2 + 128 + 4 * n) = g1 + bug;
;                 }
;             }
;             u32x4 pk[4];
; #pragma unroll
;             for (int n = 0; n < 2; ++n)
; #pragma unroll
;                 for (int ep = 0; ep < 2; ++ep) {
;                     const int e0 = 2 * ep; const LAS float* pc = P + 8 * fq + 4 * n + e0;
;                     const f32x2 bua = *(const LAS f32x2*)(pc), w0a = *(const LAS f32x2*)(pc + 32), w1a = *(const LAS f32x2*)(pc + 64), w2a = *(const LAS f32x2*)(pc + 96), cba = *(const LAS f32x2*)(pc + 128);
;                     const f32x2 bug = *(const LAS f32x2*)(pc + 160), w0g = *(const LAS f32x2*)(pc + 192), w1g = *(const LAS f32x2*)(pc + 224), w2g = *(const LAS f32x2*)(pc + 256), cbg = *(const LAS f32x2*)(pc + 288);
;                     f32x2 av[4];
;                     {
;                         f32x2 x[4], pv, nv;
; #pragma unroll
;                         for (int m = 0; m < 4; ++m) { x[m].x = acc[ai][0][m][n][e0]; x[m].y = acc[ai][0][m][n][e0 + 1]; x[m] = x[m] + bua; }
.LBB0_786:
	s_lshl_b32 s26, s98, 4
	v_add_u32_e32 v66, s26, v152
	v_add_u32_e32 v66, 8, v66
	v_or_b32_e32 v68, v66, v153
	v_mov_b64_e32 v[66:67], s[76:77]
	v_mad_i64_i32 v[66:67], s[26:27], v68, s57, v[66:67]
	v_lshl_add_u64 v[78:79], v[142:143], 2, v[66:67]
	ds_read_b128 v[66:69], v144
	ds_read_b128 v[70:73], v144 offset:640
	v_cndmask_b32_e64 v75, v55, v63, s[4:5]
	v_cndmask_b32_e64 v74, v54, v62, s[4:5]
	v_cndmask_b32_e64 v81, v51, v59, s[4:5]
	v_cndmask_b32_e64 v80, v50, v58, s[4:5]
	s_movk_i32 s26, 0x5000
	v_cndmask_b32_e64 v77, v57, v65, s[4:5]
	v_cndmask_b32_e64 v76, v56, v64, s[4:5]
	v_cndmask_b32_e64 v83, v53, v61, s[4:5]
	v_cndmask_b32_e64 v82, v52, v60, s[4:5]
	s_waitcnt lgkmcnt(0)
	v_pk_add_f32 v[74:75], v[74:75], v[66:67]
	v_pk_add_f32 v[66:67], v[80:81], v[66:67]
	v_add_co_u32_e32 v80, vcc, s26, v78
	v_cndmask_b32_e64 v85, v39, v47, s[4:5]
	v_cndmask_b32_e64 v84, v38, v46, s[4:5]
	v_cndmask_b32_e64 v87, v41, v49, s[4:5]
	v_cndmask_b32_e64 v86, v40, v48, s[4:5]
	v_cndmask_b32_e64 v89, v35, v43, s[4:5]
	v_cndmask_b32_e64 v88, v34, v42, s[4:5]
	v_cndmask_b32_e64 v91, v37, v45, s[4:5]
	v_cndmask_b32_e64 v90, v36, v44, s[4:5]
	v_pk_add_f32 v[76:77], v[76:77], v[68:69]
	v_pk_add_f32 v[68:69], v[82:83], v[68:69]
	v_addc_co_u32_e32 v81, vcc, 0, v79, vcc
	global_store_dwordx4 v[78:79], v[74:77], off
	global_store_dwordx4 v[80:81], v[66:69], off offset:2048
	v_cndmask_b32_e64 v83, v33, v25, s[4:5]
	v_pk_add_f32 v[76:77], v[86:87], v[72:73]
	v_pk_add_f32 v[74:75], v[84:85], v[70:71]
	v_pk_add_f32 v[68:69], v[90:91], v[72:73]
	v_pk_add_f32 v[66:67], v[88:89], v[70:71]
	global_store_dwordx4 v[78:79], v[74:77], off offset:512
	global_store_dwordx4 v[80:81], v[66:69], off offset:2560
	ds_read_b128 v[66:69], v144 offset:16
	ds_read_b128 v[70:73], v144 offset:656
	v_cndmask_b32_e64 v77, v29, v21, s[4:5]
	v_cndmask_b32_e64 v76, v28, v20, s[4:5]
	v_cndmask_b32_e64 v75, v27, v19, s[4:5]
	v_cndmask_b32_e64 v74, v26, v18, s[4:5]
	v_cndmask_b32_e64 v82, v32, v24, s[4:5]
	v_cndmask_b32_e64 v85, v31, v23, s[4:5]
	v_cndmask_b32_e64 v84, v30, v22, s[4:5]
	v_cndmask_b32_e64 v87, v13, v5, s[4:5]
	v_cndmask_b32_e64 v86, v12, v4, s[4:5]
	v_cndmask_b32_e64 v89, v11, v3, s[4:5]
	v_cndmask_b32_e64 v88, v10, v2, s[4:5]
	v_cndmask_b32_e64 v91, v17, v9, s[4:5]
	v_cndmask_b32_e64 v90, v16, v8, s[4:5]
	v_cndmask_b32_e64 v93, v15, v7, s[4:5]
	v_cndmask_b32_e64 v92, v14, v6, s[4:5]
	s_waitcnt lgkmcnt(0)
	v_pk_add_f32 v[74:75], v[74:75], v[66:67]
	v_pk_add_f32 v[76:77], v[76:77], v[68:69]
	v_pk_add_f32 v[66:67], v[84:85], v[66:67]
	v_pk_add_f32 v[68:69], v[82:83], v[68:69]
	global_store_dwordx4 v[78:79], v[74:77], off offset:16
	global_store_dwordx4 v[80:81], v[66:69], off offset:2064
	s_nop 0
	v_pk_add_f32 v[74:75], v[88:89], v[70:71]
	v_pk_add_f32 v[76:77], v[86:87], v[72:73]
	v_pk_add_f32 v[66:67], v[92:93], v[70:71]
	v_pk_add_f32 v[68:69], v[90:91], v[72:73]
	global_store_dwordx4 v[78:79], v[74:77], off offset:528
	global_store_dwordx4 v[80:81], v[66:69], off offset:2576
.LBB0_787:
	s_or_b64 exec, exec, s[6:7]
	ds_read2_b64 v[66:69], v144 offset1:16
	ds_read2_b64 v[70:73], v144 offset0:32 offset1:48
	ds_read2_b64 v[74:77], v144 offset0:64 offset1:80
	ds_read2_b64 v[78:81], v144 offset0:96 offset1:112
	ds_read2_b64 v[82:85], v144 offset0:128 offset1:144
	s_waitcnt lgkmcnt(0)
	v_pk_add_f32 v[50:51], v[50:51], v[66:67]
	v_pk_add_f32 v[62:63], v[62:63], v[66:67]
	v_pk_add_f32 v[58:59], v[58:59], v[66:67]
	v_pk_add_f32 v[54:55], v[54:55], v[66:67]
	v_mov_b32_dpp v66, v50 row_shr:1 row_mask:0xf bank_mask:0xf bound_ctrl:1
	v_mov_b32_dpp v67, v51 row_shr:1 row_mask:0xf bank_mask:0xf bound_ctrl:1
	v_pk_mul_f32 v[66:67], v[68:69], v[66:67]
	v_pk_mul_f32 v[88:89], v[58:59], v[70:71]
	v_mov_b32_dpp v86, v62 row_shl:1 row_mask:0xf bank_mask:0xf bound_ctrl:1
	v_mov_b32_dpp v87, v63 row_shl:1 row_mask:0xf bank_mask:0xf bound_ctrl:1
	v_pk_fma_f32 v[66:67], v[62:63], v[70:71], v[66:67]
	v_pk_fma_f32 v[62:63], v[68:69], v[62:63], v[88:89]
	v_pk_mul_f32 v[88:89], v[54:55], v[70:71]
	v_pk_fma_f32 v[66:67], v[58:59], v[72:73], v[66:67]
	v_pk_fma_f32 v[58:59], v[68:69], v[58:59], v[88:89]
	v_pk_add_f32 v[34:35], v[34:35], v[76:77]
	v_pk_fma_f32 v[58:59], v[50:51], v[72:73], v[58:59]
	v_pk_mul_f32 v[50:51], v[50:51], v[70:71]
	v_pk_fma_f32 v[62:63], v[54:55], v[72:73], v[62:63]
	v_pk_fma_f32 v[50:51], v[68:69], v[54:55], v[50:51]
	v_pk_add_f32 v[42:43], v[42:43], v[76:77]
	v_pk_add_f32 v[54:55], v[74:75], v[66:67]
	v_mov_b32_dpp v66, v34 row_shr:1 row_mask:0xf bank_mask:0xf bound_ctrl:1
	v_mov_b32_dpp v67, v35 row_shr:1 row_mask:0xf bank_mask:0xf bound_ctrl:1
	v_pk_add_f32 v[46:47], v[46:47], v[76:77]
	v_pk_add_f32 v[38:39], v[38:39], v[76:77]
	v_pk_mul_f32 v[66:67], v[78:79], v[66:67]
	v_pk_mul_f32 v[70:71], v[42:43], v[80:81]
	v_mov_b32_dpp v68, v46 row_shl:1 row_mask:0xf bank_mask:0xf bound_ctrl:1
	v_mov_b32_dpp v69, v47 row_shl:1 row_mask:0xf bank_mask:0xf bound_ctrl:1
	v_pk_fma_f32 v[66:67], v[46:47], v[80:81], v[66:67]
	v_pk_fma_f32 v[46:47], v[78:79], v[46:47], v[70:71]
	v_pk_mul_f32 v[70:71], v[38:39], v[80:81]
	v_pk_fma_f32 v[66:67], v[42:43], v[82:83], v[66:67]
	v_pk_fma_f32 v[42:43], v[78:79], v[42:43], v[70:71]
	v_pk_add_f32 v[66:67], v[84:85], v[66:67]
	v_pk_fma_f32 v[42:43], v[34:35], v[82:83], v[42:43]
	v_pk_mul_f32 v[34:35], v[34:35], v[80:81]
	s_mov_b32 s4, 0xbfb8aa3b
	v_pk_fma_f32 v[46:47], v[38:39], v[82:83], v[46:47]
	v_pk_fma_f32 v[34:35], v[78:79], v[38:39], v[34:35]
	v_pk_mul_f32 v[38:39], v[66:67], s[4:5] op_sel_hi:[1,0]
	v_pk_fma_f32 v[34:35], v[82:83], v[68:69], v[34:35]
	v_exp_f32_e32 v38, v38
	v_exp_f32_e32 v39, v39
	v_pk_add_f32 v[68:69], v[84:85], v[34:35]
; #define LAS __attribute__((address_space(3)))
;     __device__ __forceinline__ void operator()(const f32x4 (&acc)[2][2][4][2], const Unit& u, int wr_in, int wc_in, int fr_in, int fq_in) const {
;     ...
;                 for (int ep = 0; ep < 2; ++ep) {
;                     const int e0 = 2 * ep; const LAS float* pc = P + 8 * fq + 4 * n + e0;
;                     const f32x2 bua = *(const LAS f32x2*)(pc), w0a = *(const LAS f32x2*)(pc + 32), w1a = *(const LAS f32x2*)(pc + 64), w2a = *(const LAS f32x2*)(pc + 96), cba = *(const LAS f32x2*)(pc + 128);
;                     const f32x2 bug = *(const LAS f32x2*)(pc + 160), w0g = *(const LAS f32x2*)(pc + 192), w1g = *(const LAS f32x2*)(pc + 224), w2g = *(const LAS f32x2*)(pc + 256), cbg = *(const LAS f32x2*)(pc + 288);
;                     f32x2 av[4];
;                     {
;                         f32x2 x[4], pv, nv;
; #pragma unroll
;                         for (int m = 0; m < 4; ++m) { x[m].x = acc[ai][0][m][n][e0]; x[m].y = acc[ai][0][m][n][e0 + 1]; x[m] = x[m] + bua; }
;                         pv.x = dpp_shr1(x[3].x); pv.y = dpp_shr1(x[3].y); nv.x = dpp_shl1(x[0].x); nv.y = dpp_shl1(x[0].y);
;                         av[0] = w0a * pv + w1a * x[0] + w2a * x[1] + cba;
;                         av[1] = w0a * x[0] + w1a * x[1] + w2a * x[2] + cba;
;                         av[2] = w0a * x[1] + w1a * x[2] + w2a * x[3] + cba;
;                         av[3] = w0a * x[2] + w1a * x[3] + w2a * nv + cba;
;                     }
;                     {
;                         f32x2 x[4], pv, nv, gv[4];
; #pragma unroll
;                         for (int m = 0; m < 4; ++m) { x[m].x = acc[ai][1][m][n][e0]; x[m].y = acc[ai][1][m][n][e0 + 1]; x[m] = x[m] + bug; }
;                         pv.x = dpp_shr1(x[3].x); pv.y = dpp_shr1(x[3].y); nv.x = dpp_shl1(x[0].x); nv.y = dpp_shl1(x[0].y);
;                         gv[0] = w0g * pv + w1g * x[0] + w2g * x[1] + cbg;
;                         gv[1] = w0g * x[0] + w1g * x[1] + w2g * x[2] + cbg;
;                         gv[2] = w0g * x[1] + w1g * x[2] + w2g * x[3] + cbg;
;                         gv[3] = w0g * x[2] + w1g * x[3] + w2g * nv + cbg;
; #pragma unroll
;                         for (int m = 0; m < 4; ++m) {
;                             const f32x2 t = gv[m] * (-LOG2E);
	v_pk_add_f32 v[46:47], v[84:85], v[46:47]
	v_add_f32_e32 v34, 1.0, v38
	v_add_f32_e32 v35, 1.0, v39
	v_rcp_f32_e32 v34, v34
	v_rcp_f32_e32 v35, v35
	v_pk_mul_f32 v[38:39], v[54:55], v[66:67]
	v_pk_mul_f32 v[54:55], v[46:47], s[4:5] op_sel_hi:[1,0]
	v_pk_add_f32 v[42:43], v[84:85], v[42:43]
	v_exp_f32_e32 v54, v54
	v_pk_mul_f32 v[34:35], v[38:39], v[34:35]
	v_exp_f32_e32 v39, v55
	v_cvt_pk_bf16_f32 v34, v34, v35
	v_add_f32_e32 v35, 1.0, v54
	v_rcp_f32_e32 v38, v35
	v_add_f32_e32 v35, 1.0, v39
	v_rcp_f32_e32 v39, v35
	v_pk_add_f32 v[62:63], v[74:75], v[62:63]
	v_pk_mul_f32 v[54:55], v[42:43], s[4:5] op_sel_hi:[1,0]
	v_pk_mul_f32 v[46:47], v[62:63], v[46:47]
	v_exp_f32_e32 v35, v54
	v_pk_mul_f32 v[38:39], v[46:47], v[38:39]
	v_exp_f32_e32 v47, v55
	v_pk_mul_f32 v[54:55], v[68:69], s[4:5] op_sel_hi:[1,0]
	v_add_f32_e32 v35, 1.0, v35
	v_rcp_f32_e32 v46, v35
	v_add_f32_e32 v35, 1.0, v47
	v_cvt_pk_bf16_f32 v38, v38, v39
	v_exp_f32_e32 v39, v54
	v_rcp_f32_e32 v47, v35
	v_exp_f32_e32 v35, v55
	v_pk_add_f32 v[58:59], v[74:75], v[58:59]
	v_add_f32_e32 v39, 1.0, v39
	v_rcp_f32_e32 v54, v39
	v_add_f32_e32 v35, 1.0, v35
	v_rcp_f32_e32 v55, v35
	v_pk_fma_f32 v[50:51], v[72:73], v[86:87], v[50:51]
	v_pk_mul_f32 v[42:43], v[58:59], v[42:43]
	v_pk_add_f32 v[50:51], v[74:75], v[50:51]
	v_pk_mul_f32 v[42:43], v[42:43], v[46:47]
	s_nop 0
	v_cvt_pk_bf16_f32 v46, v42, v43
	v_pk_mul_f32 v[42:43], v[50:51], v[68:69]
	s_nop 0
	v_pk_mul_f32 v[42:43], v[42:43], v[54:55]
	s_nop 0
	v_cvt_pk_bf16_f32 v42, v42, v43
	ds_read2_b64 v[66:69], v144 offset0:1 offset1:17
	ds_read2_b64 v[70:73], v144 offset0:33 offset1:49
	ds_read2_b64 v[74:77], v144 offset0:65 offset1:81
	ds_read2_b64 v[78:81], v144 offset0:97 offset1:113
	ds_read2_b64 v[82:85], v144 offset0:129 offset1:145
	s_waitcnt lgkmcnt(0)
	v_pk_add_f32 v[52:53], v[52:53], v[66:67]
	v_pk_add_f32 v[54:55], v[60:61], v[66:67]
	v_pk_add_f32 v[50:51], v[64:65], v[66:67]
	v_mov_b32_dpp v58, v52 row_shr:1 row_mask:0xf bank_mask:0xf bound_ctrl:1
	v_mov_b32_dpp v59, v53 row_shr:1 row_mask:0xf bank_mask:0xf bound_ctrl:1
	v_pk_add_f32 v[56:57], v[56:57], v[66:67]
	v_pk_mul_f32 v[58:59], v[68:69], v[58:59]
	v_pk_mul_f32 v[62:63], v[54:55], v[70:71]
	v_mov_b32_dpp v60, v50 row_shl:1 row_mask:0xf bank_mask:0xf bound_ctrl:1
	v_mov_b32_dpp v61, v51 row_shl:1 row_mask:0xf bank_mask:0xf bound_ctrl:1
	v_pk_fma_f32 v[58:59], v[50:51], v[70:71], v[58:59]
	v_pk_fma_f32 v[50:51], v[68:69], v[50:51], v[62:63]
	v_pk_mul_f32 v[62:63], v[56:57], v[70:71]
	v_pk_fma_f32 v[58:59], v[54:55], v[72:73], v[58:59]
	v_pk_fma_f32 v[54:55], v[68:69], v[54:55], v[62:63]
	v_pk_add_f32 v[36:37], v[36:37], v[76:77]
	v_pk_fma_f32 v[54:55], v[52:53], v[72:73], v[54:55]
	v_pk_mul_f32 v[52:53], v[52:53], v[70:71]
	v_pk_fma_f32 v[50:51], v[56:57], v[72:73], v[50:51]
	v_pk_fma_f32 v[52:53], v[68:69], v[56:57], v[52:53]
	v_pk_add_f32 v[44:45], v[44:45], v[76:77]
	v_pk_add_f32 v[56:57], v[74:75], v[58:59]
	v_mov_b32_dpp v58, v36 row_shr:1 row_mask:0xf bank_mask:0xf bound_ctrl:1
	v_mov_b32_dpp v59, v37 row_shr:1 row_mask:0xf bank_mask:0xf bound_ctrl:1
	v_pk_add_f32 v[48:49], v[48:49], v[76:77]
	v_pk_add_f32 v[40:41], v[40:41], v[76:77]
	v_pk_mul_f32 v[58:59], v[78:79], v[58:59]
	v_pk_mul_f32 v[62:63], v[44:45], v[80:81]
	v_pk_fma_f32 v[52:53], v[72:73], v[60:61], v[52:53]
	v_mov_b32_dpp v60, v48 row_shl:1 row_mask:0xf bank_mask:0xf bound_ctrl:1
	v_mov_b32_dpp v61, v49 row_shl:1 row_mask:0xf bank_mask:0xf bound_ctrl:1
	v_pk_fma_f32 v[58:59], v[48:49], v[80:81], v[58:59]
	v_pk_fma_f32 v[48:49], v[78:79], v[48:49], v[62:63]
	v_pk_mul_f32 v[62:63], v[40:41], v[80:81]
	v_pk_fma_f32 v[58:59], v[44:45], v[82:83], v[58:59]
	v_pk_fma_f32 v[44:45], v[78:79], v[44:45], v[62:63]
	v_pk_add_f32 v[58:59], v[84:85], v[58:59]
	v_pk_fma_f32 v[44:45], v[36:37], v[82:83], v[44:45]
	v_pk_mul_f32 v[36:37], v[36:37], v[80:81]
	v_pk_fma_f32 v[48:49], v[40:41], v[82:83], v[48:49]
	v_pk_fma_f32 v[36:37], v[78:79], v[40:41], v[36:37]
	v_pk_mul_f32 v[40:41], v[58:59], s[4:5] op_sel_hi:[1,0]
	v_pk_add_f32 v[48:49], v[84:85], v[48:49]
	v_exp_f32_e32 v35, v40
	v_exp_f32_e32 v39, v41
	v_pk_mul_f32 v[56:57], v[56:57], v[58:59]
	v_pk_mul_f32 v[58:59], v[48:49], s[4:5] op_sel_hi:[1,0]
	v_add_f32_e32 v35, 1.0, v35
	v_rcp_f32_e32 v40, v35
	v_add_f32_e32 v35, 1.0, v39
	v_rcp_f32_e32 v41, v35
	v_exp_f32_e32 v39, v58
	v_exp_f32_e32 v43, v59
	v_pk_add_f32 v[50:51], v[74:75], v[50:51]
	v_pk_mul_f32 v[40:41], v[56:57], v[40:41]
	v_add_f32_e32 v39, 1.0, v39
	v_pk_add_f32 v[44:45], v[84:85], v[44:45]
	v_cvt_pk_bf16_f32 v35, v40, v41
	v_rcp_f32_e32 v40, v39
	v_add_f32_e32 v39, 1.0, v43
	v_rcp_f32_e32 v41, v39
	v_pk_mul_f32 v[48:49], v[50:51], v[48:49]
	v_pk_mul_f32 v[50:51], v[44:45], s[4:5] op_sel_hi:[1,0]
	v_pk_fma_f32 v[36:37], v[82:83], v[60:61], v[36:37]
	v_exp_f32_e32 v43, v50
	v_exp_f32_e32 v47, v51
	v_pk_add_f32 v[36:37], v[84:85], v[36:37]
	v_pk_mul_f32 v[40:41], v[48:49], v[40:41]
	v_pk_mul_f32 v[48:49], v[36:37], s[4:5] op_sel_hi:[1,0]
	v_cvt_pk_bf16_f32 v39, v40, v41
	v_add_f32_e32 v40, 1.0, v43
	v_exp_f32_e32 v43, v48
	v_add_f32_e32 v41, 1.0, v47
	v_exp_f32_e32 v47, v49
	v_rcp_f32_e32 v40, v40
	v_add_f32_e32 v43, 1.0, v43
	v_rcp_f32_e32 v48, v43
	v_add_f32_e32 v43, 1.0, v47
	v_rcp_f32_e32 v41, v41
	v_rcp_f32_e32 v49, v43
	v_pk_add_f32 v[54:55], v[74:75], v[54:55]
	v_pk_add_f32 v[52:53], v[74:75], v[52:53]
	v_pk_mul_f32 v[44:45], v[54:55], v[44:45]
	v_pk_mul_f32 v[36:37], v[52:53], v[36:37]
	v_pk_mul_f32 v[40:41], v[44:45], v[40:41]
	v_pk_mul_f32 v[36:37], v[36:37], v[48:49]
	v_cvt_pk_bf16_f32 v47, v40, v41
	s_nop 0
	v_cvt_pk_bf16_f32 v43, v36, v37
	ds_read2_b64 v[48:51], v144 offset0:2 offset1:18
	ds_read2_b64 v[52:55], v144 offset0:34 offset1:50
	ds_read2_b64 v[56:59], v144 offset0:66 offset1:82
	ds_read2_b64 v[60:63], v144 offset0:98 offset1:114
	ds_read2_b64 v[64:67], v144 offset0:130 offset1:146
	s_waitcnt lgkmcnt(0)
;     __device__ __forceinline__ void operator()(const f32x4 (&acc)[2][2][4][2], const Unit& u, int wr_in, int wc_in, int fr_in, int fq_in) const {
;     ...
;                     const int e0 = 2 * ep; const LAS float* pc = P + 8 * fq + 4 * n + e0;
;                     const f32x2 bua = *(const LAS f32x2*)(pc), w0a = *(const LAS f32x2*)(pc + 32), w1a = *(const LAS f32x2*)(pc + 64), w2a = *(const LAS f32x2*)(pc + 96), cba = *(const LAS f32x2*)(pc + 128);
;                     const f32x2 bug = *(const LAS f32x2*)(pc + 160), w0g = *(const LAS f32x2*)(pc + 192), w1g = *(const LAS f32x2*)(pc + 224), w2g = *(const LAS f32x2*)(pc + 256), cbg = *(const LAS f32x2*)(pc + 288);
;                     f32x2 av[4];
;                     {
;                         f32x2 x[4], pv, nv;
; #pragma unroll
;                         for (int m = 0; m < 4; ++m) { x[m].x = acc[ai][0][m][n][e0]; x[m].y = acc[ai][0][m][n][e0 + 1]; x[m] = x[m] + bua; }
;                         pv.x = dpp_shr1(x[3].x); pv.y = dpp_shr1(x[3].y); nv.x = dpp_shl1(x[0].x); nv.y = dpp_shl1(x[0].y);
;                         av[0] = w0a * pv + w1a * x[0] + w2a * x[1] + cba;
;                         av[1] = w0a * x[0] + w1a * x[1] + w2a * x[2] + cba;
;                         av[2] = w0a * x[1] + w1a * x[2] + w2a * x[3] + cba;
;                         av[3] = w0a * x[2] + w1a * x[3] + w2a * nv + cba;
;                     }
;                     {
;                         f32x2 x[4], pv, nv, gv[4];
; #pragma unroll
;                         for (int m = 0; m < 4; ++m) { x[m].x = acc[ai][1][m][n][e0]; x[m].y = acc[ai][1][m][n][e0 + 1]; x[m] = x[m] + bug; }
;                         pv.x = dpp_shr1(x[3].x); pv.y = dpp_shr1(x[3].y); nv.x = dpp_shl1(x[0].x); nv.y = dpp_shl1(x[0].y);
;                         gv[0] = w0g * pv + w1g * x[0] + w2g * x[1] + cbg;
;                         gv[1] = w0g * x[0] + w1g * x[1] + w2g * x[2] + cbg;
;                         gv[2] = w0g * x[1] + w1g * x[2] + w2g * x[3] + cbg;
;                         gv[3] = w0g * x[2] + w1g * x[3] + w2g * nv + cbg;
; #pragma unroll
;                         for (int m = 0; m < 4; ++m) {
;                             const f32x2 t = gv[m] * (-LOG2E);
;                             f32x2 sg; sg.x = __builtin_amdgcn_rcpf(1.0f + __builtin_amdgcn_exp2f(t.x)); sg.y = __builtin_amdgcn_rcpf(1.0f + __builtin_amdgcn_exp2f(t.y));
	v_pk_add_f32 v[30:31], v[30:31], v[48:49]
	v_pk_add_f32 v[22:23], v[22:23], v[48:49]
	v_pk_add_f32 v[18:19], v[18:19], v[48:49]
	v_mov_b32_dpp v36, v30 row_shr:1 row_mask:0xf bank_mask:0xf bound_ctrl:1
	v_mov_b32_dpp v37, v31 row_shr:1 row_mask:0xf bank_mask:0xf bound_ctrl:1
	v_pk_add_f32 v[26:27], v[26:27], v[48:49]
	v_pk_mul_f32 v[36:37], v[50:51], v[36:37]
	v_pk_mul_f32 v[44:45], v[22:23], v[52:53]
	v_mov_b32_dpp v40, v18 row_shl:1 row_mask:0xf bank_mask:0xf bound_ctrl:1
	v_mov_b32_dpp v41, v19 row_shl:1 row_mask:0xf bank_mask:0xf bound_ctrl:1
	v_pk_fma_f32 v[36:37], v[18:19], v[52:53], v[36:37]
	v_pk_fma_f32 v[18:19], v[50:51], v[18:19], v[44:45]
	v_pk_mul_f32 v[44:45], v[26:27], v[52:53]
	v_pk_fma_f32 v[36:37], v[22:23], v[54:55], v[36:37]
	v_pk_fma_f32 v[22:23], v[50:51], v[22:23], v[44:45]
	v_pk_add_f32 v[14:15], v[14:15], v[58:59]
	v_pk_fma_f32 v[22:23], v[30:31], v[54:55], v[22:23]
	v_pk_mul_f32 v[30:31], v[30:31], v[52:53]
	v_pk_fma_f32 v[18:19], v[26:27], v[54:55], v[18:19]
	v_pk_fma_f32 v[26:27], v[50:51], v[26:27], v[30:31]
	v_pk_add_f32 v[6:7], v[6:7], v[58:59]
	v_pk_add_f32 v[30:31], v[56:57], v[36:37]
	v_mov_b32_dpp v36, v14 row_shr:1 row_mask:0xf bank_mask:0xf bound_ctrl:1
	v_mov_b32_dpp v37, v15 row_shr:1 row_mask:0xf bank_mask:0xf bound_ctrl:1
	v_pk_add_f32 v[2:3], v[2:3], v[58:59]
	v_pk_add_f32 v[10:11], v[10:11], v[58:59]
	v_pk_mul_f32 v[36:37], v[60:61], v[36:37]
	v_pk_mul_f32 v[44:45], v[6:7], v[62:63]
	v_pk_fma_f32 v[26:27], v[54:55], v[40:41], v[26:27]
	v_mov_b32_dpp v40, v2 row_shl:1 row_mask:0xf bank_mask:0xf bound_ctrl:1
	v_mov_b32_dpp v41, v3 row_shl:1 row_mask:0xf bank_mask:0xf bound_ctrl:1
	v_pk_fma_f32 v[36:37], v[2:3], v[62:63], v[36:37]
	v_pk_fma_f32 v[2:3], v[60:61], v[2:3], v[44:45]
	v_pk_mul_f32 v[44:45], v[10:11], v[62:63]
	v_pk_fma_f32 v[36:37], v[6:7], v[64:65], v[36:37]
	v_pk_fma_f32 v[6:7], v[60:61], v[6:7], v[44:45]
	v_pk_add_f32 v[36:37], v[66:67], v[36:37]
	v_pk_fma_f32 v[6:7], v[14:15], v[64:65], v[6:7]
	v_pk_mul_f32 v[14:15], v[14:15], v[62:63]
	v_pk_fma_f32 v[2:3], v[10:11], v[64:65], v[2:3]
	v_pk_fma_f32 v[10:11], v[60:61], v[10:11], v[14:15]
	v_pk_mul_f32 v[14:15], v[36:37], s[4:5] op_sel_hi:[1,0]
	v_pk_add_f32 v[2:3], v[66:67], v[2:3]
	v_exp_f32_e32 v14, v14
	v_exp_f32_e32 v15, v15
	v_pk_mul_f32 v[30:31], v[30:31], v[36:37]
	v_pk_mul_f32 v[36:37], v[2:3], s[4:5] op_sel_hi:[1,0]
	v_add_f32_e32 v14, 1.0, v14
	v_add_f32_e32 v15, 1.0, v15
	v_rcp_f32_e32 v14, v14
	v_rcp_f32_e32 v15, v15
	v_pk_fma_f32 v[10:11], v[64:65], v[40:41], v[10:11]
	v_exp_f32_e32 v40, v36
	v_pk_add_f32 v[18:19], v[56:57], v[18:19]
	v_pk_mul_f32 v[14:15], v[30:31], v[14:15]
	v_exp_f32_e32 v30, v37
	v_cvt_pk_bf16_f32 v36, v14, v15
	v_add_f32_e32 v14, 1.0, v40
	v_rcp_f32_e32 v14, v14
	v_add_f32_e32 v15, 1.0, v30
	v_rcp_f32_e32 v15, v15
	v_pk_add_f32 v[6:7], v[66:67], v[6:7]
	v_pk_mul_f32 v[2:3], v[18:19], v[2:3]
	v_pk_mul_f32 v[18:19], v[6:7], s[4:5] op_sel_hi:[1,0]
	v_pk_mul_f32 v[2:3], v[2:3], v[14:15]
	v_exp_f32_e32 v14, v19
	v_pk_add_f32 v[10:11], v[66:67], v[10:11]
	v_exp_f32_e32 v18, v18
	v_cvt_pk_bf16_f32 v40, v2, v3
	v_add_f32_e32 v3, 1.0, v14
	v_pk_mul_f32 v[14:15], v[10:11], s[4:5] op_sel_hi:[1,0]
	v_add_f32_e32 v2, 1.0, v18
	v_exp_f32_e32 v14, v14
	v_exp_f32_e32 v15, v15
	v_rcp_f32_e32 v2, v2
	v_rcp_f32_e32 v3, v3
	v_add_f32_e32 v14, 1.0, v14
	v_add_f32_e32 v15, 1.0, v15
	v_pk_add_f32 v[22:23], v[56:57], v[22:23]
	v_rcp_f32_e32 v14, v14
	v_rcp_f32_e32 v15, v15
	v_pk_mul_f32 v[6:7], v[22:23], v[6:7]
	v_pk_add_f32 v[26:27], v[56:57], v[26:27]
	v_pk_mul_f32 v[2:3], v[6:7], v[2:3]
	s_nop 0
	v_cvt_pk_bf16_f32 v48, v2, v3
	v_pk_mul_f32 v[2:3], v[26:27], v[10:11]
	s_nop 0
	v_pk_mul_f32 v[2:3], v[2:3], v[14:15]
	s_nop 0
	v_cvt_pk_bf16_f32 v44, v2, v3
	ds_read2_b64 v[50:53], v144 offset0:3 offset1:19
	ds_read2_b64 v[54:57], v144 offset0:35 offset1:51
	ds_read2_b64 v[58:61], v144 offset0:67 offset1:83
	ds_read2_b64 v[62:65], v144 offset0:99 offset1:115
	ds_read2_b64 v[66:69], v144 offset0:131 offset1:147
	s_waitcnt lgkmcnt(0)
; __device__ __forceinline__ unsigned cvt_pk_bf16(float lo, float hi) { unsigned r; asm("v_cvt_pk_bf16_f32 %0, %1, %2" : "=v"(r) : "v"(lo), "v"(hi)); return r; }
; __device__ __forceinline__ float dpp_shr1(float v) { return __builtin_bit_cast(float, __builtin_amdgcn_update_dpp(0, __builtin_bit_cast(int, v), 0x111, 0xf, 0xf, true)); }
; __device__ __forceinline__ float dpp_shl1(float v) { return __builtin_bit_cast(float, __builtin_amdgcn_update_dpp(0, __builtin_bit_cast(int, v), 0x101, 0xf, 0xf, true)); }
;     __device__ __forceinline__ void operator()(const f32x4 (&acc)[2][2][4][2], const Unit& u, int wr_in, int wc_in, int fr_in, int fq_in) const {
;     ...
;                         for (int m = 0; m < 4; ++m) { x[m].x = acc[ai][1][m][n][e0]; x[m].y = acc[ai][1][m][n][e0 + 1]; x[m] = x[m] + bug; }
;                         pv.x = dpp_shr1(x[3].x); pv.y = dpp_shr1(x[3].y); nv.x = dpp_shl1(x[0].x); nv.y = dpp_shl1(x[0].y);
;                         gv[0] = w0g * pv + w1g * x[0] + w2g * x[1] + cbg;
;                         gv[1] = w0g * x[0] + w1g * x[1] + w2g * x[2] + cbg;
;                         gv[2] = w0g * x[1] + w1g * x[2] + w2g * x[3] + cbg;
;                         gv[3] = w0g * x[2] + w1g * x[3] + w2g * nv + cbg;
; #pragma unroll
;                         for (int m = 0; m < 4; ++m) {
;                             const f32x2 t = gv[m] * (-LOG2E);
;                             f32x2 sg; sg.x = __builtin_amdgcn_rcpf(1.0f + __builtin_amdgcn_exp2f(t.x)); sg.y = __builtin_amdgcn_rcpf(1.0f + __builtin_amdgcn_exp2f(t.y));
;                             const f32x2 ov = av[m] * gv[m] * sg;
;                             pk[m][2 * n + ep] = cvt_pk_bf16(ov.x, ov.y); }
;                     }
;                     __builtin_amdgcn_sched_barrier(0);
;                 }
;             bf16_t* gp = G + (size_t)(u.pm * 256 + ai * 128 + wr * 64 + 4 * fr) * FFH + ca0;
;             if (fr != 0) *(u32x4*)(gp) = pk[0];
;             *(u32x4*)(gp + FFH) = pk[1];
;             *(u32x4*)(gp + 2 * FFH) = pk[2];
;             if (fr != 15) *(u32x4*)(gp + 3 * FFH) = pk[3];
	v_pk_add_f32 v[14:15], v[32:33], v[50:51]
	v_pk_add_f32 v[6:7], v[24:25], v[50:51]
	v_pk_add_f32 v[2:3], v[20:21], v[50:51]
	v_mov_b32_dpp v18, v14 row_shr:1 row_mask:0xf bank_mask:0xf bound_ctrl:1
	v_mov_b32_dpp v19, v15 row_shr:1 row_mask:0xf bank_mask:0xf bound_ctrl:1
	v_pk_add_f32 v[10:11], v[28:29], v[50:51]
	v_pk_mul_f32 v[18:19], v[52:53], v[18:19]
	v_pk_mul_f32 v[22:23], v[6:7], v[54:55]
	v_mov_b32_dpp v20, v2 row_shl:1 row_mask:0xf bank_mask:0xf bound_ctrl:1
	v_mov_b32_dpp v21, v3 row_shl:1 row_mask:0xf bank_mask:0xf bound_ctrl:1
	v_pk_fma_f32 v[18:19], v[2:3], v[54:55], v[18:19]
	v_pk_fma_f32 v[2:3], v[52:53], v[2:3], v[22:23]
	v_pk_mul_f32 v[22:23], v[10:11], v[54:55]
	v_pk_fma_f32 v[18:19], v[6:7], v[56:57], v[18:19]
	v_pk_fma_f32 v[6:7], v[52:53], v[6:7], v[22:23]
	v_pk_fma_f32 v[2:3], v[10:11], v[56:57], v[2:3]
	v_pk_fma_f32 v[6:7], v[14:15], v[56:57], v[6:7]
	v_pk_mul_f32 v[14:15], v[14:15], v[54:55]
	v_pk_add_f32 v[8:9], v[8:9], v[60:61]
	v_pk_fma_f32 v[10:11], v[52:53], v[10:11], v[14:15]
	v_pk_add_f32 v[14:15], v[16:17], v[60:61]
	v_pk_add_f32 v[16:17], v[58:59], v[18:19]
	v_pk_add_f32 v[4:5], v[4:5], v[60:61]
	v_mov_b32_dpp v18, v14 row_shr:1 row_mask:0xf bank_mask:0xf bound_ctrl:1
	v_mov_b32_dpp v19, v15 row_shr:1 row_mask:0xf bank_mask:0xf bound_ctrl:1
	v_pk_add_f32 v[12:13], v[12:13], v[60:61]
	v_pk_mul_f32 v[18:19], v[62:63], v[18:19]
	v_pk_mul_f32 v[22:23], v[8:9], v[64:65]
	v_pk_fma_f32 v[10:11], v[56:57], v[20:21], v[10:11]
	v_mov_b32_dpp v20, v4 row_shl:1 row_mask:0xf bank_mask:0xf bound_ctrl:1
	v_mov_b32_dpp v21, v5 row_shl:1 row_mask:0xf bank_mask:0xf bound_ctrl:1
	v_pk_fma_f32 v[18:19], v[4:5], v[64:65], v[18:19]
	v_pk_fma_f32 v[4:5], v[62:63], v[4:5], v[22:23]
	v_pk_mul_f32 v[22:23], v[12:13], v[64:65]
	v_pk_fma_f32 v[18:19], v[8:9], v[66:67], v[18:19]
	v_pk_fma_f32 v[8:9], v[62:63], v[8:9], v[22:23]
	v_pk_add_f32 v[18:19], v[68:69], v[18:19]
	v_pk_fma_f32 v[8:9], v[14:15], v[66:67], v[8:9]
	v_pk_mul_f32 v[14:15], v[14:15], v[64:65]
	v_pk_fma_f32 v[4:5], v[12:13], v[66:67], v[4:5]
	v_pk_fma_f32 v[12:13], v[62:63], v[12:13], v[14:15]
	v_pk_mul_f32 v[14:15], v[18:19], s[4:5] op_sel_hi:[1,0]
	v_pk_add_f32 v[4:5], v[68:69], v[4:5]
	v_exp_f32_e32 v14, v14
	v_exp_f32_e32 v15, v15
	v_pk_mul_f32 v[16:17], v[16:17], v[18:19]
	v_pk_mul_f32 v[18:19], v[4:5], s[4:5] op_sel_hi:[1,0]
	v_add_f32_e32 v14, 1.0, v14
	v_add_f32_e32 v15, 1.0, v15
	v_rcp_f32_e32 v14, v14
	v_rcp_f32_e32 v15, v15
	v_exp_f32_e32 v18, v18
	v_pk_add_f32 v[2:3], v[58:59], v[2:3]
	v_pk_add_f32 v[8:9], v[68:69], v[8:9]
	v_pk_mul_f32 v[14:15], v[16:17], v[14:15]
	v_exp_f32_e32 v16, v19
	v_cvt_pk_bf16_f32 v37, v14, v15
	v_add_f32_e32 v14, 1.0, v18
	v_rcp_f32_e32 v14, v14
	v_add_f32_e32 v15, 1.0, v16
	v_rcp_f32_e32 v15, v15
	v_pk_mul_f32 v[2:3], v[2:3], v[4:5]
	v_pk_mul_f32 v[4:5], v[8:9], s[4:5] op_sel_hi:[1,0]
	v_pk_fma_f32 v[12:13], v[66:67], v[20:21], v[12:13]
	v_exp_f32_e32 v4, v4
	v_exp_f32_e32 v5, v5
	v_pk_add_f32 v[12:13], v[68:69], v[12:13]
	v_pk_mul_f32 v[2:3], v[2:3], v[14:15]
	v_pk_add_f32 v[6:7], v[58:59], v[6:7]
	v_cvt_pk_bf16_f32 v41, v2, v3
	v_add_f32_e32 v2, 1.0, v4
	v_add_f32_e32 v3, 1.0, v5
	v_pk_mul_f32 v[4:5], v[12:13], s[4:5] op_sel_hi:[1,0]
	v_rcp_f32_e32 v2, v2
	v_exp_f32_e32 v14, v4
	v_exp_f32_e32 v15, v5
	v_rcp_f32_e32 v3, v3
	v_pk_mul_f32 v[4:5], v[6:7], v[8:9]
	v_add_f32_e32 v6, 1.0, v14
	v_add_f32_e32 v7, 1.0, v15
	v_rcp_f32_e32 v6, v6
	v_rcp_f32_e32 v7, v7
	v_pk_add_f32 v[10:11], v[58:59], v[10:11]
	v_pk_mul_f32 v[2:3], v[4:5], v[2:3]
	s_nop 0
	v_cvt_pk_bf16_f32 v49, v2, v3
	v_pk_mul_f32 v[2:3], v[10:11], v[12:13]
	s_nop 0
	v_pk_mul_f32 v[2:3], v[2:3], v[6:7]
	s_nop 0
	v_cvt_pk_bf16_f32 v45, v2, v3
	v_readlane_b32 s4, v254, 23
	v_readlane_b32 s5, v254, 24
	v_add_u32_e32 v4, 0x80, v145
	s_nop 0
	v_mov_b64_e32 v[2:3], s[4:5]
	s_movk_i32 s4, 0x1600
	v_mad_i64_i32 v[2:3], s[4:5], v4, s4, v[2:3]
	v_lshl_add_u64 v[2:3], v[140:141], 1, v[2:3]
	s_and_saveexec_b64 s[4:5], s[0:1]
	s_cbranch_execz .LBB0_789
	global_store_dwordx4 v[2:3], v[34:37], off
.LBB0_789:
	s_or_b64 exec, exec, s[4:5]
	v_add_co_u32_e32 v4, vcc, 0x1000, v2
	s_nop 1
	v_addc_co_u32_e32 v5, vcc, 0, v3, vcc
	global_store_dwordx4 v[4:5], v[38:41], off offset:1536
	v_add_co_u32_e32 v4, vcc, 0x2000, v2
	s_nop 1
	v_addc_co_u32_e32 v5, vcc, 0, v3, vcc
	global_store_dwordx4 v[4:5], v[46:49], off offset:3072
	s_and_saveexec_b64 s[0:1], s[8:9]
	s_cbranch_execz .LBB0_791
	v_add_co_u32_e32 v2, vcc, 0x4000, v2
	s_nop 1
	v_addc_co_u32_e32 v3, vcc, 0, v3, vcc
	global_store_dwordx4 v[2:3], v[42:45], off offset:512

; __global__ void __launch_bounds__(512, 2) mk_fwd(Args args) {
;     ...
;                 for (int row0 = rbeg + wstart; row0 < rend; row0 += 2 * wstride) {
;                     const int row1 = row0 + wstride; const bool has1 = row1 < rend;
;                     f32x4 va[4], vb[4];
; #pragma unroll
;                     for (int j = 0; j < 4; ++j) vb[j] = (f32x4){0.f, 0.f, 0.f, 0.f};
;                     { const float* xp = (row0 < ML) ? XL + (size_t)row0 * DM : XC + (size_t)(row0 - ML) * DM;
; #pragma unroll
;                       for (int j = 0; j < 4; ++j) va[j] = *(const f32x4*)(xp + 4 * lane + 256 * j); }
;                     if (has1) { const float* xp = (row1 < ML) ? XL + (size_t)row1 * DM : XC + (size_t)(row1 - ML) * DM;
; #pragma unroll
;                       for (int j = 0; j < 4; ++j) vb[j] = *(const f32x4*)(xp + 4 * lane + 256 * j); }
.LBB0_816:
	v_lshlrev_b32_e32 v0, 2, v34
	v_lshl_add_u64 v[2:3], s[4:5], 0, v[0:1]
	global_load_dwordx4 v[30:33], v[2:3], off
	global_load_dwordx4 v[26:29], v[2:3], off offset:1024
	global_load_dwordx4 v[22:25], v[2:3], off offset:2048
	global_load_dwordx4 v[18:21], v[2:3], off offset:3072
	s_min_i32 s20, s17, 0x8000
	s_ashr_i32 s20, s20, 11
	s_mul_hi_i32 s26, s20, 0x6000
	s_mulk_i32 s20, 0x6000
	s_add_u32 s50, s11, s20
	s_addc_u32 s51, s14, s26
	v_lshl_add_u64 v[70:71], s[50:51], 0, v[0:1]
	s_mov_b64 s[50:51], 0x1000
	v_lshl_add_u64 v[72:73], s[50:51], 0, v[70:71]
	global_load_dwordx4 v[74:77], v[70:71], off
	global_load_dwordx4 v[90:93], v[72:73], off
	global_load_dwordx4 v[78:81], v[70:71], off offset:1024
	global_load_dwordx4 v[94:97], v[72:73], off offset:1024
	global_load_dwordx4 v[82:85], v[70:71], off offset:2048
	global_load_dwordx4 v[98:101], v[72:73], off offset:2048
	global_load_dwordx4 v[86:89], v[70:71], off offset:3072
	global_load_dwordx4 v[102:105], v[72:73], off offset:3072
	s_add_i32 s92, s12, s46
	s_add_i32 s90, s92, 0x8000
	s_cmp_lt_i32 s90, s2
	v_mov_b32_e32 v17, 0
	s_cselect_b64 s[94:95], -1, 0
	s_cmp_ge_i32 s90, s2
	v_mov_b32_e32 v16, 0
	v_mov_b32_e32 v15, 0
	v_mov_b32_e32 v14, 0
	v_mov_b32_e32 v5, 0
	v_mov_b32_e32 v4, v17
	v_mov_b32_e32 v3, 0
	v_mov_b32_e32 v2, v17
	v_mov_b32_e32 v9, 0
	v_mov_b32_e32 v8, v17
	v_mov_b32_e32 v7, 0
	v_mov_b32_e32 v6, v17
	v_mov_b32_e32 v13, 0
	v_mov_b32_e32 v12, v17
	v_mov_b32_e32 v11, 0
	v_mov_b32_e32 v10, v17
	v_mov_b32_e32 v53, 0
	v_mov_b32_e32 v52, v17
	v_mov_b32_e32 v55, 0
	v_mov_b32_e32 v54, v17
	s_cbranch_scc1 .LBB0_822
	s_cmpk_gt_i32 s90, 0x7fff
	s_mov_b64 s[50:51], -1
	s_cbranch_scc0 .LBB0_819
	s_mov_b32 s93, s47
	s_lshl_b64 s[4:5], s[92:93], 12
	s_add_u32 s4, s40, s4
	s_addc_u32 s5, s41, s5
	s_mov_b64 s[50:51], 0

; __global__ void __launch_bounds__(512, 2) mk_fwd(Args args) {
;     ...
;                 auto ln_row = [&](const int row, f32x4 (&v)[4]) __attribute__((always_inline)) {
;                     const bool lat = row < ML;
;                     float* xr = lat ? XL + (size_t)row * DM : XC + (size_t)(row - ML) * DM;
;                     const float* mp = mp0 + (size_t)(lat ? (row >> 11) : 16) * 6144;
;                     float s = 0.f;
; #pragma unroll
;                     for (int j = 0; j < 4; ++j) s += (v[j][0] + v[j][1]) + (v[j][2] + v[j][3]);
;                     const float mean = wave_sum(s) * (1.0f / DM); float s2 = 0.f;
; #pragma unroll
;                     for (int j = 0; j < 4; ++j) { v[j] = v[j] - mean; s2 += (v[j][0] * v[j][0] + v[j][1] * v[j][1]) + (v[j][2] * v[j][2] + v[j][3] * v[j][3]); }
;                     const float rstd = 1.0f / sqrtf(wave_sum(s2) * (1.0f / DM) + LN_EPS);
;                     if (lane == 0) { STAT[2 * (size_t)row] = mean; STAT[2 * (size_t)row + 1] = rstd; }
;     ...
;                     if (has1) { const float* xp = (row1 < ML) ? XL + (size_t)row1 * DM : XC + (size_t)(row1 - ML) * DM;
; #pragma unroll
;                       for (int j = 0; j < 4; ++j) vb[j] = *(const f32x4*)(xp + 4 * lane + 256 * j); }
.LBB0_821:
	v_lshl_add_u64 v[6:7], s[4:5], 0, v[0:1]
	global_load_dwordx4 v[14:17], v[6:7], off offset:3072
	global_load_dwordx4 v[2:5], v[6:7], off offset:2048
	global_load_dwordx4 v[10:13], v[6:7], off
	s_nop 0
	global_load_dwordx4 v[6:9], v[6:7], off offset:1024
	s_min_i32 s20, s90, 0x8000
	s_ashr_i32 s20, s20, 11
	s_mul_hi_i32 s26, s20, 0x6000
	s_mulk_i32 s20, 0x6000
	s_add_u32 s50, s11, s20
	s_addc_u32 s51, s14, s26
	v_lshl_add_u64 v[70:71], s[50:51], 0, v[0:1]
	s_mov_b64 s[50:51], 0x1000
	v_lshl_add_u64 v[72:73], s[50:51], 0, v[70:71]
	global_load_dwordx4 v[106:109], v[70:71], off
	global_load_dwordx4 v[122:125], v[72:73], off
	global_load_dwordx4 v[110:113], v[70:71], off offset:1024
	global_load_dwordx4 v[126:129], v[72:73], off offset:1024
	global_load_dwordx4 v[114:117], v[70:71], off offset:2048
	global_load_dwordx4 v[130:133], v[72:73], off offset:2048
	global_load_dwordx4 v[118:121], v[70:71], off offset:3072
	global_load_dwordx4 v[134:137], v[72:73], off offset:3072
	s_waitcnt vmcnt(0) lgkmcnt(0)
	v_mov_b32_e32 v53, v17
	v_mov_b32_e32 v52, v16
	v_mov_b32_e32 v55, v15
	v_mov_b32_e32 v54, v14
.LBB0_822:
	s_waitcnt vmcnt(0) lgkmcnt(0)
	v_mov_b32_e32 v56, v31
	v_mov_b32_e32 v57, v32
	v_mov_b32_e32 v58, v30
	v_mov_b32_e32 v59, v33
	v_pk_add_f32 v[56:57], v[56:57], v[58:59]
	v_mov_b32_e32 v58, v27
	v_mov_b32_e32 v59, v28
	v_mov_b32_e32 v62, v26
	v_mov_b32_e32 v63, v29
	v_pk_add_f32 v[58:59], v[58:59], v[62:63]
	v_add_f32_e32 v56, v56, v57
	v_pk_add_f32 v[58:59], v[58:59], v[58:59] op_sel_hi:[0,1]
	v_add_f32_e32 v57, 0, v56
	v_add_f32_e32 v63, v22, v23
	v_add_f32_e32 v65, v24, v25
	v_mov_b32_e32 v62, v18
	v_mov_b32_e32 v64, v19
	v_mov_b32_e32 v58, v20
	v_mov_b32_e32 v56, v21
	v_pk_add_f32 v[62:63], v[62:63], v[64:65]
	v_pk_add_f32 v[56:57], v[58:59], v[56:57]
	s_nop 0
	v_pk_add_f32 v[56:57], v[62:63], v[56:57]
	s_nop 0
	v_add_f32_e32 v56, v56, v57
	s_nop 1
	v_add_f32_dpp v56, v56, v56 quad_perm:[1,0,3,2] row_mask:0xf bank_mask:0xf
	s_nop 1
	v_add_f32_dpp v56, v56, v56 quad_perm:[2,3,0,1] row_mask:0xf bank_mask:0xf
	s_nop 1
	v_add_f32_dpp v56, v56, v56 row_half_mirror row_mask:0xf bank_mask:0xf
	s_nop 1
	v_add_f32_dpp v56, v56, v56 row_mirror row_mask:0xf bank_mask:0xf
	ds_bpermute_b32 v57, v60, v56
	s_waitcnt lgkmcnt(0)
	v_add_f32_e32 v56, v56, v57
	ds_bpermute_b32 v57, v61, v56
	s_waitcnt lgkmcnt(0)
	v_add_f32_e32 v57, v56, v57
	v_fmamk_f32 v33, v57, 0xba800000, v33
	v_fmamk_f32 v31, v57, 0xba800000, v31
	v_fmamk_f32 v32, v57, 0xba800000, v32
	v_fmac_f32_e32 v30, 0xba800000, v57
	v_mul_f32_e32 v56, v31, v31
	v_mul_f32_e32 v58, v33, v33
	v_fmamk_f32 v29, v57, 0xba800000, v29
	v_fmamk_f32 v27, v57, 0xba800000, v27
	v_fmac_f32_e32 v56, v30, v30
	v_fmac_f32_e32 v58, v32, v32
	v_fmamk_f32 v28, v57, 0xba800000, v28
	v_add_f32_e32 v56, v56, v58
	v_fmac_f32_e32 v26, 0xba800000, v57
	v_mul_f32_e32 v58, v27, v27
	v_mul_f32_e32 v59, v29, v29
	v_fmac_f32_e32 v58, v26, v26
	v_fmac_f32_e32 v59, v28, v28
	v_add_f32_e32 v58, v58, v59
	v_fmamk_f32 v25, v57, 0xba800000, v25
	v_fmamk_f32 v23, v57, 0xba800000, v23
	v_add_f32_e32 v56, v56, v58
	v_fmamk_f32 v24, v57, 0xba800000, v24
	v_fmac_f32_e32 v22, 0xba800000, v57
	v_mul_f32_e32 v58, v23, v23
	v_mul_f32_e32 v59, v25, v25
	v_fmac_f32_e32 v58, v22, v22
	v_fmac_f32_e32 v59, v24, v24
	v_add_f32_e32 v58, v58, v59
	v_fmamk_f32 v21, v57, 0xba800000, v21
	v_fmamk_f32 v19, v57, 0xba800000, v19
	v_add_f32_e32 v56, v58, v56
	v_fmamk_f32 v20, v57, 0xba800000, v20
	v_fmac_f32_e32 v18, 0xba800000, v57
	v_mul_f32_e32 v58, v19, v19
	v_mul_f32_e32 v59, v21, v21
	v_fmac_f32_e32 v58, v18, v18
	v_fmac_f32_e32 v59, v20, v20
	v_add_f32_e32 v58, v58, v59
	v_add_f32_e32 v56, v58, v56
	s_nop 1
	v_add_f32_dpp v56, v56, v56 quad_perm:[1,0,3,2] row_mask:0xf bank_mask:0xf
	s_nop 1
	v_add_f32_dpp v56, v56, v56 quad_perm:[2,3,0,1] row_mask:0xf bank_mask:0xf
	s_nop 1
	v_add_f32_dpp v56, v56, v56 row_half_mirror row_mask:0xf bank_mask:0xf
	s_nop 1
	v_add_f32_dpp v56, v56, v56 row_mirror row_mask:0xf bank_mask:0xf
	ds_bpermute_b32 v58, v60, v56
	s_waitcnt lgkmcnt(0)
	v_add_f32_e32 v56, v56, v58
	ds_bpermute_b32 v58, v61, v56
	s_waitcnt lgkmcnt(0)
	v_add_f32_e32 v56, v56, v58
	v_fmamk_f32 v56, v56, 0x3a800000, v228
	v_mul_f32_e32 v58, 0x4f800000, v56
	v_cmp_gt_f32_e32 vcc, s28, v56
	s_nop 1
	v_cndmask_b32_e32 v56, v56, v58, vcc
	v_sqrt_f32_e32 v58, v56
	s_nop 0
	v_add_u32_e32 v59, -1, v58
	v_fma_f32 v63, -v59, v58, v56
	v_add_u32_e32 v62, 1, v58
	v_cmp_ge_f32_e64 s[4:5], 0, v63
	s_nop 1
	v_cndmask_b32_e64 v59, v58, v59, s[4:5]
	v_fma_f32 v58, -v62, v58, v56
	v_cmp_lt_f32_e64 s[4:5], 0, v58
	s_nop 1
	v_cndmask_b32_e64 v58, v59, v62, s[4:5]
	v_mul_f32_e32 v59, 0x37800000, v58
	v_cndmask_b32_e32 v58, v58, v59, vcc
	v_cmp_class_f32_e32 vcc, v56, v238
	s_nop 1
	v_cndmask_b32_e32 v56, v58, v56, vcc
	v_div_scale_f32 v58, s[4:5], v56, v56, 1.0
	v_rcp_f32_e32 v59, v58
	s_nop 0
	v_fma_f32 v62, -v58, v59, 1.0
	v_fmac_f32_e32 v59, v62, v59
	v_div_scale_f32 v62, vcc, 1.0, v56, 1.0
	v_mul_f32_e32 v63, v62, v59
	v_fma_f32 v64, -v58, v63, v62
	v_fmac_f32_e32 v63, v64, v59
	v_fma_f32 v58, -v58, v63, v62
	v_div_fmas_f32 v58, v58, v59, v63
	v_div_fixup_f32 v56, v58, v56, 1.0
	s_and_saveexec_b64 s[4:5], s[0:1]
	s_cbranch_execz .LBB0_824
	v_readlane_b32 s18, v254, 36
	v_readlane_b32 s19, v254, 37
	s_add_u32 s18, s18, s15
	s_addc_u32 s19, s19, s16
	v_mul_f32_e32 v58, 0x3a800000, v57
	v_mov_b32_e32 v59, v56
	v_mov_b64_e32 v[62:63], s[18:19]
	global_store_dwordx2 v[62:63], v[58:59], off
; __device__ __forceinline__ unsigned cvt_pk_bf16(float lo, float hi) { unsigned r; asm("v_cvt_pk_bf16_f32 %0, %1, %2" : "=v"(r) : "v"(lo), "v"(hi)); return r; }
; __global__ void __launch_bounds__(512, 2) mk_fwd(Args args) {
;     ...
; #pragma unroll
;                     for (int j = 0; j < 4; ++j) { const int col = 4 * lane + 256 * j; const f32x4 y = v[j] * rstd;
;                         if (lastln) *(f32x4*)(xr + col) = y;
;                         if (!lastln) { const f32x4 sh = *(const f32x4*)(mp + col), sc = *(const f32x4*)(mp + 1024 + col); const f32x4 hv = y * (sc + 1.0f) + sh;
;                             u32x2 w; w.x = cvt_pk_bf16(hv[0], hv[1]); w.y = cvt_pk_bf16(hv[2], hv[3]); *(u32x2*)(HO + (size_t)row * DM + col) = w; } }
.LBB0_824:
	s_or_b64 exec, exec, s[4:5]
	s_and_b64 s[4:5], s[48:49], exec
	v_readlane_b32 s64, v252, 0
	s_cselect_b32 s5, s7, 0
	s_cselect_b32 s4, s6, s46
	v_readlane_b32 s76, v252, 12
	v_readlane_b32 s77, v252, 13
	s_cselect_b32 s18, s77, s41
	s_cselect_b32 s19, s76, s40
	s_lshl_b64 s[4:5], s[4:5], 12
	s_add_u32 s4, s19, s4
	s_addc_u32 s5, s18, s5
	s_min_i32 s17, s17, 0x8000
	s_ashr_i32 s17, s17, 11
	s_mul_hi_i32 s18, s17, 0x6000
	s_mulk_i32 s17, 0x6000
	s_add_u32 s48, s11, s17
	s_addc_u32 s49, s14, s18
	v_readlane_b32 s18, v254, 36
	s_add_u32 s50, s48, 0x1000
	v_readlane_b32 s19, v254, 37
	s_addc_u32 s51, s49, 0
	v_pk_mul_f32 v[32:33], v[32:33], v[56:57] op_sel_hi:[1,0]
	v_pk_mul_f32 v[30:31], v[30:31], v[56:57] op_sel_hi:[1,0]
	s_mov_b64 s[52:53], -1
	s_and_b64 vcc, exec, s[8:9]
	v_lshl_add_u64 v[58:59], s[18:19], 0, v[50:51]
	v_readlane_b32 s65, v252, 1
	v_readlane_b32 s66, v252, 2
	v_readlane_b32 s67, v252, 3
	v_readlane_b32 s68, v252, 4
	v_readlane_b32 s69, v252, 5
	v_readlane_b32 s70, v252, 6
	v_readlane_b32 s71, v252, 7
	v_readlane_b32 s72, v252, 8
	v_readlane_b32 s73, v252, 9
	v_readlane_b32 s74, v252, 10
	v_readlane_b32 s75, v252, 11
	v_readlane_b32 s78, v252, 14
	v_readlane_b32 s79, v252, 15
	s_cbranch_vccz .LBB0_826
	v_lshl_add_u64 v[66:67], s[50:51], 0, v[0:1]
	v_lshl_add_u64 v[62:63], s[48:49], 0, v[0:1]
	v_mov_b64_e32 v[66:67], v[90:91]
	v_mov_b64_e32 v[68:69], v[92:93]
	s_mov_b64 s[52:53], 0
	v_mov_b64_e32 v[62:63], v[74:75]
	v_mov_b64_e32 v[64:65], v[76:77]
	s_waitcnt lgkmcnt(0)
	v_pk_add_f32 v[68:69], v[68:69], 1.0 op_sel_hi:[1,0]
	v_pk_add_f32 v[66:67], v[66:67], 1.0 op_sel_hi:[1,0]
	v_pk_fma_f32 v[64:65], v[32:33], v[68:69], v[64:65]
	v_pk_fma_f32 v[62:63], v[30:31], v[66:67], v[62:63]
	s_nop 0
	v_cvt_pk_bf16_f32 v62, v62, v63
	v_cvt_pk_bf16_f32 v63, v64, v65
	v_add_co_u32_e32 v64, vcc, 0x7000000, v58
	s_nop 1
	v_addc_co_u32_e32 v65, vcc, 0, v59, vcc
	global_store_dwordx2 v[64:65], v[62:63], off
.LBB0_826:
	s_andn2_b64 vcc, exec, s[52:53]
	s_cbranch_vccnz .LBB0_828
	v_lshl_add_u64 v[62:63], s[4:5], 0, v[0:1]
	global_store_dwordx4 v[62:63], v[30:33], off
.LBB0_828:
	v_mov_b32_e32 v57, v56
	s_nop 0
	v_mov_b32_e32 v30, v56
	v_mov_b32_e32 v31, v56
	v_pk_mul_f32 v[28:29], v[28:29], v[30:31]
	v_pk_mul_f32 v[26:27], v[26:27], v[56:57]
	s_mov_b64 s[52:53], -1
	s_and_b64 vcc, exec, s[8:9]
	s_cbranch_vccz .LBB0_830
	v_lshlrev_b32_e32 v62, 2, v38
	v_mov_b32_e32 v63, v1
	v_lshl_add_u64 v[62:63], s[50:51], 0, v[62:63]
	v_lshl_add_u64 v[30:31], s[48:49], 0, v[0:1]
	v_mov_b64_e32 v[62:63], v[94:95]
	v_mov_b64_e32 v[64:65], v[96:97]
	s_mov_b64 s[52:53], 0
	v_mov_b64_e32 v[30:31], v[78:79]
	v_mov_b64_e32 v[32:33], v[80:81]
	s_waitcnt lgkmcnt(0)
	v_pk_add_f32 v[64:65], v[64:65], 1.0 op_sel_hi:[1,0]
	v_pk_add_f32 v[62:63], v[62:63], 1.0 op_sel_hi:[1,0]
	v_pk_fma_f32 v[32:33], v[28:29], v[64:65], v[32:33]
	v_pk_fma_f32 v[30:31], v[26:27], v[62:63], v[30:31]
	s_nop 0
	v_cvt_pk_bf16_f32 v30, v30, v31
	v_cvt_pk_bf16_f32 v31, v32, v33
	v_add_co_u32_e32 v32, vcc, 0x7000000, v58
	s_nop 1
	v_addc_co_u32_e32 v33, vcc, 0, v59, vcc
	global_store_dwordx2 v[32:33], v[30:31], off offset:512
.LBB0_830:
	s_andn2_b64 vcc, exec, s[52:53]
	s_cbranch_vccnz .LBB0_832
	v_lshl_add_u64 v[30:31], s[4:5], 0, v[0:1]
	global_store_dwordx4 v[30:31], v[26:29], off offset:1024
.LBB0_832:
	s_nop 1
	v_mov_b32_e32 v26, v56
	v_mov_b32_e32 v27, v56
	v_pk_mul_f32 v[24:25], v[24:25], v[26:27]
	v_pk_mul_f32 v[22:23], v[22:23], v[56:57]
	s_mov_b64 s[52:53], -1
	s_and_b64 vcc, exec, s[8:9]
	s_cbranch_vccz .LBB0_834
	v_lshlrev_b32_e32 v30, 2, v40
	v_mov_b32_e32 v31, v1
	v_lshl_add_u64 v[30:31], s[50:51], 0, v[30:31]
	v_lshl_add_u64 v[26:27], s[48:49], 0, v[0:1]
	v_mov_b64_e32 v[30:31], v[98:99]
	v_mov_b64_e32 v[32:33], v[100:101]
	s_mov_b64 s[52:53], 0
	v_mov_b64_e32 v[26:27], v[82:83]
	v_mov_b64_e32 v[28:29], v[84:85]
	s_waitcnt lgkmcnt(0)
	v_pk_add_f32 v[32:33], v[32:33], 1.0 op_sel_hi:[1,0]
	v_pk_add_f32 v[30:31], v[30:31], 1.0 op_sel_hi:[1,0]
	v_pk_fma_f32 v[28:29], v[24:25], v[32:33], v[28:29]
	v_pk_fma_f32 v[26:27], v[22:23], v[30:31], v[26:27]
	s_nop 0
	v_cvt_pk_bf16_f32 v26, v26, v27
	v_cvt_pk_bf16_f32 v27, v28, v29
	v_add_co_u32_e32 v28, vcc, 0x7000000, v58
	s_nop 1
	v_addc_co_u32_e32 v29, vcc, 0, v59, vcc
	global_store_dwordx2 v[28:29], v[26:27], off offset:1024
.LBB0_834:
	s_andn2_b64 vcc, exec, s[52:53]
	s_cbranch_vccnz .LBB0_836
	v_lshl_add_u64 v[26:27], s[4:5], 0, v[0:1]
	global_store_dwordx4 v[26:27], v[22:25], off offset:2048

; __device__ __forceinline__ unsigned cvt_pk_bf16(float lo, float hi) { unsigned r; asm("v_cvt_pk_bf16_f32 %0, %1, %2" : "=v"(r) : "v"(lo), "v"(hi)); return r; }
; __global__ void __launch_bounds__(512, 2) mk_fwd(Args args) {
;     ...
;                     float s = 0.f;
; #pragma unroll
;                     for (int j = 0; j < 4; ++j) s += (v[j][0] + v[j][1]) + (v[j][2] + v[j][3]);
;                     const float mean = wave_sum(s) * (1.0f / DM); float s2 = 0.f;
; #pragma unroll
;                     for (int j = 0; j < 4; ++j) { v[j] = v[j] - mean; s2 += (v[j][0] * v[j][0] + v[j][1] * v[j][1]) + (v[j][2] * v[j][2] + v[j][3] * v[j][3]); }
;                     const float rstd = 1.0f / sqrtf(wave_sum(s2) * (1.0f / DM) + LN_EPS);
;                     if (lane == 0) { STAT[2 * (size_t)row] = mean; STAT[2 * (size_t)row + 1] = rstd; }
; #pragma unroll
;                     for (int j = 0; j < 4; ++j) { const int col = 4 * lane + 256 * j; const f32x4 y = v[j] * rstd;
;                         if (lastln) *(f32x4*)(xr + col) = y;
;                         if (!lastln) { const f32x4 sh = *(const f32x4*)(mp + col), sc = *(const f32x4*)(mp + 1024 + col); const f32x4 hv = y * (sc + 1.0f) + sh;
;                             u32x2 w; w.x = cvt_pk_bf16(hv[0], hv[1]); w.y = cvt_pk_bf16(hv[2], hv[3]); *(u32x2*)(HO + (size_t)row * DM + col) = w; } }
.LBB0_839:
	v_lshlrev_b32_e32 v22, 2, v42
	v_mov_b32_e32 v23, v1
	v_lshl_add_u64 v[22:23], s[50:51], 0, v[22:23]
	v_mov_b64_e32 v[22:23], v[102:103]
	v_mov_b64_e32 v[24:25], v[104:105]
	v_lshl_add_u64 v[26:27], s[48:49], 0, v[0:1]
	v_mov_b64_e32 v[26:27], v[86:87]
	v_mov_b64_e32 v[28:29], v[88:89]
	v_add_co_u32_e32 v30, vcc, 0x7000000, v58
	s_nop 1
	v_addc_co_u32_e32 v31, vcc, 0, v59, vcc
	s_waitcnt lgkmcnt(0)
	v_pk_add_f32 v[22:23], v[22:23], 1.0 op_sel_hi:[1,0]
	v_pk_add_f32 v[24:25], v[24:25], 1.0 op_sel_hi:[1,0]
	v_pk_fma_f32 v[22:23], v[18:19], v[22:23], v[26:27]
	v_pk_fma_f32 v[24:25], v[20:21], v[24:25], v[28:29]
	v_cvt_pk_bf16_f32 v22, v22, v23
	s_nop 0
	v_cvt_pk_bf16_f32 v23, v24, v25
	global_store_dwordx2 v[30:31], v[22:23], off offset:1536
	s_cbranch_execnz .LBB0_838
.LBB0_840:
	v_lshl_add_u64 v[22:23], s[4:5], 0, v[0:1]
	global_store_dwordx4 v[22:23], v[18:21], off offset:3072
	s_andn2_b64 vcc, exec, s[94:95]
	s_cbranch_vccnz .LBB0_813
.LBB0_841:
	v_mov_b32_e32 v18, v11
	v_mov_b32_e32 v19, v12
	v_mov_b32_e32 v20, v10
	v_mov_b32_e32 v21, v13
	v_pk_add_f32 v[18:19], v[18:19], v[20:21]
	v_mov_b32_e32 v20, v7
	v_mov_b32_e32 v21, v8
	v_mov_b32_e32 v22, v6
	v_mov_b32_e32 v23, v9
	v_pk_add_f32 v[20:21], v[20:21], v[22:23]
	v_add_f32_e32 v18, v18, v19
	v_pk_add_f32 v[20:21], v[20:21], v[20:21] op_sel_hi:[0,1]
	v_add_f32_e32 v19, 0, v18
	v_add_f32_e32 v23, v2, v3
	v_add_f32_e32 v25, v4, v5
	v_mov_b32_e32 v22, v14
	v_mov_b32_e32 v24, v15
	v_mov_b32_e32 v20, v16
	v_mov_b32_e32 v18, v17
	v_pk_add_f32 v[14:15], v[22:23], v[24:25]
	v_pk_add_f32 v[16:17], v[20:21], v[18:19]
	s_ashr_i32 s91, s90, 31
	v_pk_add_f32 v[14:15], v[14:15], v[16:17]
	s_nop 0
	v_add_f32_e32 v14, v14, v15
	s_nop 1
	v_add_f32_dpp v14, v14, v14 quad_perm:[1,0,3,2] row_mask:0xf bank_mask:0xf
	s_nop 1
	v_add_f32_dpp v14, v14, v14 quad_perm:[2,3,0,1] row_mask:0xf bank_mask:0xf
	s_nop 1
	v_add_f32_dpp v14, v14, v14 row_half_mirror row_mask:0xf bank_mask:0xf
	s_nop 1
	v_add_f32_dpp v14, v14, v14 row_mirror row_mask:0xf bank_mask:0xf
	ds_bpermute_b32 v15, v60, v14
	s_waitcnt lgkmcnt(0)
	v_add_f32_e32 v14, v14, v15
	ds_bpermute_b32 v15, v61, v14
	s_waitcnt lgkmcnt(0)
	v_add_f32_e32 v15, v14, v15
	v_fmac_f32_e32 v13, 0xba800000, v15
	v_fmac_f32_e32 v11, 0xba800000, v15
	v_fmac_f32_e32 v12, 0xba800000, v15
	v_fmac_f32_e32 v10, 0xba800000, v15
	v_mul_f32_e32 v14, v11, v11
	v_mul_f32_e32 v16, v13, v13
	v_fmac_f32_e32 v9, 0xba800000, v15
	v_fmac_f32_e32 v7, 0xba800000, v15
	v_fmac_f32_e32 v14, v10, v10
	v_fmac_f32_e32 v16, v12, v12
	v_fmac_f32_e32 v8, 0xba800000, v15
	v_add_f32_e32 v14, v14, v16
	v_fmac_f32_e32 v6, 0xba800000, v15
	v_mul_f32_e32 v16, v7, v7
	v_mul_f32_e32 v17, v9, v9
	v_fmac_f32_e32 v16, v6, v6
	v_fmac_f32_e32 v17, v8, v8
	v_add_f32_e32 v16, v16, v17
	v_fmac_f32_e32 v5, 0xba800000, v15
	v_fmac_f32_e32 v3, 0xba800000, v15
	v_add_f32_e32 v14, v14, v16
	v_fmac_f32_e32 v4, 0xba800000, v15
	v_fmac_f32_e32 v2, 0xba800000, v15
	v_mul_f32_e32 v16, v3, v3
	v_mul_f32_e32 v17, v5, v5
	v_fmac_f32_e32 v16, v2, v2
	v_fmac_f32_e32 v17, v4, v4
	v_add_f32_e32 v16, v16, v17
	v_fmac_f32_e32 v53, 0xba800000, v15
	v_fmac_f32_e32 v55, 0xba800000, v15
	v_add_f32_e32 v14, v16, v14
	v_fmac_f32_e32 v52, 0xba800000, v15
	v_fmac_f32_e32 v54, 0xba800000, v15
	v_mul_f32_e32 v16, v55, v55
	v_mul_f32_e32 v17, v53, v53
	v_fmac_f32_e32 v16, v54, v54
	v_fmac_f32_e32 v17, v52, v52
	v_add_f32_e32 v16, v16, v17
	v_add_f32_e32 v14, v16, v14
	s_nop 1
	v_add_f32_dpp v14, v14, v14 quad_perm:[1,0,3,2] row_mask:0xf bank_mask:0xf
	s_nop 1
	v_add_f32_dpp v14, v14, v14 quad_perm:[2,3,0,1] row_mask:0xf bank_mask:0xf
	s_nop 1
	v_add_f32_dpp v14, v14, v14 row_half_mirror row_mask:0xf bank_mask:0xf
	s_nop 1
	v_add_f32_dpp v14, v14, v14 row_mirror row_mask:0xf bank_mask:0xf
	ds_bpermute_b32 v16, v60, v14
	s_waitcnt lgkmcnt(0)
	v_add_f32_e32 v14, v14, v16
	ds_bpermute_b32 v16, v61, v14
	s_waitcnt lgkmcnt(0)
	v_add_f32_e32 v14, v14, v16
	v_fmamk_f32 v14, v14, 0x3a800000, v228
	v_mul_f32_e32 v16, 0x4f800000, v14
	v_cmp_gt_f32_e32 vcc, s28, v14
	s_nop 1
	v_cndmask_b32_e32 v14, v14, v16, vcc
	v_sqrt_f32_e32 v16, v14
	s_nop 0
	v_add_u32_e32 v17, -1, v16
	v_fma_f32 v19, -v17, v16, v14
	v_add_u32_e32 v18, 1, v16
	v_cmp_ge_f32_e64 s[4:5], 0, v19
	s_nop 1
	v_cndmask_b32_e64 v17, v16, v17, s[4:5]
	v_fma_f32 v16, -v18, v16, v14
	v_cmp_lt_f32_e64 s[4:5], 0, v16
	s_nop 1
	v_cndmask_b32_e64 v16, v17, v18, s[4:5]
	v_mul_f32_e32 v17, 0x37800000, v16
	v_cndmask_b32_e32 v16, v16, v17, vcc
	v_cmp_class_f32_e32 vcc, v14, v238
	s_nop 1
	v_cndmask_b32_e32 v14, v16, v14, vcc
	v_div_scale_f32 v16, s[4:5], v14, v14, 1.0
	v_rcp_f32_e32 v17, v16
	s_nop 0
	v_fma_f32 v18, -v16, v17, 1.0
	v_fmac_f32_e32 v17, v18, v17
	v_div_scale_f32 v18, vcc, 1.0, v14, 1.0
	v_mul_f32_e32 v19, v18, v17
	v_fma_f32 v20, -v16, v19, v18
	v_fmac_f32_e32 v19, v20, v17
	v_fma_f32 v16, -v16, v19, v18
	v_div_fmas_f32 v16, v16, v17, v19
	v_div_fixup_f32 v14, v16, v14, 1.0
	s_and_saveexec_b64 s[4:5], s[0:1]
	s_cbranch_execz .LBB0_843
	s_lshl_b64 s[18:19], s[90:91], 3
	s_add_u32 s18, s42, s18
	s_addc_u32 s19, s43, s19
	v_mul_f32_e32 v16, 0x3a800000, v15
	v_mov_b32_e32 v17, v14
	v_mov_b64_e32 v[18:19], s[18:19]
	global_store_dwordx2 v[18:19], v[16:17], off
; __device__ __forceinline__ unsigned cvt_pk_bf16(float lo, float hi) { unsigned r; asm("v_cvt_pk_bf16_f32 %0, %1, %2" : "=v"(r) : "v"(lo), "v"(hi)); return r; }
; __global__ void __launch_bounds__(512, 2) mk_fwd(Args args) {
;     ...
; #pragma unroll
;                     for (int j = 0; j < 4; ++j) { const int col = 4 * lane + 256 * j; const f32x4 y = v[j] * rstd;
;                         if (lastln) *(f32x4*)(xr + col) = y;
;                         if (!lastln) { const f32x4 sh = *(const f32x4*)(mp + col), sc = *(const f32x4*)(mp + 1024 + col); const f32x4 hv = y * (sc + 1.0f) + sh;
;                             u32x2 w; w.x = cvt_pk_bf16(hv[0], hv[1]); w.y = cvt_pk_bf16(hv[2], hv[3]); *(u32x2*)(HO + (size_t)row * DM + col) = w; } }
.LBB0_843:
	s_or_b64 exec, exec, s[4:5]
	s_cmp_lt_i32 s90, 0x8000
	v_readlane_b32 s64, v252, 0
	s_cselect_b32 s5, s91, 0
	s_cselect_b32 s4, s90, s92
	v_readlane_b32 s76, v252, 12
	v_readlane_b32 s77, v252, 13
	s_cselect_b32 s17, s77, s41
	s_cselect_b32 s18, s76, s40
	s_lshl_b64 s[4:5], s[4:5], 12
	s_add_u32 s4, s18, s4
	s_addc_u32 s5, s17, s5
	s_min_i32 s17, s90, 0x8000
	s_ashr_i32 s17, s17, 11
	s_mul_hi_i32 s18, s17, 0x6000
	s_mulk_i32 s17, 0x6000
	s_add_u32 s52, s11, s17
	s_addc_u32 s53, s14, s18
	s_add_u32 s50, s52, 0x1000
	s_addc_u32 s51, s53, 0
	s_lshl_b64 s[48:49], s[90:91], 11
	v_pk_mul_f32 v[12:13], v[12:13], v[14:15] op_sel_hi:[1,0]
	v_pk_mul_f32 v[10:11], v[10:11], v[14:15] op_sel_hi:[1,0]
	s_mov_b64 s[54:55], -1
	s_and_b64 vcc, exec, s[8:9]
	v_readlane_b32 s65, v252, 1
	v_readlane_b32 s66, v252, 2
	v_readlane_b32 s67, v252, 3
	v_readlane_b32 s68, v252, 4
	v_readlane_b32 s69, v252, 5
	v_readlane_b32 s70, v252, 6
	v_readlane_b32 s71, v252, 7
	v_readlane_b32 s72, v252, 8
	v_readlane_b32 s73, v252, 9
	v_readlane_b32 s74, v252, 10
	v_readlane_b32 s75, v252, 11
	v_readlane_b32 s78, v252, 14
	v_readlane_b32 s79, v252, 15
	s_cbranch_vccz .LBB0_845
	v_lshl_add_u64 v[20:21], s[50:51], 0, v[0:1]
	v_lshl_add_u64 v[16:17], s[52:53], 0, v[0:1]
	v_mov_b64_e32 v[20:21], v[122:123]
	v_mov_b64_e32 v[22:23], v[124:125]
	s_mov_b64 s[54:55], 0
	v_mov_b64_e32 v[16:17], v[106:107]
	v_mov_b64_e32 v[18:19], v[108:109]
	s_waitcnt lgkmcnt(0)
	v_pk_add_f32 v[22:23], v[22:23], 1.0 op_sel_hi:[1,0]
	v_pk_add_f32 v[20:21], v[20:21], 1.0 op_sel_hi:[1,0]
	v_pk_fma_f32 v[18:19], v[12:13], v[22:23], v[18:19]
	v_pk_fma_f32 v[16:17], v[10:11], v[20:21], v[16:17]
	s_nop 0
	v_cvt_pk_bf16_f32 v16, v16, v17
	v_cvt_pk_bf16_f32 v17, v18, v19
	v_lshl_add_u64 v[18:19], v[36:37], 0, s[48:49]
	global_store_dwordx2 v[18:19], v[16:17], off
.LBB0_845:
	s_andn2_b64 vcc, exec, s[54:55]
	s_cbranch_vccnz .LBB0_847
	v_lshl_add_u64 v[16:17], s[4:5], 0, v[0:1]
	global_store_dwordx4 v[16:17], v[10:13], off
.LBB0_847:
	v_mov_b32_e32 v15, v14
	s_nop 0
	v_mov_b32_e32 v10, v14
	v_mov_b32_e32 v11, v14
	v_pk_mul_f32 v[8:9], v[8:9], v[10:11]
	v_pk_mul_f32 v[6:7], v[6:7], v[14:15]
	s_mov_b64 s[54:55], -1
	s_and_b64 vcc, exec, s[8:9]
	s_cbranch_vccz .LBB0_849
	v_lshlrev_b32_e32 v16, 2, v38
	v_mov_b32_e32 v17, v1
	v_lshl_add_u64 v[16:17], s[50:51], 0, v[16:17]
	v_lshl_add_u64 v[10:11], s[52:53], 0, v[0:1]
	v_mov_b64_e32 v[16:17], v[126:127]
	v_mov_b64_e32 v[18:19], v[128:129]
	s_mov_b64 s[54:55], 0
	v_mov_b64_e32 v[10:11], v[110:111]
	v_mov_b64_e32 v[12:13], v[112:113]
	s_waitcnt lgkmcnt(0)
	v_pk_add_f32 v[18:19], v[18:19], 1.0 op_sel_hi:[1,0]
	v_pk_add_f32 v[16:17], v[16:17], 1.0 op_sel_hi:[1,0]
	v_pk_fma_f32 v[12:13], v[8:9], v[18:19], v[12:13]
	v_pk_fma_f32 v[10:11], v[6:7], v[16:17], v[10:11]
	s_nop 0
	v_cvt_pk_bf16_f32 v10, v10, v11
	v_cvt_pk_bf16_f32 v11, v12, v13
	v_lshl_add_u64 v[12:13], v[44:45], 0, s[48:49]
	global_store_dwordx2 v[12:13], v[10:11], off
.LBB0_849:
	s_andn2_b64 vcc, exec, s[54:55]
	s_cbranch_vccnz .LBB0_851
	v_lshl_add_u64 v[10:11], s[4:5], 0, v[0:1]
	global_store_dwordx4 v[10:11], v[6:9], off offset:1024
.LBB0_851:
	s_nop 1
	v_mov_b32_e32 v6, v14
	v_mov_b32_e32 v7, v14
	v_pk_mul_f32 v[4:5], v[4:5], v[6:7]
	v_pk_mul_f32 v[2:3], v[2:3], v[14:15]
	s_mov_b64 s[54:55], -1
	s_and_b64 vcc, exec, s[8:9]
	s_cbranch_vccz .LBB0_853
	v_lshlrev_b32_e32 v10, 2, v40
	v_mov_b32_e32 v11, v1
	v_lshl_add_u64 v[10:11], s[50:51], 0, v[10:11]
	v_lshl_add_u64 v[6:7], s[52:53], 0, v[0:1]
	v_mov_b64_e32 v[10:11], v[130:131]
	v_mov_b64_e32 v[12:13], v[132:133]
	s_mov_b64 s[54:55], 0
	v_mov_b64_e32 v[6:7], v[114:115]
	v_mov_b64_e32 v[8:9], v[116:117]
	s_waitcnt lgkmcnt(0)
	v_pk_add_f32 v[12:13], v[12:13], 1.0 op_sel_hi:[1,0]
	v_pk_add_f32 v[10:11], v[10:11], 1.0 op_sel_hi:[1,0]
	v_pk_fma_f32 v[8:9], v[4:5], v[12:13], v[8:9]
	v_pk_fma_f32 v[6:7], v[2:3], v[10:11], v[6:7]
	s_nop 0
	v_cvt_pk_bf16_f32 v6, v6, v7
	v_cvt_pk_bf16_f32 v7, v8, v9
	v_lshl_add_u64 v[8:9], v[46:47], 0, s[48:49]
	global_store_dwordx2 v[8:9], v[6:7], off
.LBB0_853:
	s_andn2_b64 vcc, exec, s[54:55]
	s_cbranch_vccnz .LBB0_855
	v_lshl_add_u64 v[6:7], s[4:5], 0, v[0:1]
	global_store_dwordx4 v[6:7], v[2:5], off offset:2048
.LBB0_855:
	s_nop 1
	v_mov_b32_e32 v2, v14
	v_mov_b32_e32 v3, v14
	v_pk_mul_f32 v[4:5], v[52:53], v[2:3]
	v_pk_mul_f32 v[2:3], v[54:55], v[14:15]
	s_mov_b64 s[54:55], -1
	s_and_b64 vcc, exec, s[8:9]
	s_cbranch_vccz .LBB0_857
	v_lshlrev_b32_e32 v10, 2, v42
	v_mov_b32_e32 v11, v1
	v_lshl_add_u64 v[10:11], s[50:51], 0, v[10:11]
	v_lshl_add_u64 v[6:7], s[52:53], 0, v[0:1]
	v_mov_b64_e32 v[10:11], v[134:135]
	v_mov_b64_e32 v[12:13], v[136:137]
	s_mov_b64 s[54:55], 0
	v_mov_b64_e32 v[6:7], v[118:119]
	v_mov_b64_e32 v[8:9], v[120:121]
	s_waitcnt lgkmcnt(0)
	v_pk_add_f32 v[12:13], v[12:13], 1.0 op_sel_hi:[1,0]
	v_pk_add_f32 v[10:11], v[10:11], 1.0 op_sel_hi:[1,0]
	v_pk_fma_f32 v[8:9], v[4:5], v[12:13], v[8:9]
	v_pk_fma_f32 v[6:7], v[2:3], v[10:11], v[6:7]
	s_nop 0
	v_cvt_pk_bf16_f32 v6, v6, v7
	v_cvt_pk_bf16_f32 v7, v8, v9
	v_lshl_add_u64 v[8:9], v[48:49], 0, s[48:49]
	global_store_dwordx2 v[8:9], v[6:7], off
.LBB0_857:
	s_andn2_b64 vcc, exec, s[54:55]
	s_cbranch_vccnz .LBB0_813
	v_lshl_add_u64 v[6:7], s[4:5], 0, v[0:1]
	global_store_dwordx4 v[6:7], v[2:5], off offset:3072
	s_branch .LBB0_813
